# d4 + sc1 (write-through) on all global stores to cheapen the L2 writeback at the grid-barrier seams
# baseline (speedup 1.0000x reference)
; #define LAS __attribute__((address_space(3)))
; __device__ __forceinline__ unsigned cvtpk(float lo, float hi) { f32x2 v = {lo, hi}; bf16x2_t b = __builtin_convertvector(v, bf16x2_t); return __builtin_bit_cast(unsigned, b); }
; __device__ __forceinline__ void transpose_item(const float* W, int ldw, int k0, int srccol0, const float* gain, bf16_t* dst, int dpitch, int drow0, int dk0, LAS float* scr, int lane) {
;     ...
;     for (int i = 0; i < 32; ++i) { const int kk = 2 * i + (lane >> 5); scr[kk * 33 + (lane & 31)] = tv[i]; }
;     asm volatile("s_waitcnt lgkmcnt(0)" ::: "memory");
;     const int c = lane & 7;
; #pragma unroll
;     for (int j = 0; j < 4; ++j) { const int n = (lane >> 3) + 8 * j; const LAS float* s = scr + (8 * c) * 33 + n;
;         u32x4 o; o.x = wq(cvtpk(s[0 * 33], s[1 * 33])); o.y = wq(cvtpk(s[2 * 33], s[3 * 33])); o.z = wq(cvtpk(s[4 * 33], s[5 * 33])); o.w = wq(cvtpk(s[6 * 33], s[7 * 33]));
;         *(u32x4*)(dst + (size_t)(drow0 + n) * dpitch + dk0 + k0 + 8 * c) = o; }
;     asm volatile("s_waitcnt lgkmcnt(0)" ::: "memory");
.LBB0_12:
	s_and_b64 s[50:51], s[50:51], exec
	s_mov_b32 s9, 0x600000
	s_waitcnt vmcnt(30)
	ds_write2_b32 v48, v14, v15 offset1:66
	s_waitcnt vmcnt(28)
	ds_write2_b32 v48, v16, v17 offset0:132 offset1:198
	s_waitcnt vmcnt(26)
	ds_write2_b32 v54, v18, v19 offset0:8 offset1:74
	s_waitcnt vmcnt(24)
	ds_write2_b32 v54, v20, v21 offset0:140 offset1:206
	s_waitcnt vmcnt(22)
	ds_write2_b32 v55, v22, v23 offset0:16 offset1:82
	s_waitcnt vmcnt(20)
	ds_write2_b32 v55, v24, v25 offset0:148 offset1:214
	s_waitcnt vmcnt(18)
	ds_write2_b32 v56, v26, v27 offset0:24 offset1:90
	s_waitcnt vmcnt(16)
	ds_write2_b32 v56, v28, v29 offset0:156 offset1:222
	s_waitcnt vmcnt(14)
	ds_write2_b32 v57, v30, v31 offset0:32 offset1:98
	s_waitcnt vmcnt(12)
	ds_write2_b32 v57, v32, v33 offset0:164 offset1:230
	s_waitcnt vmcnt(10)
	ds_write2_b32 v58, v34, v35 offset0:40 offset1:106
	s_waitcnt vmcnt(8)
	ds_write2_b32 v58, v36, v37 offset0:172 offset1:238
	s_waitcnt vmcnt(6)
	ds_write2_b32 v59, v38, v39 offset0:48 offset1:114
	s_waitcnt vmcnt(4)
	ds_write2_b32 v59, v40, v41 offset0:180 offset1:246
	s_waitcnt vmcnt(2)
	ds_write2_b32 v60, v44, v45 offset0:56 offset1:122
	s_waitcnt vmcnt(0)
	ds_write2_b32 v60, v42, v43 offset0:188 offset1:254
	s_cselect_b32 s9, s9, 0x2380000
	s_waitcnt lgkmcnt(0)
	s_add_u32 s50, s74, s9
	ds_read2_b32 v[18:19], v50 offset0:33 offset1:41
	ds_read2_b32 v[20:21], v50 offset1:8
	s_addc_u32 s51, s75, 0
	s_ashr_i32 s9, s8, 31
	s_lshl_b64 s[8:9], s[8:9], 1
	ds_read2_b32 v[22:23], v50 offset0:66 offset1:74
	ds_read2_b32 v[24:25], v50 offset0:99 offset1:107
	s_add_u32 s8, s50, s8
	s_addc_u32 s9, s51, s9
	v_mov_b32_e32 v13, v3
	ds_read2_b32 v[28:29], v50 offset0:132 offset1:140
	ds_read2_b32 v[30:31], v50 offset0:165 offset1:173
	v_lshl_add_u64 v[26:27], s[8:9], 0, v[12:13]
	s_waitcnt lgkmcnt(4)
	v_cvt_pk_bf16_f32 v13, v20, v18
	v_add_u32_e32 v13, 0x20002, v13
	ds_read2_b32 v[32:33], v50 offset0:198 offset1:206
	ds_read2_b32 v[34:35], v50 offset0:231 offset1:239
	v_and_b32_e32 v14, 0xfffcfffc, v13
	s_waitcnt lgkmcnt(4)
	v_cvt_pk_bf16_f32 v13, v22, v24
	v_add_u32_e32 v13, 0x20002, v13
	v_and_b32_e32 v15, 0xfffcfffc, v13
	s_waitcnt lgkmcnt(2)
	v_cvt_pk_bf16_f32 v13, v28, v30
	v_add_u32_e32 v13, 0x20002, v13
	v_and_b32_e32 v16, 0xfffcfffc, v13
	s_waitcnt lgkmcnt(0)
	v_cvt_pk_bf16_f32 v13, v32, v34
	v_or_b32_e32 v36, s2, v49
	v_add_u32_e32 v13, 0x20002, v13
	v_ashrrev_i32_e32 v37, 31, v36
	v_and_b32_e32 v17, 0xfffcfffc, v13
	v_lshlrev_b64 v[36:37], 11, v[36:37]
	v_cvt_pk_bf16_f32 v13, v21, v19
	v_lshl_add_u64 v[36:37], v[26:27], 0, v[36:37]
	v_add_u32_e32 v13, 0x20002, v13
	global_store_dwordx4 v[36:37], v[14:17], off sc1
	v_or_b32_e32 v18, s2, v51
	v_ashrrev_i32_e32 v19, 31, v18
	v_and_b32_e32 v14, 0xfffcfffc, v13
	v_cvt_pk_bf16_f32 v13, v23, v25
	v_add_u32_e32 v13, 0x20002, v13
	v_and_b32_e32 v15, 0xfffcfffc, v13
	v_cvt_pk_bf16_f32 v13, v29, v31
	v_add_u32_e32 v13, 0x20002, v13
	v_and_b32_e32 v16, 0xfffcfffc, v13
	v_cvt_pk_bf16_f32 v13, v33, v35
	ds_read2_b32 v[20:21], v50 offset0:49 offset1:57
	ds_read2_b32 v[22:23], v50 offset0:16 offset1:24
	v_add_u32_e32 v13, 0x20002, v13
	v_lshlrev_b64 v[18:19], 11, v[18:19]
	v_and_b32_e32 v17, 0xfffcfffc, v13
	v_lshl_add_u64 v[18:19], v[26:27], 0, v[18:19]
	ds_read2_b32 v[24:25], v50 offset0:82 offset1:90
	ds_read2_b32 v[28:29], v50 offset0:115 offset1:123
	global_store_dwordx4 v[18:19], v[14:17], off sc1
	ds_read2_b32 v[18:19], v50 offset0:148 offset1:156
	ds_read2_b32 v[30:31], v50 offset0:181 offset1:189
	s_waitcnt lgkmcnt(4)
	v_cvt_pk_bf16_f32 v13, v22, v20
	v_add_u32_e32 v13, 0x20002, v13
	ds_read2_b32 v[32:33], v50 offset0:214 offset1:222
	ds_read2_b32 v[34:35], v50 offset0:247 offset1:255
	v_and_b32_e32 v14, 0xfffcfffc, v13
	s_waitcnt lgkmcnt(4)
	v_cvt_pk_bf16_f32 v13, v24, v28
	v_add_u32_e32 v13, 0x20002, v13
	v_and_b32_e32 v15, 0xfffcfffc, v13
	s_waitcnt lgkmcnt(2)
	v_cvt_pk_bf16_f32 v13, v18, v30
	v_add_u32_e32 v13, 0x20002, v13
	v_and_b32_e32 v16, 0xfffcfffc, v13
	s_waitcnt lgkmcnt(0)
	v_cvt_pk_bf16_f32 v13, v32, v34
	v_or_b32_e32 v36, s2, v52
	v_add_u32_e32 v13, 0x20002, v13
	v_ashrrev_i32_e32 v37, 31, v36
	v_and_b32_e32 v17, 0xfffcfffc, v13
	v_lshlrev_b64 v[36:37], 11, v[36:37]
	v_cvt_pk_bf16_f32 v13, v23, v21
	v_lshl_add_u64 v[36:37], v[26:27], 0, v[36:37]
	v_add_u32_e32 v13, 0x20002, v13
	global_store_dwordx4 v[36:37], v[14:17], off sc1
	v_or_b32_e32 v18, s2, v53
	s_nop 0
	v_and_b32_e32 v14, 0xfffcfffc, v13
	v_cvt_pk_bf16_f32 v13, v25, v29
	v_add_u32_e32 v13, 0x20002, v13
	v_and_b32_e32 v15, 0xfffcfffc, v13
	v_cvt_pk_bf16_f32 v13, v19, v31
	v_add_u32_e32 v13, 0x20002, v13
	v_and_b32_e32 v16, 0xfffcfffc, v13
	v_cvt_pk_bf16_f32 v13, v33, v35
	v_ashrrev_i32_e32 v19, 31, v18
	v_add_u32_e32 v13, 0x20002, v13
	v_lshlrev_b64 v[18:19], 11, v[18:19]
	v_and_b32_e32 v17, 0xfffcfffc, v13
	v_lshl_add_u64 v[18:19], v[26:27], 0, v[18:19]
	global_store_dwordx4 v[18:19], v[14:17], off sc1
	s_waitcnt lgkmcnt(0)

; __device__ __forceinline__ int map_win(int n) { if (n < 1024 || n >= 2048) return n; const int pn = n >> 8, p = n & 255, bj = p >> 7, wc = (p & 127) >> 5, j = p & 31; return 256 * pn + 64 * wc + 32 * bj + j; }
; __device__ __forceinline__ void transpose_item(const float* W, int ldw, int k0, int srccol0, const float* gain, bf16_t* dst, int dpitch, int drow0, int dk0, LAS float* scr, int lane) {
;     ...
;     for (int i = 0; i < 32; ++i) { const int kk = 2 * i + (lane >> 5); tv[i] = W[(size_t)(k0 + kk) * ldw + srccol0 + (lane & 31)]; }
;     if (gain) {
; #pragma unroll
;         for (int i = 0; i < 32; ++i) tv[i] *= gain[k0 + 2 * i + (lane >> 5)];
; __device__ __forceinline__ void prologue(const Params& P, LAS unsigned char* lds, int gw, int NGW, int wave, int lane) {
;     ...
;     for (int it = gw; it < NITEMS; it += NGW) {
;         int r = it;
;         if (r < 2 * I_IN) { const int w = r / I_IN; r -= w * I_IN; const int kb = r / 176, nb = r % 176;
;             transpose_item(P.in[w ? 23 : 4], 2 * DFF, 64 * kb, map_ffn_in(32 * nb), P.in[w ? 22 : 3], (bf16_t*)(ws + (w ? WS_W2IN : WS_W1IN)), 1024, 32 * nb, 0, scr, lane); continue; }
;         r -= 2 * I_IN;
;         if (r < 2 * I_OUT) { const int w = r / I_OUT; r -= w * I_OUT; const int kb = r / 32, nb = r % 32;
;             transpose_item(P.in[w ? 24 : 5], DM, 64 * kb, 32 * nb, nullptr, (bf16_t*)(ws + (w ? WS_W2OUT : WS_W1OUT)), DFF, 32 * nb, 0, scr, lane); continue; }
;         r -= 2 * I_OUT;
;         if (r < I_WIN) { const int kb = r / 144, nb = r % 144;
;             transpose_item(P.in[7], NIN, 64 * kb, map_win(32 * nb), P.in[6], (bf16_t*)(ws + WS_WIN), 1024, 32 * nb, 0, scr, lane); continue; }
;         r -= I_WIN;
;         if (r < 2 * I_P) { const int w = r / I_P; r -= w * I_P; const int kb = r / 32, nb = r % 32;
;             transpose_item(P.in[w ? 20 : 19], DM, 64 * kb, 32 * nb, nullptr, (bf16_t*)(ws + WS_WP), 1024, 32 * nb, w ? 512 : 0, scr, lane); continue; }
;         r -= 2 * I_P;
;         { const int kb = r / 32, nb = r % 32; transpose_item(P.in[21], DM, 64 * kb, 32 * nb, nullptr, (bf16_t*)(ws + WS_WO), 1024, 32 * nb, 0, scr, lane); }
.LBB0_14:
	s_cmpk_gt_i32 s92, 0x15ff
	s_mov_b64 s[8:9], -1
	s_cbranch_scc0 .LBB0_30
	s_cmpk_gt_u32 s92, 0x20ff
	s_cbranch_scc0 .LBB0_27
	s_cmpk_gt_u32 s92, 0x29ff
	s_cbranch_scc0 .LBB0_22
	s_cmpk_gt_u32 s92, 0x2bff
	s_cbranch_scc0 .LBB0_19
	s_and_b32 s2, s77, 0x7fffffc0
	s_add_i32 s8, s2, 0xffffa800
	s_and_b32 s50, s79, 0x3e0
	v_or_b32_e32 v14, s8, v1
	s_lshl_b32 s2, s50, 2
	v_mov_b32_e32 v15, v3
	v_or_b32_e32 v20, 2, v14
	v_mov_b32_e32 v21, v3
	v_or_b32_e32 v22, 4, v14
	v_mov_b32_e32 v23, v3
	v_or_b32_e32 v24, 6, v14
	v_mov_b32_e32 v25, v3
	v_or_b32_e32 v26, 8, v14
	v_mov_b32_e32 v27, v3
	v_or_b32_e32 v28, 10, v14
	v_mov_b32_e32 v29, v3
	v_or_b32_e32 v30, 12, v14
	v_mov_b32_e32 v31, v3
	v_or_b32_e32 v32, 14, v14
	v_mov_b32_e32 v33, v3
	v_lshl_add_u64 v[16:17], v[8:9], 0, s[2:3]
	v_lshlrev_b64 v[18:19], 12, v[14:15]
	v_lshlrev_b64 v[20:21], 12, v[20:21]
	v_lshlrev_b64 v[22:23], 12, v[22:23]
	v_lshlrev_b64 v[24:25], 12, v[24:25]
	v_lshlrev_b64 v[26:27], 12, v[26:27]
	v_lshlrev_b64 v[28:29], 12, v[28:29]
	v_lshlrev_b64 v[30:31], 12, v[30:31]
	v_lshlrev_b64 v[32:33], 12, v[32:33]
	v_lshl_add_u64 v[18:19], v[16:17], 0, v[18:19]
	v_lshl_add_u64 v[20:21], v[16:17], 0, v[20:21]
	v_lshl_add_u64 v[22:23], v[16:17], 0, v[22:23]
	v_lshl_add_u64 v[24:25], v[16:17], 0, v[24:25]
	v_lshl_add_u64 v[26:27], v[16:17], 0, v[26:27]
	v_lshl_add_u64 v[28:29], v[16:17], 0, v[28:29]
	v_lshl_add_u64 v[30:31], v[16:17], 0, v[30:31]
	v_lshl_add_u64 v[32:33], v[16:17], 0, v[32:33]
	global_load_dword v13, v[18:19], off
	global_load_dword v34, v[20:21], off
	global_load_dword v35, v[22:23], off
	global_load_dword v36, v[24:25], off
	global_load_dword v37, v[26:27], off
	global_load_dword v38, v[28:29], off
	global_load_dword v39, v[30:31], off
	global_load_dword v40, v[32:33], off
	v_or_b32_e32 v18, 16, v14
	v_mov_b32_e32 v19, v3
	v_or_b32_e32 v20, 18, v14
	v_mov_b32_e32 v21, v3
	v_or_b32_e32 v22, 20, v14
	v_mov_b32_e32 v23, v3
	v_or_b32_e32 v24, 22, v14
	v_mov_b32_e32 v25, v3
	v_or_b32_e32 v26, 24, v14
	v_mov_b32_e32 v27, v3
	v_or_b32_e32 v28, 26, v14
	v_mov_b32_e32 v29, v3
	v_or_b32_e32 v30, 28, v14
	v_mov_b32_e32 v31, v3
	v_or_b32_e32 v32, 30, v14
	v_mov_b32_e32 v33, v3
	v_lshlrev_b64 v[18:19], 12, v[18:19]
	v_lshlrev_b64 v[20:21], 12, v[20:21]
	v_lshlrev_b64 v[22:23], 12, v[22:23]
	v_lshlrev_b64 v[24:25], 12, v[24:25]
	v_lshlrev_b64 v[26:27], 12, v[26:27]
	v_lshlrev_b64 v[28:29], 12, v[28:29]
	v_lshlrev_b64 v[30:31], 12, v[30:31]
	v_lshlrev_b64 v[32:33], 12, v[32:33]
	v_lshl_add_u64 v[18:19], v[16:17], 0, v[18:19]
	v_lshl_add_u64 v[20:21], v[16:17], 0, v[20:21]
	v_lshl_add_u64 v[22:23], v[16:17], 0, v[22:23]
	v_lshl_add_u64 v[24:25], v[16:17], 0, v[24:25]
	v_lshl_add_u64 v[26:27], v[16:17], 0, v[26:27]
	v_lshl_add_u64 v[28:29], v[16:17], 0, v[28:29]
	v_lshl_add_u64 v[30:31], v[16:17], 0, v[30:31]
	v_lshl_add_u64 v[32:33], v[16:17], 0, v[32:33]
	global_load_dword v41, v[18:19], off
	global_load_dword v42, v[20:21], off
	global_load_dword v43, v[22:23], off
	global_load_dword v44, v[24:25], off
	global_load_dword v45, v[26:27], off
	global_load_dword v46, v[28:29], off
	global_load_dword v47, v[30:31], off
	global_load_dword v61, v[32:33], off
	v_or_b32_e32 v18, 32, v14
	v_mov_b32_e32 v19, v3
	v_or_b32_e32 v20, 34, v14
	v_mov_b32_e32 v21, v3
	v_or_b32_e32 v22, 36, v14
	v_mov_b32_e32 v23, v3
	v_or_b32_e32 v24, 38, v14
	v_mov_b32_e32 v25, v3
	v_or_b32_e32 v26, 40, v14
	v_mov_b32_e32 v27, v3
	v_or_b32_e32 v28, 42, v14
	v_mov_b32_e32 v29, v3
	v_or_b32_e32 v30, 44, v14
	v_mov_b32_e32 v31, v3
	v_or_b32_e32 v32, 46, v14
	v_mov_b32_e32 v33, v3
	v_lshlrev_b64 v[18:19], 12, v[18:19]
	v_lshlrev_b64 v[20:21], 12, v[20:21]
	v_lshlrev_b64 v[22:23], 12, v[22:23]
	v_lshlrev_b64 v[24:25], 12, v[24:25]
	v_lshlrev_b64 v[26:27], 12, v[26:27]
	v_lshlrev_b64 v[28:29], 12, v[28:29]
	v_lshlrev_b64 v[30:31], 12, v[30:31]
	v_lshlrev_b64 v[32:33], 12, v[32:33]
	v_lshl_add_u64 v[18:19], v[16:17], 0, v[18:19]
	v_lshl_add_u64 v[20:21], v[16:17], 0, v[20:21]
	v_lshl_add_u64 v[22:23], v[16:17], 0, v[22:23]
	v_lshl_add_u64 v[24:25], v[16:17], 0, v[24:25]
	v_lshl_add_u64 v[26:27], v[16:17], 0, v[26:27]
	v_lshl_add_u64 v[28:29], v[16:17], 0, v[28:29]
	v_lshl_add_u64 v[30:31], v[16:17], 0, v[30:31]
	v_lshl_add_u64 v[32:33], v[16:17], 0, v[32:33]
	global_load_dword v62, v[18:19], off
	global_load_dword v63, v[20:21], off
	global_load_dword v64, v[22:23], off
	global_load_dword v65, v[24:25], off
	global_load_dword v66, v[26:27], off
	global_load_dword v67, v[28:29], off
	global_load_dword v68, v[30:31], off
	s_nop 0
	global_load_dword v32, v[32:33], off
	v_or_b32_e32 v18, 48, v14
	v_mov_b32_e32 v19, v3
	v_or_b32_e32 v20, 50, v14
	v_mov_b32_e32 v21, v3
	v_or_b32_e32 v22, 52, v14
	v_mov_b32_e32 v23, v3
	v_or_b32_e32 v24, 54, v14
	v_or_b32_e32 v26, 56, v14
	v_or_b32_e32 v28, 58, v14
	v_or_b32_e32 v30, 60, v14
	v_or_b32_e32 v14, 62, v14
	v_lshlrev_b64 v[18:19], 12, v[18:19]
	v_lshlrev_b64 v[20:21], 12, v[20:21]
	v_lshlrev_b64 v[22:23], 12, v[22:23]
	v_mov_b32_e32 v25, v3
	v_mov_b32_e32 v27, v3
	v_mov_b32_e32 v29, v3
	v_mov_b32_e32 v31, v3
	v_lshlrev_b64 v[14:15], 12, v[14:15]
	v_lshl_add_u64 v[18:19], v[16:17], 0, v[18:19]
	v_lshl_add_u64 v[20:21], v[16:17], 0, v[20:21]
	v_lshl_add_u64 v[22:23], v[16:17], 0, v[22:23]
	v_lshlrev_b64 v[24:25], 12, v[24:25]
	v_lshlrev_b64 v[26:27], 12, v[26:27]
	v_lshlrev_b64 v[28:29], 12, v[28:29]
	v_lshlrev_b64 v[30:31], 12, v[30:31]
	v_lshl_add_u64 v[14:15], v[16:17], 0, v[14:15]
	v_lshl_add_u64 v[24:25], v[16:17], 0, v[24:25]
	v_lshl_add_u64 v[26:27], v[16:17], 0, v[26:27]
	v_lshl_add_u64 v[28:29], v[16:17], 0, v[28:29]
	v_lshl_add_u64 v[30:31], v[16:17], 0, v[30:31]
	global_load_dword v16, v[18:19], off
	global_load_dword v17, v[20:21], off
	s_nop 0
	global_load_dword v18, v[22:23], off
	global_load_dword v19, v[24:25], off
	global_load_dword v20, v[26:27], off
	global_load_dword v21, v[28:29], off
	s_nop 0
	global_load_dword v22, v[30:31], off
	s_nop 0
	global_load_dword v14, v[14:15], off
	s_waitcnt vmcnt(30)
; #define LAS __attribute__((address_space(3)))
; __device__ __forceinline__ unsigned cvtpk(float lo, float hi) { f32x2 v = {lo, hi}; bf16x2_t b = __builtin_convertvector(v, bf16x2_t); return __builtin_bit_cast(unsigned, b); }
; __device__ __forceinline__ void transpose_item(const float* W, int ldw, int k0, int srccol0, const float* gain, bf16_t* dst, int dpitch, int drow0, int dk0, LAS float* scr, int lane) {
;     ...
;     for (int i = 0; i < 32; ++i) { const int kk = 2 * i + (lane >> 5); scr[kk * 33 + (lane & 31)] = tv[i]; }
;     asm volatile("s_waitcnt lgkmcnt(0)" ::: "memory");
;     const int c = lane & 7;
; #pragma unroll
;     for (int j = 0; j < 4; ++j) { const int n = (lane >> 3) + 8 * j; const LAS float* s = scr + (8 * c) * 33 + n;
;         u32x4 o; o.x = wq(cvtpk(s[0 * 33], s[1 * 33])); o.y = wq(cvtpk(s[2 * 33], s[3 * 33])); o.z = wq(cvtpk(s[4 * 33], s[5 * 33])); o.w = wq(cvtpk(s[6 * 33], s[7 * 33]));
;         *(u32x4*)(dst + (size_t)(drow0 + n) * dpitch + dk0 + k0 + 8 * c) = o; }
;     asm volatile("s_waitcnt lgkmcnt(0)" ::: "memory");
	ds_write2_b32 v48, v13, v34 offset1:66
	s_waitcnt vmcnt(28)
	ds_write2_b32 v48, v35, v36 offset0:132 offset1:198
	s_waitcnt vmcnt(26)
	ds_write2_b32 v54, v37, v38 offset0:8 offset1:74
	s_waitcnt vmcnt(24)
	ds_write2_b32 v54, v39, v40 offset0:140 offset1:206
	s_waitcnt vmcnt(22)
	ds_write2_b32 v55, v41, v42 offset0:16 offset1:82
	s_waitcnt vmcnt(20)
	ds_write2_b32 v55, v43, v44 offset0:148 offset1:214
	s_waitcnt vmcnt(18)
	ds_write2_b32 v56, v45, v46 offset0:24 offset1:90
	s_waitcnt vmcnt(16)
	ds_write2_b32 v56, v47, v61 offset0:156 offset1:222
	s_waitcnt vmcnt(14)
	ds_write2_b32 v57, v62, v63 offset0:32 offset1:98
	s_waitcnt vmcnt(12)
	ds_write2_b32 v57, v64, v65 offset0:164 offset1:230
	s_waitcnt vmcnt(10)
	ds_write2_b32 v58, v66, v67 offset0:40 offset1:106
	s_waitcnt vmcnt(8)
	ds_write2_b32 v58, v68, v32 offset0:172 offset1:238
	s_waitcnt vmcnt(6)
	ds_write2_b32 v59, v16, v17 offset0:48 offset1:114
	s_waitcnt vmcnt(4)
	ds_write2_b32 v59, v18, v19 offset0:180 offset1:246
	s_waitcnt vmcnt(2)
	ds_write2_b32 v60, v20, v21 offset0:56 offset1:122
	s_waitcnt vmcnt(0)
	ds_write2_b32 v60, v22, v14 offset0:188 offset1:254
	s_waitcnt lgkmcnt(0)
	ds_read2_b32 v[18:19], v50 offset0:33 offset1:41
	ds_read2_b32 v[20:21], v50 offset1:8
	ds_read2_b32 v[22:23], v50 offset0:66 offset1:74
	ds_read2_b32 v[24:25], v50 offset0:99 offset1:107
	ds_read2_b32 v[28:29], v50 offset0:132 offset1:140
	ds_read2_b32 v[30:31], v50 offset0:165 offset1:173
	ds_read2_b32 v[32:33], v50 offset0:198 offset1:206
	ds_read2_b32 v[34:35], v50 offset0:231 offset1:239
	s_mov_b32 s9, s3
	s_waitcnt lgkmcnt(6)
	v_cvt_pk_bf16_f32 v13, v20, v18
	v_add_u32_e32 v13, 0x20002, v13
	v_and_b32_e32 v14, 0xfffcfffc, v13
	s_waitcnt lgkmcnt(4)
	v_cvt_pk_bf16_f32 v13, v22, v24
	v_add_u32_e32 v13, 0x20002, v13
	v_and_b32_e32 v15, 0xfffcfffc, v13
	s_waitcnt lgkmcnt(2)
	v_cvt_pk_bf16_f32 v13, v28, v30
	v_add_u32_e32 v13, 0x20002, v13
	v_and_b32_e32 v16, 0xfffcfffc, v13
	s_waitcnt lgkmcnt(0)
	v_cvt_pk_bf16_f32 v13, v32, v34
	v_add_u32_e32 v13, 0x20002, v13
	v_and_b32_e32 v17, 0xfffcfffc, v13
	v_or_b32_e32 v13, s50, v49
	v_lshl_add_u64 v[26:27], s[8:9], 1, v[4:5]
	v_lshlrev_b32_e32 v36, 11, v13
	v_mov_b32_e32 v37, v3
	v_cvt_pk_bf16_f32 v13, v21, v19
	v_lshl_add_u64 v[36:37], v[26:27], 0, v[36:37]
	v_add_u32_e32 v13, 0x20002, v13
	global_store_dwordx4 v[36:37], v[14:17], off sc1
	v_mov_b32_e32 v19, v3
	v_mov_b32_e32 v37, v3
	v_and_b32_e32 v14, 0xfffcfffc, v13
	v_cvt_pk_bf16_f32 v13, v23, v25
	v_add_u32_e32 v13, 0x20002, v13
	v_and_b32_e32 v15, 0xfffcfffc, v13
	v_cvt_pk_bf16_f32 v13, v29, v31
	v_add_u32_e32 v13, 0x20002, v13
	v_and_b32_e32 v16, 0xfffcfffc, v13
	v_cvt_pk_bf16_f32 v13, v33, v35
	v_add_u32_e32 v13, 0x20002, v13
	v_and_b32_e32 v17, 0xfffcfffc, v13
	v_or_b32_e32 v13, s50, v51
	ds_read2_b32 v[20:21], v50 offset0:49 offset1:57
	ds_read2_b32 v[22:23], v50 offset0:16 offset1:24
	v_lshlrev_b32_e32 v18, 11, v13
	v_lshl_add_u64 v[18:19], v[26:27], 0, v[18:19]
	ds_read2_b32 v[24:25], v50 offset0:82 offset1:90
	ds_read2_b32 v[28:29], v50 offset0:115 offset1:123
	global_store_dwordx4 v[18:19], v[14:17], off sc1
	ds_read2_b32 v[18:19], v50 offset0:148 offset1:156
	ds_read2_b32 v[30:31], v50 offset0:181 offset1:189
	s_waitcnt lgkmcnt(4)
	v_cvt_pk_bf16_f32 v13, v22, v20
	v_add_u32_e32 v13, 0x20002, v13
	ds_read2_b32 v[32:33], v50 offset0:214 offset1:222
	ds_read2_b32 v[34:35], v50 offset0:247 offset1:255
	v_and_b32_e32 v14, 0xfffcfffc, v13
	s_waitcnt lgkmcnt(4)
	v_cvt_pk_bf16_f32 v13, v24, v28
	v_add_u32_e32 v13, 0x20002, v13
	v_and_b32_e32 v15, 0xfffcfffc, v13
	s_waitcnt lgkmcnt(2)
	v_cvt_pk_bf16_f32 v13, v18, v30
	v_add_u32_e32 v13, 0x20002, v13
	v_and_b32_e32 v16, 0xfffcfffc, v13
	s_waitcnt lgkmcnt(0)
	v_cvt_pk_bf16_f32 v13, v32, v34
	v_add_u32_e32 v13, 0x20002, v13
	v_and_b32_e32 v17, 0xfffcfffc, v13
	v_or_b32_e32 v13, s50, v52
	v_lshlrev_b32_e32 v36, 11, v13
	v_cvt_pk_bf16_f32 v13, v23, v21
	v_lshl_add_u64 v[36:37], v[26:27], 0, v[36:37]
	v_add_u32_e32 v13, 0x20002, v13
	global_store_dwordx4 v[36:37], v[14:17], off sc1
	s_mov_b64 s[8:9], 0
	s_nop 0
	v_and_b32_e32 v14, 0xfffcfffc, v13
	v_cvt_pk_bf16_f32 v13, v25, v29
	v_add_u32_e32 v13, 0x20002, v13
	v_and_b32_e32 v15, 0xfffcfffc, v13
	v_cvt_pk_bf16_f32 v13, v19, v31
	v_add_u32_e32 v13, 0x20002, v13
	v_and_b32_e32 v16, 0xfffcfffc, v13
	v_cvt_pk_bf16_f32 v13, v33, v35
	v_add_u32_e32 v13, 0x20002, v13
	v_and_b32_e32 v17, 0xfffcfffc, v13
	v_or_b32_e32 v13, s50, v53
	v_lshlrev_b32_e32 v18, 11, v13
	v_mov_b32_e32 v19, v3
	v_lshl_add_u64 v[18:19], v[26:27], 0, v[18:19]
	global_store_dwordx4 v[18:19], v[14:17], off sc1
	s_waitcnt lgkmcnt(0)
; __device__ __forceinline__ void transpose_item(const float* W, int ldw, int k0, int srccol0, const float* gain, bf16_t* dst, int dpitch, int drow0, int dk0, LAS float* scr, int lane) {
;     ...
;     for (int i = 0; i < 32; ++i) { const int kk = 2 * i + (lane >> 5); tv[i] = W[(size_t)(k0 + kk) * ldw + srccol0 + (lane & 31)]; }
;     if (gain) {
; #pragma unroll
;         for (int i = 0; i < 32; ++i) tv[i] *= gain[k0 + 2 * i + (lane >> 5)];
; __device__ __forceinline__ void prologue(const Params& P, LAS unsigned char* lds, int gw, int NGW, int wave, int lane) {
;     ...
;         if (r < 2 * I_P) { const int w = r / I_P; r -= w * I_P; const int kb = r / 32, nb = r % 32;
;             transpose_item(P.in[w ? 20 : 19], DM, 64 * kb, 32 * nb, nullptr, (bf16_t*)(ws + WS_WP), 1024, 32 * nb, w ? 512 : 0, scr, lane); continue; }
.LBB0_19:
	s_andn2_b64 vcc, exec, s[8:9]
	s_cbranch_vccnz .LBB0_21
	s_and_b32 s9, s92, 0x3f00
	s_and_b32 s8, s77, 0x1c0
	s_and_b32 s2, s79, 0x3e0
	s_cmpk_eq_i32 s9, 0x2a00
	s_cselect_b32 s51, s59, s61
	s_cselect_b32 s50, s58, s60
	s_cselect_b32 s9, 0, 0x400
	s_lshl_b32 s62, s2, 2
	s_add_u32 s50, s50, s62
	v_or_b32_e32 v13, s8, v1
	s_addc_u32 s51, s51, 0
	v_lshl_add_u64 v[14:15], s[50:51], 0, v[2:3]
	v_lshlrev_b32_e32 v16, 12, v13
	v_mov_b32_e32 v17, v3
	v_lshl_add_u64 v[14:15], v[14:15], 0, v[16:17]
	s_movk_i32 s50, 0x2000
	v_add_co_u32_e32 v16, vcc, s50, v14
	s_movk_i32 s50, 0x4000
	s_nop 0
	v_addc_co_u32_e32 v17, vcc, 0, v15, vcc
	v_add_co_u32_e32 v18, vcc, s50, v14
	s_movk_i32 s50, 0x6000
	s_nop 0
	v_addc_co_u32_e32 v19, vcc, 0, v15, vcc
	v_add_co_u32_e32 v20, vcc, s50, v14
	s_mov_b32 s50, 0x8000
	s_nop 0
	v_addc_co_u32_e32 v21, vcc, 0, v15, vcc
	v_add_co_u32_e32 v22, vcc, s50, v14
	s_mov_b32 s50, 0xa000
	s_nop 0
	v_addc_co_u32_e32 v23, vcc, 0, v15, vcc
	v_add_co_u32_e32 v24, vcc, s50, v14
	s_mov_b32 s50, 0xc000
	s_nop 0
	v_addc_co_u32_e32 v25, vcc, 0, v15, vcc
	v_add_co_u32_e32 v26, vcc, s50, v14
	s_mov_b32 s50, 0xe000
	s_nop 0
	v_addc_co_u32_e32 v27, vcc, 0, v15, vcc
	v_add_co_u32_e32 v28, vcc, s50, v14
	s_mov_b32 s50, 0x10000
	s_nop 0
	v_addc_co_u32_e32 v29, vcc, 0, v15, vcc
	global_load_dword v13, v[14:15], off
	global_load_dword v32, v[16:17], off
	global_load_dword v33, v[18:19], off
	global_load_dword v34, v[20:21], off
	global_load_dword v35, v[22:23], off
	global_load_dword v36, v[24:25], off
	global_load_dword v37, v[26:27], off
	global_load_dword v38, v[28:29], off
	v_add_co_u32_e32 v16, vcc, s50, v14
	s_mov_b32 s50, 0x12000
	s_nop 0
	v_addc_co_u32_e32 v17, vcc, 0, v15, vcc
	v_add_co_u32_e32 v18, vcc, s50, v14
	s_mov_b32 s50, 0x14000
	s_nop 0
	v_addc_co_u32_e32 v19, vcc, 0, v15, vcc
	v_add_co_u32_e32 v20, vcc, s50, v14
	s_mov_b32 s50, 0x16000
	s_nop 0
	v_addc_co_u32_e32 v21, vcc, 0, v15, vcc
	v_add_co_u32_e32 v22, vcc, s50, v14
	s_mov_b32 s50, 0x18000
	s_nop 0
	v_addc_co_u32_e32 v23, vcc, 0, v15, vcc
	v_add_co_u32_e32 v24, vcc, s50, v14
	s_mov_b32 s50, 0x1a000
	s_nop 0
	v_addc_co_u32_e32 v25, vcc, 0, v15, vcc
	v_add_co_u32_e32 v26, vcc, s50, v14
	v_readlane_b32 s50, v246, 8
	s_nop 0
	v_addc_co_u32_e32 v27, vcc, 0, v15, vcc
	v_add_co_u32_e32 v28, vcc, s94, v14
	s_add_u32 s9, s50, s9
	s_nop 0
	v_addc_co_u32_e32 v29, vcc, 0, v15, vcc
	v_add_co_u32_e32 v30, vcc, s95, v14
	v_readlane_b32 s50, v246, 9
	s_nop 0
	v_addc_co_u32_e32 v31, vcc, 0, v15, vcc
	global_load_dword v39, v[16:17], off
	global_load_dword v40, v[18:19], off
	global_load_dword v41, v[20:21], off
	global_load_dword v42, v[22:23], off
	global_load_dword v43, v[24:25], off
	global_load_dword v44, v[26:27], off
	global_load_dword v45, v[28:29], off
	global_load_dword v46, v[30:31], off
	v_add_co_u32_e32 v16, vcc, s96, v14
	s_addc_u32 s50, s50, 0
	s_nop 0
	v_addc_co_u32_e32 v17, vcc, 0, v15, vcc
	v_add_co_u32_e32 v18, vcc, s97, v14
	s_lshl_b32 s8, s8, 1
	s_nop 0
	v_addc_co_u32_e32 v19, vcc, 0, v15, vcc
	v_add_co_u32_e32 v20, vcc, s33, v14
	s_add_u32 s8, s9, s8
	s_nop 0
	v_addc_co_u32_e32 v21, vcc, 0, v15, vcc
	v_add_co_u32_e32 v22, vcc, s76, v14
	s_addc_u32 s9, s50, 0
	s_nop 0
	v_addc_co_u32_e32 v23, vcc, 0, v15, vcc
	v_add_co_u32_e32 v24, vcc, s0, v14
	s_nop 1
	v_addc_co_u32_e32 v25, vcc, 0, v15, vcc
	v_add_co_u32_e32 v26, vcc, s1, v14
	s_nop 1
	v_addc_co_u32_e32 v27, vcc, 0, v15, vcc
	v_add_co_u32_e32 v28, vcc, s81, v14
	s_nop 1
	v_addc_co_u32_e32 v29, vcc, 0, v15, vcc
	v_add_co_u32_e32 v30, vcc, s82, v14
	s_nop 1
	v_addc_co_u32_e32 v31, vcc, 0, v15, vcc
	global_load_dword v47, v[16:17], off
	global_load_dword v61, v[18:19], off
	global_load_dword v62, v[20:21], off
	global_load_dword v63, v[22:23], off
	global_load_dword v64, v[24:25], off
	global_load_dword v65, v[26:27], off
	global_load_dword v66, v[28:29], off
	s_nop 0
	global_load_dword v30, v[30:31], off
	v_add_co_u32_e32 v16, vcc, s83, v14
	s_nop 1
	v_addc_co_u32_e32 v17, vcc, 0, v15, vcc
	v_add_co_u32_e32 v18, vcc, s84, v14
	s_nop 1
	v_addc_co_u32_e32 v19, vcc, 0, v15, vcc
	v_add_co_u32_e32 v20, vcc, s85, v14
	s_nop 1
	v_addc_co_u32_e32 v21, vcc, 0, v15, vcc
	v_add_co_u32_e32 v22, vcc, s86, v14
	s_nop 1
	v_addc_co_u32_e32 v23, vcc, 0, v15, vcc
	v_add_co_u32_e32 v24, vcc, s87, v14
	s_nop 1
	v_addc_co_u32_e32 v25, vcc, 0, v15, vcc
	v_add_co_u32_e32 v26, vcc, s88, v14
	s_nop 1
	v_addc_co_u32_e32 v27, vcc, 0, v15, vcc
	v_add_co_u32_e32 v28, vcc, s89, v14
	s_nop 1
	v_addc_co_u32_e32 v29, vcc, 0, v15, vcc
	v_add_co_u32_e32 v14, vcc, s90, v14
	s_nop 1
	v_addc_co_u32_e32 v15, vcc, 0, v15, vcc
	global_load_dword v16, v[16:17], off
	s_nop 0
	global_load_dword v17, v[18:19], off
	s_nop 0
	global_load_dword v18, v[20:21], off
	global_load_dword v19, v[22:23], off
	s_nop 0
	global_load_dword v20, v[24:25], off
	global_load_dword v21, v[26:27], off
	global_load_dword v22, v[28:29], off
	s_nop 0
	global_load_dword v14, v[14:15], off
	s_waitcnt vmcnt(30)
; #define LAS __attribute__((address_space(3)))
; __device__ __forceinline__ unsigned cvtpk(float lo, float hi) { f32x2 v = {lo, hi}; bf16x2_t b = __builtin_convertvector(v, bf16x2_t); return __builtin_bit_cast(unsigned, b); }
; __device__ __forceinline__ void transpose_item(const float* W, int ldw, int k0, int srccol0, const float* gain, bf16_t* dst, int dpitch, int drow0, int dk0, LAS float* scr, int lane) {
;     ...
;     for (int i = 0; i < 32; ++i) { const int kk = 2 * i + (lane >> 5); scr[kk * 33 + (lane & 31)] = tv[i]; }
;     asm volatile("s_waitcnt lgkmcnt(0)" ::: "memory");
;     const int c = lane & 7;
; #pragma unroll
;     for (int j = 0; j < 4; ++j) { const int n = (lane >> 3) + 8 * j; const LAS float* s = scr + (8 * c) * 33 + n;
;         u32x4 o; o.x = wq(cvtpk(s[0 * 33], s[1 * 33])); o.y = wq(cvtpk(s[2 * 33], s[3 * 33])); o.z = wq(cvtpk(s[4 * 33], s[5 * 33])); o.w = wq(cvtpk(s[6 * 33], s[7 * 33]));
;         *(u32x4*)(dst + (size_t)(drow0 + n) * dpitch + dk0 + k0 + 8 * c) = o; }
;     asm volatile("s_waitcnt lgkmcnt(0)" ::: "memory");
	ds_write2_b32 v48, v13, v32 offset1:66
	s_waitcnt vmcnt(28)
	ds_write2_b32 v48, v33, v34 offset0:132 offset1:198
	s_waitcnt vmcnt(26)
	ds_write2_b32 v54, v35, v36 offset0:8 offset1:74
	s_waitcnt vmcnt(24)
	ds_write2_b32 v54, v37, v38 offset0:140 offset1:206
	s_waitcnt vmcnt(22)
	ds_write2_b32 v55, v39, v40 offset0:16 offset1:82
	s_waitcnt vmcnt(20)
	ds_write2_b32 v55, v41, v42 offset0:148 offset1:214
	s_waitcnt vmcnt(18)
	ds_write2_b32 v56, v43, v44 offset0:24 offset1:90
	s_waitcnt vmcnt(16)
	ds_write2_b32 v56, v45, v46 offset0:156 offset1:222
	s_waitcnt vmcnt(14)
	ds_write2_b32 v57, v47, v61 offset0:32 offset1:98
	s_waitcnt vmcnt(12)
	ds_write2_b32 v57, v62, v63 offset0:164 offset1:230
	s_waitcnt vmcnt(10)
	ds_write2_b32 v58, v64, v65 offset0:40 offset1:106
	s_waitcnt vmcnt(8)
	ds_write2_b32 v58, v66, v30 offset0:172 offset1:238
	s_waitcnt vmcnt(6)
	ds_write2_b32 v59, v16, v17 offset0:48 offset1:114
	s_waitcnt vmcnt(4)
	ds_write2_b32 v59, v18, v19 offset0:180 offset1:246
	s_waitcnt vmcnt(2)
	ds_write2_b32 v60, v20, v21 offset0:56 offset1:122
	s_waitcnt vmcnt(0)
	ds_write2_b32 v60, v22, v14 offset0:188 offset1:254
	s_waitcnt lgkmcnt(0)
	ds_read2_b32 v[18:19], v50 offset0:33 offset1:41
	ds_read2_b32 v[20:21], v50 offset1:8
	ds_read2_b32 v[22:23], v50 offset0:66 offset1:74
	ds_read2_b32 v[24:25], v50 offset0:99 offset1:107
	v_mov_b32_e32 v13, v3
	ds_read2_b32 v[28:29], v50 offset0:132 offset1:140
	ds_read2_b32 v[30:31], v50 offset0:165 offset1:173
	v_lshl_add_u64 v[26:27], s[8:9], 0, v[12:13]
	s_waitcnt lgkmcnt(4)
	v_cvt_pk_bf16_f32 v13, v20, v18
	v_add_u32_e32 v13, 0x20002, v13
	ds_read2_b32 v[32:33], v50 offset0:198 offset1:206
	ds_read2_b32 v[34:35], v50 offset0:231 offset1:239
	v_and_b32_e32 v14, 0xfffcfffc, v13
	s_waitcnt lgkmcnt(4)
	v_cvt_pk_bf16_f32 v13, v22, v24
	v_add_u32_e32 v13, 0x20002, v13
	v_and_b32_e32 v15, 0xfffcfffc, v13
	s_waitcnt lgkmcnt(2)
	v_cvt_pk_bf16_f32 v13, v28, v30
	v_add_u32_e32 v13, 0x20002, v13
	v_and_b32_e32 v16, 0xfffcfffc, v13
	s_waitcnt lgkmcnt(0)
	v_cvt_pk_bf16_f32 v13, v32, v34
	v_add_u32_e32 v13, 0x20002, v13
	v_and_b32_e32 v17, 0xfffcfffc, v13
	v_or_b32_e32 v13, s2, v49
	v_lshlrev_b32_e32 v36, 11, v13
	v_mov_b32_e32 v37, v3
	v_cvt_pk_bf16_f32 v13, v21, v19
	v_lshl_add_u64 v[36:37], v[26:27], 0, v[36:37]
	v_add_u32_e32 v13, 0x20002, v13
	global_store_dwordx4 v[36:37], v[14:17], off sc1
	v_mov_b32_e32 v19, v3
	v_mov_b32_e32 v37, v3
	v_and_b32_e32 v14, 0xfffcfffc, v13
	v_cvt_pk_bf16_f32 v13, v23, v25
	v_add_u32_e32 v13, 0x20002, v13
	v_and_b32_e32 v15, 0xfffcfffc, v13
	v_cvt_pk_bf16_f32 v13, v29, v31
	v_add_u32_e32 v13, 0x20002, v13
	v_and_b32_e32 v16, 0xfffcfffc, v13
	v_cvt_pk_bf16_f32 v13, v33, v35
	v_add_u32_e32 v13, 0x20002, v13
	v_and_b32_e32 v17, 0xfffcfffc, v13
	v_or_b32_e32 v13, s2, v51
	ds_read2_b32 v[20:21], v50 offset0:49 offset1:57
	ds_read2_b32 v[22:23], v50 offset0:16 offset1:24
	v_lshlrev_b32_e32 v18, 11, v13
	v_lshl_add_u64 v[18:19], v[26:27], 0, v[18:19]
	ds_read2_b32 v[24:25], v50 offset0:82 offset1:90
	ds_read2_b32 v[28:29], v50 offset0:115 offset1:123
	global_store_dwordx4 v[18:19], v[14:17], off sc1
	ds_read2_b32 v[18:19], v50 offset0:148 offset1:156
	ds_read2_b32 v[30:31], v50 offset0:181 offset1:189
	s_waitcnt lgkmcnt(4)
	v_cvt_pk_bf16_f32 v13, v22, v20
	v_add_u32_e32 v13, 0x20002, v13
	ds_read2_b32 v[32:33], v50 offset0:214 offset1:222
	ds_read2_b32 v[34:35], v50 offset0:247 offset1:255
	v_and_b32_e32 v14, 0xfffcfffc, v13
	s_waitcnt lgkmcnt(4)
	v_cvt_pk_bf16_f32 v13, v24, v28
	v_add_u32_e32 v13, 0x20002, v13
	v_and_b32_e32 v15, 0xfffcfffc, v13
	s_waitcnt lgkmcnt(2)
	v_cvt_pk_bf16_f32 v13, v18, v30
	v_add_u32_e32 v13, 0x20002, v13
	v_and_b32_e32 v16, 0xfffcfffc, v13
	s_waitcnt lgkmcnt(0)
	v_cvt_pk_bf16_f32 v13, v32, v34
	v_add_u32_e32 v13, 0x20002, v13
	v_and_b32_e32 v17, 0xfffcfffc, v13
	v_or_b32_e32 v13, s2, v52
	v_lshlrev_b32_e32 v36, 11, v13
	v_cvt_pk_bf16_f32 v13, v23, v21
	v_lshl_add_u64 v[36:37], v[26:27], 0, v[36:37]
	v_add_u32_e32 v13, 0x20002, v13
	global_store_dwordx4 v[36:37], v[14:17], off sc1
	s_nop 1
	v_and_b32_e32 v14, 0xfffcfffc, v13
	v_cvt_pk_bf16_f32 v13, v25, v29
	v_add_u32_e32 v13, 0x20002, v13
	v_and_b32_e32 v15, 0xfffcfffc, v13
	v_cvt_pk_bf16_f32 v13, v19, v31
	v_add_u32_e32 v13, 0x20002, v13
	v_and_b32_e32 v16, 0xfffcfffc, v13
	v_cvt_pk_bf16_f32 v13, v33, v35
	v_add_u32_e32 v13, 0x20002, v13
	v_and_b32_e32 v17, 0xfffcfffc, v13
	v_or_b32_e32 v13, s2, v53
	v_lshlrev_b32_e32 v18, 11, v13
	v_mov_b32_e32 v19, v3
	v_lshl_add_u64 v[18:19], v[26:27], 0, v[18:19]
	global_store_dwordx4 v[18:19], v[14:17], off sc1
	s_waitcnt lgkmcnt(0)

; #define LAS __attribute__((address_space(3)))
; __device__ __forceinline__ unsigned cvtpk(float lo, float hi) { f32x2 v = {lo, hi}; bf16x2_t b = __builtin_convertvector(v, bf16x2_t); return __builtin_bit_cast(unsigned, b); }
; __device__ __forceinline__ unsigned wq(unsigned two_bf16) {
;     if (WQ_DROP == 0) return two_bf16;
;     const unsigned half = (1u << (WQ_DROP - 1)) * 0x00010001u, mask = ~(((1u << WQ_DROP) - 1u) * 0x00010001u);
;     return (two_bf16 + half) & mask;
; }
; __device__ __forceinline__ void transpose_item(const float* W, int ldw, int k0, int srccol0, const float* gain, bf16_t* dst, int dpitch, int drow0, int dk0, LAS float* scr, int lane) {
;     ...
;     for (int i = 0; i < 32; ++i) { const int kk = 2 * i + (lane >> 5); scr[kk * 33 + (lane & 31)] = tv[i]; }
;     asm volatile("s_waitcnt lgkmcnt(0)" ::: "memory");
;     const int c = lane & 7;
; #pragma unroll
;     for (int j = 0; j < 4; ++j) { const int n = (lane >> 3) + 8 * j; const LAS float* s = scr + (8 * c) * 33 + n;
;         u32x4 o; o.x = wq(cvtpk(s[0 * 33], s[1 * 33])); o.y = wq(cvtpk(s[2 * 33], s[3 * 33])); o.z = wq(cvtpk(s[4 * 33], s[5 * 33])); o.w = wq(cvtpk(s[6 * 33], s[7 * 33]));
;         *(u32x4*)(dst + (size_t)(drow0 + n) * dpitch + dk0 + k0 + 8 * c) = o; }
.LBB0_25:
	s_waitcnt vmcnt(30)
	ds_write2_b32 v48, v14, v15 offset1:66
	s_waitcnt vmcnt(28)
	ds_write2_b32 v48, v16, v17 offset0:132 offset1:198
	s_waitcnt vmcnt(26)
	ds_write2_b32 v54, v18, v19 offset0:8 offset1:74
	s_waitcnt vmcnt(24)
	ds_write2_b32 v54, v20, v21 offset0:140 offset1:206
	s_waitcnt vmcnt(22)
	ds_write2_b32 v55, v22, v23 offset0:16 offset1:82
	s_waitcnt vmcnt(20)
	ds_write2_b32 v55, v24, v25 offset0:148 offset1:214
	s_waitcnt vmcnt(18)
	ds_write2_b32 v56, v26, v27 offset0:24 offset1:90
	s_waitcnt vmcnt(16)
	ds_write2_b32 v56, v28, v29 offset0:156 offset1:222
	s_waitcnt vmcnt(14)
	ds_write2_b32 v57, v30, v31 offset0:32 offset1:98
	s_waitcnt vmcnt(12)
	ds_write2_b32 v57, v32, v33 offset0:164 offset1:230
	s_waitcnt vmcnt(10)
	ds_write2_b32 v58, v34, v35 offset0:40 offset1:106
	s_waitcnt vmcnt(8)
	ds_write2_b32 v58, v36, v37 offset0:172 offset1:238
	s_waitcnt vmcnt(6)
	ds_write2_b32 v59, v38, v39 offset0:48 offset1:114
	s_waitcnt vmcnt(4)
	ds_write2_b32 v59, v40, v41 offset0:180 offset1:246
	s_waitcnt vmcnt(2)
	ds_write2_b32 v60, v44, v45 offset0:56 offset1:122
	s_waitcnt vmcnt(0)
	ds_write2_b32 v60, v42, v43 offset0:188 offset1:254
	s_waitcnt lgkmcnt(0)
	ds_read2_b32 v[18:19], v50 offset0:33 offset1:41
	ds_read2_b32 v[20:21], v50 offset1:8
	ds_read2_b32 v[22:23], v50 offset0:66 offset1:74
	ds_read2_b32 v[24:25], v50 offset0:99 offset1:107
	ds_read2_b32 v[28:29], v50 offset0:132 offset1:140
	ds_read2_b32 v[30:31], v50 offset0:165 offset1:173
	ds_read2_b32 v[32:33], v50 offset0:198 offset1:206
	ds_read2_b32 v[34:35], v50 offset0:231 offset1:239
	s_and_b32 s2, 0xffff, s9
	s_waitcnt lgkmcnt(6)
	v_cvt_pk_bf16_f32 v13, v20, v18
	v_add_u32_e32 v13, 0x20002, v13
	v_and_b32_e32 v14, 0xfffcfffc, v13
	s_waitcnt lgkmcnt(4)
	v_cvt_pk_bf16_f32 v13, v22, v24
	v_add_u32_e32 v13, 0x20002, v13
	v_and_b32_e32 v15, 0xfffcfffc, v13
	s_waitcnt lgkmcnt(2)
	v_cvt_pk_bf16_f32 v13, v28, v30
	v_add_u32_e32 v13, 0x20002, v13
	v_and_b32_e32 v16, 0xfffcfffc, v13
	s_waitcnt lgkmcnt(0)
	v_cvt_pk_bf16_f32 v13, v32, v34
	v_add_u32_e32 v13, 0x20002, v13
	s_lshl_b32 s2, s2, 1
	v_and_b32_e32 v17, 0xfffcfffc, v13
	v_or_b32_e32 v13, s8, v49
	v_lshl_add_u64 v[26:27], v[6:7], 0, s[2:3]
	v_lshlrev_b32_e32 v36, 11, v13
	v_mov_b32_e32 v37, v3
	v_cvt_pk_bf16_f32 v13, v21, v19
	v_lshl_add_u64 v[36:37], v[26:27], 0, v[36:37]
	v_add_u32_e32 v13, 0x20002, v13
	global_store_dwordx4 v[36:37], v[14:17], off sc1
	v_mov_b32_e32 v19, v3
	v_mov_b32_e32 v37, v3
	v_and_b32_e32 v14, 0xfffcfffc, v13
	v_cvt_pk_bf16_f32 v13, v23, v25
	v_add_u32_e32 v13, 0x20002, v13
	v_and_b32_e32 v15, 0xfffcfffc, v13
	v_cvt_pk_bf16_f32 v13, v29, v31
	v_add_u32_e32 v13, 0x20002, v13
	v_and_b32_e32 v16, 0xfffcfffc, v13
	v_cvt_pk_bf16_f32 v13, v33, v35
	v_add_u32_e32 v13, 0x20002, v13
	v_and_b32_e32 v17, 0xfffcfffc, v13
	v_or_b32_e32 v13, s8, v51
	ds_read2_b32 v[20:21], v50 offset0:49 offset1:57
	ds_read2_b32 v[22:23], v50 offset0:16 offset1:24
	v_lshlrev_b32_e32 v18, 11, v13
	v_lshl_add_u64 v[18:19], v[26:27], 0, v[18:19]
	ds_read2_b32 v[24:25], v50 offset0:82 offset1:90
	ds_read2_b32 v[28:29], v50 offset0:115 offset1:123
	global_store_dwordx4 v[18:19], v[14:17], off sc1
	ds_read2_b32 v[18:19], v50 offset0:148 offset1:156
	ds_read2_b32 v[30:31], v50 offset0:181 offset1:189
	s_waitcnt lgkmcnt(4)
	v_cvt_pk_bf16_f32 v13, v22, v20
	v_add_u32_e32 v13, 0x20002, v13
	ds_read2_b32 v[32:33], v50 offset0:214 offset1:222
	ds_read2_b32 v[34:35], v50 offset0:247 offset1:255
	v_and_b32_e32 v14, 0xfffcfffc, v13
	s_waitcnt lgkmcnt(4)
	v_cvt_pk_bf16_f32 v13, v24, v28
	v_add_u32_e32 v13, 0x20002, v13
	v_and_b32_e32 v15, 0xfffcfffc, v13
	s_waitcnt lgkmcnt(2)
	v_cvt_pk_bf16_f32 v13, v18, v30
	v_add_u32_e32 v13, 0x20002, v13
	v_and_b32_e32 v16, 0xfffcfffc, v13
	s_waitcnt lgkmcnt(0)
	v_cvt_pk_bf16_f32 v13, v32, v34
	v_add_u32_e32 v13, 0x20002, v13
	v_and_b32_e32 v17, 0xfffcfffc, v13
	v_or_b32_e32 v13, s8, v52
	v_lshlrev_b32_e32 v36, 11, v13
	v_cvt_pk_bf16_f32 v13, v23, v21
	v_lshl_add_u64 v[36:37], v[26:27], 0, v[36:37]
	v_add_u32_e32 v13, 0x20002, v13
	global_store_dwordx4 v[36:37], v[14:17], off sc1
	s_nop 1
	v_and_b32_e32 v14, 0xfffcfffc, v13
	v_cvt_pk_bf16_f32 v13, v25, v29
	v_add_u32_e32 v13, 0x20002, v13
	v_and_b32_e32 v15, 0xfffcfffc, v13
	v_cvt_pk_bf16_f32 v13, v19, v31
	v_add_u32_e32 v13, 0x20002, v13
	v_and_b32_e32 v16, 0xfffcfffc, v13
	v_cvt_pk_bf16_f32 v13, v33, v35
	v_add_u32_e32 v13, 0x20002, v13
	v_and_b32_e32 v17, 0xfffcfffc, v13
	v_or_b32_e32 v13, s8, v53
	v_lshlrev_b32_e32 v18, 11, v13
	v_mov_b32_e32 v19, v3
	v_lshl_add_u64 v[18:19], v[26:27], 0, v[18:19]
	global_store_dwordx4 v[18:19], v[14:17], off sc1
	s_waitcnt lgkmcnt(0)

; __device__ __forceinline__ void transpose_item(const float* W, int ldw, int k0, int srccol0, const float* gain, bf16_t* dst, int dpitch, int drow0, int dk0, LAS float* scr, int lane) {
;     ...
;     for (int i = 0; i < 32; ++i) { const int kk = 2 * i + (lane >> 5); tv[i] = W[(size_t)(k0 + kk) * ldw + srccol0 + (lane & 31)]; }
; __device__ __forceinline__ void prologue(const Params& P, LAS unsigned char* lds, int gw, int NGW, int wave, int lane) {
;     ...
;         if (r < 2 * I_IN) { const int w = r / I_IN; r -= w * I_IN; const int kb = r / 176, nb = r % 176;
;             transpose_item(P.in[w ? 23 : 4], 2 * DFF, 64 * kb, map_ffn_in(32 * nb), P.in[w ? 22 : 3], (bf16_t*)(ws + (w ? WS_W2IN : WS_W1IN)), 1024, 32 * nb, 0, scr, lane); continue; }
;         r -= 2 * I_IN;
;         if (r < 2 * I_OUT) { const int w = r / I_OUT; r -= w * I_OUT; const int kb = r / 32, nb = r % 32;
;             transpose_item(P.in[w ? 24 : 5], DM, 64 * kb, 32 * nb, nullptr, (bf16_t*)(ws + (w ? WS_W2OUT : WS_W1OUT)), DFF, 32 * nb, 0, scr, lane); continue; }
.LBB0_27:
	s_andn2_b64 vcc, exec, s[8:9]
	s_cbranch_vccnz .LBB0_29
	s_add_i32 s2, s92, 0xffffea00
	s_add_i32 s62, s92, 0xffffe480
	s_cmpk_lt_u32 s2, 0x580
	s_cselect_b64 s[50:51], -1, 0
	s_and_b64 s[8:9], s[50:51], exec
	s_cselect_b32 s2, s2, s62
	s_cselect_b32 s63, s47, s69
	s_cselect_b32 s62, s46, s68
	s_lshl_b32 s8, s2, 1
	s_lshl_b32 s2, s2, 5
	s_and_b32 s8, s8, 0xfc0
	s_and_b32 s2, s2, 0x3e0
	s_and_b64 s[50:51], s[50:51], exec
	s_mov_b32 s9, 0x1100000
	s_cselect_b32 s9, s9, 0x2e80000
	s_add_u32 s9, s74, s9
	s_addc_u32 s50, s75, 0
	s_lshl_b32 s51, s2, 2
	s_add_u32 s62, s62, s51
	v_or_b32_e32 v13, s8, v1
	s_addc_u32 s63, s63, 0
	v_lshl_add_u64 v[14:15], s[62:63], 0, v[2:3]
	v_lshlrev_b32_e32 v16, 12, v13
	v_mov_b32_e32 v17, v3
	v_lshl_add_u64 v[14:15], v[14:15], 0, v[16:17]
	s_movk_i32 s51, 0x2000
	v_add_co_u32_e32 v16, vcc, s51, v14
	s_movk_i32 s51, 0x4000
	s_nop 0
	v_addc_co_u32_e32 v17, vcc, 0, v15, vcc
	v_add_co_u32_e32 v18, vcc, s51, v14
	s_movk_i32 s51, 0x6000
	s_nop 0
	v_addc_co_u32_e32 v19, vcc, 0, v15, vcc
	v_add_co_u32_e32 v20, vcc, s51, v14
	s_mov_b32 s51, 0x8000
	s_nop 0
	v_addc_co_u32_e32 v21, vcc, 0, v15, vcc
	v_add_co_u32_e32 v22, vcc, s51, v14
	s_mov_b32 s51, 0xa000
	s_nop 0
	v_addc_co_u32_e32 v23, vcc, 0, v15, vcc
	v_add_co_u32_e32 v24, vcc, s51, v14
	s_mov_b32 s51, 0xc000
	s_nop 0
	v_addc_co_u32_e32 v25, vcc, 0, v15, vcc
	v_add_co_u32_e32 v26, vcc, s51, v14
	s_mov_b32 s51, 0xe000
	s_nop 0
	v_addc_co_u32_e32 v27, vcc, 0, v15, vcc
	v_add_co_u32_e32 v28, vcc, s51, v14
	s_mov_b32 s51, 0x10000
	s_nop 0
	v_addc_co_u32_e32 v29, vcc, 0, v15, vcc
	global_load_dword v13, v[14:15], off
	global_load_dword v32, v[16:17], off
	global_load_dword v33, v[18:19], off
	global_load_dword v34, v[20:21], off
	global_load_dword v35, v[22:23], off
	global_load_dword v36, v[24:25], off
	global_load_dword v37, v[26:27], off
	global_load_dword v38, v[28:29], off
	v_add_co_u32_e32 v16, vcc, s51, v14
	s_mov_b32 s51, 0x12000
	s_nop 0
	v_addc_co_u32_e32 v17, vcc, 0, v15, vcc
	v_add_co_u32_e32 v18, vcc, s51, v14
	s_mov_b32 s51, 0x14000
	s_nop 0
	v_addc_co_u32_e32 v19, vcc, 0, v15, vcc
	v_add_co_u32_e32 v20, vcc, s51, v14
	s_mov_b32 s51, 0x16000
	s_nop 0
	v_addc_co_u32_e32 v21, vcc, 0, v15, vcc
	v_add_co_u32_e32 v22, vcc, s51, v14
	s_mov_b32 s51, 0x18000
	s_nop 0
	v_addc_co_u32_e32 v23, vcc, 0, v15, vcc
	v_add_co_u32_e32 v24, vcc, s51, v14
	s_mov_b32 s51, 0x1a000
	s_nop 0
	v_addc_co_u32_e32 v25, vcc, 0, v15, vcc
	v_add_co_u32_e32 v26, vcc, s51, v14
	s_lshl_b32 s8, s8, 1
	s_nop 0
	v_addc_co_u32_e32 v27, vcc, 0, v15, vcc
	v_add_co_u32_e32 v28, vcc, s94, v14
	s_add_u32 s8, s9, s8
	s_nop 0
	v_addc_co_u32_e32 v29, vcc, 0, v15, vcc
	v_add_co_u32_e32 v30, vcc, s95, v14
	s_addc_u32 s9, s50, 0
	s_nop 0
	v_addc_co_u32_e32 v31, vcc, 0, v15, vcc
	global_load_dword v39, v[16:17], off
	global_load_dword v40, v[18:19], off
	global_load_dword v41, v[20:21], off
	global_load_dword v42, v[22:23], off
	global_load_dword v43, v[24:25], off
	global_load_dword v44, v[26:27], off
	global_load_dword v45, v[28:29], off
	global_load_dword v46, v[30:31], off
	v_add_co_u32_e32 v16, vcc, s96, v14
	s_nop 1
	v_addc_co_u32_e32 v17, vcc, 0, v15, vcc
	v_add_co_u32_e32 v18, vcc, s97, v14
	s_nop 1
	v_addc_co_u32_e32 v19, vcc, 0, v15, vcc
	v_add_co_u32_e32 v20, vcc, s33, v14
	s_nop 1
	v_addc_co_u32_e32 v21, vcc, 0, v15, vcc
	v_add_co_u32_e32 v22, vcc, s76, v14
	s_nop 1
	v_addc_co_u32_e32 v23, vcc, 0, v15, vcc
	v_add_co_u32_e32 v24, vcc, s0, v14
	s_nop 1
	v_addc_co_u32_e32 v25, vcc, 0, v15, vcc
	v_add_co_u32_e32 v26, vcc, s1, v14
	s_nop 1
	v_addc_co_u32_e32 v27, vcc, 0, v15, vcc
	v_add_co_u32_e32 v28, vcc, s81, v14
	s_nop 1
	v_addc_co_u32_e32 v29, vcc, 0, v15, vcc
	v_add_co_u32_e32 v30, vcc, s82, v14
	s_nop 1
	v_addc_co_u32_e32 v31, vcc, 0, v15, vcc
	global_load_dword v47, v[16:17], off
	global_load_dword v61, v[18:19], off
	global_load_dword v62, v[20:21], off
	global_load_dword v63, v[22:23], off
	global_load_dword v64, v[24:25], off
	global_load_dword v65, v[26:27], off
	global_load_dword v66, v[28:29], off
	s_nop 0
	global_load_dword v30, v[30:31], off
	v_add_co_u32_e32 v16, vcc, s83, v14
	s_nop 1
	v_addc_co_u32_e32 v17, vcc, 0, v15, vcc
	v_add_co_u32_e32 v18, vcc, s84, v14
	s_nop 1
	v_addc_co_u32_e32 v19, vcc, 0, v15, vcc
	v_add_co_u32_e32 v20, vcc, s85, v14
	s_nop 1
	v_addc_co_u32_e32 v21, vcc, 0, v15, vcc
	v_add_co_u32_e32 v22, vcc, s86, v14
	s_nop 1
	v_addc_co_u32_e32 v23, vcc, 0, v15, vcc
	v_add_co_u32_e32 v24, vcc, s87, v14
	s_nop 1
	v_addc_co_u32_e32 v25, vcc, 0, v15, vcc
	v_add_co_u32_e32 v26, vcc, s88, v14
	s_nop 1
	v_addc_co_u32_e32 v27, vcc, 0, v15, vcc
	v_add_co_u32_e32 v28, vcc, s89, v14
	s_nop 1
	v_addc_co_u32_e32 v29, vcc, 0, v15, vcc
	v_add_co_u32_e32 v14, vcc, s90, v14
	s_nop 1
	v_addc_co_u32_e32 v15, vcc, 0, v15, vcc
	global_load_dword v16, v[16:17], off
	s_nop 0
	global_load_dword v17, v[18:19], off
	s_nop 0
	global_load_dword v18, v[20:21], off
	global_load_dword v19, v[22:23], off
	s_nop 0
	global_load_dword v20, v[24:25], off
	global_load_dword v21, v[26:27], off
	global_load_dword v22, v[28:29], off
	s_nop 0
	global_load_dword v14, v[14:15], off
	s_waitcnt vmcnt(30)
; #define LAS __attribute__((address_space(3)))
; __device__ __forceinline__ unsigned cvtpk(float lo, float hi) { f32x2 v = {lo, hi}; bf16x2_t b = __builtin_convertvector(v, bf16x2_t); return __builtin_bit_cast(unsigned, b); }
; __device__ __forceinline__ unsigned wq(unsigned two_bf16) {
;     if (WQ_DROP == 0) return two_bf16;
;     const unsigned half = (1u << (WQ_DROP - 1)) * 0x00010001u, mask = ~(((1u << WQ_DROP) - 1u) * 0x00010001u);
;     return (two_bf16 + half) & mask;
; }
; __device__ __forceinline__ void transpose_item(const float* W, int ldw, int k0, int srccol0, const float* gain, bf16_t* dst, int dpitch, int drow0, int dk0, LAS float* scr, int lane) {
;     ...
;     for (int i = 0; i < 32; ++i) { const int kk = 2 * i + (lane >> 5); scr[kk * 33 + (lane & 31)] = tv[i]; }
;     asm volatile("s_waitcnt lgkmcnt(0)" ::: "memory");
;     const int c = lane & 7;
; #pragma unroll
;     for (int j = 0; j < 4; ++j) { const int n = (lane >> 3) + 8 * j; const LAS float* s = scr + (8 * c) * 33 + n;
;         u32x4 o; o.x = wq(cvtpk(s[0 * 33], s[1 * 33])); o.y = wq(cvtpk(s[2 * 33], s[3 * 33])); o.z = wq(cvtpk(s[4 * 33], s[5 * 33])); o.w = wq(cvtpk(s[6 * 33], s[7 * 33]));
;         *(u32x4*)(dst + (size_t)(drow0 + n) * dpitch + dk0 + k0 + 8 * c) = o; }
	ds_write2_b32 v48, v13, v32 offset1:66
	s_waitcnt vmcnt(28)
	ds_write2_b32 v48, v33, v34 offset0:132 offset1:198
	s_waitcnt vmcnt(26)
	ds_write2_b32 v54, v35, v36 offset0:8 offset1:74
	s_waitcnt vmcnt(24)
	ds_write2_b32 v54, v37, v38 offset0:140 offset1:206
	s_waitcnt vmcnt(22)
	ds_write2_b32 v55, v39, v40 offset0:16 offset1:82
	s_waitcnt vmcnt(20)
	ds_write2_b32 v55, v41, v42 offset0:148 offset1:214
	s_waitcnt vmcnt(18)
	ds_write2_b32 v56, v43, v44 offset0:24 offset1:90
	s_waitcnt vmcnt(16)
	ds_write2_b32 v56, v45, v46 offset0:156 offset1:222
	s_waitcnt vmcnt(14)
	ds_write2_b32 v57, v47, v61 offset0:32 offset1:98
	s_waitcnt vmcnt(12)
	ds_write2_b32 v57, v62, v63 offset0:164 offset1:230
	s_waitcnt vmcnt(10)
	ds_write2_b32 v58, v64, v65 offset0:40 offset1:106
	s_waitcnt vmcnt(8)
	ds_write2_b32 v58, v66, v30 offset0:172 offset1:238
	s_waitcnt vmcnt(6)
	ds_write2_b32 v59, v16, v17 offset0:48 offset1:114
	s_waitcnt vmcnt(4)
	ds_write2_b32 v59, v18, v19 offset0:180 offset1:246
	s_waitcnt vmcnt(2)
	ds_write2_b32 v60, v20, v21 offset0:56 offset1:122
	s_waitcnt vmcnt(0)
	ds_write2_b32 v60, v22, v14 offset0:188 offset1:254
	s_waitcnt lgkmcnt(0)
	ds_read2_b32 v[18:19], v50 offset0:33 offset1:41
	ds_read2_b32 v[20:21], v50 offset1:8
	ds_read2_b32 v[22:23], v50 offset0:66 offset1:74
	ds_read2_b32 v[24:25], v50 offset0:99 offset1:107
	v_mov_b32_e32 v13, v3
	ds_read2_b32 v[28:29], v50 offset0:132 offset1:140
	ds_read2_b32 v[30:31], v50 offset0:165 offset1:173
	v_lshl_add_u64 v[26:27], s[8:9], 0, v[12:13]
	s_waitcnt lgkmcnt(4)
	v_cvt_pk_bf16_f32 v13, v20, v18
	v_add_u32_e32 v13, 0x20002, v13
	ds_read2_b32 v[32:33], v50 offset0:198 offset1:206
	ds_read2_b32 v[34:35], v50 offset0:231 offset1:239
	v_and_b32_e32 v14, 0xfffcfffc, v13
	s_waitcnt lgkmcnt(4)
	v_cvt_pk_bf16_f32 v13, v22, v24
	v_add_u32_e32 v13, 0x20002, v13
	v_and_b32_e32 v15, 0xfffcfffc, v13
	s_waitcnt lgkmcnt(2)
	v_cvt_pk_bf16_f32 v13, v28, v30
	v_add_u32_e32 v13, 0x20002, v13
	v_and_b32_e32 v16, 0xfffcfffc, v13
	s_waitcnt lgkmcnt(0)
	v_cvt_pk_bf16_f32 v13, v32, v34
	v_add_u32_e32 v13, 0x20002, v13
	v_and_b32_e32 v17, 0xfffcfffc, v13
	v_or_b32_e32 v13, s2, v49
	v_mul_u32_u24_e32 v13, 0xb00, v13
	v_lshlrev_b32_e32 v36, 1, v13
	v_mov_b32_e32 v37, v3
	v_cvt_pk_bf16_f32 v13, v21, v19
	v_lshl_add_u64 v[36:37], v[26:27], 0, v[36:37]
	v_add_u32_e32 v13, 0x20002, v13
	global_store_dwordx4 v[36:37], v[14:17], off sc1
	v_mov_b32_e32 v19, v3
	v_mov_b32_e32 v37, v3
	v_and_b32_e32 v14, 0xfffcfffc, v13
	v_cvt_pk_bf16_f32 v13, v23, v25
	v_add_u32_e32 v13, 0x20002, v13
	v_and_b32_e32 v15, 0xfffcfffc, v13
	v_cvt_pk_bf16_f32 v13, v29, v31
	v_add_u32_e32 v13, 0x20002, v13
	v_and_b32_e32 v16, 0xfffcfffc, v13
	v_cvt_pk_bf16_f32 v13, v33, v35
	v_add_u32_e32 v13, 0x20002, v13
	v_and_b32_e32 v17, 0xfffcfffc, v13
	v_or_b32_e32 v13, s2, v51
	v_mul_u32_u24_e32 v13, 0xb00, v13
	ds_read2_b32 v[20:21], v50 offset0:16 offset1:24
	ds_read2_b32 v[22:23], v50 offset0:49 offset1:57
	v_lshlrev_b32_e32 v18, 1, v13
	v_lshl_add_u64 v[18:19], v[26:27], 0, v[18:19]
	ds_read2_b32 v[24:25], v50 offset0:82 offset1:90
	ds_read2_b32 v[28:29], v50 offset0:115 offset1:123
	global_store_dwordx4 v[18:19], v[14:17], off sc1
	ds_read2_b32 v[18:19], v50 offset0:148 offset1:156
	ds_read2_b32 v[30:31], v50 offset0:181 offset1:189
	s_waitcnt lgkmcnt(4)
	v_cvt_pk_bf16_f32 v13, v20, v22
	v_add_u32_e32 v13, 0x20002, v13
	ds_read2_b32 v[32:33], v50 offset0:214 offset1:222
	ds_read2_b32 v[34:35], v50 offset0:247 offset1:255
	v_and_b32_e32 v14, 0xfffcfffc, v13
	s_waitcnt lgkmcnt(4)
	v_cvt_pk_bf16_f32 v13, v24, v28
	v_add_u32_e32 v13, 0x20002, v13
	v_and_b32_e32 v15, 0xfffcfffc, v13
	s_waitcnt lgkmcnt(2)
	v_cvt_pk_bf16_f32 v13, v18, v30
	v_add_u32_e32 v13, 0x20002, v13
	v_and_b32_e32 v16, 0xfffcfffc, v13
	s_waitcnt lgkmcnt(0)
	v_cvt_pk_bf16_f32 v13, v32, v34
	v_add_u32_e32 v13, 0x20002, v13
	v_and_b32_e32 v17, 0xfffcfffc, v13
	v_or_b32_e32 v13, s2, v52
	v_mul_u32_u24_e32 v13, 0xb00, v13
	v_lshlrev_b32_e32 v36, 1, v13
	v_cvt_pk_bf16_f32 v13, v21, v23
	v_lshl_add_u64 v[36:37], v[26:27], 0, v[36:37]
	v_add_u32_e32 v13, 0x20002, v13
	global_store_dwordx4 v[36:37], v[14:17], off sc1
	s_nop 1
	v_and_b32_e32 v14, 0xfffcfffc, v13
	v_cvt_pk_bf16_f32 v13, v25, v29
	v_add_u32_e32 v13, 0x20002, v13
	v_and_b32_e32 v15, 0xfffcfffc, v13
	v_cvt_pk_bf16_f32 v13, v19, v31
	v_add_u32_e32 v13, 0x20002, v13
	v_and_b32_e32 v16, 0xfffcfffc, v13
	v_cvt_pk_bf16_f32 v13, v33, v35
	v_add_u32_e32 v13, 0x20002, v13
	v_and_b32_e32 v17, 0xfffcfffc, v13
	v_or_b32_e32 v13, s2, v53
	v_mul_u32_u24_e32 v13, 0xb00, v13
	v_lshlrev_b32_e32 v18, 1, v13
	v_mov_b32_e32 v19, v3
	v_lshl_add_u64 v[18:19], v[26:27], 0, v[18:19]
	global_store_dwordx4 v[18:19], v[14:17], off sc1
	s_waitcnt lgkmcnt(0)

; __device__ __forceinline__ unsigned cvtpk(float lo, float hi) { f32x2 v = {lo, hi}; bf16x2_t b = __builtin_convertvector(v, bf16x2_t); return __builtin_bit_cast(unsigned, b); }
; __device__ __forceinline__ void prologue(const Params& P, LAS unsigned char* lds, int gw, int NGW, int wave, int lane) {
;     ...
; #pragma unroll
;           for (int k = 0; k < 4; ++k) { const int mk = m + k * NGW; ok[k] = mk < MT; mr[k] = ok[k] ? mk : m; xr[k] = (mr[k] < MP ? P.in[0] + (size_t)mr[k] * DM : P.in[1] + (size_t)(mr[k] - MP) * DM); }
;           f32x4 v[4][4];
; #pragma unroll
;           for (int k = 0; k < 4; ++k)
; #pragma unroll
;               for (int j = 0; j < 4; ++j) v[k][j] = ((const f32x4*)xr[k] + lane)[64 * j];
; #pragma unroll
;           for (int k = 0; k < 4; ++k) {
;               float sq = 0.f;
; #pragma unroll
;               for (int j = 0; j < 4; ++j) sq += (v[k][j][0] * v[k][j][0] + v[k][j][1] * v[k][j][1]) + (v[k][j][2] * v[k][j][2] + v[k][j][3] * v[k][j][3]);
;               sq = wave_sum(sq);
;               if (ok[k]) {
;                   u32x2* o = (u32x2*)(xb + (size_t)mr[k] * DM) + lane;
; #pragma unroll
;                   for (int j = 0; j < 4; ++j) { u32x2 w; w.x = cvtpk(v[k][j][0], v[k][j][1]); w.y = cvtpk(v[k][j][2], v[k][j][3]); o[64 * j] = w; }
;                   if (lane < 4) { const f32x4 z = {lane == 0 ? sq : 0.f, 0.f, 0.f, 0.f}; *(f32x4*)(st + (size_t)mr[k] * 16 + 4 * lane) = z; }
.LBB0_45:
	s_add_i32 s8, s6, 0xffff8000
	s_ashr_i32 s7, s6, 31
	s_cmp_lt_i32 s6, 0x8000
	s_cselect_b32 s9, s7, 0
	s_cselect_b32 s8, s6, s8
	s_cselect_b32 s16, s37, s39
	s_cselect_b32 s17, s36, s38
	s_lshl_b64 s[8:9], s[8:9], 12
	s_add_u32 s8, s17, s8
	s_addc_u32 s9, s16, s9
	global_load_dwordx4 v[64:67], v63, s[8:9]
	global_load_dwordx4 v[68:71], v63, s[8:9] offset:1024
	s_add_i32 s16, s11, s6
	global_load_dwordx4 v[72:75], v63, s[8:9] offset:2048
	global_load_dwordx4 v[76:79], v63, s[8:9] offset:3072
	s_cmp_lt_i32 s16, 0xc000
	s_cselect_b64 s[44:45], -1, 0
	s_and_b64 s[42:43], s[44:45], exec
	s_cselect_b32 s8, s16, s6
	s_ashr_i32 s9, s8, 31
	s_add_i32 s17, s8, 0xffff8000
	s_cmp_lt_i32 s8, 0x8000
	s_cselect_b32 s9, s9, 0
	s_cselect_b32 s8, s8, s17
	s_cselect_b32 s17, s37, s39
	s_cselect_b32 s42, s36, s38
	s_lshl_b64 s[8:9], s[8:9], 12
	s_add_u32 s46, s42, s8
	s_addc_u32 s47, s17, s9
	s_add_i32 s17, s11, s16
	s_cmp_lt_i32 s17, 0xc000
	s_cselect_b64 s[42:43], -1, 0
	s_and_b64 s[8:9], s[42:43], exec
	s_cselect_b32 s8, s17, s6
	s_ashr_i32 s9, s8, 31
	s_add_i32 s49, s8, 0xffff8000
	s_cmp_lt_i32 s8, 0x8000
	s_cselect_b32 s9, s9, 0
	s_cselect_b32 s8, s8, s49
	s_cselect_b32 s49, s37, s39
	s_cselect_b32 s50, s36, s38
	s_lshl_b64 s[8:9], s[8:9], 12
	s_add_u32 s50, s50, s8
	s_addc_u32 s51, s49, s9
	s_add_i32 s49, s11, s17
	s_cmp_lt_i32 s49, 0xc000
	s_cselect_b64 s[8:9], -1, 0
	s_and_b64 s[58:59], s[8:9], exec
	s_cselect_b32 s17, s49, s6
	s_ashr_i32 s58, s17, 31
	s_add_i32 s60, s17, 0xffff8000
	s_cmp_lt_i32 s17, 0x8000
	s_cselect_b32 s59, s58, 0
	s_cselect_b32 s58, s17, s60
	s_cselect_b32 s17, s37, s39
	s_cselect_b32 s60, s36, s38
	s_lshl_b64 s[58:59], s[58:59], 12
	s_add_u32 s58, s60, s58
	s_addc_u32 s59, s17, s59
	global_load_dwordx4 v[50:53], v63, s[46:47]
	global_load_dwordx4 v[46:49], v63, s[46:47] offset:1024
	global_load_dwordx4 v[42:45], v63, s[46:47] offset:2048
	global_load_dwordx4 v[38:41], v63, s[46:47] offset:3072
	global_load_dwordx4 v[34:37], v63, s[50:51]
	global_load_dwordx4 v[30:33], v63, s[50:51] offset:1024
	global_load_dwordx4 v[26:29], v63, s[50:51] offset:2048
	global_load_dwordx4 v[22:25], v63, s[50:51] offset:3072
	global_load_dwordx4 v[18:21], v63, s[58:59]
	global_load_dwordx4 v[14:17], v63, s[58:59] offset:1024
	global_load_dwordx4 v[10:13], v63, s[58:59] offset:2048
	global_load_dwordx4 v[6:9], v63, s[58:59] offset:3072
	s_lshl_b64 s[46:47], s[6:7], 11
	s_waitcnt vmcnt(15)
	v_mul_f32_e32 v2, v65, v65
	s_waitcnt lgkmcnt(0)
	v_mul_f32_e32 v4, v67, v67
	s_waitcnt vmcnt(14)
	v_mul_f32_e32 v5, v69, v69
	v_mul_f32_e32 v80, v71, v71
	s_waitcnt vmcnt(13)
	v_mul_f32_e32 v81, v73, v73
	v_mul_f32_e32 v82, v75, v75
	v_fmac_f32_e32 v2, v64, v64
	v_fmac_f32_e32 v4, v66, v66
	v_fmac_f32_e32 v5, v68, v68
	v_fmac_f32_e32 v80, v70, v70
	s_waitcnt vmcnt(12)
	v_mul_f32_e32 v83, v77, v77
	v_mul_f32_e32 v84, v79, v79
	v_fmac_f32_e32 v81, v72, v72
	v_fmac_f32_e32 v82, v74, v74
	v_add_f32_e32 v2, v2, v4
	v_add_f32_e32 v4, v5, v80
	v_fmac_f32_e32 v83, v76, v76
	v_add_f32_e32 v5, v81, v82
	v_add_f32_e32 v2, v2, v4
	v_fmac_f32_e32 v84, v78, v78
	v_add_f32_e32 v2, v2, v5
	v_add_f32_e32 v4, v83, v84
	v_add_f32_e32 v2, v2, v4
	ds_bpermute_b32 v4, v1, v2
	v_cvt_pk_bf16_f32 v5, v66, v67
	v_lshl_add_u64 v[80:81], v[54:55], 0, s[46:47]
	v_cvt_pk_bf16_f32 v66, v72, v73
	s_waitcnt lgkmcnt(0)
	v_add_f32_e32 v2, v2, v4
	ds_bpermute_b32 v4, v58, v2
	s_waitcnt lgkmcnt(0)
	v_add_f32_e32 v2, v2, v4
	ds_bpermute_b32 v4, v59, v2
	s_waitcnt lgkmcnt(0)
	v_add_f32_e32 v2, v2, v4
	ds_bpermute_b32 v82, v60, v2
	v_cvt_pk_bf16_f32 v4, v64, v65
	v_cvt_pk_bf16_f32 v64, v68, v69
	v_cvt_pk_bf16_f32 v65, v70, v71
	global_store_dwordx2 v[80:81], v[4:5], off sc1
	global_store_dwordx2 v[80:81], v[64:65], off offset:512 sc1
	s_waitcnt lgkmcnt(0)
	v_add_f32_e32 v2, v2, v82
	ds_bpermute_b32 v67, v61, v2
	v_cvt_pk_bf16_f32 v64, v76, v77
	v_cvt_pk_bf16_f32 v65, v78, v79
	global_store_dwordx2 v[80:81], v[64:65], off offset:1536 sc1
	s_waitcnt lgkmcnt(0)
	v_add_f32_e32 v2, v2, v67
	ds_bpermute_b32 v4, v62, v2
	v_cvt_pk_bf16_f32 v67, v74, v75
	global_store_dwordx2 v[80:81], v[66:67], off offset:1024 sc1
	s_and_saveexec_b64 s[46:47], s[0:1]
	s_cbranch_execz .LBB0_47
	s_waitcnt lgkmcnt(0)
	v_add_f32_e32 v2, v2, v4
	s_lshl_b64 s[50:51], s[6:7], 6
	v_cndmask_b32_e64 v2, 0, v2, s[2:3]
	v_lshl_add_u64 v[64:65], v[56:57], 0, s[50:51]
	v_mov_b32_e32 v4, v3
	v_mov_b32_e32 v5, v3
	global_store_dwordx4 v[64:65], v[2:5], off sc1
.LBB0_47:
	s_or_b64 exec, exec, s[46:47]
	s_waitcnt vmcnt(15)
	v_mul_f32_e32 v2, v51, v51
	s_waitcnt lgkmcnt(0)
	v_mul_f32_e32 v4, v53, v53
	v_fmac_f32_e32 v2, v50, v50
	v_fmac_f32_e32 v4, v52, v52
	v_add_f32_e32 v2, v2, v4
	s_waitcnt vmcnt(14)
	v_mul_f32_e32 v4, v47, v47
	v_mul_f32_e32 v5, v49, v49
	v_fmac_f32_e32 v4, v46, v46
	v_fmac_f32_e32 v5, v48, v48
	v_add_f32_e32 v4, v4, v5
	v_add_f32_e32 v2, v2, v4
	s_waitcnt vmcnt(13)
	v_mul_f32_e32 v4, v43, v43
	v_mul_f32_e32 v5, v45, v45
	v_fmac_f32_e32 v4, v42, v42
	v_fmac_f32_e32 v5, v44, v44
	v_add_f32_e32 v4, v4, v5
	v_add_f32_e32 v2, v2, v4
	s_waitcnt vmcnt(12)
	v_mul_f32_e32 v4, v39, v39
	v_mul_f32_e32 v5, v41, v41
	v_fmac_f32_e32 v4, v38, v38
	v_fmac_f32_e32 v5, v40, v40
	v_add_f32_e32 v4, v4, v5
	v_add_f32_e32 v2, v2, v4
	ds_bpermute_b32 v4, v1, v2
	s_andn2_b64 vcc, exec, s[44:45]
	s_waitcnt lgkmcnt(0)
	v_add_f32_e32 v2, v2, v4
	ds_bpermute_b32 v4, v58, v2
	s_waitcnt lgkmcnt(0)
	v_add_f32_e32 v2, v2, v4
	ds_bpermute_b32 v4, v59, v2
	s_waitcnt lgkmcnt(0)
	v_add_f32_e32 v2, v2, v4
	ds_bpermute_b32 v4, v60, v2
	s_waitcnt lgkmcnt(0)
	v_add_f32_e32 v2, v2, v4
	ds_bpermute_b32 v4, v61, v2
	s_waitcnt lgkmcnt(0)
	v_add_f32_e32 v2, v2, v4
	ds_bpermute_b32 v4, v62, v2
	s_cbranch_vccnz .LBB0_51
	s_ashr_i32 s17, s16, 31
	s_lshl_b64 s[44:45], s[16:17], 11
	v_lshl_add_u64 v[64:65], v[54:55], 0, s[44:45]
	v_cvt_pk_bf16_f32 v50, v50, v51
	v_cvt_pk_bf16_f32 v51, v52, v53
	v_cvt_pk_bf16_f32 v46, v46, v47
	v_cvt_pk_bf16_f32 v47, v48, v49
	v_cvt_pk_bf16_f32 v42, v42, v43
	v_cvt_pk_bf16_f32 v43, v44, v45
	v_cvt_pk_bf16_f32 v38, v38, v39
	v_cvt_pk_bf16_f32 v39, v40, v41
	global_store_dwordx2 v[64:65], v[50:51], off sc1
	global_store_dwordx2 v[64:65], v[46:47], off offset:512 sc1
	global_store_dwordx2 v[64:65], v[42:43], off offset:1024 sc1
	global_store_dwordx2 v[64:65], v[38:39], off offset:1536 sc1
	s_and_saveexec_b64 s[44:45], s[0:1]
	s_cbranch_execz .LBB0_50
	s_waitcnt lgkmcnt(0)
	v_add_f32_e32 v2, v2, v4
	s_lshl_b64 s[16:17], s[16:17], 6
	v_cndmask_b32_e64 v2, 0, v2, s[2:3]
	v_lshl_add_u64 v[38:39], v[56:57], 0, s[16:17]
	v_mov_b32_e32 v4, v3
	v_mov_b32_e32 v5, v3
	global_store_dwordx4 v[38:39], v[2:5], off sc1

; __device__ __forceinline__ unsigned cvtpk(float lo, float hi) { f32x2 v = {lo, hi}; bf16x2_t b = __builtin_convertvector(v, bf16x2_t); return __builtin_bit_cast(unsigned, b); }
; __device__ __forceinline__ void prologue(const Params& P, LAS unsigned char* lds, int gw, int NGW, int wave, int lane) {
;     ...
;           for (int k = 0; k < 4; ++k) {
;               float sq = 0.f;
; #pragma unroll
;               for (int j = 0; j < 4; ++j) sq += (v[k][j][0] * v[k][j][0] + v[k][j][1] * v[k][j][1]) + (v[k][j][2] * v[k][j][2] + v[k][j][3] * v[k][j][3]);
;               sq = wave_sum(sq);
;               if (ok[k]) {
;                   u32x2* o = (u32x2*)(xb + (size_t)mr[k] * DM) + lane;
; #pragma unroll
;                   for (int j = 0; j < 4; ++j) { u32x2 w; w.x = cvtpk(v[k][j][0], v[k][j][1]); w.y = cvtpk(v[k][j][2], v[k][j][3]); o[64 * j] = w; }
;                   if (lane < 4) { const f32x4 z = {lane == 0 ? sq : 0.f, 0.f, 0.f, 0.f}; *(f32x4*)(st + (size_t)mr[k] * 16 + 4 * lane) = z; }
.LBB0_51:
	s_waitcnt vmcnt(11)
	v_mul_f32_e32 v2, v35, v35
	s_waitcnt lgkmcnt(0)
	v_mul_f32_e32 v4, v37, v37
	v_fmac_f32_e32 v2, v34, v34
	v_fmac_f32_e32 v4, v36, v36
	v_add_f32_e32 v2, v2, v4
	s_waitcnt vmcnt(10)
	v_mul_f32_e32 v4, v31, v31
	v_mul_f32_e32 v5, v33, v33
	v_fmac_f32_e32 v4, v30, v30
	v_fmac_f32_e32 v5, v32, v32
	v_add_f32_e32 v4, v4, v5
	v_add_f32_e32 v2, v2, v4
	s_waitcnt vmcnt(9)
	v_mul_f32_e32 v4, v27, v27
	v_mul_f32_e32 v5, v29, v29
	v_fmac_f32_e32 v4, v26, v26
	v_fmac_f32_e32 v5, v28, v28
	v_add_f32_e32 v4, v4, v5
	v_add_f32_e32 v2, v2, v4
	s_waitcnt vmcnt(8)
	v_mul_f32_e32 v4, v23, v23
	v_mul_f32_e32 v5, v25, v25
	v_fmac_f32_e32 v4, v22, v22
	v_fmac_f32_e32 v5, v24, v24
	v_add_f32_e32 v4, v4, v5
	v_add_f32_e32 v2, v2, v4
	ds_bpermute_b32 v4, v1, v2
	s_andn2_b64 vcc, exec, s[42:43]
	s_waitcnt lgkmcnt(0)
	v_add_f32_e32 v2, v2, v4
	ds_bpermute_b32 v4, v58, v2
	s_waitcnt lgkmcnt(0)
	v_add_f32_e32 v2, v2, v4
	ds_bpermute_b32 v4, v59, v2
	s_waitcnt lgkmcnt(0)
	v_add_f32_e32 v2, v2, v4
	ds_bpermute_b32 v4, v60, v2
	s_waitcnt lgkmcnt(0)
	v_add_f32_e32 v2, v2, v4
	ds_bpermute_b32 v4, v61, v2
	s_waitcnt lgkmcnt(0)
	v_add_f32_e32 v2, v2, v4
	ds_bpermute_b32 v4, v62, v2
	s_cbranch_vccnz .LBB0_55
	s_add_i32 s16, s33, s6
	s_ashr_i32 s17, s16, 31
	s_lshl_b64 s[42:43], s[16:17], 11
	v_lshl_add_u64 v[38:39], v[54:55], 0, s[42:43]
	v_cvt_pk_bf16_f32 v34, v34, v35
	v_cvt_pk_bf16_f32 v35, v36, v37
	v_cvt_pk_bf16_f32 v30, v30, v31
	v_cvt_pk_bf16_f32 v31, v32, v33
	v_cvt_pk_bf16_f32 v26, v26, v27
	v_cvt_pk_bf16_f32 v27, v28, v29
	v_cvt_pk_bf16_f32 v22, v22, v23
	v_cvt_pk_bf16_f32 v23, v24, v25
	global_store_dwordx2 v[38:39], v[34:35], off sc1
	global_store_dwordx2 v[38:39], v[30:31], off offset:512 sc1
	global_store_dwordx2 v[38:39], v[26:27], off offset:1024 sc1
	global_store_dwordx2 v[38:39], v[22:23], off offset:1536 sc1
	s_and_saveexec_b64 s[42:43], s[0:1]
	s_cbranch_execz .LBB0_54
	s_waitcnt lgkmcnt(0)
	v_add_f32_e32 v2, v2, v4
	s_lshl_b64 s[16:17], s[16:17], 6
	v_cndmask_b32_e64 v2, 0, v2, s[2:3]
	v_lshl_add_u64 v[22:23], v[56:57], 0, s[16:17]
	v_mov_b32_e32 v4, v3
	v_mov_b32_e32 v5, v3
	global_store_dwordx4 v[22:23], v[2:5], off sc1

; __device__ __forceinline__ unsigned cvtpk(float lo, float hi) { f32x2 v = {lo, hi}; bf16x2_t b = __builtin_convertvector(v, bf16x2_t); return __builtin_bit_cast(unsigned, b); }
; __device__ __forceinline__ void prologue(const Params& P, LAS unsigned char* lds, int gw, int NGW, int wave, int lane) {
;     ...
;           for (int k = 0; k < 4; ++k) {
;               float sq = 0.f;
; #pragma unroll
;               for (int j = 0; j < 4; ++j) sq += (v[k][j][0] * v[k][j][0] + v[k][j][1] * v[k][j][1]) + (v[k][j][2] * v[k][j][2] + v[k][j][3] * v[k][j][3]);
;               sq = wave_sum(sq);
;               if (ok[k]) {
;                   u32x2* o = (u32x2*)(xb + (size_t)mr[k] * DM) + lane;
; #pragma unroll
;                   for (int j = 0; j < 4; ++j) { u32x2 w; w.x = cvtpk(v[k][j][0], v[k][j][1]); w.y = cvtpk(v[k][j][2], v[k][j][3]); o[64 * j] = w; }
;                   if (lane < 4) { const f32x4 z = {lane == 0 ? sq : 0.f, 0.f, 0.f, 0.f}; *(f32x4*)(st + (size_t)mr[k] * 16 + 4 * lane) = z; }
.LBB0_55:
	s_waitcnt vmcnt(7)
	v_mul_f32_e32 v2, v19, v19
	s_waitcnt lgkmcnt(0)
	v_mul_f32_e32 v4, v21, v21
	v_fmac_f32_e32 v2, v18, v18
	v_fmac_f32_e32 v4, v20, v20
	v_add_f32_e32 v2, v2, v4
	s_waitcnt vmcnt(6)
	v_mul_f32_e32 v4, v15, v15
	v_mul_f32_e32 v5, v17, v17
	v_fmac_f32_e32 v4, v14, v14
	v_fmac_f32_e32 v5, v16, v16
	v_add_f32_e32 v4, v4, v5
	v_add_f32_e32 v2, v2, v4
	s_waitcnt vmcnt(5)
	v_mul_f32_e32 v4, v11, v11
	v_mul_f32_e32 v5, v13, v13
	v_fmac_f32_e32 v4, v10, v10
	v_fmac_f32_e32 v5, v12, v12
	v_add_f32_e32 v4, v4, v5
	v_add_f32_e32 v2, v2, v4
	s_waitcnt vmcnt(4)
	v_mul_f32_e32 v4, v7, v7
	v_mul_f32_e32 v5, v9, v9
	v_fmac_f32_e32 v4, v6, v6
	v_fmac_f32_e32 v5, v8, v8
	v_add_f32_e32 v4, v4, v5
	v_add_f32_e32 v2, v2, v4
	ds_bpermute_b32 v4, v1, v2
	s_andn2_b64 vcc, exec, s[8:9]
	s_waitcnt lgkmcnt(0)
	v_add_f32_e32 v2, v2, v4
	ds_bpermute_b32 v4, v58, v2
	s_waitcnt lgkmcnt(0)
	v_add_f32_e32 v2, v2, v4
	ds_bpermute_b32 v4, v59, v2
	s_waitcnt lgkmcnt(0)
	v_add_f32_e32 v2, v2, v4
	ds_bpermute_b32 v4, v60, v2
	s_waitcnt lgkmcnt(0)
	v_add_f32_e32 v2, v2, v4
	ds_bpermute_b32 v4, v61, v2
	s_waitcnt lgkmcnt(0)
	v_add_f32_e32 v2, v2, v4
	ds_bpermute_b32 v4, v62, v2
	s_cbranch_vccnz .LBB0_44
	s_add_i32 s6, s48, s6
	s_ashr_i32 s7, s6, 31
	s_lshl_b64 s[8:9], s[6:7], 11
	v_lshl_add_u64 v[22:23], v[54:55], 0, s[8:9]
	v_cvt_pk_bf16_f32 v18, v18, v19
	v_cvt_pk_bf16_f32 v19, v20, v21
	v_cvt_pk_bf16_f32 v14, v14, v15
	v_cvt_pk_bf16_f32 v15, v16, v17
	v_cvt_pk_bf16_f32 v10, v10, v11
	v_cvt_pk_bf16_f32 v11, v12, v13
	v_cvt_pk_bf16_f32 v6, v6, v7
	v_cvt_pk_bf16_f32 v7, v8, v9
	global_store_dwordx2 v[22:23], v[18:19], off sc1
	global_store_dwordx2 v[22:23], v[14:15], off offset:512 sc1
	global_store_dwordx2 v[22:23], v[10:11], off offset:1024 sc1
	global_store_dwordx2 v[22:23], v[6:7], off offset:1536 sc1
	s_and_saveexec_b64 s[8:9], s[0:1]
	s_cbranch_execz .LBB0_43
	s_waitcnt lgkmcnt(0)
	v_add_f32_e32 v2, v2, v4
	s_lshl_b64 s[6:7], s[6:7], 6
	v_cndmask_b32_e64 v2, 0, v2, s[2:3]
	v_lshl_add_u64 v[6:7], v[56:57], 0, s[6:7]
	v_mov_b32_e32 v4, v3
	v_mov_b32_e32 v5, v3
	global_store_dwordx4 v[6:7], v[2:5], off sc1
	s_branch .LBB0_43

; #define LAS __attribute__((address_space(3)))
; __device__ __forceinline__ f32x4 sig_from_negl2(f32x4 t) { return rcp_4(exp2_4(t) + 1.0f); }
; __device__ __forceinline__ u32x2 pack4(f32x4 v) { u32x2 w; w.x = cvtpk(v[0], v[1]); w.y = cvtpk(v[2], v[3]); return w; }
; __device__ __forceinline__ void rstd8_lds(int rrel, int fq, float inv_dim, float (&rs)[2][4]) {
;     ...
;         for (int m = 0; m < 4; ++m) v[ai][m] = *(const LAS f32x4*)(lds + STAB_OFF + (rrel + ai * 128 + m * 16) * 64 + fq * 16);
; #pragma unroll
;     for (int ai = 0; ai < 2; ++ai)
; #pragma unroll
;         for (int m = 0; m < 4; ++m) { float q = (v[ai][m][0] + v[ai][m][1]) + (v[ai][m][2] + v[ai][m][3]); q += __shfl_xor(q, 16); q += __shfl_xor(q, 32); rs[ai][m] = __builtin_amdgcn_rsqf(q * inv_dim + EPS); }
;     __device__ __forceinline__ void operator()(const Acc& acc, const Unit& u, int wr, int wc, int fr, int fq) const {
;     ...
;         float rsv[2][4]; rstd8_lds(wr * 64 + fr, fq, 1.0f / 1024.0f, rsv);
; #pragma unroll
;         for (int ai = 0; ai < 2; ++ai)
; #pragma unroll
;             for (int m = 0; m < 4; ++m) {
;                 const int r = u.pm * 256 + ai * 128 + wr * 64 + m * 16 + fr;
;                 const float rs = rsv[ai][m], nrs = -LOG2E * rs, rs2 = rs * rs;
;                 u32x4 w;
; #pragma unroll
;                 for (int n = 0; n < 2; ++n) {
;                     const f32x4 ga = acc[ai][0][m][n], ua = acc[ai][1][m][n];
;                     const f32x4 sg = sig_from_negl2(ga * nrs);
;                     const u32x2 pk = pack4((ga * ua) * rs2 * sg);
.LBB0_137:
	ds_read_b128 v[156:159], v153
	ds_read_b128 v[160:163], v153 offset:1024
	ds_read_b128 v[164:167], v153 offset:2048
	ds_read_b128 v[172:175], v153 offset:3072
	v_and_b32_e32 v176, 64, v154
	v_xor_b32_e32 v169, 16, v154
	v_add_u32_e32 v178, 64, v176
	v_cmp_lt_i32_e32 vcc, v169, v178
	s_waitcnt lgkmcnt(0)
	v_mov_b32_e32 v176, v157
	v_mov_b32_e32 v177, v158
	v_mov_b32_e32 v157, v159
	v_cndmask_b32_e32 v169, v154, v169, vcc
	v_pk_add_f32 v[156:157], v[176:177], v[156:157]
	v_lshlrev_b32_e32 v169, 2, v169
	v_add_f32_e32 v156, v156, v157
	ds_bpermute_b32 v157, v169, v156
	v_xor_b32_e32 v158, 32, v154
	v_cmp_lt_i32_e32 vcc, v158, v178
	v_pk_mul_f32 v[124:125], v[128:129], v[124:125]
	v_pk_mul_f32 v[122:123], v[126:127], v[122:123]
	v_cndmask_b32_e32 v158, v154, v158, vcc
	v_lshlrev_b32_e32 v190, 2, v158
	s_waitcnt lgkmcnt(0)
	v_add_f32_e32 v188, v156, v157
	ds_bpermute_b32 v189, v190, v188
	ds_read_b128 v[156:159], v153 offset:8192
	ds_read_b128 v[176:179], v153 offset:9216
	ds_read_b128 v[180:183], v153 offset:10240
	ds_read_b128 v[184:187], v153 offset:11264
	v_pk_mul_f32 v[114:115], v[118:119], v[114:115]
	v_pk_mul_f32 v[116:117], v[120:121], v[116:117]
	v_lshl_or_b32 v168, s62, 7, v149
	s_waitcnt lgkmcnt(0)
	v_add_f32_e32 v191, v188, v189
	v_mov_b32_e32 v188, v161
	v_mov_b32_e32 v189, v162
	v_mov_b32_e32 v161, v163
	v_pk_add_f32 v[160:161], v[188:189], v[160:161]
	v_pk_mul_f32 v[106:107], v[110:111], v[106:107]
	v_add_f32_e32 v162, v160, v161
	v_mov_b32_e32 v160, v165
	v_mov_b32_e32 v161, v166
	v_mov_b32_e32 v165, v167
	v_pk_add_f32 v[160:161], v[160:161], v[164:165]
	ds_bpermute_b32 v163, v169, v162
	v_add_f32_e32 v160, v160, v161
	ds_bpermute_b32 v161, v169, v160
	v_fmamk_f32 v164, v191, 0x3a800000, v155
	v_rsq_f32_e32 v166, v164
	s_waitcnt lgkmcnt(0)
	v_add_f32_e32 v162, v162, v163
	ds_bpermute_b32 v163, v190, v162
	v_add_f32_e32 v164, v160, v161
	v_mov_b32_e32 v160, v173
	v_mov_b32_e32 v161, v174
	v_mov_b32_e32 v173, v175
	v_pk_add_f32 v[160:161], v[160:161], v[172:173]
	s_waitcnt lgkmcnt(0)
	v_add_f32_e32 v162, v162, v163
	v_add_f32_e32 v160, v160, v161
	ds_bpermute_b32 v161, v169, v160
	ds_bpermute_b32 v165, v190, v164
	v_fmamk_f32 v162, v162, 0x3a800000, v155
	v_rsq_f32_e32 v167, v162
	v_pk_mul_f32 v[108:109], v[112:113], v[108:109]
	s_waitcnt lgkmcnt(0)
	v_add_f32_e32 v163, v160, v161
	v_mov_b32_e32 v160, v157
	v_mov_b32_e32 v161, v158
	v_mov_b32_e32 v157, v159
	v_pk_add_f32 v[156:157], v[160:161], v[156:157]
	v_add_f32_e32 v162, v164, v165
	v_add_f32_e32 v156, v156, v157
	ds_bpermute_b32 v157, v169, v156
	ds_bpermute_b32 v164, v190, v163
	v_fmamk_f32 v158, v162, 0x3a800000, v155
	v_rsq_f32_e32 v159, v158
	v_pk_mul_f32 v[100:101], v[104:105], v[100:101]
	s_waitcnt lgkmcnt(0)
	v_add_f32_e32 v160, v156, v157
	v_mov_b32_e32 v156, v177
	v_mov_b32_e32 v157, v178
	v_mov_b32_e32 v177, v179
	ds_bpermute_b32 v161, v190, v160
	v_pk_add_f32 v[156:157], v[156:157], v[176:177]
	v_add_f32_e32 v158, v163, v164
	v_add_f32_e32 v156, v156, v157
	ds_bpermute_b32 v157, v169, v156
	v_fmamk_f32 v158, v158, 0x3a800000, v155
	v_rsq_f32_e32 v172, v158
	s_waitcnt lgkmcnt(0)
	v_add_f32_e32 v158, v160, v161
	v_fmamk_f32 v158, v158, 0x3a800000, v155
	v_rsq_f32_e32 v161, v158
	v_add_f32_e32 v158, v156, v157
	v_mov_b32_e32 v156, v181
	v_mov_b32_e32 v157, v182
	v_mov_b32_e32 v181, v183
	v_pk_add_f32 v[156:157], v[156:157], v[180:181]
	ds_bpermute_b32 v160, v190, v158
	v_add_f32_e32 v162, v156, v157
	ds_bpermute_b32 v163, v169, v162
	v_mov_b32_e32 v156, v185
	v_mov_b32_e32 v157, v186
	s_waitcnt lgkmcnt(0)
	v_add_f32_e32 v158, v158, v160
	v_fmamk_f32 v158, v158, 0x3a800000, v155
	v_add_f32_e32 v160, v162, v163
	ds_bpermute_b32 v162, v190, v160
	v_rsq_f32_e32 v173, v158
	v_mov_b32_e32 v185, v187
	v_pk_add_f32 v[156:157], v[156:157], v[184:185]
	v_pk_mul_f32 v[98:99], v[102:103], v[98:99]
	s_waitcnt lgkmcnt(0)
	v_add_f32_e32 v158, v160, v162
	v_mul_f32_e32 v160, 0xbfb8aa3b, v166
	v_pk_mul_f32 v[162:163], v[128:129], v[160:161] op_sel_hi:[1,0]
	v_pk_mul_f32 v[164:165], v[126:127], v[160:161] op_sel_hi:[1,0]
	v_exp_f32_e32 v162, v162
	v_exp_f32_e32 v164, v164
	v_exp_f32_e32 v163, v163
	v_exp_f32_e32 v165, v165
	v_add_f32_e32 v156, v156, v157
	ds_bpermute_b32 v157, v169, v156
	v_pk_add_f32 v[162:163], v[162:163], 1.0 op_sel_hi:[1,0]
	v_pk_add_f32 v[164:165], v[164:165], 1.0 op_sel_hi:[1,0]
	v_rcp_f32_e32 v162, v162
	v_rcp_f32_e32 v164, v164
	v_rcp_f32_e32 v165, v165
	v_rcp_f32_e32 v163, v163
	v_pk_mul_f32 v[126:127], v[120:121], v[160:161] op_sel_hi:[1,0]
	v_pk_mul_f32 v[128:129], v[118:119], v[160:161] op_sel_hi:[1,0]
	v_exp_f32_e32 v126, v126
	v_exp_f32_e32 v128, v128
	v_exp_f32_e32 v127, v127
	v_exp_f32_e32 v129, v129
	v_mul_f32_e32 v166, v166, v166
	v_pk_mul_f32 v[122:123], v[122:123], v[166:167] op_sel_hi:[1,0]
	v_pk_mul_f32 v[124:125], v[124:125], v[166:167] op_sel_hi:[1,0]
	s_waitcnt lgkmcnt(0)
	v_add_f32_e32 v156, v156, v157
	v_pk_mul_f32 v[124:125], v[124:125], v[162:163]
	v_pk_mul_f32 v[122:123], v[122:123], v[164:165]
	ds_bpermute_b32 v157, v190, v156
	v_cvt_pk_bf16_f32 v122, v122, v123
	v_cvt_pk_bf16_f32 v123, v124, v125
	v_pk_add_f32 v[124:125], v[126:127], 1.0 op_sel_hi:[1,0]
	v_pk_add_f32 v[126:127], v[128:129], 1.0 op_sel_hi:[1,0]
	v_rcp_f32_e32 v124, v124
	v_rcp_f32_e32 v126, v126
	v_rcp_f32_e32 v127, v127
	v_rcp_f32_e32 v125, v125
	v_pk_mul_f32 v[114:115], v[114:115], v[166:167] op_sel_hi:[1,0]
	v_mul_f32_e32 v120, 0xbfb8aa3b, v167
	s_waitcnt lgkmcnt(0)
; __device__ __forceinline__ f32x4 sig_from_negl2(f32x4 t) { return rcp_4(exp2_4(t) + 1.0f); }
; __device__ __forceinline__ u32x2 pack4(f32x4 v) { u32x2 w; w.x = cvtpk(v[0], v[1]); w.y = cvtpk(v[2], v[3]); return w; }
;     __device__ __forceinline__ void operator()(const Acc& acc, const Unit& u, int wr, int wc, int fr, int fq) const {
;     ...
;             for (int m = 0; m < 4; ++m) {
;                 const int r = u.pm * 256 + ai * 128 + wr * 64 + m * 16 + fr;
;                 const float rs = rsv[ai][m], nrs = -LOG2E * rs, rs2 = rs * rs;
;                 u32x4 w;
; #pragma unroll
;                 for (int n = 0; n < 2; ++n) {
;                     const f32x4 ga = acc[ai][0][m][n], ua = acc[ai][1][m][n];
;                     const f32x4 sg = sig_from_negl2(ga * nrs);
;                     const u32x2 pk = pack4((ga * ua) * rs2 * sg);
;                     if (n == 0) { w.x = pk.x; w.y = pk.y; } else { w.z = pk.x; w.w = pk.y; }
;                 }
;                 *(u32x4*)(O + (size_t)r * DFF + col) = w;
;             }
	v_add_f32_e32 v156, v156, v157
	v_pk_mul_f32 v[114:115], v[114:115], v[126:127]
	v_pk_mul_f32 v[126:127], v[112:113], v[120:121] op_sel_hi:[1,0]
	v_pk_mul_f32 v[128:129], v[110:111], v[120:121] op_sel_hi:[1,0]
	v_fmamk_f32 v156, v156, 0x3a800000, v155
	v_pk_mul_f32 v[116:117], v[116:117], v[166:167] op_sel_hi:[1,0]
	v_exp_f32_e32 v128, v128
	v_exp_f32_e32 v126, v126
	v_exp_f32_e32 v127, v127
	v_exp_f32_e32 v129, v129
	v_rsq_f32_e32 v157, v156
	v_lshl_add_u32 v156, s60, 8, v1
	v_ashrrev_i32_e32 v169, 31, v168
	v_pk_mul_f32 v[116:117], v[116:117], v[124:125]
	v_cvt_pk_bf16_f32 v124, v114, v115
	v_mov_b64_e32 v[114:115], s[16:17]
	v_cvt_pk_bf16_f32 v125, v116, v117
	v_mad_i64_i32 v[118:119], s[64:65], v156, s85, v[114:115]
	v_lshlrev_b64 v[116:117], 1, v[168:169]
	v_lshl_add_u64 v[118:119], v[118:119], 0, v[116:117]
	global_store_dwordx4 v[118:119], v[122:125], off sc1
	v_pk_mul_f32 v[110:111], v[104:105], v[120:121] op_sel_hi:[1,0]
	v_mul_f32_e32 v118, v167, v167
	v_pk_add_f32 v[122:123], v[126:127], 1.0 op_sel_hi:[1,0]
	v_pk_add_f32 v[124:125], v[128:129], 1.0 op_sel_hi:[1,0]
	v_rcp_f32_e32 v122, v122
	v_rcp_f32_e32 v124, v124
	v_rcp_f32_e32 v125, v125
	v_rcp_f32_e32 v123, v123
	v_exp_f32_e32 v110, v110
	v_exp_f32_e32 v111, v111
	v_pk_mul_f32 v[106:107], v[106:107], v[118:119] op_sel_hi:[1,0]
	v_pk_mul_f32 v[108:109], v[108:109], v[118:119] op_sel_hi:[1,0]
	v_pk_mul_f32 v[106:107], v[106:107], v[124:125]
	v_pk_mul_f32 v[108:109], v[108:109], v[122:123]
	v_cvt_pk_bf16_f32 v106, v106, v107
	v_cvt_pk_bf16_f32 v107, v108, v109
	v_pk_add_f32 v[108:109], v[110:111], 1.0 op_sel_hi:[1,0]
	v_pk_mul_f32 v[112:113], v[102:103], v[120:121] op_sel_hi:[1,0]
	v_rcp_f32_e32 v108, v108
	v_rcp_f32_e32 v109, v109
	v_exp_f32_e32 v112, v112
	v_exp_f32_e32 v113, v113
	v_pk_mul_f32 v[100:101], v[100:101], v[118:119] op_sel_hi:[1,0]
	v_pk_mul_f32 v[98:99], v[98:99], v[118:119] op_sel_hi:[1,0]
	v_pk_mul_f32 v[100:101], v[100:101], v[108:109]
	v_pk_add_f32 v[110:111], v[112:113], 1.0 op_sel_hi:[1,0]
	v_cvt_pk_bf16_f32 v109, v100, v101
	v_mul_f32_e32 v100, 0xbfb8aa3b, v159
	v_rcp_f32_e32 v110, v110
	v_rcp_f32_e32 v111, v111
	v_pk_mul_f32 v[102:103], v[96:97], v[100:101] op_sel_hi:[1,0]
	v_pk_mul_f32 v[104:105], v[94:95], v[100:101] op_sel_hi:[1,0]
	v_exp_f32_e32 v102, v102
	v_exp_f32_e32 v104, v104
	v_exp_f32_e32 v103, v103
	v_exp_f32_e32 v105, v105
	v_pk_mul_f32 v[98:99], v[98:99], v[110:111]
	v_pk_mul_f32 v[90:91], v[94:95], v[90:91]
	v_cvt_pk_bf16_f32 v108, v98, v99
	v_or_b32_e32 v98, 16, v156
	v_pk_add_f32 v[102:103], v[102:103], 1.0 op_sel_hi:[1,0]
	v_pk_add_f32 v[104:105], v[104:105], 1.0 op_sel_hi:[1,0]
	v_mad_i64_i32 v[98:99], s[64:65], v98, s85, v[114:115]
	v_rcp_f32_e32 v104, v104
	v_rcp_f32_e32 v105, v105
	v_rcp_f32_e32 v102, v102
	v_rcp_f32_e32 v103, v103
	v_pk_mul_f32 v[94:95], v[88:89], v[100:101] op_sel_hi:[1,0]
	v_lshl_add_u64 v[98:99], v[98:99], 0, v[116:117]
	v_exp_f32_e32 v94, v94
	v_exp_f32_e32 v95, v95
	global_store_dwordx4 v[98:99], v[106:109], off sc1
	v_mul_f32_e32 v98, v159, v159
	v_pk_mul_f32 v[92:93], v[96:97], v[92:93]
	v_pk_mul_f32 v[90:91], v[90:91], v[98:99] op_sel_hi:[1,0]
	v_pk_mul_f32 v[92:93], v[92:93], v[98:99] op_sel_hi:[1,0]
	v_pk_mul_f32 v[90:91], v[90:91], v[104:105]
	v_pk_mul_f32 v[92:93], v[92:93], v[102:103]
	v_cvt_pk_bf16_f32 v90, v90, v91
	v_cvt_pk_bf16_f32 v91, v92, v93
	v_pk_add_f32 v[92:93], v[94:95], 1.0 op_sel_hi:[1,0]
	v_pk_mul_f32 v[96:97], v[86:87], v[100:101] op_sel_hi:[1,0]
	v_rcp_f32_e32 v92, v92
	v_rcp_f32_e32 v93, v93
	v_exp_f32_e32 v96, v96
	v_exp_f32_e32 v97, v97
	v_pk_mul_f32 v[84:85], v[88:89], v[84:85]
	v_pk_mul_f32 v[82:83], v[86:87], v[82:83]
	v_pk_mul_f32 v[84:85], v[84:85], v[98:99] op_sel_hi:[1,0]
	v_pk_add_f32 v[94:95], v[96:97], 1.0 op_sel_hi:[1,0]
	v_pk_mul_f32 v[84:85], v[84:85], v[92:93]
	v_rcp_f32_e32 v94, v94
	v_cvt_pk_bf16_f32 v93, v84, v85
	v_mul_f32_e32 v84, 0xbfb8aa3b, v172
	v_rcp_f32_e32 v95, v95
	v_pk_mul_f32 v[86:87], v[80:81], v[84:85] op_sel_hi:[1,0]
	v_pk_mul_f32 v[88:89], v[78:79], v[84:85] op_sel_hi:[1,0]
	v_exp_f32_e32 v86, v86
	v_exp_f32_e32 v88, v88
	v_exp_f32_e32 v87, v87
	v_exp_f32_e32 v89, v89
	v_pk_mul_f32 v[82:83], v[82:83], v[98:99] op_sel_hi:[1,0]
	v_pk_mul_f32 v[76:77], v[80:81], v[76:77]
	v_pk_mul_f32 v[82:83], v[82:83], v[94:95]
	v_pk_add_f32 v[86:87], v[86:87], 1.0 op_sel_hi:[1,0]
	v_cvt_pk_bf16_f32 v92, v82, v83
	v_or_b32_e32 v82, 32, v156
	v_pk_add_f32 v[88:89], v[88:89], 1.0 op_sel_hi:[1,0]
	v_mad_i64_i32 v[82:83], s[64:65], v82, s85, v[114:115]
	v_rcp_f32_e32 v88, v88
	v_rcp_f32_e32 v89, v89
	v_rcp_f32_e32 v86, v86
	v_rcp_f32_e32 v87, v87
	v_pk_mul_f32 v[74:75], v[78:79], v[74:75]
	v_pk_mul_f32 v[78:79], v[72:73], v[84:85] op_sel_hi:[1,0]
	v_pk_mul_f32 v[80:81], v[70:71], v[84:85] op_sel_hi:[1,0]
	v_lshl_add_u64 v[82:83], v[82:83], 0, v[116:117]
	v_exp_f32_e32 v80, v80
	v_exp_f32_e32 v78, v78
	v_exp_f32_e32 v79, v79
	v_exp_f32_e32 v81, v81
	global_store_dwordx4 v[82:83], v[90:93], off sc1
	v_mul_f32_e32 v82, v172, v172
	v_pk_mul_f32 v[74:75], v[74:75], v[82:83] op_sel_hi:[1,0]
	v_pk_mul_f32 v[76:77], v[76:77], v[82:83] op_sel_hi:[1,0]
	v_pk_mul_f32 v[74:75], v[74:75], v[88:89]
	v_pk_mul_f32 v[76:77], v[76:77], v[86:87]
	v_cvt_pk_bf16_f32 v74, v74, v75
	v_cvt_pk_bf16_f32 v75, v76, v77
	v_pk_add_f32 v[76:77], v[78:79], 1.0 op_sel_hi:[1,0]
	v_pk_add_f32 v[78:79], v[80:81], 1.0 op_sel_hi:[1,0]
	v_rcp_f32_e32 v76, v76
	v_rcp_f32_e32 v78, v78
	v_rcp_f32_e32 v79, v79
	v_rcp_f32_e32 v77, v77
	v_pk_mul_f32 v[66:67], v[70:71], v[66:67]
	v_pk_mul_f32 v[68:69], v[72:73], v[68:69]
	v_pk_mul_f32 v[66:67], v[66:67], v[82:83] op_sel_hi:[1,0]
	v_pk_mul_f32 v[68:69], v[68:69], v[82:83] op_sel_hi:[1,0]
; __device__ __forceinline__ f32x4 sig_from_negl2(f32x4 t) { return rcp_4(exp2_4(t) + 1.0f); }
; __device__ __forceinline__ u32x2 pack4(f32x4 v) { u32x2 w; w.x = cvtpk(v[0], v[1]); w.y = cvtpk(v[2], v[3]); return w; }
;     __device__ __forceinline__ void operator()(const Acc& acc, const Unit& u, int wr, int wc, int fr, int fq) const {
;     ...
;             for (int m = 0; m < 4; ++m) {
;                 const int r = u.pm * 256 + ai * 128 + wr * 64 + m * 16 + fr;
;                 const float rs = rsv[ai][m], nrs = -LOG2E * rs, rs2 = rs * rs;
;                 u32x4 w;
; #pragma unroll
;                 for (int n = 0; n < 2; ++n) {
;                     const f32x4 ga = acc[ai][0][m][n], ua = acc[ai][1][m][n];
;                     const f32x4 sg = sig_from_negl2(ga * nrs);
;                     const u32x2 pk = pack4((ga * ua) * rs2 * sg);
;                     if (n == 0) { w.x = pk.x; w.y = pk.y; } else { w.z = pk.x; w.w = pk.y; }
;                 }
;                 *(u32x4*)(O + (size_t)r * DFF + col) = w;
;             }
	v_pk_mul_f32 v[66:67], v[66:67], v[78:79]
	v_pk_mul_f32 v[68:69], v[68:69], v[76:77]
	v_cvt_pk_bf16_f32 v76, v66, v67
	v_or_b32_e32 v66, 48, v156
	v_mad_i64_i32 v[66:67], s[64:65], v66, s85, v[114:115]
	v_cvt_pk_bf16_f32 v77, v68, v69
	v_lshl_add_u64 v[66:67], v[66:67], 0, v[116:117]
	global_store_dwordx4 v[66:67], v[74:77], off sc1
	v_mul_f32_e32 v66, 0xbfb8aa3b, v161
	v_pk_mul_f32 v[68:69], v[64:65], v[66:67] op_sel_hi:[1,0]
	v_pk_mul_f32 v[70:71], v[62:63], v[66:67] op_sel_hi:[1,0]
	v_exp_f32_e32 v68, v68
	v_exp_f32_e32 v70, v70
	v_exp_f32_e32 v69, v69
	v_exp_f32_e32 v71, v71
	v_add_u32_e32 v67, 0x80, v156
	v_pk_mul_f32 v[58:59], v[62:63], v[58:59]
	v_pk_add_f32 v[68:69], v[68:69], 1.0 op_sel_hi:[1,0]
	v_pk_add_f32 v[70:71], v[70:71], 1.0 op_sel_hi:[1,0]
	v_rcp_f32_e32 v68, v68
	v_rcp_f32_e32 v70, v70
	v_rcp_f32_e32 v71, v71
	v_rcp_f32_e32 v69, v69
	v_pk_mul_f32 v[62:63], v[56:57], v[66:67] op_sel_hi:[1,0]
	v_mul_f32_e32 v72, v161, v161
	v_exp_f32_e32 v62, v62
	v_exp_f32_e32 v63, v63
	v_pk_mul_f32 v[60:61], v[64:65], v[60:61]
	v_pk_mul_f32 v[58:59], v[58:59], v[72:73] op_sel_hi:[1,0]
	v_pk_mul_f32 v[60:61], v[60:61], v[72:73] op_sel_hi:[1,0]
	v_pk_mul_f32 v[58:59], v[58:59], v[70:71]
	v_pk_mul_f32 v[60:61], v[60:61], v[68:69]
	v_cvt_pk_bf16_f32 v58, v58, v59
	v_cvt_pk_bf16_f32 v59, v60, v61
	v_pk_add_f32 v[60:61], v[62:63], 1.0 op_sel_hi:[1,0]
	v_pk_mul_f32 v[64:65], v[54:55], v[66:67] op_sel_hi:[1,0]
	v_rcp_f32_e32 v60, v60
	v_rcp_f32_e32 v61, v61
	v_exp_f32_e32 v64, v64
	v_exp_f32_e32 v65, v65
	v_pk_mul_f32 v[52:53], v[56:57], v[52:53]
	v_pk_mul_f32 v[50:51], v[54:55], v[50:51]
	v_pk_mul_f32 v[52:53], v[52:53], v[72:73] op_sel_hi:[1,0]
	v_pk_add_f32 v[62:63], v[64:65], 1.0 op_sel_hi:[1,0]
	v_pk_mul_f32 v[52:53], v[52:53], v[60:61]
	v_rcp_f32_e32 v62, v62
	v_cvt_pk_bf16_f32 v61, v52, v53
	v_mul_f32_e32 v52, 0xbfb8aa3b, v173
	v_pk_mul_f32 v[54:55], v[48:49], v[52:53] op_sel_hi:[1,0]
	v_pk_mul_f32 v[56:57], v[46:47], v[52:53] op_sel_hi:[1,0]
	v_rcp_f32_e32 v63, v63
	v_exp_f32_e32 v56, v56
	v_exp_f32_e32 v54, v54
	v_exp_f32_e32 v55, v55
	v_exp_f32_e32 v57, v57
	v_pk_mul_f32 v[50:51], v[50:51], v[72:73] op_sel_hi:[1,0]
	v_pk_mul_f32 v[42:43], v[46:47], v[42:43]
	v_pk_mul_f32 v[50:51], v[50:51], v[62:63]
	v_pk_add_f32 v[54:55], v[54:55], 1.0 op_sel_hi:[1,0]
	v_pk_add_f32 v[56:57], v[56:57], 1.0 op_sel_hi:[1,0]
	v_cvt_pk_bf16_f32 v60, v50, v51
	v_mad_i64_i32 v[50:51], s[64:65], v67, s85, v[114:115]
	v_rcp_f32_e32 v56, v56
	v_rcp_f32_e32 v57, v57
	v_rcp_f32_e32 v54, v54
	v_rcp_f32_e32 v55, v55
	v_pk_mul_f32 v[46:47], v[40:41], v[52:53] op_sel_hi:[1,0]
	v_lshl_add_u64 v[50:51], v[50:51], 0, v[116:117]
	v_exp_f32_e32 v46, v46
	v_exp_f32_e32 v47, v47
	global_store_dwordx4 v[50:51], v[58:61], off sc1
	v_mul_f32_e32 v50, v173, v173
	v_pk_mul_f32 v[44:45], v[48:49], v[44:45]
	v_pk_mul_f32 v[42:43], v[42:43], v[50:51] op_sel_hi:[1,0]
	v_pk_mul_f32 v[44:45], v[44:45], v[50:51] op_sel_hi:[1,0]
	v_pk_mul_f32 v[42:43], v[42:43], v[56:57]
	v_pk_mul_f32 v[44:45], v[44:45], v[54:55]
	v_cvt_pk_bf16_f32 v42, v42, v43
	v_cvt_pk_bf16_f32 v43, v44, v45
	v_pk_add_f32 v[44:45], v[46:47], 1.0 op_sel_hi:[1,0]
	v_fmamk_f32 v158, v158, 0x3a800000, v155
	v_pk_mul_f32 v[48:49], v[38:39], v[52:53] op_sel_hi:[1,0]
	v_rcp_f32_e32 v44, v44
	v_rcp_f32_e32 v45, v45
	v_rsq_f32_e32 v158, v158
	v_exp_f32_e32 v48, v48
	v_exp_f32_e32 v49, v49
	v_pk_mul_f32 v[36:37], v[40:41], v[36:37]
	v_pk_mul_f32 v[34:35], v[38:39], v[34:35]
	v_pk_mul_f32 v[36:37], v[36:37], v[50:51] op_sel_hi:[1,0]
	v_pk_add_f32 v[46:47], v[48:49], 1.0 op_sel_hi:[1,0]
	v_pk_mul_f32 v[36:37], v[36:37], v[44:45]
	v_rcp_f32_e32 v46, v46
	v_cvt_pk_bf16_f32 v45, v36, v37
	v_mul_f32_e32 v36, 0xbfb8aa3b, v158
	v_rcp_f32_e32 v47, v47
	v_pk_mul_f32 v[38:39], v[32:33], v[36:37] op_sel_hi:[1,0]
	v_pk_mul_f32 v[40:41], v[30:31], v[36:37] op_sel_hi:[1,0]
	v_exp_f32_e32 v38, v38
	v_exp_f32_e32 v40, v40
	v_exp_f32_e32 v39, v39
	v_exp_f32_e32 v41, v41
	v_pk_mul_f32 v[34:35], v[34:35], v[50:51] op_sel_hi:[1,0]
	v_pk_mul_f32 v[26:27], v[30:31], v[26:27]
	v_pk_mul_f32 v[34:35], v[34:35], v[46:47]
	v_pk_add_f32 v[38:39], v[38:39], 1.0 op_sel_hi:[1,0]
; __device__ __forceinline__ f32x4 sig_from_negl2(f32x4 t) { return rcp_4(exp2_4(t) + 1.0f); }
; __device__ __forceinline__ u32x2 pack4(f32x4 v) { u32x2 w; w.x = cvtpk(v[0], v[1]); w.y = cvtpk(v[2], v[3]); return w; }
;     __device__ __forceinline__ void operator()(const Acc& acc, const Unit& u, int wr, int wc, int fr, int fq) const {
;     ...
;             for (int m = 0; m < 4; ++m) {
;                 const int r = u.pm * 256 + ai * 128 + wr * 64 + m * 16 + fr;
;                 const float rs = rsv[ai][m], nrs = -LOG2E * rs, rs2 = rs * rs;
;                 u32x4 w;
; #pragma unroll
;                 for (int n = 0; n < 2; ++n) {
;                     const f32x4 ga = acc[ai][0][m][n], ua = acc[ai][1][m][n];
;                     const f32x4 sg = sig_from_negl2(ga * nrs);
;                     const u32x2 pk = pack4((ga * ua) * rs2 * sg);
;                     if (n == 0) { w.x = pk.x; w.y = pk.y; } else { w.z = pk.x; w.w = pk.y; }
;                 }
;                 *(u32x4*)(O + (size_t)r * DFF + col) = w;
;             }
	v_cvt_pk_bf16_f32 v44, v34, v35
	v_add_u32_e32 v34, 0x90, v156
	v_pk_add_f32 v[40:41], v[40:41], 1.0 op_sel_hi:[1,0]
	v_mad_i64_i32 v[34:35], s[64:65], v34, s85, v[114:115]
	v_rcp_f32_e32 v40, v40
	v_rcp_f32_e32 v41, v41
	v_rcp_f32_e32 v38, v38
	v_rcp_f32_e32 v39, v39
	v_pk_mul_f32 v[30:31], v[24:25], v[36:37] op_sel_hi:[1,0]
	v_lshl_add_u64 v[34:35], v[34:35], 0, v[116:117]
	v_exp_f32_e32 v30, v30
	v_exp_f32_e32 v31, v31
	global_store_dwordx4 v[34:35], v[42:45], off sc1
	v_mul_f32_e32 v34, v158, v158
	v_pk_mul_f32 v[28:29], v[32:33], v[28:29]
	v_pk_mul_f32 v[26:27], v[26:27], v[34:35] op_sel_hi:[1,0]
	v_pk_mul_f32 v[28:29], v[28:29], v[34:35] op_sel_hi:[1,0]
	v_pk_mul_f32 v[26:27], v[26:27], v[40:41]
	v_pk_mul_f32 v[28:29], v[28:29], v[38:39]
	v_cvt_pk_bf16_f32 v26, v26, v27
	v_cvt_pk_bf16_f32 v27, v28, v29
	v_pk_add_f32 v[28:29], v[30:31], 1.0 op_sel_hi:[1,0]
	v_pk_mul_f32 v[32:33], v[22:23], v[36:37] op_sel_hi:[1,0]
	v_rcp_f32_e32 v28, v28
	v_rcp_f32_e32 v29, v29
	v_exp_f32_e32 v32, v32
	v_exp_f32_e32 v33, v33
	v_pk_mul_f32 v[20:21], v[24:25], v[20:21]
	v_pk_mul_f32 v[18:19], v[22:23], v[18:19]
	v_pk_mul_f32 v[20:21], v[20:21], v[34:35] op_sel_hi:[1,0]
	v_pk_add_f32 v[30:31], v[32:33], 1.0 op_sel_hi:[1,0]
	v_pk_mul_f32 v[20:21], v[20:21], v[28:29]
	v_rcp_f32_e32 v30, v30
	v_cvt_pk_bf16_f32 v29, v20, v21
	v_mul_f32_e32 v20, 0xbfb8aa3b, v157
	v_rcp_f32_e32 v31, v31
	v_pk_mul_f32 v[22:23], v[16:17], v[20:21] op_sel_hi:[1,0]
	v_pk_mul_f32 v[24:25], v[14:15], v[20:21] op_sel_hi:[1,0]
	v_exp_f32_e32 v22, v22
	v_exp_f32_e32 v24, v24
	v_exp_f32_e32 v23, v23
	v_exp_f32_e32 v25, v25
	v_pk_mul_f32 v[18:19], v[18:19], v[34:35] op_sel_hi:[1,0]
	v_pk_mul_f32 v[12:13], v[16:17], v[12:13]
	v_pk_mul_f32 v[18:19], v[18:19], v[30:31]
	v_pk_add_f32 v[22:23], v[22:23], 1.0 op_sel_hi:[1,0]
	v_cvt_pk_bf16_f32 v28, v18, v19
	v_add_u32_e32 v18, 0xa0, v156
	v_pk_add_f32 v[24:25], v[24:25], 1.0 op_sel_hi:[1,0]
	v_mad_i64_i32 v[18:19], s[64:65], v18, s85, v[114:115]
	v_rcp_f32_e32 v24, v24
	v_rcp_f32_e32 v25, v25
	v_rcp_f32_e32 v22, v22
	v_rcp_f32_e32 v23, v23
	v_pk_mul_f32 v[10:11], v[14:15], v[10:11]
	v_pk_mul_f32 v[14:15], v[8:9], v[20:21] op_sel_hi:[1,0]
	v_pk_mul_f32 v[16:17], v[6:7], v[20:21] op_sel_hi:[1,0]
	v_lshl_add_u64 v[18:19], v[18:19], 0, v[116:117]
	v_exp_f32_e32 v16, v16
	v_exp_f32_e32 v14, v14
	v_exp_f32_e32 v15, v15
	v_exp_f32_e32 v17, v17
	global_store_dwordx4 v[18:19], v[26:29], off sc1
	v_mul_f32_e32 v18, v157, v157
	v_pk_mul_f32 v[10:11], v[10:11], v[18:19] op_sel_hi:[1,0]
	v_pk_mul_f32 v[12:13], v[12:13], v[18:19] op_sel_hi:[1,0]
	v_pk_mul_f32 v[10:11], v[10:11], v[24:25]
	v_pk_mul_f32 v[12:13], v[12:13], v[22:23]
	v_cvt_pk_bf16_f32 v10, v10, v11
	v_cvt_pk_bf16_f32 v11, v12, v13
	v_pk_add_f32 v[12:13], v[14:15], 1.0 op_sel_hi:[1,0]
	v_pk_add_f32 v[14:15], v[16:17], 1.0 op_sel_hi:[1,0]
	v_rcp_f32_e32 v12, v12
	v_rcp_f32_e32 v14, v14
	v_rcp_f32_e32 v15, v15
	v_rcp_f32_e32 v13, v13
	v_pk_mul_f32 v[2:3], v[6:7], v[2:3]
	v_pk_mul_f32 v[4:5], v[8:9], v[4:5]
	v_pk_mul_f32 v[2:3], v[2:3], v[18:19] op_sel_hi:[1,0]
	v_pk_mul_f32 v[4:5], v[4:5], v[18:19] op_sel_hi:[1,0]
	v_pk_mul_f32 v[2:3], v[2:3], v[14:15]
	v_pk_mul_f32 v[4:5], v[4:5], v[12:13]
	v_cvt_pk_bf16_f32 v12, v2, v3
	v_add_u32_e32 v2, 0xb0, v156
	v_mad_i64_i32 v[2:3], s[64:65], v2, s85, v[114:115]
	v_cvt_pk_bf16_f32 v13, v4, v5
	v_lshl_add_u64 v[2:3], v[2:3], 0, v[116:117]
	s_andn2_b64 vcc, exec, s[2:3]
	s_mov_b64 s[2:3], -1
	global_store_dwordx4 v[2:3], v[10:13], off sc1
	s_cbranch_vccnz .LBB0_130
	s_and_b64 vcc, exec, s[0:1]
	s_cbranch_vccnz .LBB0_129
	s_lshl_b64 s[2:3], s[48:49], 14
	v_lshl_add_u64 v[2:3], v[138:139], 0, s[2:3]
	s_add_i32 s2, 0, 0x20400
	v_lshl_add_u64 v[4:5], v[2:3], 0, s[36:37]
	s_add_i32 m0, s2, s36
	s_barrier
	global_load_lds_dwordx4 v[4:5], off
	v_lshl_add_u64 v[4:5], v[2:3], 0, s[6:7]
	s_add_i32 m0, s2, s6
	s_nop 0
	global_load_lds_dwordx4 v[4:5], off
	v_lshl_add_u64 v[4:5], v[2:3], 0, s[42:43]
	s_add_i32 m0, s2, s42
	v_lshl_add_u64 v[2:3], v[2:3], 0, s[44:45]
	global_load_lds_dwordx4 v[4:5], off
	s_add_i32 m0, s2, s44
	s_nop 0
	global_load_lds_dwordx4 v[2:3], off
	s_branch .LBB0_129

; __device__ __forceinline__ float bflo(unsigned w) { return __uint_as_float(w << 16); }
; #define FENCE() asm volatile("" ::: "memory")
;     __device__ __forceinline__ void operator()(const Acc& acc, const Unit& u, int wr, int wc, int fr, int fq) const {
;     ...
; #pragma unroll
;         for (int bj = 0; bj < 2; ++bj) {
;             if constexpr (RES_BF16) preb[0][bj] = *(const u32x4*)(rbase + bj * 128);
;             else { pre[0][bj][0] = *(const f32x4*)(bbase + bj * 128); pre[0][bj][1] = *(const f32x4*)(bbase + bj * 128 + 4); }
;         }
; #pragma unroll
;         for (int i = 0; i < 8; ++i) {
;             const int ai = i >> 2, m = i & 3, cb = i & 1, nb = cb ^ 1;
;             if (i < 7) { const int ai2 = (i + 1) >> 2, m2 = (i + 1) & 3; const size_t ro = (size_t)(ai2 * 128 + m2 * 16) * DM;
; #pragma unroll
;                 for (int bj = 0; bj < 2; ++bj) {
;                     if constexpr (RES_BF16) preb[nb][bj] = *(const u32x4*)(rbase + ro + bj * 128);
;                     else { pre[nb][bj][0] = *(const f32x4*)(bbase + ro + bj * 128); pre[nb][bj][1] = *(const f32x4*)(bbase + ro + bj * 128 + 4); }
;                 }
;             }
;             FENCE();
;             const int r = rb + ai * 128 + m * 16;
;             float q = 0.f;
; #pragma unroll
;             for (int bj = 0; bj < 2; ++bj) {
;                 f32x4 b0, b1;
;                 if constexpr (RES_BF16) { const u32x4 w = preb[cb][bj]; b0 = (f32x4){bflo(w.x), bfhi(w.x), bflo(w.y), bfhi(w.y)}; b1 = (f32x4){bflo(w.z), bfhi(w.z), bflo(w.w), bfhi(w.w)}; }
;                 else { b0 = pre[cb][bj][0]; b1 = pre[cb][bj][1]; }
;                 const f32x4 v0 = b0 + acc[ai][bj][m][0] * scale, v1 = b1 + acc[ai][bj][m][1] * scale;
;                 if constexpr (OUT_F32) { float* op = out + (size_t)r * DM + col + bj * 128; *(f32x4*)op = v0; *(f32x4*)(op + 4) = v1; }
;                 q += (v0[0] * v0[0] + v0[1] * v0[1]) + (v0[2] * v0[2] + v0[3] * v0[3]) + (v1[0] * v1[0] + v1[1] * v1[1]) + (v1[2] * v1[2] + v1[3] * v1[3]);
;                 if (xb) { u32x4 w; w.x = cvtpk(v0[0], v0[1]); w.y = cvtpk(v0[2], v0[3]); w.z = cvtpk(v1[0], v1[1]); w.w = cvtpk(v1[2], v1[3]);
;                     *(u32x4*)(xb + (size_t)r * DM + col + bj * 128) = w; }
;             }
;             q += __shfl_xor(q, 16); q += __shfl_xor(q, 32);
;             if (fq == 0) st[(size_t)r * 16 + u.pn * 4 + wc] = q;
.LBB0_224:
	v_lshl_add_u32 v158, s81, 8, v1
	v_ashrrev_i32_e32 v159, 31, v158
	v_lshl_or_b32 v154, s8, 8, v161
	v_lshlrev_b64 v[130:131], 11, v[158:159]
	v_lshl_add_u64 v[130:131], s[34:35], 0, v[130:131]
	v_ashrrev_i32_e32 v155, 31, v154
	v_lshl_add_u64 v[156:157], v[154:155], 1, v[130:131]
	global_load_dwordx4 v[172:175], v[156:157], off
	global_load_dwordx4 v[176:179], v[156:157], off offset:256
	v_add_co_u32_e32 v130, vcc, 0x8000, v156
	v_and_b32_e32 v167, 64, v165
	s_nop 0
	v_addc_co_u32_e32 v131, vcc, 0, v157, vcc
	global_load_dwordx4 v[134:137], v[130:131], off
	s_nop 0
	global_load_dwordx4 v[130:133], v[130:131], off offset:256
	v_xor_b32_e32 v166, 16, v165
	v_add_u32_e32 v167, 64, v167
	v_xor_b32_e32 v168, 32, v165
	v_cmp_lt_i32_e32 vcc, v166, v167
	s_lshl_b32 s46, s8, 2
	s_ashr_i32 s47, s46, 31
	v_cndmask_b32_e32 v166, v165, v166, vcc
	v_cmp_lt_i32_e32 vcc, v168, v167
	v_lshlrev_b32_e32 v166, 2, v166
	s_waitcnt vmcnt(0)
	v_and_b32_e32 v169, 0xffff0000, v172
	v_cndmask_b32_e32 v167, v165, v168, vcc
	v_lshlrev_b32_e32 v168, 16, v172
	v_lshlrev_b32_e32 v172, 16, v173
	v_and_b32_e32 v173, 0xffff0000, v173
	v_lshlrev_b32_e32 v182, 16, v176
	v_and_b32_e32 v183, 0xffff0000, v176
	v_lshlrev_b32_e32 v176, 16, v177
	v_and_b32_e32 v177, 0xffff0000, v177
	v_lshlrev_b32_e32 v180, 16, v174
	v_and_b32_e32 v181, 0xffff0000, v174
	v_lshlrev_b32_e32 v184, 16, v178
	v_and_b32_e32 v185, 0xffff0000, v178
	v_lshlrev_b32_e32 v178, 16, v179
	v_and_b32_e32 v179, 0xffff0000, v179
	v_pk_fma_f32 v[128:129], v[128:129], 0.5, v[172:173] op_sel_hi:[1,0,1]
	v_pk_fma_f32 v[126:127], v[126:127], 0.5, v[168:169] op_sel_hi:[1,0,1]
	v_pk_fma_f32 v[120:121], v[120:121], 0.5, v[176:177] op_sel_hi:[1,0,1]
	v_pk_fma_f32 v[118:119], v[118:119], 0.5, v[182:183] op_sel_hi:[1,0,1]
	v_lshlrev_b32_e32 v174, 16, v175
	v_and_b32_e32 v175, 0xffff0000, v175
	v_pk_fma_f32 v[122:123], v[122:123], 0.5, v[180:181] op_sel_hi:[1,0,1]
	v_pk_fma_f32 v[168:169], v[116:117], 0.5, v[178:179] op_sel_hi:[1,0,1]
	v_pk_fma_f32 v[172:173], v[114:115], 0.5, v[184:185] op_sel_hi:[1,0,1]
	v_mul_f32_e32 v116, v127, v127
	v_mul_f32_e32 v117, v129, v129
	v_cvt_pk_bf16_f32 v114, v126, v127
	v_cvt_pk_bf16_f32 v115, v128, v129
	v_mul_f32_e32 v127, v119, v119
	v_mul_f32_e32 v129, v121, v121
	v_pk_fma_f32 v[124:125], v[124:125], 0.5, v[174:175] op_sel_hi:[1,0,1]
	v_mul_f32_e32 v174, v123, v123
	v_mul_f32_e32 v176, v173, v173
	v_fmac_f32_e32 v116, v126, v126
	v_fmac_f32_e32 v117, v128, v128
	v_fmac_f32_e32 v127, v118, v118
	v_fmac_f32_e32 v129, v120, v120
	v_mul_f32_e32 v175, v125, v125
	v_mul_f32_e32 v177, v169, v169
	v_fmac_f32_e32 v174, v122, v122
	v_fmac_f32_e32 v176, v172, v172
	v_add_f32_e32 v116, v116, v117
	v_add_f32_e32 v117, v127, v129
	v_fmac_f32_e32 v175, v124, v124
	v_fmac_f32_e32 v177, v168, v168
	v_add_f32_e32 v116, v174, v116
	v_add_f32_e32 v117, v176, v117
	v_add_f32_e32 v116, v175, v116
	v_add_f32_e32 v117, v177, v117
	v_add_f32_e32 v126, v116, v117
	ds_bpermute_b32 v127, v166, v126
	v_cvt_pk_bf16_f32 v116, v122, v123
	v_cvt_pk_bf16_f32 v117, v124, v125
	global_store_dwordx4 v[156:157], v[114:117], off sc1
	v_lshlrev_b32_e32 v124, 2, v167
	v_cvt_pk_bf16_f32 v118, v118, v119
	s_waitcnt lgkmcnt(0)
	v_add_f32_e32 v114, v126, v127
	ds_bpermute_b32 v115, v124, v114
	v_cvt_pk_bf16_f32 v119, v120, v121
	v_cvt_pk_bf16_f32 v120, v172, v173
	v_cvt_pk_bf16_f32 v121, v168, v169
	global_store_dwordx4 v[156:157], v[118:121], off offset:256 sc1
	s_and_saveexec_b64 s[48:49], s[0:1]
	s_cbranch_execz .LBB0_226
	v_lshlrev_b64 v[116:117], 6, v[158:159]
	v_lshl_add_u64 v[116:117], s[74:75], 0, v[116:117]
	v_lshl_add_u64 v[116:117], s[46:47], 2, v[116:117]
	s_lshl_b32 s8, s63, 2
	v_lshl_add_u64 v[116:117], v[116:117], 0, s[8:9]
	s_waitcnt lgkmcnt(0)
	v_add_f32_e32 v114, v114, v115
	global_store_dword v[116:117], v114, off sc1
.LBB0_226:
	s_or_b64 exec, exec, s[48:49]
	v_add_co_u32_e32 v114, vcc, 0x10000, v156
	v_lshlrev_b32_e32 v128, 16, v134
	s_waitcnt lgkmcnt(0)
	v_addc_co_u32_e32 v115, vcc, 0, v157, vcc
	global_load_dwordx4 v[118:121], v[114:115], off
	s_nop 0
	global_load_dwordx4 v[114:117], v[114:115], off offset:256
	v_and_b32_e32 v129, 0xffff0000, v134
	v_lshlrev_b32_e32 v134, 16, v135
	v_and_b32_e32 v135, 0xffff0000, v135
	v_lshlrev_b32_e32 v168, 16, v136
	v_and_b32_e32 v169, 0xffff0000, v136
	v_lshlrev_b32_e32 v136, 16, v137
	v_and_b32_e32 v137, 0xffff0000, v137
	v_pk_fma_f32 v[112:113], v[112:113], 0.5, v[134:135] op_sel_hi:[1,0,1]
	v_pk_fma_f32 v[110:111], v[110:111], 0.5, v[128:129] op_sel_hi:[1,0,1]
	v_pk_fma_f32 v[128:129], v[108:109], 0.5, v[136:137] op_sel_hi:[1,0,1]
	v_pk_fma_f32 v[108:109], v[106:107], 0.5, v[168:169] op_sel_hi:[1,0,1]
	v_mul_f32_e32 v106, v111, v111
	v_mul_f32_e32 v107, v113, v113
	v_fmac_f32_e32 v106, v110, v110
	v_fmac_f32_e32 v107, v112, v112
	v_add_f32_e32 v106, v106, v107
	v_mul_f32_e32 v107, v109, v109
	v_fmac_f32_e32 v107, v108, v108
	v_add_f32_e32 v106, v107, v106
	v_mul_f32_e32 v107, v129, v129
	v_fmac_f32_e32 v107, v128, v128
	v_add_f32_e32 v125, v107, v106
	v_cvt_pk_bf16_f32 v106, v110, v111
	v_cvt_pk_bf16_f32 v107, v112, v113
	v_lshlrev_b32_e32 v110, 16, v130
	v_and_b32_e32 v111, 0xffff0000, v130
	v_lshlrev_b32_e32 v112, 16, v131
	v_and_b32_e32 v113, 0xffff0000, v131
	v_cvt_pk_bf16_f32 v108, v108, v109
	v_cvt_pk_bf16_f32 v109, v128, v129
	v_lshlrev_b32_e32 v128, 16, v132
	v_and_b32_e32 v129, 0xffff0000, v132
	v_pk_fma_f32 v[104:105], v[104:105], 0.5, v[112:113] op_sel_hi:[1,0,1]
	v_pk_fma_f32 v[102:103], v[102:103], 0.5, v[110:111] op_sel_hi:[1,0,1]
	v_pk_fma_f32 v[112:113], v[98:99], 0.5, v[128:129] op_sel_hi:[1,0,1]
	v_mul_f32_e32 v98, v103, v103
	v_mul_f32_e32 v99, v105, v105
	v_fmac_f32_e32 v98, v102, v102
	v_fmac_f32_e32 v99, v104, v104
	v_lshlrev_b32_e32 v130, 16, v133
	v_and_b32_e32 v131, 0xffff0000, v133
	v_add_f32_e32 v98, v98, v99
	v_mul_f32_e32 v99, v113, v113
	v_pk_fma_f32 v[110:111], v[100:101], 0.5, v[130:131] op_sel_hi:[1,0,1]
	v_fmac_f32_e32 v99, v112, v112
	v_add_f32_e32 v98, v99, v98
	v_mul_f32_e32 v99, v111, v111
	v_fmac_f32_e32 v99, v110, v110
	v_add_f32_e32 v98, v99, v98
	v_add_f32_e32 v101, v125, v98
	ds_bpermute_b32 v125, v166, v101
	v_or_b32_e32 v122, 16, v158
	v_ashrrev_i32_e32 v123, 31, v122
	v_lshlrev_b64 v[126:127], 11, v[122:123]
	v_lshl_add_u64 v[98:99], s[34:35], 0, v[126:127]
	v_lshl_add_u64 v[126:127], v[154:155], 1, v[98:99]
	s_waitcnt lgkmcnt(0)
	v_add_f32_e32 v98, v101, v125
	ds_bpermute_b32 v99, v124, v98
	v_cvt_pk_bf16_f32 v100, v102, v103
	v_cvt_pk_bf16_f32 v101, v104, v105
	v_cvt_pk_bf16_f32 v102, v112, v113
	v_cvt_pk_bf16_f32 v103, v110, v111
	global_store_dwordx4 v[126:127], v[106:109], off sc1
	global_store_dwordx4 v[126:127], v[100:103], off offset:256 sc1
	s_and_saveexec_b64 s[48:49], s[0:1]
	s_cbranch_execz .LBB0_228
; __device__ __forceinline__ unsigned cvtpk(float lo, float hi) { f32x2 v = {lo, hi}; bf16x2_t b = __builtin_convertvector(v, bf16x2_t); return __builtin_bit_cast(unsigned, b); }
; __device__ __forceinline__ float bflo(unsigned w) { return __uint_as_float(w << 16); }
; __device__ __forceinline__ float bfhi(unsigned w) { return __uint_as_float(w & 0xffff0000u); }
; #define FENCE() asm volatile("" ::: "memory")
;     __device__ __forceinline__ void operator()(const Acc& acc, const Unit& u, int wr, int wc, int fr, int fq) const {
;     ...
;         for (int i = 0; i < 8; ++i) {
;             const int ai = i >> 2, m = i & 3, cb = i & 1, nb = cb ^ 1;
;             if (i < 7) { const int ai2 = (i + 1) >> 2, m2 = (i + 1) & 3; const size_t ro = (size_t)(ai2 * 128 + m2 * 16) * DM;
; #pragma unroll
;                 for (int bj = 0; bj < 2; ++bj) {
;                     if constexpr (RES_BF16) preb[nb][bj] = *(const u32x4*)(rbase + ro + bj * 128);
;                     else { pre[nb][bj][0] = *(const f32x4*)(bbase + ro + bj * 128); pre[nb][bj][1] = *(const f32x4*)(bbase + ro + bj * 128 + 4); }
;                 }
;             }
;             FENCE();
;             const int r = rb + ai * 128 + m * 16;
;             float q = 0.f;
; #pragma unroll
;             for (int bj = 0; bj < 2; ++bj) {
;                 f32x4 b0, b1;
;                 if constexpr (RES_BF16) { const u32x4 w = preb[cb][bj]; b0 = (f32x4){bflo(w.x), bfhi(w.x), bflo(w.y), bfhi(w.y)}; b1 = (f32x4){bflo(w.z), bfhi(w.z), bflo(w.w), bfhi(w.w)}; }
;                 else { b0 = pre[cb][bj][0]; b1 = pre[cb][bj][1]; }
;                 const f32x4 v0 = b0 + acc[ai][bj][m][0] * scale, v1 = b1 + acc[ai][bj][m][1] * scale;
;                 if constexpr (OUT_F32) { float* op = out + (size_t)r * DM + col + bj * 128; *(f32x4*)op = v0; *(f32x4*)(op + 4) = v1; }
;                 q += (v0[0] * v0[0] + v0[1] * v0[1]) + (v0[2] * v0[2] + v0[3] * v0[3]) + (v1[0] * v1[0] + v1[1] * v1[1]) + (v1[2] * v1[2] + v1[3] * v1[3]);
;                 if (xb) { u32x4 w; w.x = cvtpk(v0[0], v0[1]); w.y = cvtpk(v0[2], v0[3]); w.z = cvtpk(v1[0], v1[1]); w.w = cvtpk(v1[2], v1[3]);
;                     *(u32x4*)(xb + (size_t)r * DM + col + bj * 128) = w; }
;             }
;             q += __shfl_xor(q, 16); q += __shfl_xor(q, 32);
;             if (fq == 0) st[(size_t)r * 16 + u.pn * 4 + wc] = q;
	v_lshlrev_b64 v[100:101], 6, v[122:123]
	v_lshl_add_u64 v[100:101], s[74:75], 0, v[100:101]
	v_lshl_add_u64 v[100:101], s[46:47], 2, v[100:101]
	s_lshl_b32 s8, s63, 2
	v_lshl_add_u64 v[100:101], v[100:101], 0, s[8:9]
	s_waitcnt lgkmcnt(0)
	v_add_f32_e32 v98, v98, v99
	global_store_dword v[100:101], v98, off sc1
.LBB0_228:
	s_or_b64 exec, exec, s[48:49]
	v_add_co_u32_e32 v98, vcc, 0x18000, v156
	s_waitcnt vmcnt(3)
	v_lshlrev_b32_e32 v110, 16, v118
	s_waitcnt lgkmcnt(0)
	v_addc_co_u32_e32 v99, vcc, 0, v157, vcc
	global_load_dwordx4 v[102:105], v[98:99], off
	s_nop 0
	global_load_dwordx4 v[98:101], v[98:99], off offset:256
	v_and_b32_e32 v111, 0xffff0000, v118
	v_lshlrev_b32_e32 v112, 16, v119
	v_and_b32_e32 v113, 0xffff0000, v119
	v_lshlrev_b32_e32 v118, 16, v120
	v_and_b32_e32 v119, 0xffff0000, v120
	v_lshlrev_b32_e32 v120, 16, v121
	v_and_b32_e32 v121, 0xffff0000, v121
	v_pk_fma_f32 v[96:97], v[96:97], 0.5, v[112:113] op_sel_hi:[1,0,1]
	v_pk_fma_f32 v[94:95], v[94:95], 0.5, v[110:111] op_sel_hi:[1,0,1]
	v_pk_fma_f32 v[110:111], v[92:93], 0.5, v[120:121] op_sel_hi:[1,0,1]
	v_pk_fma_f32 v[92:93], v[90:91], 0.5, v[118:119] op_sel_hi:[1,0,1]
	v_mul_f32_e32 v90, v95, v95
	v_mul_f32_e32 v91, v97, v97
	v_fmac_f32_e32 v90, v94, v94
	v_fmac_f32_e32 v91, v96, v96
	v_add_f32_e32 v90, v90, v91
	v_mul_f32_e32 v91, v93, v93
	v_fmac_f32_e32 v91, v92, v92
	v_add_f32_e32 v90, v91, v90
	v_mul_f32_e32 v91, v111, v111
	v_fmac_f32_e32 v91, v110, v110
	v_add_f32_e32 v118, v91, v90
	v_cvt_pk_bf16_f32 v90, v94, v95
	v_cvt_pk_bf16_f32 v91, v96, v97
	s_waitcnt vmcnt(4)
	v_lshlrev_b32_e32 v94, 16, v114
	v_and_b32_e32 v95, 0xffff0000, v114
	v_lshlrev_b32_e32 v96, 16, v115
	v_and_b32_e32 v97, 0xffff0000, v115
	v_cvt_pk_bf16_f32 v92, v92, v93
	v_cvt_pk_bf16_f32 v93, v110, v111
	v_lshlrev_b32_e32 v110, 16, v116
	v_and_b32_e32 v111, 0xffff0000, v116
	v_pk_fma_f32 v[88:89], v[88:89], 0.5, v[96:97] op_sel_hi:[1,0,1]
	v_pk_fma_f32 v[86:87], v[86:87], 0.5, v[94:95] op_sel_hi:[1,0,1]
	v_pk_fma_f32 v[96:97], v[82:83], 0.5, v[110:111] op_sel_hi:[1,0,1]
	v_mul_f32_e32 v82, v87, v87
	v_mul_f32_e32 v83, v89, v89
	v_fmac_f32_e32 v82, v86, v86
	v_fmac_f32_e32 v83, v88, v88
	v_lshlrev_b32_e32 v112, 16, v117
	v_and_b32_e32 v113, 0xffff0000, v117
	v_add_f32_e32 v82, v82, v83
	v_mul_f32_e32 v83, v97, v97
	v_pk_fma_f32 v[94:95], v[84:85], 0.5, v[112:113] op_sel_hi:[1,0,1]
	v_fmac_f32_e32 v83, v96, v96
	v_add_f32_e32 v82, v83, v82
	v_mul_f32_e32 v83, v95, v95
	v_fmac_f32_e32 v83, v94, v94
	v_add_f32_e32 v82, v83, v82
	v_add_f32_e32 v85, v118, v82
	ds_bpermute_b32 v110, v166, v85
	v_or_b32_e32 v106, 32, v158
	v_ashrrev_i32_e32 v107, 31, v106
	v_lshlrev_b64 v[108:109], 11, v[106:107]
	v_lshl_add_u64 v[82:83], s[34:35], 0, v[108:109]
	v_lshl_add_u64 v[108:109], v[154:155], 1, v[82:83]
	s_waitcnt lgkmcnt(0)
	v_add_f32_e32 v82, v85, v110
	ds_bpermute_b32 v83, v124, v82
	v_cvt_pk_bf16_f32 v84, v86, v87
	v_cvt_pk_bf16_f32 v85, v88, v89
	v_cvt_pk_bf16_f32 v86, v96, v97
	v_cvt_pk_bf16_f32 v87, v94, v95
	global_store_dwordx4 v[108:109], v[90:93], off sc1
	global_store_dwordx4 v[108:109], v[84:87], off offset:256 sc1
	s_and_saveexec_b64 s[48:49], s[0:1]
	s_cbranch_execz .LBB0_230
	v_lshlrev_b64 v[84:85], 6, v[106:107]
	v_lshl_add_u64 v[84:85], s[74:75], 0, v[84:85]
	v_lshl_add_u64 v[84:85], s[46:47], 2, v[84:85]
	s_lshl_b32 s8, s63, 2
	v_lshl_add_u64 v[84:85], v[84:85], 0, s[8:9]
	s_waitcnt lgkmcnt(0)
	v_add_f32_e32 v82, v82, v83
	global_store_dword v[84:85], v82, off sc1
.LBB0_230:
	s_or_b64 exec, exec, s[48:49]
	v_add_co_u32_e32 v82, vcc, 0x40000, v156
	s_waitcnt vmcnt(3)
	v_lshlrev_b32_e32 v94, 16, v102
	s_waitcnt lgkmcnt(0)
	v_addc_co_u32_e32 v83, vcc, 0, v157, vcc
	global_load_dwordx4 v[86:89], v[82:83], off
	s_nop 0
	global_load_dwordx4 v[82:85], v[82:83], off offset:256
	v_and_b32_e32 v95, 0xffff0000, v102
	v_lshlrev_b32_e32 v96, 16, v103
	v_and_b32_e32 v97, 0xffff0000, v103
	v_lshlrev_b32_e32 v102, 16, v104
	v_and_b32_e32 v103, 0xffff0000, v104
	v_lshlrev_b32_e32 v104, 16, v105
	v_and_b32_e32 v105, 0xffff0000, v105
	v_pk_fma_f32 v[80:81], v[80:81], 0.5, v[96:97] op_sel_hi:[1,0,1]
	v_pk_fma_f32 v[78:79], v[78:79], 0.5, v[94:95] op_sel_hi:[1,0,1]
	v_pk_fma_f32 v[94:95], v[76:77], 0.5, v[104:105] op_sel_hi:[1,0,1]
	v_pk_fma_f32 v[76:77], v[74:75], 0.5, v[102:103] op_sel_hi:[1,0,1]
	v_mul_f32_e32 v74, v79, v79
	v_mul_f32_e32 v75, v81, v81
	v_fmac_f32_e32 v74, v78, v78
	v_fmac_f32_e32 v75, v80, v80
	v_add_f32_e32 v74, v74, v75
	v_mul_f32_e32 v75, v77, v77
	v_fmac_f32_e32 v75, v76, v76
	v_add_f32_e32 v74, v75, v74
	v_mul_f32_e32 v75, v95, v95
	v_fmac_f32_e32 v75, v94, v94
	v_add_f32_e32 v102, v75, v74
	v_cvt_pk_bf16_f32 v74, v78, v79
	v_cvt_pk_bf16_f32 v75, v80, v81
	s_waitcnt vmcnt(4)
	v_lshlrev_b32_e32 v78, 16, v98
	v_and_b32_e32 v79, 0xffff0000, v98
	v_lshlrev_b32_e32 v80, 16, v99
	v_and_b32_e32 v81, 0xffff0000, v99
	v_cvt_pk_bf16_f32 v76, v76, v77
	v_cvt_pk_bf16_f32 v77, v94, v95
	v_lshlrev_b32_e32 v94, 16, v100
	v_and_b32_e32 v95, 0xffff0000, v100
	v_pk_fma_f32 v[72:73], v[72:73], 0.5, v[80:81] op_sel_hi:[1,0,1]
	v_pk_fma_f32 v[70:71], v[70:71], 0.5, v[78:79] op_sel_hi:[1,0,1]
	v_pk_fma_f32 v[80:81], v[66:67], 0.5, v[94:95] op_sel_hi:[1,0,1]
	v_mul_f32_e32 v66, v71, v71
	v_mul_f32_e32 v67, v73, v73
	v_fmac_f32_e32 v66, v70, v70
	v_fmac_f32_e32 v67, v72, v72
	v_lshlrev_b32_e32 v96, 16, v101
	v_and_b32_e32 v97, 0xffff0000, v101
	v_add_f32_e32 v66, v66, v67
	v_mul_f32_e32 v67, v81, v81
	v_pk_fma_f32 v[78:79], v[68:69], 0.5, v[96:97] op_sel_hi:[1,0,1]
	v_fmac_f32_e32 v67, v80, v80
	v_add_f32_e32 v66, v67, v66
	v_mul_f32_e32 v67, v79, v79
	v_fmac_f32_e32 v67, v78, v78
	v_add_f32_e32 v66, v67, v66
	v_add_f32_e32 v69, v102, v66
	ds_bpermute_b32 v94, v166, v69
	v_or_b32_e32 v90, 48, v158
	v_ashrrev_i32_e32 v91, 31, v90
	v_lshlrev_b64 v[92:93], 11, v[90:91]
	v_lshl_add_u64 v[66:67], s[34:35], 0, v[92:93]
	v_lshl_add_u64 v[92:93], v[154:155], 1, v[66:67]
	s_waitcnt lgkmcnt(0)
	v_add_f32_e32 v66, v69, v94
	ds_bpermute_b32 v67, v124, v66
	v_cvt_pk_bf16_f32 v68, v70, v71
	v_cvt_pk_bf16_f32 v69, v72, v73
	v_cvt_pk_bf16_f32 v70, v80, v81
	v_cvt_pk_bf16_f32 v71, v78, v79
	global_store_dwordx4 v[92:93], v[74:77], off sc1
	global_store_dwordx4 v[92:93], v[68:71], off offset:256 sc1
	s_and_saveexec_b64 s[48:49], s[0:1]
	s_cbranch_execz .LBB0_232
	v_lshlrev_b64 v[68:69], 6, v[90:91]
	v_lshl_add_u64 v[68:69], s[74:75], 0, v[68:69]
	v_lshl_add_u64 v[68:69], s[46:47], 2, v[68:69]
	s_lshl_b32 s8, s63, 2
	v_lshl_add_u64 v[68:69], v[68:69], 0, s[8:9]
	s_waitcnt lgkmcnt(0)
	v_add_f32_e32 v66, v66, v67
	global_store_dword v[68:69], v66, off sc1
; __device__ __forceinline__ unsigned cvtpk(float lo, float hi) { f32x2 v = {lo, hi}; bf16x2_t b = __builtin_convertvector(v, bf16x2_t); return __builtin_bit_cast(unsigned, b); }
; __device__ __forceinline__ float bflo(unsigned w) { return __uint_as_float(w << 16); }
; __device__ __forceinline__ float bfhi(unsigned w) { return __uint_as_float(w & 0xffff0000u); }
; #define FENCE() asm volatile("" ::: "memory")
;     __device__ __forceinline__ void operator()(const Acc& acc, const Unit& u, int wr, int wc, int fr, int fq) const {
;     ...
;         for (int i = 0; i < 8; ++i) {
;             const int ai = i >> 2, m = i & 3, cb = i & 1, nb = cb ^ 1;
;             if (i < 7) { const int ai2 = (i + 1) >> 2, m2 = (i + 1) & 3; const size_t ro = (size_t)(ai2 * 128 + m2 * 16) * DM;
; #pragma unroll
;                 for (int bj = 0; bj < 2; ++bj) {
;                     if constexpr (RES_BF16) preb[nb][bj] = *(const u32x4*)(rbase + ro + bj * 128);
;                     else { pre[nb][bj][0] = *(const f32x4*)(bbase + ro + bj * 128); pre[nb][bj][1] = *(const f32x4*)(bbase + ro + bj * 128 + 4); }
;                 }
;             }
;             FENCE();
;             const int r = rb + ai * 128 + m * 16;
;             float q = 0.f;
; #pragma unroll
;             for (int bj = 0; bj < 2; ++bj) {
;                 f32x4 b0, b1;
;                 if constexpr (RES_BF16) { const u32x4 w = preb[cb][bj]; b0 = (f32x4){bflo(w.x), bfhi(w.x), bflo(w.y), bfhi(w.y)}; b1 = (f32x4){bflo(w.z), bfhi(w.z), bflo(w.w), bfhi(w.w)}; }
;                 else { b0 = pre[cb][bj][0]; b1 = pre[cb][bj][1]; }
;                 const f32x4 v0 = b0 + acc[ai][bj][m][0] * scale, v1 = b1 + acc[ai][bj][m][1] * scale;
;                 if constexpr (OUT_F32) { float* op = out + (size_t)r * DM + col + bj * 128; *(f32x4*)op = v0; *(f32x4*)(op + 4) = v1; }
;                 q += (v0[0] * v0[0] + v0[1] * v0[1]) + (v0[2] * v0[2] + v0[3] * v0[3]) + (v1[0] * v1[0] + v1[1] * v1[1]) + (v1[2] * v1[2] + v1[3] * v1[3]);
;                 if (xb) { u32x4 w; w.x = cvtpk(v0[0], v0[1]); w.y = cvtpk(v0[2], v0[3]); w.z = cvtpk(v1[0], v1[1]); w.w = cvtpk(v1[2], v1[3]);
;                     *(u32x4*)(xb + (size_t)r * DM + col + bj * 128) = w; }
;             }
;             q += __shfl_xor(q, 16); q += __shfl_xor(q, 32);
;             if (fq == 0) st[(size_t)r * 16 + u.pn * 4 + wc] = q;
.LBB0_232:
	s_or_b64 exec, exec, s[48:49]
	v_add_co_u32_e32 v66, vcc, 0x48000, v156
	s_waitcnt vmcnt(3)
	v_lshlrev_b32_e32 v78, 16, v86
	s_waitcnt lgkmcnt(0)
	v_addc_co_u32_e32 v67, vcc, 0, v157, vcc
	global_load_dwordx4 v[70:73], v[66:67], off
	s_nop 0
	global_load_dwordx4 v[66:69], v[66:67], off offset:256
	v_and_b32_e32 v79, 0xffff0000, v86
	v_lshlrev_b32_e32 v80, 16, v87
	v_and_b32_e32 v81, 0xffff0000, v87
	v_lshlrev_b32_e32 v86, 16, v88
	v_and_b32_e32 v87, 0xffff0000, v88
	v_lshlrev_b32_e32 v88, 16, v89
	v_and_b32_e32 v89, 0xffff0000, v89
	v_pk_fma_f32 v[64:65], v[64:65], 0.5, v[80:81] op_sel_hi:[1,0,1]
	v_pk_fma_f32 v[62:63], v[62:63], 0.5, v[78:79] op_sel_hi:[1,0,1]
	v_pk_fma_f32 v[78:79], v[60:61], 0.5, v[88:89] op_sel_hi:[1,0,1]
	v_pk_fma_f32 v[60:61], v[58:59], 0.5, v[86:87] op_sel_hi:[1,0,1]
	v_mul_f32_e32 v58, v63, v63
	v_mul_f32_e32 v59, v65, v65
	v_fmac_f32_e32 v58, v62, v62
	v_fmac_f32_e32 v59, v64, v64
	v_add_f32_e32 v58, v58, v59
	v_mul_f32_e32 v59, v61, v61
	v_fmac_f32_e32 v59, v60, v60
	v_add_f32_e32 v58, v59, v58
	v_mul_f32_e32 v59, v79, v79
	v_fmac_f32_e32 v59, v78, v78
	v_add_f32_e32 v86, v59, v58
	v_cvt_pk_bf16_f32 v58, v62, v63
	v_cvt_pk_bf16_f32 v59, v64, v65
	s_waitcnt vmcnt(4)
	v_lshlrev_b32_e32 v62, 16, v82
	v_and_b32_e32 v63, 0xffff0000, v82
	v_lshlrev_b32_e32 v64, 16, v83
	v_and_b32_e32 v65, 0xffff0000, v83
	v_cvt_pk_bf16_f32 v60, v60, v61
	v_cvt_pk_bf16_f32 v61, v78, v79
	v_lshlrev_b32_e32 v78, 16, v84
	v_and_b32_e32 v79, 0xffff0000, v84
	v_pk_fma_f32 v[56:57], v[56:57], 0.5, v[64:65] op_sel_hi:[1,0,1]
	v_pk_fma_f32 v[54:55], v[54:55], 0.5, v[62:63] op_sel_hi:[1,0,1]
	v_pk_fma_f32 v[64:65], v[50:51], 0.5, v[78:79] op_sel_hi:[1,0,1]
	v_mul_f32_e32 v50, v55, v55
	v_mul_f32_e32 v51, v57, v57
	v_fmac_f32_e32 v50, v54, v54
	v_fmac_f32_e32 v51, v56, v56
	v_lshlrev_b32_e32 v80, 16, v85
	v_and_b32_e32 v81, 0xffff0000, v85
	v_add_f32_e32 v50, v50, v51
	v_mul_f32_e32 v51, v65, v65
	v_pk_fma_f32 v[62:63], v[52:53], 0.5, v[80:81] op_sel_hi:[1,0,1]
	v_fmac_f32_e32 v51, v64, v64
	v_add_f32_e32 v50, v51, v50
	v_mul_f32_e32 v51, v63, v63
	v_fmac_f32_e32 v51, v62, v62
	v_add_f32_e32 v50, v51, v50
	v_add_f32_e32 v53, v86, v50
	ds_bpermute_b32 v78, v166, v53
	v_add_u32_e32 v74, 0x80, v158
	v_ashrrev_i32_e32 v75, 31, v74
	v_lshlrev_b64 v[76:77], 11, v[74:75]
	v_lshl_add_u64 v[50:51], s[34:35], 0, v[76:77]
	v_lshl_add_u64 v[76:77], v[154:155], 1, v[50:51]
	s_waitcnt lgkmcnt(0)
	v_add_f32_e32 v50, v53, v78
	ds_bpermute_b32 v51, v124, v50
	v_cvt_pk_bf16_f32 v52, v54, v55
	v_cvt_pk_bf16_f32 v53, v56, v57
	v_cvt_pk_bf16_f32 v54, v64, v65
	v_cvt_pk_bf16_f32 v55, v62, v63
	global_store_dwordx4 v[76:77], v[58:61], off sc1
	global_store_dwordx4 v[76:77], v[52:55], off offset:256 sc1
	s_and_saveexec_b64 s[48:49], s[0:1]
	s_cbranch_execz .LBB0_234
	v_lshlrev_b64 v[52:53], 6, v[74:75]
	v_lshl_add_u64 v[52:53], s[74:75], 0, v[52:53]
	v_lshl_add_u64 v[52:53], s[46:47], 2, v[52:53]
	s_lshl_b32 s8, s63, 2
	v_lshl_add_u64 v[52:53], v[52:53], 0, s[8:9]
	s_waitcnt lgkmcnt(0)
	v_add_f32_e32 v50, v50, v51
	global_store_dword v[52:53], v50, off sc1
.LBB0_234:
	s_or_b64 exec, exec, s[48:49]
	v_add_co_u32_e32 v50, vcc, 0x50000, v156
	s_waitcnt vmcnt(3)
	v_lshlrev_b32_e32 v62, 16, v70
	s_waitcnt lgkmcnt(0)
	v_addc_co_u32_e32 v51, vcc, 0, v157, vcc
	global_load_dwordx4 v[54:57], v[50:51], off
	s_nop 0
	global_load_dwordx4 v[50:53], v[50:51], off offset:256
	v_and_b32_e32 v63, 0xffff0000, v70
	v_lshlrev_b32_e32 v64, 16, v71
	v_and_b32_e32 v65, 0xffff0000, v71
	v_lshlrev_b32_e32 v70, 16, v72
	v_and_b32_e32 v71, 0xffff0000, v72
	v_lshlrev_b32_e32 v72, 16, v73
	v_and_b32_e32 v73, 0xffff0000, v73
	v_pk_fma_f32 v[48:49], v[48:49], 0.5, v[64:65] op_sel_hi:[1,0,1]
	v_pk_fma_f32 v[46:47], v[46:47], 0.5, v[62:63] op_sel_hi:[1,0,1]
	v_pk_fma_f32 v[62:63], v[44:45], 0.5, v[72:73] op_sel_hi:[1,0,1]
	v_pk_fma_f32 v[44:45], v[42:43], 0.5, v[70:71] op_sel_hi:[1,0,1]
	v_mul_f32_e32 v42, v47, v47
	v_mul_f32_e32 v43, v49, v49
	v_fmac_f32_e32 v42, v46, v46
	v_fmac_f32_e32 v43, v48, v48
	v_add_f32_e32 v42, v42, v43
	v_mul_f32_e32 v43, v45, v45
	v_fmac_f32_e32 v43, v44, v44
	v_add_f32_e32 v42, v43, v42
	v_mul_f32_e32 v43, v63, v63
	v_fmac_f32_e32 v43, v62, v62
	v_add_f32_e32 v70, v43, v42
	v_cvt_pk_bf16_f32 v42, v46, v47
	v_cvt_pk_bf16_f32 v43, v48, v49
	s_waitcnt vmcnt(4)
	v_lshlrev_b32_e32 v46, 16, v66
	v_and_b32_e32 v47, 0xffff0000, v66
	v_lshlrev_b32_e32 v48, 16, v67
	v_and_b32_e32 v49, 0xffff0000, v67
	v_cvt_pk_bf16_f32 v44, v44, v45
	v_cvt_pk_bf16_f32 v45, v62, v63
	v_lshlrev_b32_e32 v62, 16, v68
	v_and_b32_e32 v63, 0xffff0000, v68
	v_pk_fma_f32 v[40:41], v[40:41], 0.5, v[48:49] op_sel_hi:[1,0,1]
	v_pk_fma_f32 v[38:39], v[38:39], 0.5, v[46:47] op_sel_hi:[1,0,1]
	v_pk_fma_f32 v[48:49], v[34:35], 0.5, v[62:63] op_sel_hi:[1,0,1]
	v_mul_f32_e32 v34, v39, v39
	v_mul_f32_e32 v35, v41, v41
	v_fmac_f32_e32 v34, v38, v38
	v_fmac_f32_e32 v35, v40, v40
	v_lshlrev_b32_e32 v64, 16, v69
	v_and_b32_e32 v65, 0xffff0000, v69
	v_add_f32_e32 v34, v34, v35
	v_mul_f32_e32 v35, v49, v49
	v_pk_fma_f32 v[46:47], v[36:37], 0.5, v[64:65] op_sel_hi:[1,0,1]
	v_fmac_f32_e32 v35, v48, v48
	v_add_f32_e32 v34, v35, v34
	v_mul_f32_e32 v35, v47, v47
	v_fmac_f32_e32 v35, v46, v46
	v_add_f32_e32 v34, v35, v34
	v_add_f32_e32 v37, v70, v34
	ds_bpermute_b32 v62, v166, v37
	v_or_b32_e32 v58, 16, v74
	v_ashrrev_i32_e32 v59, 31, v58
	v_lshlrev_b64 v[60:61], 11, v[58:59]
	v_lshl_add_u64 v[34:35], s[34:35], 0, v[60:61]
	v_lshl_add_u64 v[60:61], v[154:155], 1, v[34:35]
	s_waitcnt lgkmcnt(0)
	v_add_f32_e32 v34, v37, v62
	ds_bpermute_b32 v35, v124, v34
	v_cvt_pk_bf16_f32 v36, v38, v39
	v_cvt_pk_bf16_f32 v37, v40, v41
	v_cvt_pk_bf16_f32 v38, v48, v49
	v_cvt_pk_bf16_f32 v39, v46, v47
	global_store_dwordx4 v[60:61], v[42:45], off sc1
	global_store_dwordx4 v[60:61], v[36:39], off offset:256 sc1
	s_and_saveexec_b64 s[48:49], s[0:1]
	s_cbranch_execz .LBB0_236
	v_lshlrev_b64 v[36:37], 6, v[58:59]
	v_lshl_add_u64 v[36:37], s[74:75], 0, v[36:37]
	v_lshl_add_u64 v[36:37], s[46:47], 2, v[36:37]
	s_lshl_b32 s8, s63, 2
	v_lshl_add_u64 v[36:37], v[36:37], 0, s[8:9]
	s_waitcnt lgkmcnt(0)
	v_add_f32_e32 v34, v34, v35
	global_store_dword v[36:37], v34, off sc1
; __device__ __forceinline__ unsigned cvtpk(float lo, float hi) { f32x2 v = {lo, hi}; bf16x2_t b = __builtin_convertvector(v, bf16x2_t); return __builtin_bit_cast(unsigned, b); }
; __device__ __forceinline__ float bflo(unsigned w) { return __uint_as_float(w << 16); }
; __device__ __forceinline__ float bfhi(unsigned w) { return __uint_as_float(w & 0xffff0000u); }
; #define FENCE() asm volatile("" ::: "memory")
;     __device__ __forceinline__ void operator()(const Acc& acc, const Unit& u, int wr, int wc, int fr, int fq) const {
;     ...
;         for (int i = 0; i < 8; ++i) {
;             const int ai = i >> 2, m = i & 3, cb = i & 1, nb = cb ^ 1;
;             if (i < 7) { const int ai2 = (i + 1) >> 2, m2 = (i + 1) & 3; const size_t ro = (size_t)(ai2 * 128 + m2 * 16) * DM;
; #pragma unroll
;                 for (int bj = 0; bj < 2; ++bj) {
;                     if constexpr (RES_BF16) preb[nb][bj] = *(const u32x4*)(rbase + ro + bj * 128);
;                     else { pre[nb][bj][0] = *(const f32x4*)(bbase + ro + bj * 128); pre[nb][bj][1] = *(const f32x4*)(bbase + ro + bj * 128 + 4); }
;                 }
;             }
;             FENCE();
;             const int r = rb + ai * 128 + m * 16;
;             float q = 0.f;
; #pragma unroll
;             for (int bj = 0; bj < 2; ++bj) {
;                 f32x4 b0, b1;
;                 if constexpr (RES_BF16) { const u32x4 w = preb[cb][bj]; b0 = (f32x4){bflo(w.x), bfhi(w.x), bflo(w.y), bfhi(w.y)}; b1 = (f32x4){bflo(w.z), bfhi(w.z), bflo(w.w), bfhi(w.w)}; }
;                 else { b0 = pre[cb][bj][0]; b1 = pre[cb][bj][1]; }
;                 const f32x4 v0 = b0 + acc[ai][bj][m][0] * scale, v1 = b1 + acc[ai][bj][m][1] * scale;
;                 if constexpr (OUT_F32) { float* op = out + (size_t)r * DM + col + bj * 128; *(f32x4*)op = v0; *(f32x4*)(op + 4) = v1; }
;                 q += (v0[0] * v0[0] + v0[1] * v0[1]) + (v0[2] * v0[2] + v0[3] * v0[3]) + (v1[0] * v1[0] + v1[1] * v1[1]) + (v1[2] * v1[2] + v1[3] * v1[3]);
;                 if (xb) { u32x4 w; w.x = cvtpk(v0[0], v0[1]); w.y = cvtpk(v0[2], v0[3]); w.z = cvtpk(v1[0], v1[1]); w.w = cvtpk(v1[2], v1[3]);
;                     *(u32x4*)(xb + (size_t)r * DM + col + bj * 128) = w; }
;             }
;             q += __shfl_xor(q, 16); q += __shfl_xor(q, 32);
;             if (fq == 0) st[(size_t)r * 16 + u.pn * 4 + wc] = q;
.LBB0_236:
	s_or_b64 exec, exec, s[48:49]
	v_add_co_u32_e32 v34, vcc, 0x58000, v156
	s_waitcnt vmcnt(3)
	v_lshlrev_b32_e32 v46, 16, v54
	s_waitcnt lgkmcnt(0)
	v_addc_co_u32_e32 v35, vcc, 0, v157, vcc
	global_load_dwordx4 v[38:41], v[34:35], off
	s_nop 0
	global_load_dwordx4 v[34:37], v[34:35], off offset:256
	v_and_b32_e32 v47, 0xffff0000, v54
	v_lshlrev_b32_e32 v48, 16, v55
	v_and_b32_e32 v49, 0xffff0000, v55
	v_lshlrev_b32_e32 v54, 16, v56
	v_and_b32_e32 v55, 0xffff0000, v56
	v_lshlrev_b32_e32 v56, 16, v57
	v_and_b32_e32 v57, 0xffff0000, v57
	v_pk_fma_f32 v[32:33], v[32:33], 0.5, v[48:49] op_sel_hi:[1,0,1]
	v_pk_fma_f32 v[30:31], v[30:31], 0.5, v[46:47] op_sel_hi:[1,0,1]
	v_pk_fma_f32 v[46:47], v[28:29], 0.5, v[56:57] op_sel_hi:[1,0,1]
	v_pk_fma_f32 v[28:29], v[26:27], 0.5, v[54:55] op_sel_hi:[1,0,1]
	v_mul_f32_e32 v26, v31, v31
	v_mul_f32_e32 v27, v33, v33
	v_fmac_f32_e32 v26, v30, v30
	v_fmac_f32_e32 v27, v32, v32
	v_add_f32_e32 v26, v26, v27
	v_mul_f32_e32 v27, v29, v29
	v_fmac_f32_e32 v27, v28, v28
	v_add_f32_e32 v26, v27, v26
	v_mul_f32_e32 v27, v47, v47
	v_fmac_f32_e32 v27, v46, v46
	v_add_f32_e32 v54, v27, v26
	v_cvt_pk_bf16_f32 v26, v30, v31
	v_cvt_pk_bf16_f32 v27, v32, v33
	s_waitcnt vmcnt(4)
	v_lshlrev_b32_e32 v30, 16, v50
	v_and_b32_e32 v31, 0xffff0000, v50
	v_lshlrev_b32_e32 v32, 16, v51
	v_and_b32_e32 v33, 0xffff0000, v51
	v_cvt_pk_bf16_f32 v28, v28, v29
	v_cvt_pk_bf16_f32 v29, v46, v47
	v_lshlrev_b32_e32 v46, 16, v52
	v_and_b32_e32 v47, 0xffff0000, v52
	v_pk_fma_f32 v[24:25], v[24:25], 0.5, v[32:33] op_sel_hi:[1,0,1]
	v_pk_fma_f32 v[22:23], v[22:23], 0.5, v[30:31] op_sel_hi:[1,0,1]
	v_pk_fma_f32 v[32:33], v[18:19], 0.5, v[46:47] op_sel_hi:[1,0,1]
	v_mul_f32_e32 v18, v23, v23
	v_mul_f32_e32 v19, v25, v25
	v_fmac_f32_e32 v18, v22, v22
	v_fmac_f32_e32 v19, v24, v24
	v_lshlrev_b32_e32 v48, 16, v53
	v_and_b32_e32 v49, 0xffff0000, v53
	v_add_f32_e32 v18, v18, v19
	v_mul_f32_e32 v19, v33, v33
	v_pk_fma_f32 v[30:31], v[20:21], 0.5, v[48:49] op_sel_hi:[1,0,1]
	v_fmac_f32_e32 v19, v32, v32
	v_add_f32_e32 v18, v19, v18
	v_mul_f32_e32 v19, v31, v31
	v_fmac_f32_e32 v19, v30, v30
	v_add_f32_e32 v18, v19, v18
	v_add_f32_e32 v21, v54, v18
	ds_bpermute_b32 v46, v166, v21
	v_or_b32_e32 v42, 32, v74
	v_ashrrev_i32_e32 v43, 31, v42
	v_lshlrev_b64 v[44:45], 11, v[42:43]
	v_lshl_add_u64 v[18:19], s[34:35], 0, v[44:45]
	v_lshl_add_u64 v[44:45], v[154:155], 1, v[18:19]
	s_waitcnt lgkmcnt(0)
	v_add_f32_e32 v18, v21, v46
	ds_bpermute_b32 v19, v124, v18
	v_cvt_pk_bf16_f32 v20, v22, v23
	v_cvt_pk_bf16_f32 v21, v24, v25
	v_cvt_pk_bf16_f32 v22, v32, v33
	v_cvt_pk_bf16_f32 v23, v30, v31
	global_store_dwordx4 v[44:45], v[26:29], off sc1
	global_store_dwordx4 v[44:45], v[20:23], off offset:256 sc1
	s_and_saveexec_b64 s[48:49], s[0:1]
	s_cbranch_execz .LBB0_238
	v_lshlrev_b64 v[20:21], 6, v[42:43]
	v_lshl_add_u64 v[20:21], s[74:75], 0, v[20:21]
	v_lshl_add_u64 v[20:21], s[46:47], 2, v[20:21]
	s_lshl_b32 s8, s63, 2
	v_lshl_add_u64 v[20:21], v[20:21], 0, s[8:9]
	s_waitcnt lgkmcnt(0)
	v_add_f32_e32 v18, v18, v19
	global_store_dword v[20:21], v18, off sc1
.LBB0_238:
	s_or_b64 exec, exec, s[48:49]
	s_waitcnt vmcnt(3)
	v_lshlrev_b32_e32 v22, 16, v38
	v_and_b32_e32 v23, 0xffff0000, v38
	v_lshlrev_b32_e32 v24, 16, v39
	v_and_b32_e32 v25, 0xffff0000, v39
	v_lshlrev_b32_e32 v26, 16, v40
	v_and_b32_e32 v27, 0xffff0000, v40
	v_lshlrev_b32_e32 v28, 16, v41
	v_and_b32_e32 v29, 0xffff0000, v41
	v_pk_fma_f32 v[16:17], v[16:17], 0.5, v[24:25] op_sel_hi:[1,0,1]
	v_pk_fma_f32 v[14:15], v[14:15], 0.5, v[22:23] op_sel_hi:[1,0,1]
	v_pk_fma_f32 v[22:23], v[12:13], 0.5, v[28:29] op_sel_hi:[1,0,1]
	v_pk_fma_f32 v[12:13], v[10:11], 0.5, v[26:27] op_sel_hi:[1,0,1]
	v_mul_f32_e32 v10, v15, v15
	v_mul_f32_e32 v11, v17, v17
	v_fmac_f32_e32 v10, v14, v14
	v_fmac_f32_e32 v11, v16, v16
	v_add_f32_e32 v10, v10, v11
	v_mul_f32_e32 v11, v13, v13
	v_fmac_f32_e32 v11, v12, v12
	v_add_f32_e32 v10, v11, v10
	v_mul_f32_e32 v11, v23, v23
	v_fmac_f32_e32 v11, v22, v22
	v_add_f32_e32 v26, v11, v10
	v_cvt_pk_bf16_f32 v10, v14, v15
	v_cvt_pk_bf16_f32 v11, v16, v17
	s_waitcnt vmcnt(2)
	v_lshlrev_b32_e32 v14, 16, v34
	v_and_b32_e32 v15, 0xffff0000, v34
	v_lshlrev_b32_e32 v16, 16, v35
	v_and_b32_e32 v17, 0xffff0000, v35
	v_cvt_pk_bf16_f32 v12, v12, v13
	v_cvt_pk_bf16_f32 v13, v22, v23
	v_lshlrev_b32_e32 v22, 16, v36
	v_and_b32_e32 v23, 0xffff0000, v36
	v_pk_fma_f32 v[8:9], v[8:9], 0.5, v[16:17] op_sel_hi:[1,0,1]
	v_pk_fma_f32 v[6:7], v[6:7], 0.5, v[14:15] op_sel_hi:[1,0,1]
	v_pk_fma_f32 v[16:17], v[2:3], 0.5, v[22:23] op_sel_hi:[1,0,1]
	v_mul_f32_e32 v2, v7, v7
	v_mul_f32_e32 v3, v9, v9
	v_fmac_f32_e32 v2, v6, v6
	v_fmac_f32_e32 v3, v8, v8
	v_lshlrev_b32_e32 v24, 16, v37
	v_and_b32_e32 v25, 0xffff0000, v37
	v_add_f32_e32 v2, v2, v3
	v_mul_f32_e32 v3, v17, v17
	v_pk_fma_f32 v[14:15], v[4:5], 0.5, v[24:25] op_sel_hi:[1,0,1]
	v_fmac_f32_e32 v3, v16, v16
	v_add_f32_e32 v2, v3, v2
	v_mul_f32_e32 v3, v15, v15
	v_fmac_f32_e32 v3, v14, v14
	v_add_f32_e32 v2, v3, v2
	v_add_f32_e32 v5, v26, v2
	ds_bpermute_b32 v22, v166, v5
	v_or_b32_e32 v18, 48, v74
	s_waitcnt lgkmcnt(1)
	v_ashrrev_i32_e32 v19, 31, v18
	v_lshlrev_b64 v[20:21], 11, v[18:19]
	v_lshl_add_u64 v[2:3], s[34:35], 0, v[20:21]
	v_lshl_add_u64 v[20:21], v[154:155], 1, v[2:3]
	s_waitcnt lgkmcnt(0)
	v_add_f32_e32 v2, v5, v22
	ds_bpermute_b32 v3, v124, v2
	v_cvt_pk_bf16_f32 v4, v6, v7
	v_cvt_pk_bf16_f32 v5, v8, v9
	v_cvt_pk_bf16_f32 v6, v16, v17
	v_cvt_pk_bf16_f32 v7, v14, v15
	global_store_dwordx4 v[20:21], v[10:13], off sc1
	global_store_dwordx4 v[20:21], v[4:7], off offset:256 sc1
	s_and_saveexec_b64 s[48:49], s[0:1]
	s_cbranch_execz .LBB0_240
	v_lshlrev_b64 v[4:5], 6, v[18:19]
	v_lshl_add_u64 v[4:5], s[74:75], 0, v[4:5]
	v_lshl_add_u64 v[4:5], s[46:47], 2, v[4:5]
	s_lshl_b32 s8, s63, 2
	v_lshl_add_u64 v[4:5], v[4:5], 0, s[8:9]
	s_waitcnt lgkmcnt(0)
	v_add_f32_e32 v2, v2, v3
	global_store_dword v[4:5], v2, off sc1

; #define LAS __attribute__((address_space(3)))
; __device__ __forceinline__ void rstd8_lds(int rrel, int fq, float inv_dim, float (&rs)[2][4]) {
;     ...
;         for (int m = 0; m < 4; ++m) v[ai][m] = *(const LAS f32x4*)(lds + STAB_OFF + (rrel + ai * 128 + m * 16) * 64 + fq * 16);
; #pragma unroll
;     for (int ai = 0; ai < 2; ++ai)
; #pragma unroll
;         for (int m = 0; m < 4; ++m) { float q = (v[ai][m][0] + v[ai][m][1]) + (v[ai][m][2] + v[ai][m][3]); q += __shfl_xor(q, 16); q += __shfl_xor(q, 32); rs[ai][m] = __builtin_amdgcn_rsqf(q * inv_dim + EPS); }
;     __device__ __forceinline__ void operator()(const Acc& acc, const Unit& u, int wr, int wc, int fr, int fq) const {
;     ...
;             const bool isq = t < 6;
;             const float* gn = isq ? qn : kn; const float sc = isq ? QSCALE : 1.0f;
;             f32x4 gv[2][2];
; #pragma unroll
;             for (int bj = 0; bj < 2; ++bj)
; #pragma unroll
;                 for (int n = 0; n < 2; ++n) gv[bj][n] = *(const f32x4*)(gn + 32 * bj + 8 * fq + 4 * n) * sc;
;             bf16_t* base = isq ? (UQ + 512 + 256 * (t - 4)) : (KB + 256 * (t - 6));
;             const int pitch = isq ? DM : 512;
;             const int col = wc * 64 + fq * 8;
;             float rsv[2][4]; rstd8_lds(wr * 64 + fr, fq, 1.0f / 1024.0f, rsv);
; #pragma unroll
;             for (int ai = 0; ai < 2; ++ai)
; #pragma unroll
;                 for (int m = 0; m < 4; ++m) {
;                     const int r = u.pm * 256 + ai * 128 + wr * 64 + m * 16 + fr;
;                     const float rs = rsv[ai][m];
;                     f32x4 v[2][2]; float q = 0.f;
; #pragma unroll
;                     for (int bj = 0; bj < 2; ++bj)
; #pragma unroll
;                         for (int n = 0; n < 2; ++n) { v[bj][n] = acc[ai][bj][m][n] * rs; const f32x4 x = v[bj][n]; q += (x[0] * x[0] + x[1] * x[1]) + (x[2] * x[2] + x[3] * x[3]); }
;                     q += __shfl_xor(q, 16); q += __shfl_xor(q, 32);
;                     const float rq = __builtin_amdgcn_rsqf(q * (1.0f / 64.0f) + EPS);
.LBB0_325:
	s_add_i32 s1, s8, -8
	s_mov_b64 s[88:89], -1
	s_cmp_gt_u32 s1, -5
	v_lshl_add_u32 v166, s6, 8, v1
	s_cbranch_scc0 .LBB0_327
	s_cmp_lt_u32 s8, 6
	s_cselect_b64 vcc, -1, 0
	s_and_b64 s[6:7], vcc, exec
	s_cselect_b32 s7, s21, s23
	s_cselect_b32 s6, s20, s22
	global_load_dwordx4 v[130:133], v195, s[6:7] offset:16
	global_load_dwordx4 v[134:137], v195, s[6:7]
	v_cndmask_b32_e32 v138, 1.0, v198, vcc
	v_readlane_b32 s1, v246, 9
	s_cselect_b32 s1, s37, s1
	v_and_b32_e32 v186, 64, v199
	v_xor_b32_e32 v167, 16, v199
	v_add_u32_e32 v186, 64, v186
	s_waitcnt vmcnt(0)
	v_pk_mul_f32 v[168:169], v[138:139], v[132:133] op_sel_hi:[0,1]
	v_pk_mul_f32 v[174:175], v[138:139], v[136:137] op_sel_hi:[0,1]
	v_pk_mul_f32 v[176:177], v[138:139], v[134:135] op_sel_hi:[0,1]
	v_pk_mul_f32 v[172:173], v[138:139], v[130:131] op_sel_hi:[0,1]
	global_load_dwordx4 v[130:133], v195, s[6:7] offset:144
	global_load_dwordx4 v[134:137], v195, s[6:7] offset:128
	v_readlane_b32 s6, v246, 8
	s_movk_i32 s7, 0xfc00
	s_cselect_b32 s6, s36, s6
	s_cselect_b32 s7, s7, 0xfffff400
	s_lshl_b32 s9, s8, 9
	s_add_u32 s6, s6, s9
	s_addc_u32 s1, s1, 0
	s_add_u32 s88, s6, s7
	v_cmp_lt_i32_e64 s[6:7], v167, v186
	s_addc_u32 s89, s1, -1
	s_waitcnt vmcnt(1)
	v_pk_mul_f32 v[178:179], v[138:139], v[132:133] op_sel_hi:[0,1]
	v_cndmask_b32_e64 v167, v199, v167, s[6:7]
	s_waitcnt vmcnt(0)
	v_pk_mul_f32 v[180:181], v[138:139], v[136:137] op_sel_hi:[0,1]
	v_pk_mul_f32 v[184:185], v[138:139], v[134:135] op_sel_hi:[0,1]
	v_pk_mul_f32 v[182:183], v[138:139], v[130:131] op_sel_hi:[0,1]
	ds_read_b128 v[202:205], v197
	ds_read_b128 v[206:209], v197 offset:1024
	ds_read_b128 v[210:213], v197 offset:2048
	ds_read_b128 v[214:217], v197 offset:3072
	ds_read_b128 v[142:145], v197 offset:8192
	ds_read_b128 v[138:141], v197 offset:9216
	ds_read_b128 v[134:137], v197 offset:10240
	ds_read_b128 v[130:133], v197 offset:11264
	v_lshlrev_b32_e32 v200, 2, v167
	v_xor_b32_e32 v167, 32, v199
	v_cmp_lt_i32_e64 s[6:7], v167, v186
	s_waitcnt lgkmcnt(7)
	v_mov_b32_e32 v218, v203
	v_mov_b32_e32 v219, v204
	v_mov_b32_e32 v203, v205
	v_cndmask_b32_e64 v167, v199, v167, s[6:7]
	v_pk_add_f32 v[202:203], v[218:219], v[202:203]
	v_lshlrev_b32_e32 v201, 2, v167
	v_add_f32_e32 v167, v202, v203
	ds_bpermute_b32 v186, v200, v167
	s_waitcnt lgkmcnt(7)
	v_mov_b32_e32 v202, v207
	v_mov_b32_e32 v203, v208
	v_mov_b32_e32 v207, v209
	v_pk_add_f32 v[202:203], v[202:203], v[206:207]
	s_waitcnt lgkmcnt(0)
	v_add_f32_e32 v167, v167, v186
	ds_bpermute_b32 v186, v201, v167
	s_and_b64 s[6:7], vcc, exec
	s_cselect_b32 s1, 10, 9
	s_waitcnt lgkmcnt(0)
	v_add_f32_e32 v167, v167, v186
	v_fmamk_f32 v167, v167, 0x3a800000, v196
	v_rsq_f32_e32 v192, v167
	v_add_f32_e32 v167, v202, v203
	ds_bpermute_b32 v186, v200, v167
	v_mov_b32_e32 v202, v211
	v_mov_b32_e32 v203, v212
	v_mov_b32_e32 v211, v213
	v_pk_add_f32 v[202:203], v[202:203], v[210:211]
	s_waitcnt lgkmcnt(0)
	v_add_f32_e32 v167, v167, v186
	ds_bpermute_b32 v186, v201, v167
	v_pk_mul_f32 v[218:219], v[114:115], v[192:193] op_sel_hi:[1,0]
	s_waitcnt lgkmcnt(0)
	v_add_f32_e32 v167, v167, v186
	v_fmamk_f32 v167, v167, 0x3a800000, v196
	v_rsq_f32_e32 v190, v167
	v_add_f32_e32 v167, v202, v203
	ds_bpermute_b32 v186, v200, v167
	v_mov_b32_e32 v202, v215
	v_mov_b32_e32 v203, v216
	v_mov_b32_e32 v215, v217
	v_pk_add_f32 v[202:203], v[202:203], v[214:215]
	s_waitcnt lgkmcnt(0)
	v_add_f32_e32 v167, v167, v186
	ds_bpermute_b32 v186, v201, v167
	v_pk_mul_f32 v[216:217], v[116:117], v[192:193] op_sel_hi:[1,0]
	s_waitcnt lgkmcnt(0)
	v_add_f32_e32 v167, v167, v186
	v_fmamk_f32 v167, v167, 0x3a800000, v196
	v_rsq_f32_e32 v188, v167
	v_add_f32_e32 v167, v202, v203
	v_mov_b32_e32 v202, v143
	v_mov_b32_e32 v203, v144
	v_mov_b32_e32 v143, v145
	v_mov_b32_e32 v144, v139
	v_mov_b32_e32 v145, v140
	v_mov_b32_e32 v139, v141
	v_mov_b32_e32 v140, v135
	v_mov_b32_e32 v141, v136
	v_mov_b32_e32 v135, v137
	v_mov_b32_e32 v136, v131
	v_mov_b32_e32 v137, v132
	v_mov_b32_e32 v131, v133
	v_pk_add_f32 v[134:135], v[140:141], v[134:135]
	v_pk_add_f32 v[130:131], v[136:137], v[130:131]
	v_pk_mul_f32 v[136:137], v[126:127], v[192:193] op_sel_hi:[1,0]
	v_pk_mul_f32 v[140:141], v[128:129], v[192:193] op_sel_hi:[1,0]
	v_pk_add_f32 v[142:143], v[202:203], v[142:143]
	v_pk_add_f32 v[138:139], v[144:145], v[138:139]
	v_pk_mul_f32 v[144:145], v[140:141], v[140:141]
	v_pk_mul_f32 v[202:203], v[136:137], v[136:137]
	v_add_f32_e32 v134, v134, v135
	v_pk_mov_b32 v[204:205], v[202:203], v[144:145] op_sel:[1,0]
	v_mov_b32_e32 v203, v145
	ds_bpermute_b32 v135, v200, v134
	v_pk_add_f32 v[144:145], v[204:205], v[202:203]
	v_pk_mul_f32 v[202:203], v[122:123], v[192:193] op_sel_hi:[1,0]
	v_pk_mul_f32 v[204:205], v[124:125], v[192:193] op_sel_hi:[1,0]
	v_pk_mul_f32 v[208:209], v[202:203], v[202:203]
	v_pk_mul_f32 v[206:207], v[204:205], v[204:205]
	v_pk_add_f32 v[144:145], v[144:145], v[144:145] op_sel_hi:[0,1]
	v_pk_mov_b32 v[210:211], v[208:209], v[206:207] op_sel:[1,0]
	v_mov_b32_e32 v209, v207
	v_pk_add_f32 v[206:207], v[210:211], v[208:209]
	v_pk_mul_f32 v[210:211], v[118:119], v[192:193] op_sel_hi:[1,0]
	v_pk_mul_f32 v[208:209], v[120:121], v[192:193] op_sel_hi:[1,0]
	v_mul_f32_e32 v144, v210, v210
	s_waitcnt lgkmcnt(0)
	v_add_f32_e32 v134, v134, v135
	v_pk_fma_f32 v[212:213], v[210:211], v[210:211], v[144:145] op_sel_hi:[1,1,0]
	v_mul_f32_e32 v144, v208, v208
	ds_bpermute_b32 v135, v201, v134
	v_pk_add_f32 v[206:207], v[206:207], v[206:207] op_sel_hi:[0,1]
	v_pk_fma_f32 v[214:215], v[208:209], v[208:209], v[144:145] op_sel_hi:[1,1,0]
	v_mul_f32_e32 v212, v218, v218
	v_mul_f32_e32 v214, v219, v219
	v_mul_f32_e32 v144, v216, v216
	v_mul_f32_e32 v206, v217, v217
	v_pk_add_f32 v[212:213], v[212:213], v[214:215]
	v_pk_add_f32 v[144:145], v[144:145], v[206:207]
	s_waitcnt lgkmcnt(0)
; __device__ __forceinline__ unsigned cvtpk(float lo, float hi) { f32x2 v = {lo, hi}; bf16x2_t b = __builtin_convertvector(v, bf16x2_t); return __builtin_bit_cast(unsigned, b); }
;     __device__ __forceinline__ void operator()(const Acc& acc, const Unit& u, int wr, int wc, int fr, int fq) const {
;     ...
;                 for (int m = 0; m < 4; ++m) {
;                     const int r = u.pm * 256 + ai * 128 + wr * 64 + m * 16 + fr;
;                     const float rs = rsv[ai][m];
;                     f32x4 v[2][2]; float q = 0.f;
; #pragma unroll
;                     for (int bj = 0; bj < 2; ++bj)
; #pragma unroll
;                         for (int n = 0; n < 2; ++n) { v[bj][n] = acc[ai][bj][m][n] * rs; const f32x4 x = v[bj][n]; q += (x[0] * x[0] + x[1] * x[1]) + (x[2] * x[2] + x[3] * x[3]); }
;                     q += __shfl_xor(q, 16); q += __shfl_xor(q, 32);
;                     const float rq = __builtin_amdgcn_rsqf(q * (1.0f / 64.0f) + EPS);
; #pragma unroll
;                     for (int bj = 0; bj < 2; ++bj) {
;                         const f32x4 a = v[bj][0] * gv[bj][0] * rq, b = v[bj][1] * gv[bj][1] * rq;
;                         u32x4 w; w.x = cvtpk(a[0], a[1]); w.y = cvtpk(a[2], a[3]); w.z = cvtpk(b[0], b[1]); w.w = cvtpk(b[2], b[3]);
;                         *(u32x4*)(base + (size_t)r * pitch + col + bj * 32) = w;
;                     }
	v_add_f32_e32 v134, v134, v135
	v_pk_add_f32 v[144:145], v[212:213], v[144:145]
	ds_bpermute_b32 v186, v200, v167
	v_add_f32_e32 v133, v144, v145
	ds_bpermute_b32 v135, v200, v133
	v_add_f32_e32 v130, v130, v131
	ds_bpermute_b32 v131, v200, v130
	s_waitcnt lgkmcnt(2)
	v_add_f32_e32 v167, v167, v186
	ds_bpermute_b32 v186, v201, v167
	s_waitcnt lgkmcnt(2)
	v_add_f32_e32 v133, v133, v135
	ds_bpermute_b32 v135, v201, v133
	s_waitcnt lgkmcnt(2)
	v_add_f32_e32 v130, v130, v131
	ds_bpermute_b32 v131, v201, v130
	s_waitcnt lgkmcnt(2)
	v_add_f32_e32 v167, v167, v186
	v_fmamk_f32 v167, v167, 0x3a800000, v196
	s_waitcnt lgkmcnt(1)
	v_add_f32_e32 v133, v133, v135
	v_fmamk_f32 v133, v133, 0x3c800000, v196
	v_rsq_f32_e32 v144, v133
	s_waitcnt lgkmcnt(0)
	v_add_f32_e32 v130, v130, v131
	v_rsq_f32_e32 v186, v167
	v_fmamk_f32 v130, v130, 0x3a800000, v196
	v_ashrrev_i32_e32 v167, 31, v166
	v_pk_mul_f32 v[136:137], v[176:177], v[136:137]
	v_pk_mul_f32 v[140:141], v[174:175], v[140:141]
	v_pk_mul_f32 v[202:203], v[172:173], v[202:203]
	v_pk_mul_f32 v[204:205], v[168:169], v[204:205]
	v_rsq_f32_e32 v132, v130
	v_lshl_add_u64 v[130:131], s[88:89], 0, v[154:155]
	v_lshlrev_b64 v[206:207], s1, v[166:167]
	v_pk_mul_f32 v[140:141], v[140:141], v[144:145] op_sel_hi:[1,0]
	v_pk_mul_f32 v[136:137], v[136:137], v[144:145] op_sel_hi:[1,0]
	v_pk_mul_f32 v[212:213], v[204:205], v[144:145] op_sel_hi:[1,0]
	v_pk_mul_f32 v[204:205], v[202:203], v[144:145] op_sel_hi:[1,0]
	v_lshl_add_u64 v[206:207], v[206:207], 1, v[130:131]
	v_cvt_pk_bf16_f32 v202, v136, v137
	v_cvt_pk_bf16_f32 v203, v140, v141
	v_cvt_pk_bf16_f32 v204, v204, v205
	v_cvt_pk_bf16_f32 v205, v212, v213
	global_store_dwordx4 v[206:207], v[202:205], off sc1
	v_pk_mul_f32 v[136:137], v[184:185], v[210:211]
	v_pk_mul_f32 v[140:141], v[180:181], v[208:209]
	v_pk_mul_f32 v[202:203], v[182:183], v[218:219]
	v_pk_mul_f32 v[204:205], v[178:179], v[216:217]
	v_pk_mul_f32 v[140:141], v[140:141], v[144:145] op_sel_hi:[1,0]
	v_pk_mul_f32 v[136:137], v[136:137], v[144:145] op_sel_hi:[1,0]
	v_pk_mul_f32 v[208:209], v[204:205], v[144:145] op_sel_hi:[1,0]
	v_pk_mul_f32 v[144:145], v[202:203], v[144:145] op_sel_hi:[1,0]
	v_cvt_pk_bf16_f32 v202, v136, v137
	v_cvt_pk_bf16_f32 v203, v140, v141
	v_cvt_pk_bf16_f32 v204, v144, v145
	v_cvt_pk_bf16_f32 v205, v208, v209
	v_pk_mul_f32 v[136:137], v[110:111], v[190:191] op_sel_hi:[1,0]
	v_pk_mul_f32 v[140:141], v[112:113], v[190:191] op_sel_hi:[1,0]
	global_store_dwordx4 v[206:207], v[202:205], off offset:64 sc1
	v_pk_mul_f32 v[144:145], v[140:141], v[140:141]
	v_pk_mul_f32 v[216:217], v[100:101], v[190:191] op_sel_hi:[1,0]
	v_pk_mul_f32 v[202:203], v[136:137], v[136:137]
	v_pk_mul_f32 v[218:219], v[98:99], v[190:191] op_sel_hi:[1,0]
	v_pk_mov_b32 v[204:205], v[202:203], v[144:145] op_sel:[1,0]
	v_mov_b32_e32 v203, v145
	v_pk_add_f32 v[144:145], v[204:205], v[202:203]
	v_pk_mul_f32 v[202:203], v[106:107], v[190:191] op_sel_hi:[1,0]
	v_pk_mul_f32 v[204:205], v[108:109], v[190:191] op_sel_hi:[1,0]
	v_pk_mul_f32 v[208:209], v[202:203], v[202:203]
	v_pk_mul_f32 v[206:207], v[204:205], v[204:205]
	v_pk_add_f32 v[144:145], v[144:145], v[144:145] op_sel_hi:[0,1]
	v_pk_mov_b32 v[210:211], v[208:209], v[206:207] op_sel:[1,0]
	v_mov_b32_e32 v209, v207
	v_pk_add_f32 v[206:207], v[210:211], v[208:209]
	v_pk_mul_f32 v[210:211], v[102:103], v[190:191] op_sel_hi:[1,0]
	v_pk_mul_f32 v[208:209], v[104:105], v[190:191] op_sel_hi:[1,0]
	v_mul_f32_e32 v144, v210, v210
	v_pk_fma_f32 v[212:213], v[210:211], v[210:211], v[144:145] op_sel_hi:[1,1,0]
	v_mul_f32_e32 v144, v208, v208
	v_pk_add_f32 v[206:207], v[206:207], v[206:207] op_sel_hi:[0,1]
	v_pk_fma_f32 v[214:215], v[208:209], v[208:209], v[144:145] op_sel_hi:[1,1,0]
	v_mul_f32_e32 v212, v218, v218
	v_mul_f32_e32 v214, v219, v219
	v_mul_f32_e32 v144, v216, v216
	v_mul_f32_e32 v206, v217, v217
	v_pk_add_f32 v[212:213], v[212:213], v[214:215]
	v_pk_add_f32 v[144:145], v[144:145], v[206:207]
	v_pk_mul_f32 v[136:137], v[176:177], v[136:137]
	v_pk_add_f32 v[144:145], v[212:213], v[144:145]
	v_pk_mul_f32 v[140:141], v[174:175], v[140:141]
	v_add_f32_e32 v133, v144, v145
	ds_bpermute_b32 v135, v200, v133
	v_or_b32_e32 v144, 16, v166
	v_ashrrev_i32_e32 v145, 31, v144
	v_pk_mul_f32 v[202:203], v[172:173], v[202:203]
	v_pk_mul_f32 v[204:205], v[168:169], v[204:205]
	s_waitcnt lgkmcnt(0)
	v_add_f32_e32 v133, v133, v135
	ds_bpermute_b32 v135, v201, v133
	v_lshlrev_b64 v[144:145], s1, v[144:145]
	v_lshl_add_u64 v[144:145], v[144:145], 1, v[130:131]
	v_add_f32_e32 v142, v142, v143
	ds_bpermute_b32 v143, v200, v142
	s_waitcnt lgkmcnt(1)
	v_add_f32_e32 v133, v133, v135
	v_fmamk_f32 v133, v133, 0x3c800000, v196
	v_rsq_f32_e32 v190, v133
	v_add_f32_e32 v138, v138, v139
	s_waitcnt lgkmcnt(0)
; __device__ __forceinline__ unsigned cvtpk(float lo, float hi) { f32x2 v = {lo, hi}; bf16x2_t b = __builtin_convertvector(v, bf16x2_t); return __builtin_bit_cast(unsigned, b); }
;     __device__ __forceinline__ void operator()(const Acc& acc, const Unit& u, int wr, int wc, int fr, int fq) const {
;     ...
;                 for (int m = 0; m < 4; ++m) {
;                     const int r = u.pm * 256 + ai * 128 + wr * 64 + m * 16 + fr;
;                     const float rs = rsv[ai][m];
;                     f32x4 v[2][2]; float q = 0.f;
; #pragma unroll
;                     for (int bj = 0; bj < 2; ++bj)
; #pragma unroll
;                         for (int n = 0; n < 2; ++n) { v[bj][n] = acc[ai][bj][m][n] * rs; const f32x4 x = v[bj][n]; q += (x[0] * x[0] + x[1] * x[1]) + (x[2] * x[2] + x[3] * x[3]); }
;                     q += __shfl_xor(q, 16); q += __shfl_xor(q, 32);
;                     const float rq = __builtin_amdgcn_rsqf(q * (1.0f / 64.0f) + EPS);
; #pragma unroll
;                     for (int bj = 0; bj < 2; ++bj) {
;                         const f32x4 a = v[bj][0] * gv[bj][0] * rq, b = v[bj][1] * gv[bj][1] * rq;
;                         u32x4 w; w.x = cvtpk(a[0], a[1]); w.y = cvtpk(a[2], a[3]); w.z = cvtpk(b[0], b[1]); w.w = cvtpk(b[2], b[3]);
;                         *(u32x4*)(base + (size_t)r * pitch + col + bj * 32) = w;
;                     }
	v_add_f32_e32 v142, v142, v143
	ds_bpermute_b32 v143, v201, v142
	v_pk_mul_f32 v[140:141], v[140:141], v[190:191] op_sel_hi:[1,0]
	v_pk_mul_f32 v[136:137], v[136:137], v[190:191] op_sel_hi:[1,0]
	v_pk_mul_f32 v[206:207], v[204:205], v[190:191] op_sel_hi:[1,0]
	v_pk_mul_f32 v[204:205], v[202:203], v[190:191] op_sel_hi:[1,0]
	v_cvt_pk_bf16_f32 v202, v136, v137
	v_cvt_pk_bf16_f32 v203, v140, v141
	v_cvt_pk_bf16_f32 v204, v204, v205
	v_cvt_pk_bf16_f32 v205, v206, v207
	global_store_dwordx4 v[144:145], v[202:205], off sc1
	v_pk_mul_f32 v[136:137], v[184:185], v[210:211]
	v_pk_mul_f32 v[140:141], v[180:181], v[208:209]
	v_pk_mul_f32 v[202:203], v[182:183], v[218:219]
	v_pk_mul_f32 v[204:205], v[178:179], v[216:217]
	v_pk_mul_f32 v[140:141], v[140:141], v[190:191] op_sel_hi:[1,0]
	v_pk_mul_f32 v[136:137], v[136:137], v[190:191] op_sel_hi:[1,0]
	v_pk_mul_f32 v[206:207], v[204:205], v[190:191] op_sel_hi:[1,0]
	v_pk_mul_f32 v[204:205], v[202:203], v[190:191] op_sel_hi:[1,0]
	v_cvt_pk_bf16_f32 v202, v136, v137
	v_cvt_pk_bf16_f32 v203, v140, v141
	v_cvt_pk_bf16_f32 v204, v204, v205
	v_cvt_pk_bf16_f32 v205, v206, v207
	v_pk_mul_f32 v[136:137], v[94:95], v[188:189] op_sel_hi:[1,0]
	v_pk_mul_f32 v[140:141], v[96:97], v[188:189] op_sel_hi:[1,0]
	global_store_dwordx4 v[144:145], v[202:205], off offset:64 sc1
	v_pk_mul_f32 v[144:145], v[140:141], v[140:141]
	v_pk_mul_f32 v[216:217], v[84:85], v[188:189] op_sel_hi:[1,0]
	v_pk_mul_f32 v[202:203], v[136:137], v[136:137]
	v_pk_mul_f32 v[218:219], v[82:83], v[188:189] op_sel_hi:[1,0]
	v_pk_mov_b32 v[204:205], v[202:203], v[144:145] op_sel:[1,0]
	v_mov_b32_e32 v203, v145
	v_pk_add_f32 v[144:145], v[204:205], v[202:203]
	v_pk_mul_f32 v[202:203], v[90:91], v[188:189] op_sel_hi:[1,0]
	v_pk_mul_f32 v[204:205], v[92:93], v[188:189] op_sel_hi:[1,0]
	v_pk_mul_f32 v[208:209], v[202:203], v[202:203]
	v_pk_mul_f32 v[206:207], v[204:205], v[204:205]
	v_pk_add_f32 v[144:145], v[144:145], v[144:145] op_sel_hi:[0,1]
	v_pk_mov_b32 v[210:211], v[208:209], v[206:207] op_sel:[1,0]
	v_mov_b32_e32 v209, v207
	v_pk_add_f32 v[206:207], v[210:211], v[208:209]
	v_pk_mul_f32 v[210:211], v[86:87], v[188:189] op_sel_hi:[1,0]
	v_pk_mul_f32 v[208:209], v[88:89], v[188:189] op_sel_hi:[1,0]
	v_mul_f32_e32 v144, v210, v210
	v_pk_fma_f32 v[212:213], v[210:211], v[210:211], v[144:145] op_sel_hi:[1,1,0]
	v_mul_f32_e32 v144, v208, v208
	v_pk_add_f32 v[206:207], v[206:207], v[206:207] op_sel_hi:[0,1]
	v_pk_fma_f32 v[214:215], v[208:209], v[208:209], v[144:145] op_sel_hi:[1,1,0]
	v_mul_f32_e32 v212, v218, v218
	v_mul_f32_e32 v214, v219, v219
	v_mul_f32_e32 v144, v216, v216
	v_mul_f32_e32 v206, v217, v217
	v_pk_add_f32 v[212:213], v[212:213], v[214:215]
	v_pk_add_f32 v[144:145], v[144:145], v[206:207]
	v_pk_mul_f32 v[136:137], v[176:177], v[136:137]
	v_pk_add_f32 v[144:145], v[212:213], v[144:145]
	v_pk_mul_f32 v[140:141], v[174:175], v[140:141]
	v_add_f32_e32 v133, v144, v145
	ds_bpermute_b32 v135, v200, v133
	v_or_b32_e32 v144, 32, v166
	v_ashrrev_i32_e32 v145, 31, v144
	v_pk_mul_f32 v[202:203], v[172:173], v[202:203]
	v_pk_mul_f32 v[204:205], v[168:169], v[204:205]
	s_waitcnt lgkmcnt(0)
	v_add_f32_e32 v133, v133, v135
	ds_bpermute_b32 v135, v201, v133
	v_lshlrev_b64 v[144:145], s1, v[144:145]
	v_lshl_add_u64 v[144:145], v[144:145], 1, v[130:131]
	v_add_f32_e32 v142, v142, v143
	v_fmamk_f32 v142, v142, 0x3a800000, v196
	s_waitcnt lgkmcnt(0)
	v_add_f32_e32 v133, v133, v135
	v_fmamk_f32 v133, v133, 0x3c800000, v196
	v_rsq_f32_e32 v188, v133
	v_rsq_f32_e32 v142, v142
	ds_bpermute_b32 v139, v200, v138
	v_fmamk_f32 v134, v134, 0x3a800000, v196
	v_pk_mul_f32 v[140:141], v[140:141], v[188:189] op_sel_hi:[1,0]
	v_pk_mul_f32 v[136:137], v[136:137], v[188:189] op_sel_hi:[1,0]
	v_pk_mul_f32 v[206:207], v[204:205], v[188:189] op_sel_hi:[1,0]
	v_pk_mul_f32 v[204:205], v[202:203], v[188:189] op_sel_hi:[1,0]
	v_cvt_pk_bf16_f32 v202, v136, v137
	v_cvt_pk_bf16_f32 v203, v140, v141
	v_cvt_pk_bf16_f32 v204, v204, v205
	v_cvt_pk_bf16_f32 v205, v206, v207
	global_store_dwordx4 v[144:145], v[202:205], off sc1
	v_pk_mul_f32 v[136:137], v[184:185], v[210:211]
	v_pk_mul_f32 v[140:141], v[180:181], v[208:209]
	v_pk_mul_f32 v[202:203], v[182:183], v[218:219]
	v_pk_mul_f32 v[204:205], v[178:179], v[216:217]
	v_pk_mul_f32 v[140:141], v[140:141], v[188:189] op_sel_hi:[1,0]
	v_pk_mul_f32 v[136:137], v[136:137], v[188:189] op_sel_hi:[1,0]
	v_pk_mul_f32 v[206:207], v[204:205], v[188:189] op_sel_hi:[1,0]
	v_pk_mul_f32 v[204:205], v[202:203], v[188:189] op_sel_hi:[1,0]
	v_cvt_pk_bf16_f32 v202, v136, v137
	v_cvt_pk_bf16_f32 v203, v140, v141
	v_cvt_pk_bf16_f32 v204, v204, v205
	v_cvt_pk_bf16_f32 v205, v206, v207
	v_pk_mul_f32 v[136:137], v[78:79], v[186:187] op_sel_hi:[1,0]
	v_pk_mul_f32 v[140:141], v[80:81], v[186:187] op_sel_hi:[1,0]
	global_store_dwordx4 v[144:145], v[202:205], off offset:64 sc1
	v_pk_mul_f32 v[144:145], v[140:141], v[140:141]
	v_pk_mul_f32 v[216:217], v[68:69], v[186:187] op_sel_hi:[1,0]
	v_pk_mul_f32 v[202:203], v[136:137], v[136:137]
	v_pk_mul_f32 v[218:219], v[66:67], v[186:187] op_sel_hi:[1,0]
	v_pk_mov_b32 v[204:205], v[202:203], v[144:145] op_sel:[1,0]
	v_mov_b32_e32 v203, v145
	v_pk_add_f32 v[144:145], v[204:205], v[202:203]
	v_pk_mul_f32 v[202:203], v[74:75], v[186:187] op_sel_hi:[1,0]
	v_pk_mul_f32 v[204:205], v[76:77], v[186:187] op_sel_hi:[1,0]
	v_pk_mul_f32 v[208:209], v[202:203], v[202:203]
	v_pk_mul_f32 v[206:207], v[204:205], v[204:205]
	v_pk_add_f32 v[144:145], v[144:145], v[144:145] op_sel_hi:[0,1]
	v_pk_mov_b32 v[210:211], v[208:209], v[206:207] op_sel:[1,0]
	v_mov_b32_e32 v209, v207
	v_pk_add_f32 v[206:207], v[210:211], v[208:209]
	v_pk_mul_f32 v[210:211], v[70:71], v[186:187] op_sel_hi:[1,0]
	v_pk_mul_f32 v[208:209], v[72:73], v[186:187] op_sel_hi:[1,0]
	v_mul_f32_e32 v144, v210, v210
	v_pk_fma_f32 v[212:213], v[210:211], v[210:211], v[144:145] op_sel_hi:[1,1,0]
	v_mul_f32_e32 v144, v208, v208
	v_pk_add_f32 v[206:207], v[206:207], v[206:207] op_sel_hi:[0,1]
	v_pk_fma_f32 v[214:215], v[208:209], v[208:209], v[144:145] op_sel_hi:[1,1,0]
	v_mul_f32_e32 v212, v218, v218
	v_mul_f32_e32 v214, v219, v219
	v_mul_f32_e32 v144, v216, v216
	v_mul_f32_e32 v206, v217, v217
	v_pk_add_f32 v[212:213], v[212:213], v[214:215]
	v_pk_add_f32 v[144:145], v[144:145], v[206:207]
	v_pk_mul_f32 v[136:137], v[176:177], v[136:137]
	v_pk_add_f32 v[144:145], v[212:213], v[144:145]
	v_pk_mul_f32 v[140:141], v[174:175], v[140:141]
	v_add_f32_e32 v133, v144, v145
	ds_bpermute_b32 v135, v200, v133
	v_or_b32_e32 v144, 48, v166
	v_ashrrev_i32_e32 v145, 31, v144
	v_pk_mul_f32 v[202:203], v[172:173], v[202:203]
	v_pk_mul_f32 v[204:205], v[168:169], v[204:205]
	s_waitcnt lgkmcnt(0)
; __device__ __forceinline__ unsigned cvtpk(float lo, float hi) { f32x2 v = {lo, hi}; bf16x2_t b = __builtin_convertvector(v, bf16x2_t); return __builtin_bit_cast(unsigned, b); }
;     __device__ __forceinline__ void operator()(const Acc& acc, const Unit& u, int wr, int wc, int fr, int fq) const {
;     ...
;                 for (int m = 0; m < 4; ++m) {
;                     const int r = u.pm * 256 + ai * 128 + wr * 64 + m * 16 + fr;
;                     const float rs = rsv[ai][m];
;                     f32x4 v[2][2]; float q = 0.f;
; #pragma unroll
;                     for (int bj = 0; bj < 2; ++bj)
; #pragma unroll
;                         for (int n = 0; n < 2; ++n) { v[bj][n] = acc[ai][bj][m][n] * rs; const f32x4 x = v[bj][n]; q += (x[0] * x[0] + x[1] * x[1]) + (x[2] * x[2] + x[3] * x[3]); }
;                     q += __shfl_xor(q, 16); q += __shfl_xor(q, 32);
;                     const float rq = __builtin_amdgcn_rsqf(q * (1.0f / 64.0f) + EPS);
; #pragma unroll
;                     for (int bj = 0; bj < 2; ++bj) {
;                         const f32x4 a = v[bj][0] * gv[bj][0] * rq, b = v[bj][1] * gv[bj][1] * rq;
;                         u32x4 w; w.x = cvtpk(a[0], a[1]); w.y = cvtpk(a[2], a[3]); w.z = cvtpk(b[0], b[1]); w.w = cvtpk(b[2], b[3]);
;                         *(u32x4*)(base + (size_t)r * pitch + col + bj * 32) = w;
;                     }
	v_add_f32_e32 v133, v133, v135
	ds_bpermute_b32 v135, v201, v133
	v_lshlrev_b64 v[144:145], s1, v[144:145]
	v_lshl_add_u64 v[144:145], v[144:145], 1, v[130:131]
	v_pk_mul_f32 v[220:221], v[50:51], v[142:143] op_sel_hi:[1,0]
	v_add_f32_e32 v138, v138, v139
	s_waitcnt lgkmcnt(0)
	v_add_f32_e32 v133, v133, v135
	v_fmamk_f32 v133, v133, 0x3c800000, v196
	v_rsq_f32_e32 v186, v133
	ds_bpermute_b32 v139, v201, v138
	v_rsq_f32_e32 v134, v134
	s_mov_b64 s[88:89], 0
	v_pk_mul_f32 v[140:141], v[140:141], v[186:187] op_sel_hi:[1,0]
	v_pk_mul_f32 v[136:137], v[136:137], v[186:187] op_sel_hi:[1,0]
	v_pk_mul_f32 v[206:207], v[204:205], v[186:187] op_sel_hi:[1,0]
	v_pk_mul_f32 v[204:205], v[202:203], v[186:187] op_sel_hi:[1,0]
	v_cvt_pk_bf16_f32 v202, v136, v137
	v_cvt_pk_bf16_f32 v203, v140, v141
	v_cvt_pk_bf16_f32 v204, v204, v205
	v_cvt_pk_bf16_f32 v205, v206, v207
	global_store_dwordx4 v[144:145], v[202:205], off sc1
	v_pk_mul_f32 v[136:137], v[184:185], v[210:211]
	v_pk_mul_f32 v[140:141], v[180:181], v[208:209]
	v_pk_mul_f32 v[202:203], v[182:183], v[218:219]
	v_pk_mul_f32 v[204:205], v[178:179], v[216:217]
	v_pk_mul_f32 v[140:141], v[140:141], v[186:187] op_sel_hi:[1,0]
	v_pk_mul_f32 v[136:137], v[136:137], v[186:187] op_sel_hi:[1,0]
	v_pk_mul_f32 v[206:207], v[204:205], v[186:187] op_sel_hi:[1,0]
	v_pk_mul_f32 v[204:205], v[202:203], v[186:187] op_sel_hi:[1,0]
	v_cvt_pk_bf16_f32 v202, v136, v137
	v_cvt_pk_bf16_f32 v203, v140, v141
	v_cvt_pk_bf16_f32 v204, v204, v205
	v_cvt_pk_bf16_f32 v205, v206, v207
	global_store_dwordx4 v[144:145], v[202:205], off offset:64 sc1
	v_pk_mul_f32 v[140:141], v[62:63], v[142:143] op_sel_hi:[1,0]
	v_pk_mul_f32 v[144:145], v[64:65], v[142:143] op_sel_hi:[1,0]
	v_pk_mul_f32 v[204:205], v[140:141], v[140:141]
	v_pk_mul_f32 v[202:203], v[144:145], v[144:145]
	v_pk_mul_f32 v[218:219], v[52:53], v[142:143] op_sel_hi:[1,0]
	v_pk_mov_b32 v[206:207], v[204:205], v[202:203] op_sel:[1,0]
	v_mov_b32_e32 v205, v203
	v_pk_add_f32 v[202:203], v[206:207], v[204:205]
	v_pk_mul_f32 v[204:205], v[58:59], v[142:143] op_sel_hi:[1,0]
	v_pk_mul_f32 v[206:207], v[60:61], v[142:143] op_sel_hi:[1,0]
	v_pk_mul_f32 v[210:211], v[204:205], v[204:205]
	v_pk_mul_f32 v[208:209], v[206:207], v[206:207]
	v_pk_add_f32 v[202:203], v[202:203], v[202:203] op_sel_hi:[0,1]
	v_pk_mov_b32 v[212:213], v[210:211], v[208:209] op_sel:[1,0]
	v_mov_b32_e32 v211, v209
	v_pk_add_f32 v[208:209], v[212:213], v[210:211]
	v_pk_mul_f32 v[212:213], v[54:55], v[142:143] op_sel_hi:[1,0]
	v_pk_mul_f32 v[210:211], v[56:57], v[142:143] op_sel_hi:[1,0]
	v_mul_f32_e32 v186, v212, v212
	v_pk_fma_f32 v[214:215], v[212:213], v[212:213], v[186:187] op_sel_hi:[1,1,0]
	v_mul_f32_e32 v186, v210, v210
	v_pk_add_f32 v[208:209], v[208:209], v[208:209] op_sel_hi:[0,1]
	v_pk_fma_f32 v[216:217], v[210:211], v[210:211], v[186:187] op_sel_hi:[1,1,0]
	v_mul_f32_e32 v214, v220, v220
	v_mul_f32_e32 v216, v221, v221
	v_mul_f32_e32 v202, v218, v218
	v_mul_f32_e32 v208, v219, v219
	v_pk_add_f32 v[142:143], v[214:215], v[216:217]
	v_pk_add_f32 v[202:203], v[202:203], v[208:209]
	v_add_u32_e32 v136, 0x80, v166
	v_pk_add_f32 v[142:143], v[142:143], v[202:203]
	s_waitcnt lgkmcnt(0)
	v_add_f32_e32 v138, v138, v139
	v_add_f32_e32 v133, v142, v143
	ds_bpermute_b32 v135, v200, v133
	v_ashrrev_i32_e32 v137, 31, v136
	v_pk_mul_f32 v[140:141], v[176:177], v[140:141]
	v_pk_mul_f32 v[142:143], v[174:175], v[144:145]
	v_pk_mul_f32 v[144:145], v[172:173], v[204:205]
	s_waitcnt lgkmcnt(0)
	v_add_f32_e32 v133, v133, v135
	ds_bpermute_b32 v135, v201, v133
	v_pk_mul_f32 v[202:203], v[168:169], v[206:207]
	v_fmamk_f32 v138, v138, 0x3a800000, v196
	v_lshlrev_b64 v[136:137], s1, v[136:137]
	v_rsq_f32_e32 v138, v138
	s_waitcnt lgkmcnt(0)
	v_add_f32_e32 v133, v133, v135
	v_fmamk_f32 v133, v133, 0x3c800000, v196
	v_rsq_f32_e32 v186, v133
	v_lshl_add_u64 v[136:137], v[136:137], 1, v[130:131]
	v_pk_mul_f32 v[214:215], v[36:37], v[138:139] op_sel_hi:[1,0]
	v_pk_mul_f32 v[216:217], v[34:35], v[138:139] op_sel_hi:[1,0]
	v_pk_mul_f32 v[142:143], v[142:143], v[186:187] op_sel_hi:[1,0]
	v_pk_mul_f32 v[140:141], v[140:141], v[186:187] op_sel_hi:[1,0]
	v_pk_mul_f32 v[202:203], v[202:203], v[186:187] op_sel_hi:[1,0]
	v_pk_mul_f32 v[144:145], v[144:145], v[186:187] op_sel_hi:[1,0]
	v_cvt_pk_bf16_f32 v140, v140, v141
	v_cvt_pk_bf16_f32 v141, v142, v143
	v_cvt_pk_bf16_f32 v142, v144, v145
	v_cvt_pk_bf16_f32 v143, v202, v203
	global_store_dwordx4 v[136:137], v[140:143], off sc1
	v_pk_mul_f32 v[144:145], v[182:183], v[220:221]
	v_pk_mul_f32 v[202:203], v[178:179], v[218:219]
	v_pk_mul_f32 v[140:141], v[184:185], v[212:213]
	v_pk_mul_f32 v[142:143], v[180:181], v[210:211]
	v_pk_mul_f32 v[140:141], v[140:141], v[186:187] op_sel_hi:[1,0]
	v_pk_mul_f32 v[142:143], v[142:143], v[186:187] op_sel_hi:[1,0]
	v_pk_mul_f32 v[202:203], v[202:203], v[186:187] op_sel_hi:[1,0]
	v_pk_mul_f32 v[144:145], v[144:145], v[186:187] op_sel_hi:[1,0]
	v_cvt_pk_bf16_f32 v140, v140, v141
	v_cvt_pk_bf16_f32 v141, v142, v143
	v_cvt_pk_bf16_f32 v142, v144, v145
	v_cvt_pk_bf16_f32 v143, v202, v203
	global_store_dwordx4 v[136:137], v[140:143], off offset:64 sc1
	v_pk_mul_f32 v[136:137], v[46:47], v[138:139] op_sel_hi:[1,0]
	s_nop 0
	v_pk_mul_f32 v[140:141], v[48:49], v[138:139] op_sel_hi:[1,0]
	v_pk_mul_f32 v[144:145], v[136:137], v[136:137]
	v_pk_mul_f32 v[142:143], v[140:141], v[140:141]
	v_pk_mul_f32 v[136:137], v[176:177], v[136:137]
	v_pk_mov_b32 v[202:203], v[144:145], v[142:143] op_sel:[1,0]
	v_mov_b32_e32 v145, v143
	v_pk_add_f32 v[142:143], v[202:203], v[144:145]
	v_pk_mul_f32 v[144:145], v[42:43], v[138:139] op_sel_hi:[1,0]
	v_pk_mul_f32 v[202:203], v[44:45], v[138:139] op_sel_hi:[1,0]
	v_pk_mul_f32 v[206:207], v[144:145], v[144:145]
	v_pk_mul_f32 v[204:205], v[202:203], v[202:203]
	v_pk_add_f32 v[142:143], v[142:143], v[142:143] op_sel_hi:[0,1]
	v_pk_mov_b32 v[208:209], v[206:207], v[204:205] op_sel:[1,0]
	v_mov_b32_e32 v207, v205
	v_pk_add_f32 v[204:205], v[208:209], v[206:207]
	v_pk_mul_f32 v[208:209], v[38:39], v[138:139] op_sel_hi:[1,0]
	v_pk_mul_f32 v[206:207], v[40:41], v[138:139] op_sel_hi:[1,0]
	v_mul_f32_e32 v142, v208, v208
	v_pk_fma_f32 v[210:211], v[208:209], v[208:209], v[142:143] op_sel_hi:[1,1,0]
	v_mul_f32_e32 v142, v206, v206
	v_pk_add_f32 v[204:205], v[204:205], v[204:205] op_sel_hi:[0,1]
	v_pk_fma_f32 v[212:213], v[206:207], v[206:207], v[142:143] op_sel_hi:[1,1,0]
	v_mul_f32_e32 v210, v216, v216
	v_mul_f32_e32 v212, v217, v217
	v_mul_f32_e32 v142, v214, v214
	v_mul_f32_e32 v204, v215, v215
	v_pk_add_f32 v[138:139], v[210:211], v[212:213]
	v_pk_add_f32 v[142:143], v[142:143], v[204:205]
	s_nop 0
	v_pk_add_f32 v[138:139], v[138:139], v[142:143]
	s_nop 0
	v_add_f32_e32 v133, v138, v139
	ds_bpermute_b32 v135, v200, v133
	v_add_u32_e32 v138, 0x90, v166
	v_ashrrev_i32_e32 v139, 31, v138
	v_lshlrev_b64 v[138:139], s1, v[138:139]
	v_lshl_add_u64 v[204:205], v[138:139], 1, v[130:131]
	s_waitcnt lgkmcnt(0)
; __device__ __forceinline__ unsigned cvtpk(float lo, float hi) { f32x2 v = {lo, hi}; bf16x2_t b = __builtin_convertvector(v, bf16x2_t); return __builtin_bit_cast(unsigned, b); }
;     __device__ __forceinline__ void operator()(const Acc& acc, const Unit& u, int wr, int wc, int fr, int fq) const {
;     ...
;                 for (int m = 0; m < 4; ++m) {
;                     const int r = u.pm * 256 + ai * 128 + wr * 64 + m * 16 + fr;
;                     const float rs = rsv[ai][m];
;                     f32x4 v[2][2]; float q = 0.f;
; #pragma unroll
;                     for (int bj = 0; bj < 2; ++bj)
; #pragma unroll
;                         for (int n = 0; n < 2; ++n) { v[bj][n] = acc[ai][bj][m][n] * rs; const f32x4 x = v[bj][n]; q += (x[0] * x[0] + x[1] * x[1]) + (x[2] * x[2] + x[3] * x[3]); }
;                     q += __shfl_xor(q, 16); q += __shfl_xor(q, 32);
;                     const float rq = __builtin_amdgcn_rsqf(q * (1.0f / 64.0f) + EPS);
; #pragma unroll
;                     for (int bj = 0; bj < 2; ++bj) {
;                         const f32x4 a = v[bj][0] * gv[bj][0] * rq, b = v[bj][1] * gv[bj][1] * rq;
;                         u32x4 w; w.x = cvtpk(a[0], a[1]); w.y = cvtpk(a[2], a[3]); w.z = cvtpk(b[0], b[1]); w.w = cvtpk(b[2], b[3]);
;                         *(u32x4*)(base + (size_t)r * pitch + col + bj * 32) = w;
;                     }
	v_add_f32_e32 v133, v133, v135
	ds_bpermute_b32 v135, v201, v133
	v_pk_mul_f32 v[138:139], v[174:175], v[140:141]
	v_pk_mul_f32 v[140:141], v[172:173], v[144:145]
	v_pk_mul_f32 v[144:145], v[168:169], v[202:203]
	s_waitcnt lgkmcnt(0)
	v_add_f32_e32 v133, v133, v135
	v_fmamk_f32 v133, v133, 0x3c800000, v196
	v_rsq_f32_e32 v142, v133
	v_pk_mul_f32 v[212:213], v[20:21], v[134:135] op_sel_hi:[1,0]
	v_pk_mul_f32 v[138:139], v[138:139], v[142:143] op_sel_hi:[1,0]
	v_pk_mul_f32 v[136:137], v[136:137], v[142:143] op_sel_hi:[1,0]
	v_pk_mul_f32 v[144:145], v[144:145], v[142:143] op_sel_hi:[1,0]
	v_pk_mul_f32 v[140:141], v[140:141], v[142:143] op_sel_hi:[1,0]
	v_cvt_pk_bf16_f32 v136, v136, v137
	v_cvt_pk_bf16_f32 v137, v138, v139
	v_cvt_pk_bf16_f32 v138, v140, v141
	v_cvt_pk_bf16_f32 v139, v144, v145
	global_store_dwordx4 v[204:205], v[136:139], off sc1
	v_pk_mul_f32 v[140:141], v[182:183], v[216:217]
	v_pk_mul_f32 v[144:145], v[178:179], v[214:215]
	v_pk_mul_f32 v[136:137], v[184:185], v[208:209]
	v_pk_mul_f32 v[138:139], v[180:181], v[206:207]
	v_pk_mul_f32 v[136:137], v[136:137], v[142:143] op_sel_hi:[1,0]
	v_pk_mul_f32 v[138:139], v[138:139], v[142:143] op_sel_hi:[1,0]
	v_pk_mul_f32 v[144:145], v[144:145], v[142:143] op_sel_hi:[1,0]
	v_pk_mul_f32 v[140:141], v[140:141], v[142:143] op_sel_hi:[1,0]
	v_cvt_pk_bf16_f32 v136, v136, v137
	v_cvt_pk_bf16_f32 v137, v138, v139
	v_cvt_pk_bf16_f32 v138, v140, v141
	v_cvt_pk_bf16_f32 v139, v144, v145
	global_store_dwordx4 v[204:205], v[136:139], off offset:64 sc1
	v_pk_mul_f32 v[214:215], v[18:19], v[134:135] op_sel_hi:[1,0]
	s_nop 0
	v_pk_mul_f32 v[136:137], v[30:31], v[134:135] op_sel_hi:[1,0]
	v_pk_mul_f32 v[138:139], v[32:33], v[134:135] op_sel_hi:[1,0]
	v_pk_mul_f32 v[142:143], v[136:137], v[136:137]
	v_pk_mul_f32 v[140:141], v[138:139], v[138:139]
	s_nop 0
	v_pk_mov_b32 v[144:145], v[142:143], v[140:141] op_sel:[1,0]
	v_mov_b32_e32 v143, v141
	v_pk_add_f32 v[140:141], v[144:145], v[142:143]
	v_pk_mul_f32 v[142:143], v[26:27], v[134:135] op_sel_hi:[1,0]
	v_pk_mul_f32 v[144:145], v[28:29], v[134:135] op_sel_hi:[1,0]
	v_pk_mul_f32 v[204:205], v[142:143], v[142:143]
	v_pk_mul_f32 v[202:203], v[144:145], v[144:145]
	v_pk_add_f32 v[140:141], v[140:141], v[140:141] op_sel_hi:[0,1]
	v_pk_mov_b32 v[206:207], v[204:205], v[202:203] op_sel:[1,0]
	v_mov_b32_e32 v205, v203
	v_pk_add_f32 v[202:203], v[206:207], v[204:205]
	v_pk_mul_f32 v[206:207], v[22:23], v[134:135] op_sel_hi:[1,0]
	v_pk_mul_f32 v[204:205], v[24:25], v[134:135] op_sel_hi:[1,0]
	v_mul_f32_e32 v140, v206, v206
	v_pk_fma_f32 v[208:209], v[206:207], v[206:207], v[140:141] op_sel_hi:[1,1,0]
	v_mul_f32_e32 v140, v204, v204
	v_pk_add_f32 v[202:203], v[202:203], v[202:203] op_sel_hi:[0,1]
	v_pk_fma_f32 v[210:211], v[204:205], v[204:205], v[140:141] op_sel_hi:[1,1,0]
	v_mul_f32_e32 v208, v214, v214
	v_mul_f32_e32 v210, v215, v215
	v_mul_f32_e32 v140, v212, v212
	v_mul_f32_e32 v202, v213, v213
	v_pk_add_f32 v[134:135], v[208:209], v[210:211]
	v_pk_add_f32 v[140:141], v[140:141], v[202:203]
	s_nop 0
	v_pk_add_f32 v[134:135], v[134:135], v[140:141]
	s_nop 0
	v_add_f32_e32 v133, v134, v135
	ds_bpermute_b32 v135, v200, v133
	v_add_u32_e32 v134, 0xa0, v166
	s_waitcnt lgkmcnt(0)
	v_add_f32_e32 v133, v133, v135
	ds_bpermute_b32 v135, v201, v133
	s_waitcnt lgkmcnt(0)
; __device__ __forceinline__ unsigned cvtpk(float lo, float hi) { f32x2 v = {lo, hi}; bf16x2_t b = __builtin_convertvector(v, bf16x2_t); return __builtin_bit_cast(unsigned, b); }
;     __device__ __forceinline__ void operator()(const Acc& acc, const Unit& u, int wr, int wc, int fr, int fq) const {
;     ...
;                 for (int m = 0; m < 4; ++m) {
;                     const int r = u.pm * 256 + ai * 128 + wr * 64 + m * 16 + fr;
;                     const float rs = rsv[ai][m];
;                     f32x4 v[2][2]; float q = 0.f;
; #pragma unroll
;                     for (int bj = 0; bj < 2; ++bj)
; #pragma unroll
;                         for (int n = 0; n < 2; ++n) { v[bj][n] = acc[ai][bj][m][n] * rs; const f32x4 x = v[bj][n]; q += (x[0] * x[0] + x[1] * x[1]) + (x[2] * x[2] + x[3] * x[3]); }
;                     q += __shfl_xor(q, 16); q += __shfl_xor(q, 32);
;                     const float rq = __builtin_amdgcn_rsqf(q * (1.0f / 64.0f) + EPS);
; #pragma unroll
;                     for (int bj = 0; bj < 2; ++bj) {
;                         const f32x4 a = v[bj][0] * gv[bj][0] * rq, b = v[bj][1] * gv[bj][1] * rq;
;                         u32x4 w; w.x = cvtpk(a[0], a[1]); w.y = cvtpk(a[2], a[3]); w.z = cvtpk(b[0], b[1]); w.w = cvtpk(b[2], b[3]);
;                         *(u32x4*)(base + (size_t)r * pitch + col + bj * 32) = w;
;                     }
	v_add_f32_e32 v133, v133, v135
	v_fmamk_f32 v133, v133, 0x3c800000, v196
	v_rsq_f32_e32 v140, v133
	v_ashrrev_i32_e32 v135, 31, v134
	v_lshlrev_b64 v[134:135], s1, v[134:135]
	v_lshl_add_u64 v[202:203], v[134:135], 1, v[130:131]
	v_pk_mul_f32 v[134:135], v[176:177], v[136:137]
	v_pk_mul_f32 v[136:137], v[174:175], v[138:139]
	v_pk_mul_f32 v[138:139], v[172:173], v[142:143]
	v_pk_mul_f32 v[142:143], v[168:169], v[144:145]
	v_pk_mul_f32 v[136:137], v[136:137], v[140:141] op_sel_hi:[1,0]
	v_pk_mul_f32 v[134:135], v[134:135], v[140:141] op_sel_hi:[1,0]
	v_pk_mul_f32 v[142:143], v[142:143], v[140:141] op_sel_hi:[1,0]
	v_pk_mul_f32 v[138:139], v[138:139], v[140:141] op_sel_hi:[1,0]
	v_cvt_pk_bf16_f32 v134, v134, v135
	v_cvt_pk_bf16_f32 v135, v136, v137
	v_cvt_pk_bf16_f32 v136, v138, v139
	v_cvt_pk_bf16_f32 v137, v142, v143
	global_store_dwordx4 v[202:203], v[134:137], off sc1
	v_pk_mul_f32 v[138:139], v[182:183], v[214:215]
	v_pk_mul_f32 v[142:143], v[178:179], v[212:213]
	v_pk_mul_f32 v[134:135], v[184:185], v[206:207]
	v_pk_mul_f32 v[136:137], v[180:181], v[204:205]
	v_pk_mul_f32 v[134:135], v[134:135], v[140:141] op_sel_hi:[1,0]
	v_pk_mul_f32 v[136:137], v[136:137], v[140:141] op_sel_hi:[1,0]
	v_pk_mul_f32 v[142:143], v[142:143], v[140:141] op_sel_hi:[1,0]
	v_pk_mul_f32 v[138:139], v[138:139], v[140:141] op_sel_hi:[1,0]
	v_cvt_pk_bf16_f32 v134, v134, v135
	v_cvt_pk_bf16_f32 v135, v136, v137
	v_cvt_pk_bf16_f32 v136, v138, v139
	v_cvt_pk_bf16_f32 v137, v142, v143
	global_store_dwordx4 v[202:203], v[134:137], off offset:64 sc1
	v_pk_mul_f32 v[210:211], v[4:5], v[132:133] op_sel_hi:[1,0]
	v_pk_mul_f32 v[212:213], v[2:3], v[132:133] op_sel_hi:[1,0]
	v_pk_mul_f32 v[134:135], v[14:15], v[132:133] op_sel_hi:[1,0]
	v_pk_mul_f32 v[136:137], v[16:17], v[132:133] op_sel_hi:[1,0]
	v_pk_mul_f32 v[140:141], v[134:135], v[134:135]
	v_pk_mul_f32 v[138:139], v[136:137], v[136:137]
	s_nop 0
	v_pk_mov_b32 v[142:143], v[140:141], v[138:139] op_sel:[1,0]
	v_mov_b32_e32 v141, v139
	v_pk_add_f32 v[138:139], v[142:143], v[140:141]
	v_pk_mul_f32 v[140:141], v[10:11], v[132:133] op_sel_hi:[1,0]
	v_pk_mul_f32 v[142:143], v[12:13], v[132:133] op_sel_hi:[1,0]
	v_pk_mul_f32 v[202:203], v[140:141], v[140:141]
	v_pk_mul_f32 v[144:145], v[142:143], v[142:143]
	v_pk_add_f32 v[138:139], v[138:139], v[138:139] op_sel_hi:[0,1]
	v_pk_mov_b32 v[204:205], v[202:203], v[144:145] op_sel:[1,0]
	v_mov_b32_e32 v203, v145
	v_pk_add_f32 v[144:145], v[204:205], v[202:203]
	v_pk_mul_f32 v[204:205], v[6:7], v[132:133] op_sel_hi:[1,0]
	v_pk_mul_f32 v[202:203], v[8:9], v[132:133] op_sel_hi:[1,0]
	v_mul_f32_e32 v138, v204, v204
	v_pk_fma_f32 v[206:207], v[204:205], v[204:205], v[138:139] op_sel_hi:[1,1,0]
	v_mul_f32_e32 v138, v202, v202
	v_pk_add_f32 v[144:145], v[144:145], v[144:145] op_sel_hi:[0,1]
	v_pk_fma_f32 v[208:209], v[202:203], v[202:203], v[138:139] op_sel_hi:[1,1,0]
	v_mul_f32_e32 v206, v212, v212
	v_mul_f32_e32 v208, v213, v213
	v_mul_f32_e32 v138, v210, v210
	v_mul_f32_e32 v144, v211, v211
	v_pk_add_f32 v[132:133], v[206:207], v[208:209]
	v_pk_add_f32 v[138:139], v[138:139], v[144:145]
	s_nop 0
	v_pk_add_f32 v[132:133], v[132:133], v[138:139]
	s_nop 0
	v_add_f32_e32 v133, v132, v133
	ds_bpermute_b32 v138, v200, v133
	v_add_u32_e32 v132, 0xb0, v166
	s_waitcnt lgkmcnt(0)
	v_add_f32_e32 v133, v133, v138
	ds_bpermute_b32 v138, v201, v133
	s_waitcnt lgkmcnt(0)
	v_add_f32_e32 v133, v133, v138
	v_fmamk_f32 v133, v133, 0x3c800000, v196
	v_rsq_f32_e32 v138, v133
	v_ashrrev_i32_e32 v133, 31, v132
	v_lshlrev_b64 v[132:133], s1, v[132:133]
	v_lshl_add_u64 v[144:145], v[132:133], 1, v[130:131]
	v_pk_mul_f32 v[130:131], v[176:177], v[134:135]
	v_pk_mul_f32 v[132:133], v[174:175], v[136:137]
	v_pk_mul_f32 v[134:135], v[172:173], v[140:141]
	v_pk_mul_f32 v[136:137], v[168:169], v[142:143]
	v_pk_mul_f32 v[132:133], v[132:133], v[138:139] op_sel_hi:[1,0]
	v_pk_mul_f32 v[130:131], v[130:131], v[138:139] op_sel_hi:[1,0]
	v_pk_mul_f32 v[136:137], v[136:137], v[138:139] op_sel_hi:[1,0]
	v_pk_mul_f32 v[134:135], v[134:135], v[138:139] op_sel_hi:[1,0]
	v_cvt_pk_bf16_f32 v130, v130, v131
	v_cvt_pk_bf16_f32 v131, v132, v133
	v_cvt_pk_bf16_f32 v132, v134, v135
	v_cvt_pk_bf16_f32 v133, v136, v137
	global_store_dwordx4 v[144:145], v[130:133], off sc1
	v_pk_mul_f32 v[134:135], v[182:183], v[212:213]
	v_pk_mul_f32 v[136:137], v[178:179], v[210:211]
	v_pk_mul_f32 v[130:131], v[184:185], v[204:205]
	v_pk_mul_f32 v[132:133], v[180:181], v[202:203]
	v_pk_mul_f32 v[130:131], v[130:131], v[138:139] op_sel_hi:[1,0]
	v_pk_mul_f32 v[132:133], v[132:133], v[138:139] op_sel_hi:[1,0]
	v_pk_mul_f32 v[136:137], v[136:137], v[138:139] op_sel_hi:[1,0]
	v_pk_mul_f32 v[134:135], v[134:135], v[138:139] op_sel_hi:[1,0]
	v_cvt_pk_bf16_f32 v130, v130, v131
	v_cvt_pk_bf16_f32 v131, v132, v133
	v_cvt_pk_bf16_f32 v132, v134, v135
	v_cvt_pk_bf16_f32 v133, v136, v137
	global_store_dwordx4 v[144:145], v[130:133], off offset:64 sc1

; __device__ __forceinline__ f32x4 sig_from_negl2(f32x4 t) { return rcp_4(exp2_4(t) + 1.0f); }
; __device__ __forceinline__ u32x2 pack4(f32x4 v) { u32x2 w; w.x = cvtpk(v[0], v[1]); w.y = cvtpk(v[2], v[3]); return w; }
;     __device__ __forceinline__ void operator()(const Acc& acc, const Unit& u, int wr, int wc, int fr, int fq) const {
;     ...
;                     for (int bj = 0; bj < 2; ++bj) {
;                         u32x4 w;
; #pragma unroll
;                         for (int n = 0; n < 2; ++n) {
;                             f32x4 v = acc[ai][bj][m][n] * rs;
;                             if (act) {
;                                 const f32x4 x2 = v * v;
;                                 const f32x4 t = v * (x2 * (-2.0f * 0.7978845608028654f * LOG2E * 0.044715f) + (-2.0f * 0.7978845608028654f * LOG2E));
;                                 v = v * sig_from_negl2(t);
;                             }
;                             if (t == 2 || t == 3) { const f32x4 v2 = v * v; q += (v2[0] + v2[1]) + (v2[2] + v2[3]); }
;                             const u32x2 pk = pack4(v);
;                             if (n == 0) { w.x = pk.x; w.y = pk.y; } else { w.z = pk.x; w.w = pk.y; }
;                         }
;                         *(u32x4*)(base + (size_t)r * pitch + col + bj * 128) = w;
.LBB0_339:
	v_add_u32_e32 v122, s1, v189
	v_ashrrev_i32_e32 v123, 31, v122
	v_lshl_add_u64 v[122:123], v[122:123], 1, s[90:91]
	v_mad_i64_i32 v[134:135], s[76:77], s88, v166, 0
	v_cvt_pk_bf16_f32 v178, v126, v127
	v_cvt_pk_bf16_f32 v179, v128, v129
	v_lshl_add_u64 v[134:135], v[134:135], 1, v[122:123]
	v_cvt_pk_bf16_f32 v180, v132, v133
	v_cvt_pk_bf16_f32 v181, v124, v125
	v_pk_mul_f32 v[120:121], v[120:121], v[136:137]
	s_and_b64 vcc, exec, s[6:7]
	v_pk_mul_f32 v[118:119], v[118:119], v[130:131]
	global_store_dwordx4 v[134:135], v[178:181], off sc1
	s_cbranch_vccnz .LBB0_341
	v_pk_mul_f32 v[136:137], v[120:121], v[120:121]
	v_pk_mul_f32 v[178:179], v[118:119], v[118:119]
	v_mov_b64_e32 v[180:181], s[66:67]
	v_pk_fma_f32 v[136:137], v[136:137], s[68:69], v[180:181] op_sel_hi:[1,0,0]
	v_pk_fma_f32 v[178:179], v[178:179], s[68:69], v[180:181] op_sel_hi:[1,0,0]
	v_pk_mul_f32 v[136:137], v[120:121], v[136:137]
	v_pk_mul_f32 v[178:179], v[118:119], v[178:179]
	v_exp_f32_e32 v136, v136
	v_exp_f32_e32 v178, v178
	v_exp_f32_e32 v137, v137
	v_exp_f32_e32 v179, v179
	v_pk_add_f32 v[136:137], v[136:137], 1.0 op_sel_hi:[1,0]
	v_pk_add_f32 v[178:179], v[178:179], 1.0 op_sel_hi:[1,0]
	v_rcp_f32_e32 v136, v136
	v_rcp_f32_e32 v178, v178
	v_rcp_f32_e32 v137, v137
	v_rcp_f32_e32 v179, v179
	v_pk_mul_f32 v[120:121], v[120:121], v[136:137]
	v_pk_mul_f32 v[118:119], v[118:119], v[178:179]

; __device__ __forceinline__ u32x2 pack4(f32x4 v) { u32x2 w; w.x = cvtpk(v[0], v[1]); w.y = cvtpk(v[2], v[3]); return w; }
;     __device__ __forceinline__ void operator()(const Acc& acc, const Unit& u, int wr, int wc, int fr, int fq) const {
;     ...
;                             if (t == 2 || t == 3) { const f32x4 v2 = v * v; q += (v2[0] + v2[1]) + (v2[2] + v2[3]); }
;                             const u32x2 pk = pack4(v);
;                             if (n == 0) { w.x = pk.x; w.y = pk.y; } else { w.z = pk.x; w.w = pk.y; }
;                         }
;                         *(u32x4*)(base + (size_t)r * pitch + col + bj * 128) = w;
;                     }
;                     if (t == 2 || t == 3) { q += __shfl_xor(q, 16); q += __shfl_xor(q, 32); if (fq == 0) stv[(size_t)r * 16 + (t - 2) * 4 + wc] = q; }
.LBB0_343:
	s_and_b32 s1, s8, -2
	s_cmp_eq_u32 s1, 2
	s_cselect_b64 s[90:91], -1, 0
	s_lshl_b32 s46, s8, 2
	v_ashrrev_i32_e32 v167, 31, v166
	v_cvt_pk_bf16_f32 v178, v118, v119
	v_cvt_pk_bf16_f32 v179, v120, v121
	s_cmp_lg_u32 s1, 2
	v_cvt_pk_bf16_f32 v180, v114, v115
	v_cvt_pk_bf16_f32 v181, v116, v117
	global_store_dwordx4 v[134:135], v[178:181], off offset:256 sc1
	s_cbranch_scc1 .LBB0_347
	v_pk_mul_f32 v[128:129], v[128:129], v[128:129]
	v_pk_mul_f32 v[126:127], v[126:127], v[126:127]
	v_pk_mul_f32 v[124:125], v[124:125], v[124:125]
	v_add_f32_e32 v126, v126, v127
	v_add_f32_e32 v127, v128, v129
	v_add_f32_e32 v128, v126, v127
	v_pk_mul_f32 v[126:127], v[132:133], v[132:133]
	v_add_f32_e32 v124, v124, v125
	v_add_f32_e32 v126, v126, v127
	v_pk_mul_f32 v[120:121], v[120:121], v[120:121]
	v_pk_mul_f32 v[118:119], v[118:119], v[118:119]
	v_add_f32_e32 v124, v126, v124
	v_add_f32_e32 v118, v118, v119
	v_add_f32_e32 v119, v120, v121
	v_pk_mul_f32 v[116:117], v[116:117], v[116:117]
	v_pk_mul_f32 v[114:115], v[114:115], v[114:115]
	v_add_f32_e32 v124, v128, v124
	v_add_f32_e32 v118, v118, v119
	v_add_f32_e32 v114, v114, v115
	v_add_f32_e32 v115, v116, v117
	v_add_f32_e32 v118, v124, v118
	v_add_f32_e32 v114, v114, v115
	v_add_f32_e32 v114, v118, v114
	ds_bpermute_b32 v115, v138, v114
	s_waitcnt lgkmcnt(0)
	v_add_f32_e32 v114, v114, v115
	ds_bpermute_b32 v115, v139, v114
	s_and_saveexec_b64 s[8:9], s[2:3]
	s_cbranch_execz .LBB0_346
	v_lshlrev_b64 v[116:117], 6, v[166:167]
	v_lshl_add_u64 v[116:117], s[38:39], 0, v[116:117]
	v_lshl_add_u64 v[116:117], s[46:47], 2, v[116:117]
	s_lshl_b32 s76, s78, 2
	s_mov_b32 s77, s47
	v_lshl_add_u64 v[116:117], v[116:117], 0, s[76:77]
	s_waitcnt lgkmcnt(0)
	v_add_f32_e32 v114, v114, v115
	global_store_dword v[116:117], v114, off offset:-32 sc1

; __device__ __forceinline__ f32x4 sig_from_negl2(f32x4 t) { return rcp_4(exp2_4(t) + 1.0f); }
; __device__ __forceinline__ u32x2 pack4(f32x4 v) { u32x2 w; w.x = cvtpk(v[0], v[1]); w.y = cvtpk(v[2], v[3]); return w; }
;     __device__ __forceinline__ void operator()(const Acc& acc, const Unit& u, int wr, int wc, int fr, int fq) const {
;     ...
;                     for (int bj = 0; bj < 2; ++bj) {
;                         u32x4 w;
; #pragma unroll
;                         for (int n = 0; n < 2; ++n) {
;                             f32x4 v = acc[ai][bj][m][n] * rs;
;                             if (act) {
;                                 const f32x4 x2 = v * v;
;                                 const f32x4 t = v * (x2 * (-2.0f * 0.7978845608028654f * LOG2E * 0.044715f) + (-2.0f * 0.7978845608028654f * LOG2E));
;                                 v = v * sig_from_negl2(t);
;                             }
;                             if (t == 2 || t == 3) { const f32x4 v2 = v * v; q += (v2[0] + v2[1]) + (v2[2] + v2[3]); }
;                             const u32x2 pk = pack4(v);
;                             if (n == 0) { w.x = pk.x; w.y = pk.y; } else { w.z = pk.x; w.w = pk.y; }
;                         }
;                         *(u32x4*)(base + (size_t)r * pitch + col + bj * 128) = w;
.LBB0_351:
	v_or_b32_e32 v116, 16, v166
	v_mad_i64_i32 v[118:119], s[8:9], s88, v116, 0
	v_cvt_pk_bf16_f32 v124, v110, v111
	v_cvt_pk_bf16_f32 v125, v112, v113
	v_lshl_add_u64 v[118:119], v[118:119], 1, v[122:123]
	v_cvt_pk_bf16_f32 v126, v106, v107
	v_cvt_pk_bf16_f32 v127, v108, v109
	v_pk_mul_f32 v[104:105], v[104:105], v[120:121]
	s_and_b64 vcc, exec, s[6:7]
	v_pk_mul_f32 v[102:103], v[102:103], v[114:115]
	global_store_dwordx4 v[118:119], v[124:127], off sc1
	s_cbranch_vccnz .LBB0_353
	v_pk_mul_f32 v[120:121], v[104:105], v[104:105]
	v_pk_mul_f32 v[124:125], v[102:103], v[102:103]
	v_mov_b64_e32 v[126:127], s[66:67]
	v_pk_fma_f32 v[120:121], v[120:121], s[68:69], v[126:127] op_sel_hi:[1,0,0]
	v_pk_fma_f32 v[124:125], v[124:125], s[68:69], v[126:127] op_sel_hi:[1,0,0]
	v_pk_mul_f32 v[120:121], v[104:105], v[120:121]
	v_pk_mul_f32 v[124:125], v[102:103], v[124:125]
	v_exp_f32_e32 v120, v120
	v_exp_f32_e32 v124, v124
	v_exp_f32_e32 v121, v121
	v_exp_f32_e32 v125, v125
	v_pk_add_f32 v[120:121], v[120:121], 1.0 op_sel_hi:[1,0]
	v_pk_add_f32 v[124:125], v[124:125], 1.0 op_sel_hi:[1,0]
	v_rcp_f32_e32 v120, v120
	v_rcp_f32_e32 v124, v124
	v_rcp_f32_e32 v121, v121
	v_rcp_f32_e32 v125, v125
	v_pk_mul_f32 v[104:105], v[104:105], v[120:121]
	v_pk_mul_f32 v[102:103], v[102:103], v[124:125]

; __device__ __forceinline__ u32x2 pack4(f32x4 v) { u32x2 w; w.x = cvtpk(v[0], v[1]); w.y = cvtpk(v[2], v[3]); return w; }
;     __device__ __forceinline__ void operator()(const Acc& acc, const Unit& u, int wr, int wc, int fr, int fq) const {
;     ...
;                             if (t == 2 || t == 3) { const f32x4 v2 = v * v; q += (v2[0] + v2[1]) + (v2[2] + v2[3]); }
;                             const u32x2 pk = pack4(v);
;                             if (n == 0) { w.x = pk.x; w.y = pk.y; } else { w.z = pk.x; w.w = pk.y; }
;                         }
;                         *(u32x4*)(base + (size_t)r * pitch + col + bj * 128) = w;
;                     }
;                     if (t == 2 || t == 3) { q += __shfl_xor(q, 16); q += __shfl_xor(q, 32); if (fq == 0) stv[(size_t)r * 16 + (t - 2) * 4 + wc] = q; }
.LBB0_355:
	v_cndmask_b32_e64 v114, 0, 1, s[90:91]
	v_cvt_pk_bf16_f32 v124, v102, v103
	v_cvt_pk_bf16_f32 v125, v104, v105
	v_cvt_pk_bf16_f32 v126, v98, v99
	v_cvt_pk_bf16_f32 v127, v100, v101
	v_cmp_ne_u32_e64 s[8:9], 1, v114
	s_andn2_b64 vcc, exec, s[90:91]
	global_store_dwordx4 v[118:119], v[124:127], off offset:256 sc1
	s_cbranch_vccnz .LBB0_359
	v_pk_mul_f32 v[112:113], v[112:113], v[112:113]
	v_pk_mul_f32 v[110:111], v[110:111], v[110:111]
	v_pk_mul_f32 v[108:109], v[108:109], v[108:109]
	v_pk_mul_f32 v[106:107], v[106:107], v[106:107]
	v_add_f32_e32 v110, v110, v111
	v_add_f32_e32 v111, v112, v113
	v_add_f32_e32 v106, v106, v107
	v_add_f32_e32 v107, v108, v109
	v_pk_mul_f32 v[104:105], v[104:105], v[104:105]
	v_pk_mul_f32 v[102:103], v[102:103], v[102:103]
	v_add_f32_e32 v110, v110, v111
	v_add_f32_e32 v106, v106, v107
	v_add_f32_e32 v102, v102, v103
	v_add_f32_e32 v103, v104, v105
	v_pk_mul_f32 v[100:101], v[100:101], v[100:101]
	v_pk_mul_f32 v[98:99], v[98:99], v[98:99]
	v_add_f32_e32 v106, v110, v106
	v_add_f32_e32 v102, v102, v103
	v_add_f32_e32 v98, v98, v99
	v_add_f32_e32 v99, v100, v101
	v_add_f32_e32 v102, v106, v102
	v_add_f32_e32 v98, v98, v99
	v_add_f32_e32 v98, v102, v98
	ds_bpermute_b32 v99, v138, v98
	s_waitcnt lgkmcnt(0)
	v_add_f32_e32 v98, v98, v99
	ds_bpermute_b32 v99, v139, v98
	s_and_saveexec_b64 s[90:91], s[2:3]
	s_cbranch_execz .LBB0_358
	v_ashrrev_i32_e32 v117, 31, v116
	v_lshlrev_b64 v[100:101], 6, v[116:117]
	v_lshl_add_u64 v[100:101], s[38:39], 0, v[100:101]
	v_lshl_add_u64 v[100:101], s[46:47], 2, v[100:101]
	s_lshl_b32 s76, s78, 2
	s_mov_b32 s77, s47
	v_lshl_add_u64 v[100:101], v[100:101], 0, s[76:77]
	s_waitcnt lgkmcnt(0)
	v_add_f32_e32 v98, v98, v99
	global_store_dword v[100:101], v98, off offset:-32 sc1

; __device__ __forceinline__ f32x4 sig_from_negl2(f32x4 t) { return rcp_4(exp2_4(t) + 1.0f); }
; __device__ __forceinline__ u32x2 pack4(f32x4 v) { u32x2 w; w.x = cvtpk(v[0], v[1]); w.y = cvtpk(v[2], v[3]); return w; }
;     __device__ __forceinline__ void operator()(const Acc& acc, const Unit& u, int wr, int wc, int fr, int fq) const {
;     ...
;                     for (int bj = 0; bj < 2; ++bj) {
;                         u32x4 w;
; #pragma unroll
;                         for (int n = 0; n < 2; ++n) {
;                             f32x4 v = acc[ai][bj][m][n] * rs;
;                             if (act) {
;                                 const f32x4 x2 = v * v;
;                                 const f32x4 t = v * (x2 * (-2.0f * 0.7978845608028654f * LOG2E * 0.044715f) + (-2.0f * 0.7978845608028654f * LOG2E));
;                                 v = v * sig_from_negl2(t);
;                             }
;                             if (t == 2 || t == 3) { const f32x4 v2 = v * v; q += (v2[0] + v2[1]) + (v2[2] + v2[3]); }
;                             const u32x2 pk = pack4(v);
;                             if (n == 0) { w.x = pk.x; w.y = pk.y; } else { w.z = pk.x; w.w = pk.y; }
;                         }
;                         *(u32x4*)(base + (size_t)r * pitch + col + bj * 128) = w;
.LBB0_363:
	v_or_b32_e32 v100, 32, v166
	v_mad_i64_i32 v[102:103], s[76:77], s88, v100, 0
	v_cvt_pk_bf16_f32 v106, v94, v95
	v_cvt_pk_bf16_f32 v107, v96, v97
	v_lshl_add_u64 v[102:103], v[102:103], 1, v[122:123]
	v_cvt_pk_bf16_f32 v108, v90, v91
	v_cvt_pk_bf16_f32 v109, v92, v93
	v_pk_mul_f32 v[88:89], v[88:89], v[104:105]
	s_and_b64 vcc, exec, s[6:7]
	v_pk_mul_f32 v[86:87], v[86:87], v[98:99]
	global_store_dwordx4 v[102:103], v[106:109], off sc1
	s_cbranch_vccnz .LBB0_365
	v_pk_mul_f32 v[104:105], v[88:89], v[88:89]
	v_pk_mul_f32 v[106:107], v[86:87], v[86:87]
	v_mov_b64_e32 v[108:109], s[66:67]
	v_pk_fma_f32 v[104:105], v[104:105], s[68:69], v[108:109] op_sel_hi:[1,0,0]
	v_pk_fma_f32 v[106:107], v[106:107], s[68:69], v[108:109] op_sel_hi:[1,0,0]
	v_pk_mul_f32 v[104:105], v[88:89], v[104:105]
	v_pk_mul_f32 v[106:107], v[86:87], v[106:107]
	v_exp_f32_e32 v104, v104
	v_exp_f32_e32 v106, v106
	v_exp_f32_e32 v105, v105
	v_exp_f32_e32 v107, v107
	v_pk_add_f32 v[104:105], v[104:105], 1.0 op_sel_hi:[1,0]
	v_pk_add_f32 v[106:107], v[106:107], 1.0 op_sel_hi:[1,0]
	v_rcp_f32_e32 v104, v104
	v_rcp_f32_e32 v106, v106
	v_rcp_f32_e32 v105, v105
	v_rcp_f32_e32 v107, v107
	v_pk_mul_f32 v[88:89], v[88:89], v[104:105]
	v_pk_mul_f32 v[86:87], v[86:87], v[106:107]

; __device__ __forceinline__ u32x2 pack4(f32x4 v) { u32x2 w; w.x = cvtpk(v[0], v[1]); w.y = cvtpk(v[2], v[3]); return w; }
;     __device__ __forceinline__ void operator()(const Acc& acc, const Unit& u, int wr, int wc, int fr, int fq) const {
;     ...
;                             if (t == 2 || t == 3) { const f32x4 v2 = v * v; q += (v2[0] + v2[1]) + (v2[2] + v2[3]); }
;                             const u32x2 pk = pack4(v);
;                             if (n == 0) { w.x = pk.x; w.y = pk.y; } else { w.z = pk.x; w.w = pk.y; }
;                         }
;                         *(u32x4*)(base + (size_t)r * pitch + col + bj * 128) = w;
;                     }
;                     if (t == 2 || t == 3) { q += __shfl_xor(q, 16); q += __shfl_xor(q, 32); if (fq == 0) stv[(size_t)r * 16 + (t - 2) * 4 + wc] = q; }
.LBB0_367:
	v_cvt_pk_bf16_f32 v104, v86, v87
	v_cvt_pk_bf16_f32 v105, v88, v89
	v_cvt_pk_bf16_f32 v106, v82, v83
	v_cvt_pk_bf16_f32 v107, v84, v85
	s_and_b64 vcc, exec, s[8:9]
	global_store_dwordx4 v[102:103], v[104:107], off offset:256 sc1
	s_cbranch_vccnz .LBB0_371
	v_pk_mul_f32 v[96:97], v[96:97], v[96:97]
	v_pk_mul_f32 v[94:95], v[94:95], v[94:95]
	v_pk_mul_f32 v[92:93], v[92:93], v[92:93]
	v_pk_mul_f32 v[90:91], v[90:91], v[90:91]
	v_add_f32_e32 v94, v94, v95
	v_add_f32_e32 v95, v96, v97
	v_add_f32_e32 v90, v90, v91
	v_add_f32_e32 v91, v92, v93
	v_pk_mul_f32 v[88:89], v[88:89], v[88:89]
	v_pk_mul_f32 v[86:87], v[86:87], v[86:87]
	v_add_f32_e32 v94, v94, v95
	v_add_f32_e32 v90, v90, v91
	v_add_f32_e32 v86, v86, v87
	v_add_f32_e32 v87, v88, v89
	v_pk_mul_f32 v[84:85], v[84:85], v[84:85]
	v_pk_mul_f32 v[82:83], v[82:83], v[82:83]
	v_add_f32_e32 v90, v94, v90
	v_add_f32_e32 v86, v86, v87
	v_add_f32_e32 v82, v82, v83
	v_add_f32_e32 v83, v84, v85
	v_add_f32_e32 v86, v90, v86
	v_add_f32_e32 v82, v82, v83
	v_add_f32_e32 v82, v86, v82
	ds_bpermute_b32 v83, v138, v82
	s_waitcnt lgkmcnt(0)
	v_add_f32_e32 v82, v82, v83
	ds_bpermute_b32 v83, v139, v82
	s_and_saveexec_b64 s[90:91], s[2:3]
	s_cbranch_execz .LBB0_370
	v_ashrrev_i32_e32 v101, 31, v100
	v_lshlrev_b64 v[84:85], 6, v[100:101]
	v_lshl_add_u64 v[84:85], s[38:39], 0, v[84:85]
	v_lshl_add_u64 v[84:85], s[46:47], 2, v[84:85]
	s_lshl_b32 s76, s78, 2
	s_mov_b32 s77, s47
	v_lshl_add_u64 v[84:85], v[84:85], 0, s[76:77]
	s_waitcnt lgkmcnt(0)
	v_add_f32_e32 v82, v82, v83
	global_store_dword v[84:85], v82, off offset:-32 sc1

; __device__ __forceinline__ f32x4 sig_from_negl2(f32x4 t) { return rcp_4(exp2_4(t) + 1.0f); }
; __device__ __forceinline__ u32x2 pack4(f32x4 v) { u32x2 w; w.x = cvtpk(v[0], v[1]); w.y = cvtpk(v[2], v[3]); return w; }
;     __device__ __forceinline__ void operator()(const Acc& acc, const Unit& u, int wr, int wc, int fr, int fq) const {
;     ...
;                     for (int bj = 0; bj < 2; ++bj) {
;                         u32x4 w;
; #pragma unroll
;                         for (int n = 0; n < 2; ++n) {
;                             f32x4 v = acc[ai][bj][m][n] * rs;
;                             if (act) {
;                                 const f32x4 x2 = v * v;
;                                 const f32x4 t = v * (x2 * (-2.0f * 0.7978845608028654f * LOG2E * 0.044715f) + (-2.0f * 0.7978845608028654f * LOG2E));
;                                 v = v * sig_from_negl2(t);
;                             }
;                             if (t == 2 || t == 3) { const f32x4 v2 = v * v; q += (v2[0] + v2[1]) + (v2[2] + v2[3]); }
;                             const u32x2 pk = pack4(v);
;                             if (n == 0) { w.x = pk.x; w.y = pk.y; } else { w.z = pk.x; w.w = pk.y; }
;                         }
;                         *(u32x4*)(base + (size_t)r * pitch + col + bj * 128) = w;
.LBB0_375:
	v_or_b32_e32 v84, 48, v166
	v_mad_i64_i32 v[86:87], s[76:77], s88, v84, 0
	v_cvt_pk_bf16_f32 v90, v78, v79
	v_cvt_pk_bf16_f32 v91, v80, v81
	v_lshl_add_u64 v[86:87], v[86:87], 1, v[122:123]
	v_cvt_pk_bf16_f32 v92, v74, v75
	v_cvt_pk_bf16_f32 v93, v76, v77
	v_pk_mul_f32 v[72:73], v[72:73], v[88:89]
	s_and_b64 vcc, exec, s[6:7]
	v_pk_mul_f32 v[70:71], v[70:71], v[82:83]
	global_store_dwordx4 v[86:87], v[90:93], off sc1
	s_cbranch_vccnz .LBB0_377
	v_pk_mul_f32 v[88:89], v[72:73], v[72:73]
	v_pk_mul_f32 v[90:91], v[70:71], v[70:71]
	v_mov_b64_e32 v[92:93], s[66:67]
	v_pk_fma_f32 v[88:89], v[88:89], s[68:69], v[92:93] op_sel_hi:[1,0,0]
	v_pk_fma_f32 v[90:91], v[90:91], s[68:69], v[92:93] op_sel_hi:[1,0,0]
	v_pk_mul_f32 v[88:89], v[72:73], v[88:89]
	v_pk_mul_f32 v[90:91], v[70:71], v[90:91]
	v_exp_f32_e32 v88, v88
	v_exp_f32_e32 v90, v90
	v_exp_f32_e32 v89, v89
	v_exp_f32_e32 v91, v91
	v_pk_add_f32 v[88:89], v[88:89], 1.0 op_sel_hi:[1,0]
	v_pk_add_f32 v[90:91], v[90:91], 1.0 op_sel_hi:[1,0]
	v_rcp_f32_e32 v88, v88
	v_rcp_f32_e32 v90, v90
	v_rcp_f32_e32 v89, v89
	v_rcp_f32_e32 v91, v91
	v_pk_mul_f32 v[72:73], v[72:73], v[88:89]
	v_pk_mul_f32 v[70:71], v[70:71], v[90:91]

; __device__ __forceinline__ u32x2 pack4(f32x4 v) { u32x2 w; w.x = cvtpk(v[0], v[1]); w.y = cvtpk(v[2], v[3]); return w; }
;     __device__ __forceinline__ void operator()(const Acc& acc, const Unit& u, int wr, int wc, int fr, int fq) const {
;     ...
;                             if (t == 2 || t == 3) { const f32x4 v2 = v * v; q += (v2[0] + v2[1]) + (v2[2] + v2[3]); }
;                             const u32x2 pk = pack4(v);
;                             if (n == 0) { w.x = pk.x; w.y = pk.y; } else { w.z = pk.x; w.w = pk.y; }
;                         }
;                         *(u32x4*)(base + (size_t)r * pitch + col + bj * 128) = w;
;                     }
;                     if (t == 2 || t == 3) { q += __shfl_xor(q, 16); q += __shfl_xor(q, 32); if (fq == 0) stv[(size_t)r * 16 + (t - 2) * 4 + wc] = q; }
.LBB0_379:
	v_cvt_pk_bf16_f32 v88, v70, v71
	v_cvt_pk_bf16_f32 v89, v72, v73
	v_cvt_pk_bf16_f32 v90, v66, v67
	v_cvt_pk_bf16_f32 v91, v68, v69
	s_and_b64 vcc, exec, s[8:9]
	global_store_dwordx4 v[86:87], v[88:91], off offset:256 sc1
	s_cbranch_vccnz .LBB0_383
	v_pk_mul_f32 v[80:81], v[80:81], v[80:81]
	v_pk_mul_f32 v[78:79], v[78:79], v[78:79]
	v_pk_mul_f32 v[76:77], v[76:77], v[76:77]
	v_pk_mul_f32 v[74:75], v[74:75], v[74:75]
	v_add_f32_e32 v78, v78, v79
	v_add_f32_e32 v79, v80, v81
	v_add_f32_e32 v74, v74, v75
	v_add_f32_e32 v75, v76, v77
	v_pk_mul_f32 v[72:73], v[72:73], v[72:73]
	v_pk_mul_f32 v[70:71], v[70:71], v[70:71]
	v_add_f32_e32 v78, v78, v79
	v_add_f32_e32 v74, v74, v75
	v_add_f32_e32 v70, v70, v71
	v_add_f32_e32 v71, v72, v73
	v_pk_mul_f32 v[68:69], v[68:69], v[68:69]
	v_pk_mul_f32 v[66:67], v[66:67], v[66:67]
	v_add_f32_e32 v74, v78, v74
	v_add_f32_e32 v70, v70, v71
	v_add_f32_e32 v66, v66, v67
	v_add_f32_e32 v67, v68, v69
	v_add_f32_e32 v70, v74, v70
	v_add_f32_e32 v66, v66, v67
	v_add_f32_e32 v66, v70, v66
	ds_bpermute_b32 v67, v138, v66
	s_waitcnt lgkmcnt(0)
	v_add_f32_e32 v66, v66, v67
	ds_bpermute_b32 v67, v139, v66
	s_and_saveexec_b64 s[90:91], s[2:3]
	s_cbranch_execz .LBB0_382
	v_ashrrev_i32_e32 v85, 31, v84
	v_lshlrev_b64 v[68:69], 6, v[84:85]
	v_lshl_add_u64 v[68:69], s[38:39], 0, v[68:69]
	v_lshl_add_u64 v[68:69], s[46:47], 2, v[68:69]
	s_lshl_b32 s76, s78, 2
	s_mov_b32 s77, s47
	v_lshl_add_u64 v[68:69], v[68:69], 0, s[76:77]
	s_waitcnt lgkmcnt(0)
	v_add_f32_e32 v66, v66, v67
	global_store_dword v[68:69], v66, off offset:-32 sc1

; __device__ __forceinline__ f32x4 sig_from_negl2(f32x4 t) { return rcp_4(exp2_4(t) + 1.0f); }
; __device__ __forceinline__ u32x2 pack4(f32x4 v) { u32x2 w; w.x = cvtpk(v[0], v[1]); w.y = cvtpk(v[2], v[3]); return w; }
;     __device__ __forceinline__ void operator()(const Acc& acc, const Unit& u, int wr, int wc, int fr, int fq) const {
;     ...
;                     for (int bj = 0; bj < 2; ++bj) {
;                         u32x4 w;
; #pragma unroll
;                         for (int n = 0; n < 2; ++n) {
;                             f32x4 v = acc[ai][bj][m][n] * rs;
;                             if (act) {
;                                 const f32x4 x2 = v * v;
;                                 const f32x4 t = v * (x2 * (-2.0f * 0.7978845608028654f * LOG2E * 0.044715f) + (-2.0f * 0.7978845608028654f * LOG2E));
;                                 v = v * sig_from_negl2(t);
;                             }
;                             if (t == 2 || t == 3) { const f32x4 v2 = v * v; q += (v2[0] + v2[1]) + (v2[2] + v2[3]); }
;                             const u32x2 pk = pack4(v);
;                             if (n == 0) { w.x = pk.x; w.y = pk.y; } else { w.z = pk.x; w.w = pk.y; }
;                         }
;                         *(u32x4*)(base + (size_t)r * pitch + col + bj * 128) = w;
.LBB0_387:
	v_add_u32_e32 v68, 0x80, v166
	v_mad_i64_i32 v[70:71], s[76:77], s88, v68, 0
	v_cvt_pk_bf16_f32 v74, v62, v63
	v_cvt_pk_bf16_f32 v75, v64, v65
	v_lshl_add_u64 v[70:71], v[70:71], 1, v[122:123]
	v_cvt_pk_bf16_f32 v76, v58, v59
	v_cvt_pk_bf16_f32 v77, v60, v61
	v_pk_mul_f32 v[56:57], v[56:57], v[72:73]
	s_and_b64 vcc, exec, s[6:7]
	v_pk_mul_f32 v[54:55], v[54:55], v[66:67]
	global_store_dwordx4 v[70:71], v[74:77], off sc1
	s_cbranch_vccnz .LBB0_389
	v_pk_mul_f32 v[72:73], v[56:57], v[56:57]
	v_pk_mul_f32 v[74:75], v[54:55], v[54:55]
	v_mov_b64_e32 v[76:77], s[66:67]
	v_pk_fma_f32 v[72:73], v[72:73], s[68:69], v[76:77] op_sel_hi:[1,0,0]
	v_pk_fma_f32 v[74:75], v[74:75], s[68:69], v[76:77] op_sel_hi:[1,0,0]
	v_pk_mul_f32 v[72:73], v[56:57], v[72:73]
	v_pk_mul_f32 v[74:75], v[54:55], v[74:75]
	v_exp_f32_e32 v72, v72
	v_exp_f32_e32 v74, v74
	v_exp_f32_e32 v73, v73
	v_exp_f32_e32 v75, v75
	v_pk_add_f32 v[72:73], v[72:73], 1.0 op_sel_hi:[1,0]
	v_pk_add_f32 v[74:75], v[74:75], 1.0 op_sel_hi:[1,0]
	v_rcp_f32_e32 v72, v72
	v_rcp_f32_e32 v74, v74
	v_rcp_f32_e32 v73, v73
	v_rcp_f32_e32 v75, v75
	v_pk_mul_f32 v[56:57], v[56:57], v[72:73]
	v_pk_mul_f32 v[54:55], v[54:55], v[74:75]

; __device__ __forceinline__ u32x2 pack4(f32x4 v) { u32x2 w; w.x = cvtpk(v[0], v[1]); w.y = cvtpk(v[2], v[3]); return w; }
;     __device__ __forceinline__ void operator()(const Acc& acc, const Unit& u, int wr, int wc, int fr, int fq) const {
;     ...
;                             if (t == 2 || t == 3) { const f32x4 v2 = v * v; q += (v2[0] + v2[1]) + (v2[2] + v2[3]); }
;                             const u32x2 pk = pack4(v);
;                             if (n == 0) { w.x = pk.x; w.y = pk.y; } else { w.z = pk.x; w.w = pk.y; }
;                         }
;                         *(u32x4*)(base + (size_t)r * pitch + col + bj * 128) = w;
;                     }
;                     if (t == 2 || t == 3) { q += __shfl_xor(q, 16); q += __shfl_xor(q, 32); if (fq == 0) stv[(size_t)r * 16 + (t - 2) * 4 + wc] = q; }
.LBB0_391:
	v_cvt_pk_bf16_f32 v72, v54, v55
	v_cvt_pk_bf16_f32 v73, v56, v57
	v_cvt_pk_bf16_f32 v74, v50, v51
	v_cvt_pk_bf16_f32 v75, v52, v53
	s_and_b64 vcc, exec, s[8:9]
	global_store_dwordx4 v[70:71], v[72:75], off offset:256 sc1
	s_cbranch_vccnz .LBB0_395
	v_pk_mul_f32 v[64:65], v[64:65], v[64:65]
	v_pk_mul_f32 v[62:63], v[62:63], v[62:63]
	v_pk_mul_f32 v[60:61], v[60:61], v[60:61]
	v_pk_mul_f32 v[58:59], v[58:59], v[58:59]
	v_add_f32_e32 v62, v62, v63
	v_add_f32_e32 v63, v64, v65
	v_add_f32_e32 v58, v58, v59
	v_add_f32_e32 v59, v60, v61
	v_pk_mul_f32 v[56:57], v[56:57], v[56:57]
	v_pk_mul_f32 v[54:55], v[54:55], v[54:55]
	v_add_f32_e32 v62, v62, v63
	v_add_f32_e32 v58, v58, v59
	v_add_f32_e32 v54, v54, v55
	v_add_f32_e32 v55, v56, v57
	v_pk_mul_f32 v[52:53], v[52:53], v[52:53]
	v_pk_mul_f32 v[50:51], v[50:51], v[50:51]
	v_add_f32_e32 v58, v62, v58
	v_add_f32_e32 v54, v54, v55
	v_add_f32_e32 v50, v50, v51
	v_add_f32_e32 v51, v52, v53
	v_add_f32_e32 v54, v58, v54
	v_add_f32_e32 v50, v50, v51
	v_add_f32_e32 v50, v54, v50
	ds_bpermute_b32 v51, v138, v50
	s_waitcnt lgkmcnt(0)
	v_add_f32_e32 v50, v50, v51
	ds_bpermute_b32 v51, v139, v50
	s_and_saveexec_b64 s[90:91], s[2:3]
	s_cbranch_execz .LBB0_394
	v_ashrrev_i32_e32 v69, 31, v68
	v_lshlrev_b64 v[52:53], 6, v[68:69]
	v_lshl_add_u64 v[52:53], s[38:39], 0, v[52:53]
	v_lshl_add_u64 v[52:53], s[46:47], 2, v[52:53]
	s_lshl_b32 s76, s78, 2
	s_mov_b32 s77, s47
	v_lshl_add_u64 v[52:53], v[52:53], 0, s[76:77]
	s_waitcnt lgkmcnt(0)
	v_add_f32_e32 v50, v50, v51
	global_store_dword v[52:53], v50, off offset:-32 sc1

; __device__ __forceinline__ f32x4 sig_from_negl2(f32x4 t) { return rcp_4(exp2_4(t) + 1.0f); }
; __device__ __forceinline__ u32x2 pack4(f32x4 v) { u32x2 w; w.x = cvtpk(v[0], v[1]); w.y = cvtpk(v[2], v[3]); return w; }
;     __device__ __forceinline__ void operator()(const Acc& acc, const Unit& u, int wr, int wc, int fr, int fq) const {
;     ...
;                     for (int bj = 0; bj < 2; ++bj) {
;                         u32x4 w;
; #pragma unroll
;                         for (int n = 0; n < 2; ++n) {
;                             f32x4 v = acc[ai][bj][m][n] * rs;
;                             if (act) {
;                                 const f32x4 x2 = v * v;
;                                 const f32x4 t = v * (x2 * (-2.0f * 0.7978845608028654f * LOG2E * 0.044715f) + (-2.0f * 0.7978845608028654f * LOG2E));
;                                 v = v * sig_from_negl2(t);
;                             }
;                             if (t == 2 || t == 3) { const f32x4 v2 = v * v; q += (v2[0] + v2[1]) + (v2[2] + v2[3]); }
;                             const u32x2 pk = pack4(v);
;                             if (n == 0) { w.x = pk.x; w.y = pk.y; } else { w.z = pk.x; w.w = pk.y; }
;                         }
;                         *(u32x4*)(base + (size_t)r * pitch + col + bj * 128) = w;
.LBB0_399:
	v_add_u32_e32 v52, 0x90, v166
	v_mad_i64_i32 v[54:55], s[76:77], s88, v52, 0
	v_cvt_pk_bf16_f32 v58, v46, v47
	v_cvt_pk_bf16_f32 v59, v48, v49
	v_lshl_add_u64 v[54:55], v[54:55], 1, v[122:123]
	v_cvt_pk_bf16_f32 v60, v42, v43
	v_cvt_pk_bf16_f32 v61, v44, v45
	v_pk_mul_f32 v[40:41], v[40:41], v[56:57]
	s_and_b64 vcc, exec, s[6:7]
	v_pk_mul_f32 v[38:39], v[38:39], v[50:51]
	global_store_dwordx4 v[54:55], v[58:61], off sc1
	s_cbranch_vccnz .LBB0_401
	v_pk_mul_f32 v[56:57], v[40:41], v[40:41]
	v_pk_mul_f32 v[58:59], v[38:39], v[38:39]
	v_mov_b64_e32 v[60:61], s[66:67]
	v_pk_fma_f32 v[56:57], v[56:57], s[68:69], v[60:61] op_sel_hi:[1,0,0]
	v_pk_fma_f32 v[58:59], v[58:59], s[68:69], v[60:61] op_sel_hi:[1,0,0]
	v_pk_mul_f32 v[56:57], v[40:41], v[56:57]
	v_pk_mul_f32 v[58:59], v[38:39], v[58:59]
	v_exp_f32_e32 v56, v56
	v_exp_f32_e32 v58, v58
	v_exp_f32_e32 v57, v57
	v_exp_f32_e32 v59, v59
	v_pk_add_f32 v[56:57], v[56:57], 1.0 op_sel_hi:[1,0]
	v_pk_add_f32 v[58:59], v[58:59], 1.0 op_sel_hi:[1,0]
	v_rcp_f32_e32 v56, v56
	v_rcp_f32_e32 v58, v58
	v_rcp_f32_e32 v57, v57
	v_rcp_f32_e32 v59, v59
	v_pk_mul_f32 v[40:41], v[40:41], v[56:57]
	v_pk_mul_f32 v[38:39], v[38:39], v[58:59]

; __device__ __forceinline__ f32x4 sig_from_negl2(f32x4 t) { return rcp_4(exp2_4(t) + 1.0f); }
; __device__ __forceinline__ u32x2 pack4(f32x4 v) { u32x2 w; w.x = cvtpk(v[0], v[1]); w.y = cvtpk(v[2], v[3]); return w; }
;     __device__ __forceinline__ void operator()(const Acc& acc, const Unit& u, int wr, int wc, int fr, int fq) const {
;     ...
;                     for (int bj = 0; bj < 2; ++bj) {
;                         u32x4 w;
; #pragma unroll
;                         for (int n = 0; n < 2; ++n) {
;                             f32x4 v = acc[ai][bj][m][n] * rs;
;                             if (act) {
;                                 const f32x4 x2 = v * v;
;                                 const f32x4 t = v * (x2 * (-2.0f * 0.7978845608028654f * LOG2E * 0.044715f) + (-2.0f * 0.7978845608028654f * LOG2E));
;                                 v = v * sig_from_negl2(t);
;                             }
;                             if (t == 2 || t == 3) { const f32x4 v2 = v * v; q += (v2[0] + v2[1]) + (v2[2] + v2[3]); }
;                             const u32x2 pk = pack4(v);
;                             if (n == 0) { w.x = pk.x; w.y = pk.y; } else { w.z = pk.x; w.w = pk.y; }
;                         }
;                         *(u32x4*)(base + (size_t)r * pitch + col + bj * 128) = w;
;                     }
;                     if (t == 2 || t == 3) { q += __shfl_xor(q, 16); q += __shfl_xor(q, 32); if (fq == 0) stv[(size_t)r * 16 + (t - 2) * 4 + wc] = q; }
.LBB0_403:
	v_cvt_pk_bf16_f32 v56, v38, v39
	v_cvt_pk_bf16_f32 v57, v40, v41
	v_cvt_pk_bf16_f32 v58, v34, v35
	v_cvt_pk_bf16_f32 v59, v36, v37
	s_and_b64 vcc, exec, s[8:9]
	global_store_dwordx4 v[54:55], v[56:59], off offset:256 sc1
	s_cbranch_vccnz .LBB0_407
	v_pk_mul_f32 v[48:49], v[48:49], v[48:49]
	v_pk_mul_f32 v[46:47], v[46:47], v[46:47]
	v_pk_mul_f32 v[44:45], v[44:45], v[44:45]
	v_pk_mul_f32 v[42:43], v[42:43], v[42:43]
	v_add_f32_e32 v46, v46, v47
	v_add_f32_e32 v47, v48, v49
	v_add_f32_e32 v42, v42, v43
	v_add_f32_e32 v43, v44, v45
	v_pk_mul_f32 v[40:41], v[40:41], v[40:41]
	v_pk_mul_f32 v[38:39], v[38:39], v[38:39]
	v_add_f32_e32 v46, v46, v47
	v_add_f32_e32 v42, v42, v43
	v_add_f32_e32 v38, v38, v39
	v_add_f32_e32 v39, v40, v41
	v_pk_mul_f32 v[36:37], v[36:37], v[36:37]
	v_pk_mul_f32 v[34:35], v[34:35], v[34:35]
	v_add_f32_e32 v42, v46, v42
	v_add_f32_e32 v38, v38, v39
	v_add_f32_e32 v34, v34, v35
	v_add_f32_e32 v35, v36, v37
	v_add_f32_e32 v38, v42, v38
	v_add_f32_e32 v34, v34, v35
	v_add_f32_e32 v34, v38, v34
	ds_bpermute_b32 v35, v138, v34
	s_waitcnt lgkmcnt(0)
	v_add_f32_e32 v34, v34, v35
	ds_bpermute_b32 v35, v139, v34
	s_and_saveexec_b64 s[90:91], s[2:3]
	s_cbranch_execz .LBB0_406
	v_ashrrev_i32_e32 v53, 31, v52
	v_lshlrev_b64 v[36:37], 6, v[52:53]
	v_lshl_add_u64 v[36:37], s[38:39], 0, v[36:37]
	v_lshl_add_u64 v[36:37], s[46:47], 2, v[36:37]
	s_lshl_b32 s76, s78, 2
	s_mov_b32 s77, s47
	v_lshl_add_u64 v[36:37], v[36:37], 0, s[76:77]
	s_waitcnt lgkmcnt(0)
	v_add_f32_e32 v34, v34, v35
	global_store_dword v[36:37], v34, off offset:-32 sc1

; __device__ __forceinline__ f32x4 sig_from_negl2(f32x4 t) { return rcp_4(exp2_4(t) + 1.0f); }
;     __device__ __forceinline__ void operator()(const Acc& acc, const Unit& u, int wr, int wc, int fr, int fq) const {
;     ...
;                     for (int bj = 0; bj < 2; ++bj) {
;                         u32x4 w;
; #pragma unroll
;                         for (int n = 0; n < 2; ++n) {
;                             f32x4 v = acc[ai][bj][m][n] * rs;
;                             if (act) {
;                                 const f32x4 x2 = v * v;
;                                 const f32x4 t = v * (x2 * (-2.0f * 0.7978845608028654f * LOG2E * 0.044715f) + (-2.0f * 0.7978845608028654f * LOG2E));
;                                 v = v * sig_from_negl2(t);
;                             }
.LBB0_411:
	v_add_u32_e32 v36, 0xa0, v166
	v_mad_i64_i32 v[38:39], s[76:77], s88, v36, 0
	v_cvt_pk_bf16_f32 v42, v30, v31
	v_cvt_pk_bf16_f32 v43, v32, v33
	v_lshl_add_u64 v[38:39], v[38:39], 1, v[122:123]
	v_cvt_pk_bf16_f32 v44, v26, v27
	v_cvt_pk_bf16_f32 v45, v28, v29
	v_pk_mul_f32 v[24:25], v[24:25], v[40:41]
	s_and_b64 vcc, exec, s[6:7]
	v_pk_mul_f32 v[22:23], v[22:23], v[34:35]
	global_store_dwordx4 v[38:39], v[42:45], off sc1
	s_cbranch_vccnz .LBB0_413
	v_pk_mul_f32 v[40:41], v[24:25], v[24:25]
	v_pk_mul_f32 v[42:43], v[22:23], v[22:23]
	v_mov_b64_e32 v[44:45], s[66:67]
	v_pk_fma_f32 v[40:41], v[40:41], s[68:69], v[44:45] op_sel_hi:[1,0,0]
	v_pk_fma_f32 v[42:43], v[42:43], s[68:69], v[44:45] op_sel_hi:[1,0,0]
	v_pk_mul_f32 v[40:41], v[24:25], v[40:41]
	v_pk_mul_f32 v[42:43], v[22:23], v[42:43]
	v_exp_f32_e32 v40, v40
	v_exp_f32_e32 v42, v42
	v_exp_f32_e32 v41, v41
	v_exp_f32_e32 v43, v43
	v_pk_add_f32 v[40:41], v[40:41], 1.0 op_sel_hi:[1,0]
	v_pk_add_f32 v[42:43], v[42:43], 1.0 op_sel_hi:[1,0]
	v_rcp_f32_e32 v40, v40
	v_rcp_f32_e32 v42, v42
	v_rcp_f32_e32 v41, v41
	v_rcp_f32_e32 v43, v43
	v_pk_mul_f32 v[24:25], v[24:25], v[40:41]
	v_pk_mul_f32 v[22:23], v[22:23], v[42:43]

; __device__ __forceinline__ f32x4 sig_from_negl2(f32x4 t) { return rcp_4(exp2_4(t) + 1.0f); }
; __device__ __forceinline__ u32x2 pack4(f32x4 v) { u32x2 w; w.x = cvtpk(v[0], v[1]); w.y = cvtpk(v[2], v[3]); return w; }
;     __device__ __forceinline__ void operator()(const Acc& acc, const Unit& u, int wr, int wc, int fr, int fq) const {
;     ...
;                     for (int bj = 0; bj < 2; ++bj) {
;                         u32x4 w;
; #pragma unroll
;                         for (int n = 0; n < 2; ++n) {
;                             f32x4 v = acc[ai][bj][m][n] * rs;
;                             if (act) {
;                                 const f32x4 x2 = v * v;
;                                 const f32x4 t = v * (x2 * (-2.0f * 0.7978845608028654f * LOG2E * 0.044715f) + (-2.0f * 0.7978845608028654f * LOG2E));
;                                 v = v * sig_from_negl2(t);
;                             }
;                             if (t == 2 || t == 3) { const f32x4 v2 = v * v; q += (v2[0] + v2[1]) + (v2[2] + v2[3]); }
;                             const u32x2 pk = pack4(v);
;                             if (n == 0) { w.x = pk.x; w.y = pk.y; } else { w.z = pk.x; w.w = pk.y; }
;                         }
;                         *(u32x4*)(base + (size_t)r * pitch + col + bj * 128) = w;
;                     }
;                     if (t == 2 || t == 3) { q += __shfl_xor(q, 16); q += __shfl_xor(q, 32); if (fq == 0) stv[(size_t)r * 16 + (t - 2) * 4 + wc] = q; }
.LBB0_415:
	v_cvt_pk_bf16_f32 v40, v22, v23
	v_cvt_pk_bf16_f32 v41, v24, v25
	v_cvt_pk_bf16_f32 v42, v18, v19
	v_cvt_pk_bf16_f32 v43, v20, v21
	s_and_b64 vcc, exec, s[8:9]
	global_store_dwordx4 v[38:39], v[40:43], off offset:256 sc1
	s_cbranch_vccnz .LBB0_419
	v_pk_mul_f32 v[32:33], v[32:33], v[32:33]
	v_pk_mul_f32 v[30:31], v[30:31], v[30:31]
	v_pk_mul_f32 v[28:29], v[28:29], v[28:29]
	v_pk_mul_f32 v[26:27], v[26:27], v[26:27]
	v_add_f32_e32 v30, v30, v31
	v_add_f32_e32 v31, v32, v33
	v_add_f32_e32 v26, v26, v27
	v_add_f32_e32 v27, v28, v29
	v_pk_mul_f32 v[24:25], v[24:25], v[24:25]
	v_pk_mul_f32 v[22:23], v[22:23], v[22:23]
	v_add_f32_e32 v30, v30, v31
	v_add_f32_e32 v26, v26, v27
	v_add_f32_e32 v22, v22, v23
	v_add_f32_e32 v23, v24, v25
	v_pk_mul_f32 v[20:21], v[20:21], v[20:21]
	v_pk_mul_f32 v[18:19], v[18:19], v[18:19]
	v_add_f32_e32 v26, v30, v26
	v_add_f32_e32 v22, v22, v23
	v_add_f32_e32 v18, v18, v19
	v_add_f32_e32 v19, v20, v21
	v_add_f32_e32 v22, v26, v22
	v_add_f32_e32 v18, v18, v19
	v_add_f32_e32 v18, v22, v18
	ds_bpermute_b32 v19, v138, v18
	s_waitcnt lgkmcnt(0)
	v_add_f32_e32 v18, v18, v19
	ds_bpermute_b32 v19, v139, v18
	s_and_saveexec_b64 s[90:91], s[2:3]
	s_cbranch_execz .LBB0_418
	v_ashrrev_i32_e32 v37, 31, v36
	v_lshlrev_b64 v[20:21], 6, v[36:37]
	v_lshl_add_u64 v[20:21], s[38:39], 0, v[20:21]
	v_lshl_add_u64 v[20:21], s[46:47], 2, v[20:21]
	s_lshl_b32 s76, s78, 2
	s_mov_b32 s77, s47
	v_lshl_add_u64 v[20:21], v[20:21], 0, s[76:77]
	s_waitcnt lgkmcnt(0)
	v_add_f32_e32 v18, v18, v19
	global_store_dword v[20:21], v18, off offset:-32 sc1

; __device__ __forceinline__ f32x4 sig_from_negl2(f32x4 t) { return rcp_4(exp2_4(t) + 1.0f); }
;     __device__ __forceinline__ void operator()(const Acc& acc, const Unit& u, int wr, int wc, int fr, int fq) const {
;     ...
;                     for (int bj = 0; bj < 2; ++bj) {
;                         u32x4 w;
; #pragma unroll
;                         for (int n = 0; n < 2; ++n) {
;                             f32x4 v = acc[ai][bj][m][n] * rs;
;                             if (act) {
;                                 const f32x4 x2 = v * v;
;                                 const f32x4 t = v * (x2 * (-2.0f * 0.7978845608028654f * LOG2E * 0.044715f) + (-2.0f * 0.7978845608028654f * LOG2E));
;                                 v = v * sig_from_negl2(t);
;                             }
.LBB0_423:
	v_add_u32_e32 v20, 0xb0, v166
	v_mad_i64_i32 v[22:23], s[76:77], s88, v20, 0
	v_cvt_pk_bf16_f32 v26, v14, v15
	v_cvt_pk_bf16_f32 v27, v16, v17
	v_lshl_add_u64 v[22:23], v[22:23], 1, v[122:123]
	v_cvt_pk_bf16_f32 v28, v10, v11
	v_cvt_pk_bf16_f32 v29, v12, v13
	v_pk_mul_f32 v[8:9], v[8:9], v[24:25]
	s_and_b64 vcc, exec, s[6:7]
	v_pk_mul_f32 v[6:7], v[6:7], v[18:19]
	global_store_dwordx4 v[22:23], v[26:29], off sc1
	s_cbranch_vccnz .LBB0_425
	v_pk_mul_f32 v[24:25], v[8:9], v[8:9]
	v_pk_mul_f32 v[26:27], v[6:7], v[6:7]
	v_mov_b64_e32 v[28:29], s[66:67]
	v_pk_fma_f32 v[24:25], v[24:25], s[68:69], v[28:29] op_sel_hi:[1,0,0]
	v_pk_fma_f32 v[26:27], v[26:27], s[68:69], v[28:29] op_sel_hi:[1,0,0]
	v_pk_mul_f32 v[24:25], v[8:9], v[24:25]
	v_pk_mul_f32 v[26:27], v[6:7], v[26:27]
	v_exp_f32_e32 v24, v24
	v_exp_f32_e32 v26, v26
	v_exp_f32_e32 v25, v25
	v_exp_f32_e32 v27, v27
	v_pk_add_f32 v[24:25], v[24:25], 1.0 op_sel_hi:[1,0]
	v_pk_add_f32 v[26:27], v[26:27], 1.0 op_sel_hi:[1,0]
	v_rcp_f32_e32 v24, v24
	v_rcp_f32_e32 v26, v26
	v_rcp_f32_e32 v25, v25
	v_rcp_f32_e32 v27, v27
	v_pk_mul_f32 v[8:9], v[8:9], v[24:25]
	v_pk_mul_f32 v[6:7], v[6:7], v[26:27]

; __device__ __forceinline__ f32x4 sig_from_negl2(f32x4 t) { return rcp_4(exp2_4(t) + 1.0f); }
; __device__ __forceinline__ u32x2 pack4(f32x4 v) { u32x2 w; w.x = cvtpk(v[0], v[1]); w.y = cvtpk(v[2], v[3]); return w; }
;     __device__ __forceinline__ void operator()(const Acc& acc, const Unit& u, int wr, int wc, int fr, int fq) const {
;     ...
;                     for (int bj = 0; bj < 2; ++bj) {
;                         u32x4 w;
; #pragma unroll
;                         for (int n = 0; n < 2; ++n) {
;                             f32x4 v = acc[ai][bj][m][n] * rs;
;                             if (act) {
;                                 const f32x4 x2 = v * v;
;                                 const f32x4 t = v * (x2 * (-2.0f * 0.7978845608028654f * LOG2E * 0.044715f) + (-2.0f * 0.7978845608028654f * LOG2E));
;                                 v = v * sig_from_negl2(t);
;                             }
;                             if (t == 2 || t == 3) { const f32x4 v2 = v * v; q += (v2[0] + v2[1]) + (v2[2] + v2[3]); }
;                             const u32x2 pk = pack4(v);
;                             if (n == 0) { w.x = pk.x; w.y = pk.y; } else { w.z = pk.x; w.w = pk.y; }
;                         }
;                         *(u32x4*)(base + (size_t)r * pitch + col + bj * 128) = w;
;                     }
;                     if (t == 2 || t == 3) { q += __shfl_xor(q, 16); q += __shfl_xor(q, 32); if (fq == 0) stv[(size_t)r * 16 + (t - 2) * 4 + wc] = q; }
.LBB0_427:
	v_cvt_pk_bf16_f32 v24, v6, v7
	v_cvt_pk_bf16_f32 v25, v8, v9
	v_cvt_pk_bf16_f32 v26, v2, v3
	v_cvt_pk_bf16_f32 v27, v4, v5
	s_and_b64 vcc, exec, s[8:9]
	global_store_dwordx4 v[22:23], v[24:27], off offset:256 sc1
	s_cbranch_vccnz .LBB0_431
	v_pk_mul_f32 v[16:17], v[16:17], v[16:17]
	v_pk_mul_f32 v[14:15], v[14:15], v[14:15]
	v_pk_mul_f32 v[12:13], v[12:13], v[12:13]
	v_pk_mul_f32 v[10:11], v[10:11], v[10:11]
	v_add_f32_e32 v14, v14, v15
	v_add_f32_e32 v15, v16, v17
	v_add_f32_e32 v10, v10, v11
	v_add_f32_e32 v11, v12, v13
	v_pk_mul_f32 v[8:9], v[8:9], v[8:9]
	v_pk_mul_f32 v[6:7], v[6:7], v[6:7]
	v_add_f32_e32 v14, v14, v15
	v_add_f32_e32 v10, v10, v11
	v_add_f32_e32 v6, v6, v7
	v_add_f32_e32 v7, v8, v9
	v_pk_mul_f32 v[4:5], v[4:5], v[4:5]
	v_pk_mul_f32 v[2:3], v[2:3], v[2:3]
	v_add_f32_e32 v10, v14, v10
	v_add_f32_e32 v6, v6, v7
	v_add_f32_e32 v2, v2, v3
	v_add_f32_e32 v3, v4, v5
	v_add_f32_e32 v6, v10, v6
	v_add_f32_e32 v2, v2, v3
	v_add_f32_e32 v2, v6, v2
	ds_bpermute_b32 v3, v138, v2
	s_waitcnt lgkmcnt(0)
	v_add_f32_e32 v2, v2, v3
	ds_bpermute_b32 v3, v139, v2
	s_and_saveexec_b64 s[6:7], s[2:3]
	s_cbranch_execz .LBB0_430
	v_ashrrev_i32_e32 v21, 31, v20
	v_lshlrev_b64 v[4:5], 6, v[20:21]
	v_lshl_add_u64 v[4:5], s[38:39], 0, v[4:5]
	v_lshl_add_u64 v[4:5], s[46:47], 2, v[4:5]
	s_lshl_b32 s46, s78, 2
	v_lshl_add_u64 v[4:5], v[4:5], 0, s[46:47]
	s_waitcnt lgkmcnt(0)
	v_add_f32_e32 v2, v2, v3
	global_store_dword v[4:5], v2, off offset:-32 sc1

; __device__ __forceinline__ void attn_pv(unsigned vaddr, const int (&vo)[8], const bf16x8 (&pf)[2][2], f32x4 (&o)[2][8], f32x4 (&ol)[2]) {
;     s16x4 r[3][4];
;     ...
;     AT_TR4(0, 0); AT_TR4(1, 1);
;     { const bf16x8 ones = (bf16x8){0x3f80, 0x3f80, 0x3f80, 0x3f80, 0x3f80, 0x3f80, 0x3f80, 0x3f80};
; template <bool QK, bool PV> ...
;     ...
;     if constexpr (PV) { AT_TR4(0, 0); AT_TR4(1, 1);
;         const bf16x8 ones = (bf16x8){0x3f80, 0x3f80, 0x3f80, 0x3f80, 0x3f80, 0x3f80, 0x3f80, 0x3f80};
; #pragma unroll
;         for (int c = 0; c < 2; ++c)
; #pragma unroll
;             for (int si = 0; si < 2; ++si) ol[c] = __builtin_amdgcn_mfma_f32_16x16x32_bf16(ones, pf[c][si], ol[c], 0, 0, 0); }
; #pragma unroll
;     for (int dt = 0; dt < 8; ++dt) {
;         if constexpr (PV) {
;             const int cb = dt % 3;
;             if (dt < 6) { AT_TR4((dt + 2) % 3, dt + 2); asm volatile("s_waitcnt lgkmcnt(8)" : "+v"(r[cb][0]), "+v"(r[cb][1]), "+v"(r[cb][2]), "+v"(r[cb][3])); }
;             else if (dt == 6) asm volatile("s_waitcnt lgkmcnt(4)" : "+v"(r[cb][0]), "+v"(r[cb][1]), "+v"(r[cb][2]), "+v"(r[cb][3]));
;             else asm volatile("s_waitcnt lgkmcnt(0)" : "+v"(r[cb][0]), "+v"(r[cb][1]), "+v"(r[cb][2]), "+v"(r[cb][3]));
; #pragma unroll
;             for (int si = 0; si < 2; ++si) {
;                 const s16x4 lo = r[cb][2 * si], hi = r[cb][2 * si + 1];
;                 const bf16x8 vf = (bf16x8){lo[0], lo[1], lo[2], lo[3], hi[0], hi[1], hi[2], hi[3]};
;                 o[0][dt] = __builtin_amdgcn_mfma_f32_16x16x32_bf16(vf, pf[0][si], o[0][dt], 0, 0, 0);
;                 o[1][dt] = __builtin_amdgcn_mfma_f32_16x16x32_bf16(vf, pf[1][si], o[1][dt], 0, 0, 0);
;             }
;         }
;         {
;             const int c = dt >> 2, kt = dt & 3;
; #pragma unroll
;             for (int j = 0; j < 4; ++j) s[c][kt][j] = fast_exp2(s[c][kt][j]);
;             if (kt & 1) { const int si = kt >> 1;
;                 u32x4 wv; wv.x = cvtpk(s[c][2 * si][0], s[c][2 * si][1]); wv.y = cvtpk(s[c][2 * si][2], s[c][2 * si][3]);
;                 wv.z = cvtpk(s[c][2 * si + 1][0], s[c][2 * si + 1][1]); wv.w = cvtpk(s[c][2 * si + 1][2], s[c][2 * si + 1][3]);
;                 pn[c][si] = __builtin_bit_cast(bf16x8, wv); }
;         }
;     }
;     ...
; #pragma unroll
;     for (int c = 0; c < 2; ++c)
; #pragma unroll
;         for (int si = 0; si < 2; ++si) pf[c][si] = pn[c][si];
.Lat_yskip_s:
	v_mov_b64_e32 v[140:141], s[6:7]
	v_mov_b64_e32 v[138:139], s[4:5]
	ds_read_b64_tr_b16 v[2:3], v194 offset:0
	ds_read_b64_tr_b16 v[4:5], v194 offset:0x1000
	ds_read_b64_tr_b16 v[10:11], v194 offset:0x2000
	ds_read_b64_tr_b16 v[12:13], v194 offset:0x3000
	v_exp_f32_e32 v154, v74
	s_nop 0
	v_mfma_f32_16x16x32_bf16 v[6:9], v[138:141], v[58:61], v[134:137]
	v_exp_f32_e32 v161, v75
	v_exp_f32_e32 v90, v90
	v_exp_f32_e32 v91, v91
	v_mfma_f32_16x16x32_bf16 v[134:137], v[138:141], v[34:37], v[6:9]
	ds_read_b64_tr_b16 v[6:7], v195 offset:0
	ds_read_b64_tr_b16 v[8:9], v195 offset:0x1000
	ds_read_b64_tr_b16 v[14:15], v195 offset:0x2000
	ds_read_b64_tr_b16 v[16:17], v195 offset:0x3000
	ds_read_b64_tr_b16 v[142:143], v196 offset:0
	ds_read_b64_tr_b16 v[144:145], v196 offset:0x1000
	ds_read_b64_tr_b16 v[146:147], v196 offset:0x2000
	ds_read_b64_tr_b16 v[148:149], v196 offset:0x3000
	s_waitcnt lgkmcnt(8)
	ds_read_b64_tr_b16 v[150:151], v197 offset:0
	ds_read_b64_tr_b16 v[152:153], v197 offset:0x1000
	v_mfma_f32_16x16x32_bf16 v[130:133], v[138:141], v[42:45], v[130:133]
	v_exp_f32_e32 v92, v92
	v_exp_f32_e32 v93, v93
	v_exp_f32_e32 v94, v94
	v_mfma_f32_16x16x32_bf16 v[126:129], v[2:5], v[58:61], v[126:129]
	v_exp_f32_e32 v95, v95
	v_exp_f32_e32 v96, v96
	v_exp_f32_e32 v97, v97
	v_mfma_f32_16x16x32_bf16 v[2:5], v[2:5], v[42:45], v[122:125]
	v_exp_f32_e32 v38, v38
	v_exp_f32_e32 v39, v39
	v_exp_f32_e32 v40, v40
	v_mfma_f32_16x16x32_bf16 v[122:125], v[10:13], v[34:37], v[126:129]
	v_exp_f32_e32 v41, v41
	v_exp_f32_e32 v62, v62
	v_exp_f32_e32 v63, v63
	v_mfma_f32_16x16x32_bf16 v[126:129], v[10:13], v[18:21], v[2:5]
	ds_read_b64_tr_b16 v[2:3], v197 offset:0x2000
	ds_read_b64_tr_b16 v[4:5], v197 offset:0x3000
	s_waitcnt lgkmcnt(8)
	v_mfma_f32_16x16x32_bf16 v[130:133], v[138:141], v[18:21], v[130:133]
	v_cvt_pk_bf16_f32 v38, v38, v39
	v_cvt_pk_bf16_f32 v39, v40, v41
	v_cvt_pk_bf16_f32 v40, v62, v63
	v_mfma_f32_16x16x32_bf16 v[10:13], v[6:9], v[58:61], v[114:117]
	s_add_i32 s44, s44, s30
	s_add_i32 s43, s43, s30
	s_cmpk_gt_i32 s44, 0x1ff
	v_mfma_f32_16x16x32_bf16 v[6:9], v[6:9], v[42:45], v[118:121]
	v_mfma_f32_16x16x32_bf16 v[118:121], v[14:17], v[34:37], v[10:13]
	ds_read_b64_tr_b16 v[10:11], v198 offset:0
	ds_read_b64_tr_b16 v[12:13], v198 offset:0x1000
	v_mfma_f32_16x16x32_bf16 v[114:117], v[14:17], v[18:21], v[6:9]
	ds_read_b64_tr_b16 v[14:15], v198 offset:0x2000
	ds_read_b64_tr_b16 v[16:17], v198 offset:0x3000
	s_waitcnt lgkmcnt(8)
	s_nop 0
	v_mfma_f32_16x16x32_bf16 v[6:9], v[142:145], v[58:61], v[106:109]
	v_mfma_f32_16x16x32_bf16 v[106:109], v[142:145], v[42:45], v[110:113]
	ds_read_b64_tr_b16 v[142:143], v199 offset:0
	ds_read_b64_tr_b16 v[144:145], v199 offset:0x1000
	v_mfma_f32_16x16x32_bf16 v[110:113], v[146:149], v[34:37], v[6:9]
	v_mfma_f32_16x16x32_bf16 v[106:109], v[146:149], v[18:21], v[106:109]
	ds_read_b64_tr_b16 v[146:147], v199 offset:0x2000
	ds_read_b64_tr_b16 v[148:149], v199 offset:0x3000
	s_waitcnt lgkmcnt(8)
	s_nop 0
	v_mfma_f32_16x16x32_bf16 v[6:9], v[150:153], v[58:61], v[98:101]
	s_nop 2
	v_exp_f32_e32 v98, v76
	v_exp_f32_e32 v99, v77
	v_mfma_f32_16x16x32_bf16 v[74:77], v[150:153], v[42:45], v[102:105]
	v_exp_f32_e32 v100, v86
	v_exp_f32_e32 v101, v87
	ds_read_b64_tr_b16 v[86:87], v200 offset:0
	v_mfma_f32_16x16x32_bf16 v[6:9], v[2:5], v[34:37], v[6:9]
	v_exp_f32_e32 v102, v88
	v_exp_f32_e32 v103, v89
	ds_read_b64_tr_b16 v[88:89], v200 offset:0x1000
	v_mfma_f32_16x16x32_bf16 v[2:5], v[2:5], v[18:21], v[74:77]
	ds_read_b64_tr_b16 v[74:75], v200 offset:0x2000
	ds_read_b64_tr_b16 v[76:77], v200 offset:0x3000
	s_waitcnt lgkmcnt(8)
	v_exp_f32_e32 v104, v22
	v_mfma_f32_16x16x32_bf16 v[78:81], v[10:13], v[58:61], v[78:81]
	v_exp_f32_e32 v105, v23
	v_exp_f32_e32 v150, v24
	v_mfma_f32_16x16x32_bf16 v[82:85], v[10:13], v[42:45], v[82:85]
	v_mfma_f32_16x16x32_bf16 v[10:13], v[14:17], v[34:37], v[78:81]
	ds_read_b64_tr_b16 v[78:79], v201 offset:0
	ds_read_b64_tr_b16 v[80:81], v201 offset:0x1000
	v_mfma_f32_16x16x32_bf16 v[14:17], v[14:17], v[18:21], v[82:85]
	ds_read_b64_tr_b16 v[82:83], v201 offset:0x2000
	ds_read_b64_tr_b16 v[84:85], v201 offset:0x3000
	s_waitcnt lgkmcnt(8)
	s_waitcnt lgkmcnt(4)
	s_nop 0
	v_mfma_f32_16x16x32_bf16 v[66:69], v[142:145], v[58:61], v[66:69]
	s_waitcnt lgkmcnt(0)
	v_mfma_f32_16x16x32_bf16 v[54:57], v[86:89], v[58:61], v[54:57]
	v_mfma_f32_16x16x32_bf16 v[58:61], v[78:81], v[58:61], v[30:33]
	v_mfma_f32_16x16x32_bf16 v[70:73], v[142:145], v[42:45], v[70:73]
	v_exp_f32_e32 v142, v25
	v_exp_f32_e32 v143, v26
	v_exp_f32_e32 v144, v27
	v_mfma_f32_16x16x32_bf16 v[22:25], v[146:149], v[34:37], v[66:69]
	v_cvt_pk_bf16_f32 v30, v90, v91
	v_cvt_pk_bf16_f32 v31, v92, v93
	v_cvt_pk_bf16_f32 v32, v94, v95
	v_exp_f32_e32 v66, v28
	v_exp_f32_e32 v67, v29
	v_mfma_f32_16x16x32_bf16 v[50:53], v[86:89], v[42:45], v[50:53]
	v_exp_f32_e32 v68, v64
	v_exp_f32_e32 v69, v65
	v_cvt_pk_bf16_f32 v33, v96, v97
	v_mfma_f32_16x16x32_bf16 v[54:57], v[74:77], v[34:37], v[54:57]
	v_cvt_pk_bf16_f32 v41, v68, v69
	v_mfma_f32_16x16x32_bf16 v[42:45], v[78:81], v[42:45], v[46:49]
	v_mfma_f32_16x16x32_bf16 v[46:49], v[82:85], v[34:37], v[58:61]
	v_cvt_pk_bf16_f32 v34, v154, v161
	v_cvt_pk_bf16_f32 v35, v98, v99
	v_cvt_pk_bf16_f32 v36, v100, v101
	v_cvt_pk_bf16_f32 v37, v102, v103
	v_mfma_f32_16x16x32_bf16 v[62:65], v[74:77], v[18:21], v[50:53]
	v_lshlrev_b32_e32 v154, 1, v156
	v_mfma_f32_16x16x32_bf16 v[58:61], v[138:141], v[34:37], v[134:137]
	s_nop 0
	v_cvt_pk_bf16_f32 v50, v104, v105
	v_cvt_pk_bf16_f32 v51, v150, v142
	v_cvt_pk_bf16_f32 v52, v143, v144
	v_cvt_pk_bf16_f32 v53, v66, v67
	v_mfma_f32_16x16x32_bf16 v[58:61], v[138:141], v[30:33], v[58:61]
	s_nop 0
	v_mfma_f32_16x16x32_bf16 v[78:81], v[138:141], v[50:53], v[130:133]
	v_mfma_f32_16x16x32_bf16 v[78:81], v[138:141], v[38:41], v[78:81]
	s_nop 4
	v_div_scale_f32 v59, s[2:3], v58, v58, 1.0
	v_mfma_f32_16x16x32_bf16 v[26:29], v[146:149], v[18:21], v[70:73]
	v_mfma_f32_16x16x32_bf16 v[18:21], v[82:85], v[18:21], v[42:45]
	v_rcp_f32_e32 v79, v59
	ds_read_b64_tr_b16 v[42:43], v202 offset:0
	ds_read_b64_tr_b16 v[44:45], v202 offset:0x1000
	ds_read_b64_tr_b16 v[66:67], v202 offset:0x2000
	ds_read_b64_tr_b16 v[68:69], v202 offset:0x3000
	ds_read_b64_tr_b16 v[70:71], v203 offset:0
	ds_read_b64_tr_b16 v[72:73], v203 offset:0x1000
	ds_read_b64_tr_b16 v[74:75], v203 offset:0x2000
	ds_read_b64_tr_b16 v[76:77], v203 offset:0x3000
	ds_read_b64_tr_b16 v[82:83], v204 offset:0
	ds_read_b64_tr_b16 v[84:85], v204 offset:0x1000
	ds_read_b64_tr_b16 v[86:87], v204 offset:0x2000
	ds_read_b64_tr_b16 v[88:89], v204 offset:0x3000
	s_nop 0
	s_waitcnt lgkmcnt(8)
; #define AT_TR4(slot, d) do { const unsigned _a = vaddr + (unsigned)vo[d]; AT_TR(r[slot][0], _a, 0); AT_TR(r[slot][1], _a, 16 * 256); AT_TR(r[slot][2], _a, 32 * 256); AT_TR(r[slot][3], _a, 48 * 256); } while (0)
; #define AT_TR4(slot, d) do { const unsigned _a = vaddr + (unsigned)vo[d]; AT_TR(r[slot][0], _a, 0); AT_TR(r[slot][1], _a, 16 * 256); AT_TR(r[slot][2], _a, 32 * 256); AT_TR(r[slot][3], _a, 48 * 256); } while (0)
; __device__ __forceinline__ void attn_pv(unsigned vaddr, const int (&vo)[8], const bf16x8 (&pf)[2][2], f32x4 (&o)[2][8], f32x4 (&ol)[2]) {
;     ...
; #pragma unroll
;     for (int dt = 0; dt < 8; ++dt) {
;         const int cb = dt % 3;
;         if (dt < 6) { AT_TR4((dt + 2) % 3, dt + 2); asm volatile("s_waitcnt lgkmcnt(8)" : "+v"(r[cb][0]), "+v"(r[cb][1]), "+v"(r[cb][2]), "+v"(r[cb][3])); }
;         else if (dt == 6) asm volatile("s_waitcnt lgkmcnt(4)" : "+v"(r[cb][0]), "+v"(r[cb][1]), "+v"(r[cb][2]), "+v"(r[cb][3]));
;         else asm volatile("s_waitcnt lgkmcnt(0)" : "+v"(r[cb][0]), "+v"(r[cb][1]), "+v"(r[cb][2]), "+v"(r[cb][3]));
; #pragma unroll
;         for (int si = 0; si < 2; ++si) {
;             const s16x4 lo = r[cb][2 * si], hi = r[cb][2 * si + 1];
;             const bf16x8 vf = (bf16x8){lo[0], lo[1], lo[2], lo[3], hi[0], hi[1], hi[2], hi[3]};
;             o[0][dt] = __builtin_amdgcn_mfma_f32_16x16x32_bf16(vf, pf[0][si], o[0][dt], 0, 0, 0);
;             o[1][dt] = __builtin_amdgcn_mfma_f32_16x16x32_bf16(vf, pf[1][si], o[1][dt], 0, 0, 0);
;         }
;     }
;     ...
; }
; __device__ __forceinline__ void attn_unit(LAS unsigned char* lds, int seq, int h, int qb, bf16_t* UQ, const bf16_t* KB, const bf16_t* VB, const float* rel_bias, const float* subln, float lam, float bmax) {
;     ...
;     const float i0 = 1.0f / ol[0][0], i1 = lam / ol[1][0];
;     float ss = 0.f;
; #pragma unroll
;     for (int dt = 0; dt < 8; ++dt)
; #pragma unroll
;         for (int j = 0; j < 4; ++j) { const float v = o[0][dt][j] * i0 - o[1][dt][j] * i1; o[0][dt][j] = v; ss += v * v; }
	ds_read_b64_tr_b16 v[90:91], v205 offset:0
	ds_read_b64_tr_b16 v[92:93], v205 offset:0x1000
	ds_read_b64_tr_b16 v[98:99], v205 offset:0x2000
	ds_read_b64_tr_b16 v[100:101], v205 offset:0x3000
	s_waitcnt lgkmcnt(8)
	s_nop 0
	v_mfma_f32_16x16x32_bf16 v[94:97], v[42:45], v[34:37], v[122:125]
	v_fma_f32 v60, -v59, v79, 1.0
	ds_read_b64_tr_b16 v[102:103], v206 offset:0
	ds_read_b64_tr_b16 v[104:105], v206 offset:0x1000
	v_mfma_f32_16x16x32_bf16 v[42:45], v[42:45], v[50:53], v[126:129]
	ds_read_b64_tr_b16 v[122:123], v206 offset:0x2000
	ds_read_b64_tr_b16 v[124:125], v206 offset:0x3000
	s_waitcnt lgkmcnt(8)
	v_mfma_f32_16x16x32_bf16 v[118:121], v[70:73], v[34:37], v[118:121]
	v_fmac_f32_e32 v79, v60, v79
	v_div_scale_f32 v60, vcc, 1.0, v58, 1.0
	v_mfma_f32_16x16x32_bf16 v[70:73], v[70:73], v[50:53], v[114:117]
	v_mfma_f32_16x16x32_bf16 v[110:113], v[82:85], v[34:37], v[110:113]
	v_mfma_f32_16x16x32_bf16 v[80:83], v[82:85], v[50:53], v[106:109]
	v_mul_f32_e32 v84, v60, v79
	v_fma_f32 v61, -v59, v84, v60
	v_fmac_f32_e32 v84, v61, v79
	v_mfma_f32_16x16x32_bf16 v[94:97], v[66:69], v[30:33], v[94:97]
	v_fma_f32 v59, -v59, v84, v60
	v_div_fmas_f32 v59, v59, v79, v84
	v_mfma_f32_16x16x32_bf16 v[42:45], v[66:69], v[38:41], v[42:45]
	ds_read_b64_tr_b16 v[66:67], v207 offset:0
	ds_read_b64_tr_b16 v[68:69], v207 offset:0x1000
	ds_read_b64_tr_b16 v[126:127], v207 offset:0x2000
	ds_read_b64_tr_b16 v[128:129], v207 offset:0x3000
	s_waitcnt lgkmcnt(8)
	ds_read_b64_tr_b16 v[130:131], v208 offset:0
	ds_read_b64_tr_b16 v[132:133], v208 offset:0x1000
	ds_read_b64_tr_b16 v[114:115], v208 offset:0x2000
	ds_read_b64_tr_b16 v[116:117], v208 offset:0x3000
	v_mfma_f32_16x16x32_bf16 v[118:121], v[74:77], v[30:33], v[118:121]
	s_waitcnt lgkmcnt(8)
	ds_read_b64_tr_b16 v[134:135], v209 offset:0
	ds_read_b64_tr_b16 v[136:137], v209 offset:0x1000
	v_mfma_f32_16x16x32_bf16 v[70:73], v[74:77], v[38:41], v[70:73]
	ds_read_b64_tr_b16 v[74:75], v209 offset:0x2000
	ds_read_b64_tr_b16 v[76:77], v209 offset:0x3000
	s_waitcnt lgkmcnt(8)
	s_waitcnt lgkmcnt(4)
	v_mfma_f32_16x16x32_bf16 v[2:5], v[90:93], v[50:53], v[2:5]
	s_waitcnt lgkmcnt(0)
	v_mfma_f32_16x16x32_bf16 v[60:63], v[130:133], v[50:53], v[62:65]
	s_nop 2
	v_div_scale_f32 v65, s[2:3], v78, v78, v174
	v_rcp_f32_e32 v85, v65
	v_mfma_f32_16x16x32_bf16 v[18:21], v[134:137], v[50:53], v[18:21]
	v_div_fixup_f32 v64, v59, v58, 1.0
	v_fma_f32 v79, -v65, v85, 1.0
	v_mfma_f32_16x16x32_bf16 v[58:61], v[114:117], v[38:41], v[60:63]
	v_fmac_f32_e32 v85, v79, v85
	s_nop 1
	v_div_scale_f32 v62, vcc, v174, v78, v174
	v_mfma_f32_16x16x32_bf16 v[46:49], v[134:137], v[34:37], v[46:49]
	v_mul_f32_e32 v63, v62, v85
	v_fma_f32 v79, -v65, v63, v62
	v_fmac_f32_e32 v63, v79, v85
	v_mfma_f32_16x16x32_bf16 v[18:21], v[74:77], v[38:41], v[18:21]
	v_fma_f32 v62, -v65, v63, v62
	v_div_fmas_f32 v62, v62, v85, v63
	v_div_fixup_f32 v78, v62, v78, v174
	v_mfma_f32_16x16x32_bf16 v[46:49], v[74:77], v[30:33], v[46:49]
	v_mul_f32_e64 v42, v78, v42
	v_mul_f32_e64 v43, v78, v43
	s_nop 1
	v_pk_mul_f32 v[18:19], v[78:79], v[18:19] op_sel_hi:[0,1]
	v_pk_fma_f32 v[42:43], v[64:65], v[94:95], v[42:43] op_sel_hi:[0,1,1] neg_lo:[0,0,1] neg_hi:[0,0,1]
	v_mfma_f32_16x16x32_bf16 v[6:9], v[90:93], v[34:37], v[6:9]
	v_mul_f32_e64 v44, v78, v44
	v_mul_f32_e64 v45, v78, v45
	v_pk_fma_f32 v[46:47], v[64:65], v[46:47], v[18:19] op_sel_hi:[0,1,1] neg_lo:[0,0,1] neg_hi:[0,0,1]
	v_pk_mul_f32 v[18:19], v[78:79], v[20:21] op_sel_hi:[0,1]
	v_pk_fma_f32 v[48:49], v[64:65], v[48:49], v[18:19] op_sel_hi:[0,1,1] neg_lo:[0,0,1] neg_hi:[0,0,1]
	global_load_dwordx4 v[18:21], v[158:159], off
	v_mfma_f32_16x16x32_bf16 v[2:5], v[98:101], v[38:41], v[2:5]
	v_mul_f32_e64 v60, v78, v60
	v_mul_f32_e64 v61, v78, v61
	v_pk_fma_f32 v[44:45], v[64:65], v[96:97], v[44:45] op_sel_hi:[0,1,1] neg_lo:[0,0,1] neg_hi:[0,0,1]
	v_pk_mul_f32 v[84:85], v[42:43], v[42:43]
	v_mfma_f32_16x16x32_bf16 v[54:57], v[130:133], v[34:37], v[54:57]
	v_mul_f32_e64 v70, v78, v70
	v_mul_f32_e64 v71, v78, v71
	s_nop 0
	v_pk_mul_f32 v[4:5], v[78:79], v[4:5] op_sel_hi:[0,1]
	v_pk_fma_f32 v[70:71], v[64:65], v[118:119], v[70:71] op_sel_hi:[0,1,1] neg_lo:[0,0,1] neg_hi:[0,0,1]
	v_mfma_f32_16x16x32_bf16 v[6:9], v[98:101], v[30:33], v[6:9]
	v_mul_f32_e64 v72, v78, v72
	v_mul_f32_e64 v73, v78, v73
	v_pk_fma_f32 v[72:73], v[64:65], v[120:121], v[72:73] op_sel_hi:[0,1,1] neg_lo:[0,0,1] neg_hi:[0,0,1]
	v_pk_mul_f32 v[76:77], v[46:47], v[46:47]
	v_mfma_f32_16x16x32_bf16 v[54:57], v[114:117], v[30:33], v[54:57]
	v_mfma_f32_16x16x32_bf16 v[10:13], v[102:105], v[34:37], v[10:13]
	s_nop 1
	v_fma_f32 v94, v64, v8, -v4
	v_fma_f32 v95, v64, v9, -v5
	v_pk_mul_f32 v[8:9], v[78:79], v[2:3] op_sel_hi:[0,1]
	s_nop 1
	v_pk_fma_f32 v[56:57], v[64:65], v[56:57], v[60:61] op_sel_hi:[0,1,1] neg_lo:[0,0,1] neg_hi:[0,0,1]
	v_mfma_f32_16x16x32_bf16 v[2:5], v[66:69], v[34:37], v[22:25]
	v_mul_f32_e64 v96, v94, v94
	v_mul_f32_e64 v97, v95, v95
	v_pk_mul_f32 v[74:75], v[56:57], v[56:57]
	v_mfma_f32_16x16x32_bf16 v[106:109], v[86:89], v[30:33], v[110:113]
	v_fma_f32 v22, v64, v6, -v8
	v_fma_f32 v23, v64, v7, -v9
	v_pk_mul_f32 v[24:25], v[22:23], v[22:23]
	v_mfma_f32_16x16x32_bf16 v[60:63], v[86:89], v[38:41], v[80:83]
	v_mul_f32_e64 v88, v70, v70
	v_mul_f32_e64 v89, v71, v71
	v_pk_mul_f32 v[86:87], v[72:73], v[72:73]
	v_pk_mul_f32 v[82:83], v[44:45], v[44:45]
	v_mfma_f32_16x16x32_bf16 v[10:13], v[122:125], v[30:33], v[10:13]
	s_nop 2
	v_mul_f32_e64 v60, v78, v60
	v_mul_f32_e64 v61, v78, v61
	v_pk_fma_f32 v[60:61], v[64:65], v[106:107], v[60:61] op_sel_hi:[0,1,1] neg_lo:[0,0,1] neg_hi:[0,0,1]
	v_pk_mul_f32 v[62:63], v[78:79], v[62:63] op_sel_hi:[0,1]
; __device__ __forceinline__ unsigned cvtpk(float lo, float hi) { f32x2 v = {lo, hi}; bf16x2_t b = __builtin_convertvector(v, bf16x2_t); return __builtin_bit_cast(unsigned, b); }
; #define AT_BAR(N) asm volatile("s_waitcnt vmcnt(" #N ") lgkmcnt(0)\n\ts_barrier" ::: "memory")
; __device__ __forceinline__ void attn_unit(LAS unsigned char* lds, int seq, int h, int qb, bf16_t* UQ, const bf16_t* KB, const bf16_t* VB, const float* rel_bias, const float* subln, float lam, float bmax) {
;     ...
;     const float i0 = 1.0f / ol[0][0], i1 = lam / ol[1][0];
;     float ss = 0.f;
; #pragma unroll
;     for (int dt = 0; dt < 8; ++dt)
; #pragma unroll
;         for (int j = 0; j < 4; ++j) { const float v = o[0][dt][j] * i0 - o[1][dt][j] * i1; o[0][dt][j] = v; ss += v * v; }
;     ss += __shfl_xor(ss, 16); ss += __shfl_xor(ss, 32);
;     const float rs = __builtin_amdgcn_rsqf(ss * (1.0f / 128.0f) + EPS) * 0.8f;
;     bf16_t* op = UQ + (size_t)(row0 + q0 + 16 * w + r16) * DM + 512 + 128 * h + 4 * fq;
; #pragma unroll
;     for (int dt = 0; dt < 8; ++dt) {
;         const f32x4 gsl = *(const f32x4*)(subln + 16 * dt + 4 * fq);
;         u32x2 wv; wv.x = cvtpk(o[0][dt][0] * rs * gsl[0], o[0][dt][1] * rs * gsl[1]); wv.y = cvtpk(o[0][dt][2] * rs * gsl[2], o[0][dt][3] * rs * gsl[3]);
;         *(u32x2*)(op + 16 * dt) = wv;
;     }
;     AT_BAR(0);
	v_mfma_f32_16x16x32_bf16 v[2:5], v[126:129], v[30:33], v[2:5]
	v_add_f32_e32 v30, v84, v85
	v_add_f32_e32 v30, v82, v30
	v_add_f32_e32 v30, v83, v30
	v_add_f32_e32 v30, v30, v88
	v_mfma_f32_16x16x32_bf16 v[14:17], v[102:105], v[50:53], v[14:17]
	v_add_f32_e32 v30, v89, v30
	v_add_f32_e32 v30, v86, v30
	v_pk_mul_f32 v[92:93], v[60:61], v[60:61]
	v_add_f32_e32 v30, v87, v30
	v_pk_fma_f32 v[62:63], v[64:65], v[108:109], v[62:63] op_sel_hi:[0,1,1] neg_lo:[0,0,1] neg_hi:[0,0,1]
	v_add_f32_e32 v30, v30, v92
	v_pk_mul_f32 v[90:91], v[62:63], v[62:63]
	v_mfma_f32_16x16x32_bf16 v[14:17], v[122:125], v[38:41], v[14:17]
	v_add_f32_e32 v30, v93, v30
	v_add_f32_e32 v30, v90, v30
	v_add_f32_e32 v30, v91, v30
	v_mfma_f32_16x16x32_bf16 v[6:9], v[66:69], v[50:53], v[26:29]
	v_add_f32_e32 v24, v30, v24
	s_nop 2
	v_pk_mul_f32 v[14:15], v[78:79], v[14:15] op_sel_hi:[0,1]
	v_add_f32_e32 v24, v25, v24
	v_mfma_f32_16x16x32_bf16 v[6:9], v[126:129], v[38:41], v[6:9]
	v_fma_f32 v10, v64, v10, -v14
	v_fma_f32 v11, v64, v11, -v15
	v_add_f32_e32 v24, v96, v24
	v_pk_mul_f32 v[16:17], v[78:79], v[16:17] op_sel_hi:[0,1]
	v_pk_mul_f32 v[14:15], v[10:11], v[10:11]
	v_add_f32_e32 v24, v97, v24
	v_pk_fma_f32 v[12:13], v[64:65], v[12:13], v[16:17] op_sel_hi:[0,1,1] neg_lo:[0,0,1] neg_hi:[0,0,1]
	v_add_f32_e32 v14, v24, v14
	v_pk_mul_f32 v[16:17], v[12:13], v[12:13]
	v_pk_mul_f32 v[6:7], v[78:79], v[6:7] op_sel_hi:[0,1]
	v_add_f32_e32 v14, v15, v14
	v_pk_fma_f32 v[6:7], v[64:65], v[2:3], v[6:7] op_sel_hi:[0,1,1] neg_lo:[0,0,1] neg_hi:[0,0,1]
	v_add_f32_e32 v14, v16, v14
	v_pk_mul_f32 v[8:9], v[78:79], v[8:9] op_sel_hi:[0,1]
	v_pk_mul_f32 v[2:3], v[6:7], v[6:7]
	v_add_f32_e32 v14, v17, v14
	v_pk_fma_f32 v[8:9], v[64:65], v[4:5], v[8:9] op_sel_hi:[0,1,1] neg_lo:[0,0,1] neg_hi:[0,0,1]
	v_add_f32_e32 v2, v14, v2
	v_pk_mul_f32 v[4:5], v[8:9], v[8:9]
	v_pk_mul_f32 v[26:27], v[78:79], v[58:59] op_sel_hi:[0,1]
	v_add_f32_e32 v2, v3, v2
	v_pk_fma_f32 v[26:27], v[64:65], v[54:55], v[26:27] op_sel_hi:[0,1,1] neg_lo:[0,0,1] neg_hi:[0,0,1]
	v_add_f32_e32 v2, v4, v2
	v_pk_mul_f32 v[28:29], v[26:27], v[26:27]
	v_add_f32_e32 v2, v5, v2
	v_add_f32_e32 v2, v2, v28
	v_add_f32_e32 v2, v29, v2
	v_add_f32_e32 v2, v74, v2
	v_add_f32_e32 v2, v75, v2
	v_add_f32_e32 v2, v2, v76
	v_pk_mul_f32 v[80:81], v[48:49], v[48:49]
	v_add_f32_e32 v2, v77, v2
	v_add_f32_e32 v2, v80, v2
	v_add_f32_e32 v2, v81, v2
	ds_bpermute_b32 v3, v1, v2
	v_lshl_add_u64 v[14:15], v[162:163], 0, v[154:155]
	s_waitcnt lgkmcnt(0)
	v_add_f32_e32 v2, v2, v3
	ds_bpermute_b32 v3, v157, v2
	s_waitcnt lgkmcnt(0)
	v_add_f32_e32 v2, v2, v3
	v_fmamk_f32 v2, v2, 0x3c000000, v211
	v_rsq_f32_e32 v2, v2
	s_nop 0
	v_mul_f32_e32 v16, 0x3f4ccccd, v2
	v_pk_mul_f32 v[2:3], v[42:43], v[16:17] op_sel_hi:[1,0]
	v_pk_mul_f32 v[4:5], v[44:45], v[16:17] op_sel_hi:[1,0]
	s_waitcnt vmcnt(0)
	v_pk_mul_f32 v[2:3], v[18:19], v[2:3]
	v_pk_mul_f32 v[4:5], v[20:21], v[4:5]
	v_cvt_pk_bf16_f32 v2, v2, v3
	v_cvt_pk_bf16_f32 v3, v4, v5
	global_store_dwordx2 v[14:15], v[2:3], off offset:1024 sc1
	global_load_dwordx4 v[2:5], v[158:159], off offset:64
	v_pk_mul_f32 v[18:19], v[70:71], v[16:17] op_sel_hi:[1,0]
	v_pk_mul_f32 v[20:21], v[94:95], v[16:17] op_sel_hi:[1,0]
	v_pk_mul_f32 v[10:11], v[10:11], v[16:17] op_sel_hi:[1,0]
	v_pk_mul_f32 v[12:13], v[12:13], v[16:17] op_sel_hi:[1,0]
	v_pk_mul_f32 v[6:7], v[6:7], v[16:17] op_sel_hi:[1,0]
	v_pk_mul_f32 v[8:9], v[8:9], v[16:17] op_sel_hi:[1,0]
	s_waitcnt vmcnt(0)
	v_pk_mul_f32 v[2:3], v[2:3], v[18:19]
	v_pk_mul_f32 v[18:19], v[72:73], v[16:17] op_sel_hi:[1,0]
	v_cvt_pk_bf16_f32 v2, v2, v3
	v_pk_mul_f32 v[4:5], v[4:5], v[18:19]
	v_pk_mul_f32 v[18:19], v[60:61], v[16:17] op_sel_hi:[1,0]
	v_cvt_pk_bf16_f32 v3, v4, v5
	global_store_dwordx2 v[14:15], v[2:3], off offset:1056 sc1
	global_load_dwordx4 v[2:5], v[158:159], off offset:128
	s_waitcnt vmcnt(0)
	v_pk_mul_f32 v[2:3], v[2:3], v[18:19]
	v_pk_mul_f32 v[18:19], v[62:63], v[16:17] op_sel_hi:[1,0]
	v_cvt_pk_bf16_f32 v2, v2, v3
	v_pk_mul_f32 v[4:5], v[4:5], v[18:19]
	v_pk_mul_f32 v[18:19], v[22:23], v[16:17] op_sel_hi:[1,0]
	v_cvt_pk_bf16_f32 v3, v4, v5
	global_store_dwordx2 v[14:15], v[2:3], off offset:1088 sc1
	global_load_dwordx4 v[2:5], v[158:159], off offset:192
	s_waitcnt vmcnt(0)
	v_pk_mul_f32 v[2:3], v[2:3], v[18:19]
	v_pk_mul_f32 v[4:5], v[4:5], v[20:21]
	v_cvt_pk_bf16_f32 v2, v2, v3
	v_cvt_pk_bf16_f32 v3, v4, v5
	global_store_dwordx2 v[14:15], v[2:3], off offset:1120 sc1
	global_load_dwordx4 v[2:5], v[158:159], off offset:256
	s_waitcnt vmcnt(0)
	v_pk_mul_f32 v[2:3], v[2:3], v[10:11]
	v_pk_mul_f32 v[4:5], v[4:5], v[12:13]
	v_cvt_pk_bf16_f32 v2, v2, v3
	v_cvt_pk_bf16_f32 v3, v4, v5
	global_store_dwordx2 v[14:15], v[2:3], off offset:1152 sc1
	global_load_dwordx4 v[2:5], v[158:159], off offset:320
	s_waitcnt vmcnt(0)
	v_pk_mul_f32 v[2:3], v[2:3], v[6:7]
	v_pk_mul_f32 v[4:5], v[4:5], v[8:9]
	v_cvt_pk_bf16_f32 v2, v2, v3
	v_cvt_pk_bf16_f32 v3, v4, v5
	global_store_dwordx2 v[14:15], v[2:3], off offset:1184 sc1
	global_load_dwordx4 v[2:5], v[158:159], off offset:384
	v_pk_mul_f32 v[6:7], v[26:27], v[16:17] op_sel_hi:[1,0]
	v_pk_mul_f32 v[8:9], v[56:57], v[16:17] op_sel_hi:[1,0]
	s_waitcnt vmcnt(0)
	v_pk_mul_f32 v[2:3], v[2:3], v[6:7]
	v_pk_mul_f32 v[4:5], v[4:5], v[8:9]
	v_cvt_pk_bf16_f32 v2, v2, v3
	v_cvt_pk_bf16_f32 v3, v4, v5
	global_store_dwordx2 v[14:15], v[2:3], off offset:1216 sc1
	global_load_dwordx4 v[2:5], v[158:159], off offset:448
	v_pk_mul_f32 v[6:7], v[46:47], v[16:17] op_sel_hi:[1,0]
	v_pk_mul_f32 v[8:9], v[48:49], v[16:17] op_sel_hi:[1,0]
	s_waitcnt vmcnt(0)
	v_pk_mul_f32 v[2:3], v[6:7], v[2:3]
	v_pk_mul_f32 v[4:5], v[8:9], v[4:5]
	v_cvt_pk_bf16_f32 v2, v2, v3
	v_cvt_pk_bf16_f32 v3, v4, v5
	global_store_dwordx2 v[14:15], v[2:3], off offset:1248 sc1
	s_waitcnt vmcnt(0) lgkmcnt(0)
	s_barrier
	s_cbranch_scc1 .LBB0_520

; __device__ __forceinline__ void attn_pv(unsigned vaddr, const int (&vo)[8], const bf16x8 (&pf)[2][2], f32x4 (&o)[2][8], f32x4 (&ol)[2]) {
;     s16x4 r[3][4];
;     ...
;     AT_TR4(0, 0); AT_TR4(1, 1);
;     { const bf16x8 ones = (bf16x8){0x3f80, 0x3f80, 0x3f80, 0x3f80, 0x3f80, 0x3f80, 0x3f80, 0x3f80};
; template <bool QK, bool PV> ...
;     ...
;     if constexpr (PV) { AT_TR4(0, 0); AT_TR4(1, 1);
;         const bf16x8 ones = (bf16x8){0x3f80, 0x3f80, 0x3f80, 0x3f80, 0x3f80, 0x3f80, 0x3f80, 0x3f80};
; #pragma unroll
;         for (int c = 0; c < 2; ++c)
; #pragma unroll
;             for (int si = 0; si < 2; ++si) ol[c] = __builtin_amdgcn_mfma_f32_16x16x32_bf16(ones, pf[c][si], ol[c], 0, 0, 0); }
; #pragma unroll
;     for (int dt = 0; dt < 8; ++dt) {
;         if constexpr (PV) {
;             const int cb = dt % 3;
;             if (dt < 6) { AT_TR4((dt + 2) % 3, dt + 2); asm volatile("s_waitcnt lgkmcnt(8)" : "+v"(r[cb][0]), "+v"(r[cb][1]), "+v"(r[cb][2]), "+v"(r[cb][3])); }
;             else if (dt == 6) asm volatile("s_waitcnt lgkmcnt(4)" : "+v"(r[cb][0]), "+v"(r[cb][1]), "+v"(r[cb][2]), "+v"(r[cb][3]));
;             else asm volatile("s_waitcnt lgkmcnt(0)" : "+v"(r[cb][0]), "+v"(r[cb][1]), "+v"(r[cb][2]), "+v"(r[cb][3]));
; #pragma unroll
;             for (int si = 0; si < 2; ++si) {
;                 const s16x4 lo = r[cb][2 * si], hi = r[cb][2 * si + 1];
;                 const bf16x8 vf = (bf16x8){lo[0], lo[1], lo[2], lo[3], hi[0], hi[1], hi[2], hi[3]};
;                 o[0][dt] = __builtin_amdgcn_mfma_f32_16x16x32_bf16(vf, pf[0][si], o[0][dt], 0, 0, 0);
;                 o[1][dt] = __builtin_amdgcn_mfma_f32_16x16x32_bf16(vf, pf[1][si], o[1][dt], 0, 0, 0);
;             }
;         }
;         {
;             const int c = dt >> 2, kt = dt & 3;
; #pragma unroll
;             for (int j = 0; j < 4; ++j) s[c][kt][j] = fast_exp2(s[c][kt][j]);
;             if (kt & 1) { const int si = kt >> 1;
;                 u32x4 wv; wv.x = cvtpk(s[c][2 * si][0], s[c][2 * si][1]); wv.y = cvtpk(s[c][2 * si][2], s[c][2 * si][3]);
;                 wv.z = cvtpk(s[c][2 * si + 1][0], s[c][2 * si + 1][1]); wv.w = cvtpk(s[c][2 * si + 1][2], s[c][2 * si + 1][3]);
;                 pn[c][si] = __builtin_bit_cast(bf16x8, wv); }
;         }
;     }
;     ...
; #pragma unroll
;     for (int c = 0; c < 2; ++c)
; #pragma unroll
;         for (int si = 0; si < 2; ++si) pf[c][si] = pn[c][si];
.Lat_yskip_p:
	v_mov_b64_e32 v[140:141], s[6:7]
	v_mov_b64_e32 v[138:139], s[4:5]
	ds_read_b64_tr_b16 v[2:3], v192 offset:0
	ds_read_b64_tr_b16 v[4:5], v192 offset:0x1000
	ds_read_b64_tr_b16 v[10:11], v192 offset:0x2000
	ds_read_b64_tr_b16 v[12:13], v192 offset:0x3000
	v_exp_f32_e32 v154, v74
	s_nop 0
	v_mfma_f32_16x16x32_bf16 v[6:9], v[138:141], v[58:61], v[134:137]
	v_exp_f32_e32 v164, v75
	v_exp_f32_e32 v90, v90
	v_exp_f32_e32 v91, v91
	v_mfma_f32_16x16x32_bf16 v[134:137], v[138:141], v[34:37], v[6:9]
	ds_read_b64_tr_b16 v[6:7], v193 offset:0
	ds_read_b64_tr_b16 v[8:9], v193 offset:0x1000
	ds_read_b64_tr_b16 v[14:15], v193 offset:0x2000
	ds_read_b64_tr_b16 v[16:17], v193 offset:0x3000
	ds_read_b64_tr_b16 v[142:143], v194 offset:0
	ds_read_b64_tr_b16 v[144:145], v194 offset:0x1000
	ds_read_b64_tr_b16 v[146:147], v194 offset:0x2000
	ds_read_b64_tr_b16 v[148:149], v194 offset:0x3000
	s_waitcnt lgkmcnt(8)
	ds_read_b64_tr_b16 v[150:151], v195 offset:0
	ds_read_b64_tr_b16 v[152:153], v195 offset:0x1000
	v_mfma_f32_16x16x32_bf16 v[130:133], v[138:141], v[42:45], v[130:133]
	v_exp_f32_e32 v92, v92
	v_exp_f32_e32 v93, v93
	v_exp_f32_e32 v94, v94
	v_mfma_f32_16x16x32_bf16 v[126:129], v[2:5], v[58:61], v[126:129]
	v_exp_f32_e32 v95, v95
	v_exp_f32_e32 v96, v96
	v_exp_f32_e32 v97, v97
	v_mfma_f32_16x16x32_bf16 v[2:5], v[2:5], v[42:45], v[122:125]
	v_exp_f32_e32 v38, v38
	v_exp_f32_e32 v39, v39
	v_exp_f32_e32 v40, v40
	v_mfma_f32_16x16x32_bf16 v[122:125], v[10:13], v[34:37], v[126:129]
	v_exp_f32_e32 v41, v41
	v_exp_f32_e32 v62, v62
	v_exp_f32_e32 v63, v63
	v_mfma_f32_16x16x32_bf16 v[126:129], v[10:13], v[18:21], v[2:5]
	ds_read_b64_tr_b16 v[2:3], v195 offset:0x2000
	ds_read_b64_tr_b16 v[4:5], v195 offset:0x3000
	s_waitcnt lgkmcnt(8)
	v_mfma_f32_16x16x32_bf16 v[130:133], v[138:141], v[18:21], v[130:133]
	v_cvt_pk_bf16_f32 v38, v38, v39
	v_cvt_pk_bf16_f32 v39, v40, v41
	v_cvt_pk_bf16_f32 v40, v62, v63
	v_mfma_f32_16x16x32_bf16 v[10:13], v[6:9], v[58:61], v[114:117]
	s_add_i32 s43, s43, s30
	s_add_i32 s42, s42, s30
	s_cmpk_gt_i32 s43, 0x3ff
	v_mfma_f32_16x16x32_bf16 v[6:9], v[6:9], v[42:45], v[118:121]
	v_mfma_f32_16x16x32_bf16 v[118:121], v[14:17], v[34:37], v[10:13]
	ds_read_b64_tr_b16 v[10:11], v196 offset:0
	ds_read_b64_tr_b16 v[12:13], v196 offset:0x1000
	v_mfma_f32_16x16x32_bf16 v[114:117], v[14:17], v[18:21], v[6:9]
	ds_read_b64_tr_b16 v[14:15], v196 offset:0x2000
	ds_read_b64_tr_b16 v[16:17], v196 offset:0x3000
	s_waitcnt lgkmcnt(8)
	s_nop 0
	v_mfma_f32_16x16x32_bf16 v[6:9], v[142:145], v[58:61], v[106:109]
	v_mfma_f32_16x16x32_bf16 v[106:109], v[142:145], v[42:45], v[110:113]
	ds_read_b64_tr_b16 v[142:143], v197 offset:0
	ds_read_b64_tr_b16 v[144:145], v197 offset:0x1000
	v_mfma_f32_16x16x32_bf16 v[110:113], v[146:149], v[34:37], v[6:9]
	v_mfma_f32_16x16x32_bf16 v[106:109], v[146:149], v[18:21], v[106:109]
	ds_read_b64_tr_b16 v[146:147], v197 offset:0x2000
	ds_read_b64_tr_b16 v[148:149], v197 offset:0x3000
	s_waitcnt lgkmcnt(8)
	s_nop 0
	v_mfma_f32_16x16x32_bf16 v[6:9], v[150:153], v[58:61], v[98:101]
	s_nop 2
	v_exp_f32_e32 v98, v76
	v_exp_f32_e32 v99, v77
	v_mfma_f32_16x16x32_bf16 v[74:77], v[150:153], v[42:45], v[102:105]
	v_exp_f32_e32 v100, v86
	v_exp_f32_e32 v101, v87
	ds_read_b64_tr_b16 v[86:87], v198 offset:0
	v_mfma_f32_16x16x32_bf16 v[6:9], v[2:5], v[34:37], v[6:9]
	v_exp_f32_e32 v102, v88
	v_exp_f32_e32 v103, v89
	ds_read_b64_tr_b16 v[88:89], v198 offset:0x1000
	v_mfma_f32_16x16x32_bf16 v[2:5], v[2:5], v[18:21], v[74:77]
	ds_read_b64_tr_b16 v[74:75], v198 offset:0x2000
	ds_read_b64_tr_b16 v[76:77], v198 offset:0x3000
	s_waitcnt lgkmcnt(8)
	v_exp_f32_e32 v104, v22
	v_mfma_f32_16x16x32_bf16 v[78:81], v[10:13], v[58:61], v[78:81]
	v_exp_f32_e32 v105, v23
	v_exp_f32_e32 v150, v24
	v_mfma_f32_16x16x32_bf16 v[82:85], v[10:13], v[42:45], v[82:85]
	v_mfma_f32_16x16x32_bf16 v[10:13], v[14:17], v[34:37], v[78:81]
	ds_read_b64_tr_b16 v[78:79], v199 offset:0
	ds_read_b64_tr_b16 v[80:81], v199 offset:0x1000
	v_mfma_f32_16x16x32_bf16 v[14:17], v[14:17], v[18:21], v[82:85]
	ds_read_b64_tr_b16 v[82:83], v199 offset:0x2000
	ds_read_b64_tr_b16 v[84:85], v199 offset:0x3000
	s_waitcnt lgkmcnt(8)
	s_waitcnt lgkmcnt(4)
	s_nop 0
	v_mfma_f32_16x16x32_bf16 v[66:69], v[142:145], v[58:61], v[66:69]
	s_waitcnt lgkmcnt(0)
	v_mfma_f32_16x16x32_bf16 v[54:57], v[86:89], v[58:61], v[54:57]
	v_mfma_f32_16x16x32_bf16 v[58:61], v[78:81], v[58:61], v[30:33]
	v_mfma_f32_16x16x32_bf16 v[70:73], v[142:145], v[42:45], v[70:73]
	v_exp_f32_e32 v142, v25
	v_exp_f32_e32 v143, v26
	v_exp_f32_e32 v144, v27
	v_mfma_f32_16x16x32_bf16 v[22:25], v[146:149], v[34:37], v[66:69]
	v_cvt_pk_bf16_f32 v30, v90, v91
	v_cvt_pk_bf16_f32 v31, v92, v93
	v_cvt_pk_bf16_f32 v32, v94, v95
	v_exp_f32_e32 v66, v28
	v_exp_f32_e32 v67, v29
	v_mfma_f32_16x16x32_bf16 v[50:53], v[86:89], v[42:45], v[50:53]
	v_exp_f32_e32 v68, v64
	v_exp_f32_e32 v69, v65
	v_cvt_pk_bf16_f32 v33, v96, v97
	v_mfma_f32_16x16x32_bf16 v[54:57], v[74:77], v[34:37], v[54:57]
	v_cvt_pk_bf16_f32 v41, v68, v69
	v_mfma_f32_16x16x32_bf16 v[42:45], v[78:81], v[42:45], v[46:49]
	v_mfma_f32_16x16x32_bf16 v[46:49], v[82:85], v[34:37], v[58:61]
	v_cvt_pk_bf16_f32 v34, v154, v164
	v_cvt_pk_bf16_f32 v35, v98, v99
	v_cvt_pk_bf16_f32 v36, v100, v101
	v_cvt_pk_bf16_f32 v37, v102, v103
	v_mfma_f32_16x16x32_bf16 v[62:65], v[74:77], v[18:21], v[50:53]
	v_lshlrev_b32_e32 v154, 1, v156
	v_mfma_f32_16x16x32_bf16 v[58:61], v[138:141], v[34:37], v[134:137]
	s_nop 0
	v_cvt_pk_bf16_f32 v50, v104, v105
	v_cvt_pk_bf16_f32 v51, v150, v142
	v_cvt_pk_bf16_f32 v52, v143, v144
	v_cvt_pk_bf16_f32 v53, v66, v67
	v_mfma_f32_16x16x32_bf16 v[58:61], v[138:141], v[30:33], v[58:61]
	s_nop 0
	v_mfma_f32_16x16x32_bf16 v[78:81], v[138:141], v[50:53], v[130:133]
	v_mfma_f32_16x16x32_bf16 v[78:81], v[138:141], v[38:41], v[78:81]
	s_nop 4
	v_div_scale_f32 v59, s[2:3], v58, v58, 1.0
	v_mfma_f32_16x16x32_bf16 v[26:29], v[146:149], v[18:21], v[70:73]
	v_mfma_f32_16x16x32_bf16 v[18:21], v[82:85], v[18:21], v[42:45]
	v_rcp_f32_e32 v79, v59
	ds_read_b64_tr_b16 v[42:43], v200 offset:0
	ds_read_b64_tr_b16 v[44:45], v200 offset:0x1000
	ds_read_b64_tr_b16 v[66:67], v200 offset:0x2000
	ds_read_b64_tr_b16 v[68:69], v200 offset:0x3000
	ds_read_b64_tr_b16 v[70:71], v201 offset:0
	ds_read_b64_tr_b16 v[72:73], v201 offset:0x1000
	ds_read_b64_tr_b16 v[74:75], v201 offset:0x2000
	ds_read_b64_tr_b16 v[76:77], v201 offset:0x3000
	ds_read_b64_tr_b16 v[82:83], v202 offset:0
	ds_read_b64_tr_b16 v[84:85], v202 offset:0x1000
	ds_read_b64_tr_b16 v[86:87], v202 offset:0x2000
	ds_read_b64_tr_b16 v[88:89], v202 offset:0x3000
	s_nop 0
	s_waitcnt lgkmcnt(8)
; #define AT_TR4(slot, d) do { const unsigned _a = vaddr + (unsigned)vo[d]; AT_TR(r[slot][0], _a, 0); AT_TR(r[slot][1], _a, 16 * 256); AT_TR(r[slot][2], _a, 32 * 256); AT_TR(r[slot][3], _a, 48 * 256); } while (0)
; #define AT_TR4(slot, d) do { const unsigned _a = vaddr + (unsigned)vo[d]; AT_TR(r[slot][0], _a, 0); AT_TR(r[slot][1], _a, 16 * 256); AT_TR(r[slot][2], _a, 32 * 256); AT_TR(r[slot][3], _a, 48 * 256); } while (0)
; __device__ __forceinline__ void attn_pv(unsigned vaddr, const int (&vo)[8], const bf16x8 (&pf)[2][2], f32x4 (&o)[2][8], f32x4 (&ol)[2]) {
;     ...
; #pragma unroll
;     for (int dt = 0; dt < 8; ++dt) {
;         const int cb = dt % 3;
;         if (dt < 6) { AT_TR4((dt + 2) % 3, dt + 2); asm volatile("s_waitcnt lgkmcnt(8)" : "+v"(r[cb][0]), "+v"(r[cb][1]), "+v"(r[cb][2]), "+v"(r[cb][3])); }
;         else if (dt == 6) asm volatile("s_waitcnt lgkmcnt(4)" : "+v"(r[cb][0]), "+v"(r[cb][1]), "+v"(r[cb][2]), "+v"(r[cb][3]));
;         else asm volatile("s_waitcnt lgkmcnt(0)" : "+v"(r[cb][0]), "+v"(r[cb][1]), "+v"(r[cb][2]), "+v"(r[cb][3]));
; #pragma unroll
;         for (int si = 0; si < 2; ++si) {
;             const s16x4 lo = r[cb][2 * si], hi = r[cb][2 * si + 1];
;             const bf16x8 vf = (bf16x8){lo[0], lo[1], lo[2], lo[3], hi[0], hi[1], hi[2], hi[3]};
;             o[0][dt] = __builtin_amdgcn_mfma_f32_16x16x32_bf16(vf, pf[0][si], o[0][dt], 0, 0, 0);
;             o[1][dt] = __builtin_amdgcn_mfma_f32_16x16x32_bf16(vf, pf[1][si], o[1][dt], 0, 0, 0);
;         }
;     }
;     ...
; }
; __device__ __forceinline__ void attn_unit(LAS unsigned char* lds, int seq, int h, int qb, bf16_t* UQ, const bf16_t* KB, const bf16_t* VB, const float* rel_bias, const float* subln, float lam, float bmax) {
;     ...
;     const float i0 = 1.0f / ol[0][0], i1 = lam / ol[1][0];
;     float ss = 0.f;
; #pragma unroll
;     for (int dt = 0; dt < 8; ++dt)
; #pragma unroll
;         for (int j = 0; j < 4; ++j) { const float v = o[0][dt][j] * i0 - o[1][dt][j] * i1; o[0][dt][j] = v; ss += v * v; }
	ds_read_b64_tr_b16 v[90:91], v203 offset:0
	ds_read_b64_tr_b16 v[92:93], v203 offset:0x1000
	ds_read_b64_tr_b16 v[98:99], v203 offset:0x2000
	ds_read_b64_tr_b16 v[100:101], v203 offset:0x3000
	s_waitcnt lgkmcnt(8)
	s_nop 0
	v_mfma_f32_16x16x32_bf16 v[94:97], v[42:45], v[34:37], v[122:125]
	v_fma_f32 v60, -v59, v79, 1.0
	ds_read_b64_tr_b16 v[102:103], v204 offset:0
	ds_read_b64_tr_b16 v[104:105], v204 offset:0x1000
	v_mfma_f32_16x16x32_bf16 v[42:45], v[42:45], v[50:53], v[126:129]
	ds_read_b64_tr_b16 v[122:123], v204 offset:0x2000
	ds_read_b64_tr_b16 v[124:125], v204 offset:0x3000
	s_waitcnt lgkmcnt(8)
	v_mfma_f32_16x16x32_bf16 v[118:121], v[70:73], v[34:37], v[118:121]
	v_fmac_f32_e32 v79, v60, v79
	v_div_scale_f32 v60, vcc, 1.0, v58, 1.0
	v_mfma_f32_16x16x32_bf16 v[70:73], v[70:73], v[50:53], v[114:117]
	v_mfma_f32_16x16x32_bf16 v[110:113], v[82:85], v[34:37], v[110:113]
	v_mfma_f32_16x16x32_bf16 v[80:83], v[82:85], v[50:53], v[106:109]
	v_mul_f32_e32 v84, v60, v79
	v_fma_f32 v61, -v59, v84, v60
	v_fmac_f32_e32 v84, v61, v79
	v_mfma_f32_16x16x32_bf16 v[94:97], v[66:69], v[30:33], v[94:97]
	v_fma_f32 v59, -v59, v84, v60
	v_div_fmas_f32 v59, v59, v79, v84
	v_mfma_f32_16x16x32_bf16 v[42:45], v[66:69], v[38:41], v[42:45]
	ds_read_b64_tr_b16 v[66:67], v205 offset:0
	ds_read_b64_tr_b16 v[68:69], v205 offset:0x1000
	ds_read_b64_tr_b16 v[126:127], v205 offset:0x2000
	ds_read_b64_tr_b16 v[128:129], v205 offset:0x3000
	s_waitcnt lgkmcnt(8)
	ds_read_b64_tr_b16 v[130:131], v206 offset:0
	ds_read_b64_tr_b16 v[132:133], v206 offset:0x1000
	ds_read_b64_tr_b16 v[114:115], v206 offset:0x2000
	ds_read_b64_tr_b16 v[116:117], v206 offset:0x3000
	v_mfma_f32_16x16x32_bf16 v[118:121], v[74:77], v[30:33], v[118:121]
	s_waitcnt lgkmcnt(8)
	ds_read_b64_tr_b16 v[134:135], v207 offset:0
	ds_read_b64_tr_b16 v[136:137], v207 offset:0x1000
	v_mfma_f32_16x16x32_bf16 v[70:73], v[74:77], v[38:41], v[70:73]
	ds_read_b64_tr_b16 v[74:75], v207 offset:0x2000
	ds_read_b64_tr_b16 v[76:77], v207 offset:0x3000
	s_waitcnt lgkmcnt(8)
	s_waitcnt lgkmcnt(4)
	v_mfma_f32_16x16x32_bf16 v[2:5], v[90:93], v[50:53], v[2:5]
	s_waitcnt lgkmcnt(0)
	v_mfma_f32_16x16x32_bf16 v[60:63], v[130:133], v[50:53], v[62:65]
	s_nop 2
	v_div_scale_f32 v65, s[2:3], v78, v78, v174
	v_rcp_f32_e32 v85, v65
	v_mfma_f32_16x16x32_bf16 v[18:21], v[134:137], v[50:53], v[18:21]
	v_div_fixup_f32 v64, v59, v58, 1.0
	v_fma_f32 v79, -v65, v85, 1.0
	v_mfma_f32_16x16x32_bf16 v[58:61], v[114:117], v[38:41], v[60:63]
	v_fmac_f32_e32 v85, v79, v85
	s_nop 1
	v_div_scale_f32 v62, vcc, v174, v78, v174
	v_mfma_f32_16x16x32_bf16 v[46:49], v[134:137], v[34:37], v[46:49]
	v_mul_f32_e32 v63, v62, v85
	v_fma_f32 v79, -v65, v63, v62
	v_fmac_f32_e32 v63, v79, v85
	v_mfma_f32_16x16x32_bf16 v[18:21], v[74:77], v[38:41], v[18:21]
	v_fma_f32 v62, -v65, v63, v62
	v_div_fmas_f32 v62, v62, v85, v63
	v_div_fixup_f32 v78, v62, v78, v174
	v_mfma_f32_16x16x32_bf16 v[46:49], v[74:77], v[30:33], v[46:49]
	v_mul_f32_e64 v42, v78, v42
	v_mul_f32_e64 v43, v78, v43
	s_nop 1
	v_pk_mul_f32 v[18:19], v[78:79], v[18:19] op_sel_hi:[0,1]
	v_pk_fma_f32 v[42:43], v[64:65], v[94:95], v[42:43] op_sel_hi:[0,1,1] neg_lo:[0,0,1] neg_hi:[0,0,1]
	v_mfma_f32_16x16x32_bf16 v[6:9], v[90:93], v[34:37], v[6:9]
	v_mul_f32_e64 v44, v78, v44
	v_mul_f32_e64 v45, v78, v45
	v_pk_fma_f32 v[46:47], v[64:65], v[46:47], v[18:19] op_sel_hi:[0,1,1] neg_lo:[0,0,1] neg_hi:[0,0,1]
	v_pk_mul_f32 v[18:19], v[78:79], v[20:21] op_sel_hi:[0,1]
	v_pk_fma_f32 v[48:49], v[64:65], v[48:49], v[18:19] op_sel_hi:[0,1,1] neg_lo:[0,0,1] neg_hi:[0,0,1]
	global_load_dwordx4 v[18:21], v[158:159], off
	v_mfma_f32_16x16x32_bf16 v[2:5], v[98:101], v[38:41], v[2:5]
	v_mul_f32_e64 v60, v78, v60
	v_mul_f32_e64 v61, v78, v61
	v_pk_fma_f32 v[44:45], v[64:65], v[96:97], v[44:45] op_sel_hi:[0,1,1] neg_lo:[0,0,1] neg_hi:[0,0,1]
	v_pk_mul_f32 v[84:85], v[42:43], v[42:43]
	v_mfma_f32_16x16x32_bf16 v[54:57], v[130:133], v[34:37], v[54:57]
	v_mul_f32_e64 v70, v78, v70
	v_mul_f32_e64 v71, v78, v71
	s_nop 0
	v_pk_mul_f32 v[4:5], v[78:79], v[4:5] op_sel_hi:[0,1]
	v_pk_fma_f32 v[70:71], v[64:65], v[118:119], v[70:71] op_sel_hi:[0,1,1] neg_lo:[0,0,1] neg_hi:[0,0,1]
	v_mfma_f32_16x16x32_bf16 v[6:9], v[98:101], v[30:33], v[6:9]
	v_mul_f32_e64 v72, v78, v72
	v_mul_f32_e64 v73, v78, v73
	v_pk_fma_f32 v[72:73], v[64:65], v[120:121], v[72:73] op_sel_hi:[0,1,1] neg_lo:[0,0,1] neg_hi:[0,0,1]
	v_pk_mul_f32 v[76:77], v[46:47], v[46:47]
	v_mfma_f32_16x16x32_bf16 v[54:57], v[114:117], v[30:33], v[54:57]
	v_mfma_f32_16x16x32_bf16 v[10:13], v[102:105], v[34:37], v[10:13]
	s_nop 1
	v_fma_f32 v94, v64, v8, -v4
	v_fma_f32 v95, v64, v9, -v5
	v_pk_mul_f32 v[8:9], v[78:79], v[2:3] op_sel_hi:[0,1]
	s_nop 1
	v_pk_fma_f32 v[56:57], v[64:65], v[56:57], v[60:61] op_sel_hi:[0,1,1] neg_lo:[0,0,1] neg_hi:[0,0,1]
	v_mfma_f32_16x16x32_bf16 v[2:5], v[66:69], v[34:37], v[22:25]
	v_mul_f32_e64 v96, v94, v94
	v_mul_f32_e64 v97, v95, v95
	v_pk_mul_f32 v[74:75], v[56:57], v[56:57]
	v_mfma_f32_16x16x32_bf16 v[106:109], v[86:89], v[30:33], v[110:113]
	v_fma_f32 v22, v64, v6, -v8
	v_fma_f32 v23, v64, v7, -v9
	v_pk_mul_f32 v[24:25], v[22:23], v[22:23]
	v_mfma_f32_16x16x32_bf16 v[60:63], v[86:89], v[38:41], v[80:83]
	v_mul_f32_e64 v88, v70, v70
	v_mul_f32_e64 v89, v71, v71
	v_pk_mul_f32 v[86:87], v[72:73], v[72:73]
	v_pk_mul_f32 v[82:83], v[44:45], v[44:45]
	v_mfma_f32_16x16x32_bf16 v[10:13], v[122:125], v[30:33], v[10:13]
	s_nop 2
	v_mul_f32_e64 v60, v78, v60
	v_mul_f32_e64 v61, v78, v61
	v_pk_fma_f32 v[60:61], v[64:65], v[106:107], v[60:61] op_sel_hi:[0,1,1] neg_lo:[0,0,1] neg_hi:[0,0,1]
	v_pk_mul_f32 v[62:63], v[78:79], v[62:63] op_sel_hi:[0,1]
; __device__ __forceinline__ unsigned cvtpk(float lo, float hi) { f32x2 v = {lo, hi}; bf16x2_t b = __builtin_convertvector(v, bf16x2_t); return __builtin_bit_cast(unsigned, b); }
; #define AT_BAR(N) asm volatile("s_waitcnt vmcnt(" #N ") lgkmcnt(0)\n\ts_barrier" ::: "memory")
; __device__ __forceinline__ void attn_unit(LAS unsigned char* lds, int seq, int h, int qb, bf16_t* UQ, const bf16_t* KB, const bf16_t* VB, const float* rel_bias, const float* subln, float lam, float bmax) {
;     ...
;     const float i0 = 1.0f / ol[0][0], i1 = lam / ol[1][0];
;     float ss = 0.f;
; #pragma unroll
;     for (int dt = 0; dt < 8; ++dt)
; #pragma unroll
;         for (int j = 0; j < 4; ++j) { const float v = o[0][dt][j] * i0 - o[1][dt][j] * i1; o[0][dt][j] = v; ss += v * v; }
;     ss += __shfl_xor(ss, 16); ss += __shfl_xor(ss, 32);
;     const float rs = __builtin_amdgcn_rsqf(ss * (1.0f / 128.0f) + EPS) * 0.8f;
;     bf16_t* op = UQ + (size_t)(row0 + q0 + 16 * w + r16) * DM + 512 + 128 * h + 4 * fq;
; #pragma unroll
;     for (int dt = 0; dt < 8; ++dt) {
;         const f32x4 gsl = *(const f32x4*)(subln + 16 * dt + 4 * fq);
;         u32x2 wv; wv.x = cvtpk(o[0][dt][0] * rs * gsl[0], o[0][dt][1] * rs * gsl[1]); wv.y = cvtpk(o[0][dt][2] * rs * gsl[2], o[0][dt][3] * rs * gsl[3]);
;         *(u32x2*)(op + 16 * dt) = wv;
;     }
;     AT_BAR(0);
	v_mfma_f32_16x16x32_bf16 v[2:5], v[126:129], v[30:33], v[2:5]
	v_add_f32_e32 v30, v84, v85
	v_add_f32_e32 v30, v82, v30
	v_add_f32_e32 v30, v83, v30
	v_add_f32_e32 v30, v30, v88
	v_mfma_f32_16x16x32_bf16 v[14:17], v[102:105], v[50:53], v[14:17]
	v_add_f32_e32 v30, v89, v30
	v_add_f32_e32 v30, v86, v30
	v_pk_mul_f32 v[92:93], v[60:61], v[60:61]
	v_add_f32_e32 v30, v87, v30
	v_pk_fma_f32 v[62:63], v[64:65], v[108:109], v[62:63] op_sel_hi:[0,1,1] neg_lo:[0,0,1] neg_hi:[0,0,1]
	v_add_f32_e32 v30, v30, v92
	v_pk_mul_f32 v[90:91], v[62:63], v[62:63]
	v_mfma_f32_16x16x32_bf16 v[14:17], v[122:125], v[38:41], v[14:17]
	v_add_f32_e32 v30, v93, v30
	v_add_f32_e32 v30, v90, v30
	v_add_f32_e32 v30, v91, v30
	v_mfma_f32_16x16x32_bf16 v[6:9], v[66:69], v[50:53], v[26:29]
	v_add_f32_e32 v24, v30, v24
	s_nop 2
	v_pk_mul_f32 v[14:15], v[78:79], v[14:15] op_sel_hi:[0,1]
	v_add_f32_e32 v24, v25, v24
	v_mfma_f32_16x16x32_bf16 v[6:9], v[126:129], v[38:41], v[6:9]
	v_fma_f32 v10, v64, v10, -v14
	v_fma_f32 v11, v64, v11, -v15
	v_add_f32_e32 v24, v96, v24
	v_pk_mul_f32 v[16:17], v[78:79], v[16:17] op_sel_hi:[0,1]
	v_pk_mul_f32 v[14:15], v[10:11], v[10:11]
	v_add_f32_e32 v24, v97, v24
	v_pk_fma_f32 v[12:13], v[64:65], v[12:13], v[16:17] op_sel_hi:[0,1,1] neg_lo:[0,0,1] neg_hi:[0,0,1]
	v_add_f32_e32 v14, v24, v14
	v_pk_mul_f32 v[16:17], v[12:13], v[12:13]
	v_pk_mul_f32 v[6:7], v[78:79], v[6:7] op_sel_hi:[0,1]
	v_add_f32_e32 v14, v15, v14
	v_pk_fma_f32 v[6:7], v[64:65], v[2:3], v[6:7] op_sel_hi:[0,1,1] neg_lo:[0,0,1] neg_hi:[0,0,1]
	v_add_f32_e32 v14, v16, v14
	v_pk_mul_f32 v[8:9], v[78:79], v[8:9] op_sel_hi:[0,1]
	v_pk_mul_f32 v[2:3], v[6:7], v[6:7]
	v_add_f32_e32 v14, v17, v14
	v_pk_fma_f32 v[8:9], v[64:65], v[4:5], v[8:9] op_sel_hi:[0,1,1] neg_lo:[0,0,1] neg_hi:[0,0,1]
	v_add_f32_e32 v2, v14, v2
	v_pk_mul_f32 v[4:5], v[8:9], v[8:9]
	v_pk_mul_f32 v[26:27], v[78:79], v[58:59] op_sel_hi:[0,1]
	v_add_f32_e32 v2, v3, v2
	v_pk_fma_f32 v[26:27], v[64:65], v[54:55], v[26:27] op_sel_hi:[0,1,1] neg_lo:[0,0,1] neg_hi:[0,0,1]
	v_add_f32_e32 v2, v4, v2
	v_pk_mul_f32 v[28:29], v[26:27], v[26:27]
	v_add_f32_e32 v2, v5, v2
	v_add_f32_e32 v2, v2, v28
	v_add_f32_e32 v2, v29, v2
	v_add_f32_e32 v2, v74, v2
	v_add_f32_e32 v2, v75, v2
	v_add_f32_e32 v2, v2, v76
	v_pk_mul_f32 v[80:81], v[48:49], v[48:49]
	v_add_f32_e32 v2, v77, v2
	v_add_f32_e32 v2, v80, v2
	v_add_f32_e32 v2, v81, v2
	ds_bpermute_b32 v3, v1, v2
	v_lshl_add_u64 v[14:15], v[162:163], 0, v[154:155]
	s_waitcnt lgkmcnt(0)
	v_add_f32_e32 v2, v2, v3
	ds_bpermute_b32 v3, v157, v2
	s_waitcnt lgkmcnt(0)
	v_add_f32_e32 v2, v2, v3
	v_fmamk_f32 v2, v2, 0x3c000000, v209
	v_rsq_f32_e32 v2, v2
	s_nop 0
	v_mul_f32_e32 v16, 0x3f4ccccd, v2
	v_pk_mul_f32 v[2:3], v[42:43], v[16:17] op_sel_hi:[1,0]
	v_pk_mul_f32 v[4:5], v[44:45], v[16:17] op_sel_hi:[1,0]
	s_waitcnt vmcnt(0)
	v_pk_mul_f32 v[2:3], v[18:19], v[2:3]
	v_pk_mul_f32 v[4:5], v[20:21], v[4:5]
	v_cvt_pk_bf16_f32 v2, v2, v3
	v_cvt_pk_bf16_f32 v3, v4, v5
	global_store_dwordx2 v[14:15], v[2:3], off offset:1024 sc1
	global_load_dwordx4 v[2:5], v[158:159], off offset:64
	v_pk_mul_f32 v[18:19], v[70:71], v[16:17] op_sel_hi:[1,0]
	v_pk_mul_f32 v[20:21], v[94:95], v[16:17] op_sel_hi:[1,0]
	v_pk_mul_f32 v[10:11], v[10:11], v[16:17] op_sel_hi:[1,0]
	v_pk_mul_f32 v[12:13], v[12:13], v[16:17] op_sel_hi:[1,0]
	v_pk_mul_f32 v[6:7], v[6:7], v[16:17] op_sel_hi:[1,0]
	v_pk_mul_f32 v[8:9], v[8:9], v[16:17] op_sel_hi:[1,0]
	s_waitcnt vmcnt(0)
	v_pk_mul_f32 v[2:3], v[2:3], v[18:19]
	v_pk_mul_f32 v[18:19], v[72:73], v[16:17] op_sel_hi:[1,0]
	v_cvt_pk_bf16_f32 v2, v2, v3
	v_pk_mul_f32 v[4:5], v[4:5], v[18:19]
	v_pk_mul_f32 v[18:19], v[60:61], v[16:17] op_sel_hi:[1,0]
	v_cvt_pk_bf16_f32 v3, v4, v5
	global_store_dwordx2 v[14:15], v[2:3], off offset:1056 sc1
	global_load_dwordx4 v[2:5], v[158:159], off offset:128
	s_waitcnt vmcnt(0)
	v_pk_mul_f32 v[2:3], v[2:3], v[18:19]
	v_pk_mul_f32 v[18:19], v[62:63], v[16:17] op_sel_hi:[1,0]
	v_cvt_pk_bf16_f32 v2, v2, v3
	v_pk_mul_f32 v[4:5], v[4:5], v[18:19]
	v_pk_mul_f32 v[18:19], v[22:23], v[16:17] op_sel_hi:[1,0]
	v_cvt_pk_bf16_f32 v3, v4, v5
	global_store_dwordx2 v[14:15], v[2:3], off offset:1088 sc1
	global_load_dwordx4 v[2:5], v[158:159], off offset:192
	s_waitcnt vmcnt(0)
	v_pk_mul_f32 v[2:3], v[2:3], v[18:19]
	v_pk_mul_f32 v[4:5], v[4:5], v[20:21]
	v_cvt_pk_bf16_f32 v2, v2, v3
	v_cvt_pk_bf16_f32 v3, v4, v5
	global_store_dwordx2 v[14:15], v[2:3], off offset:1120 sc1
	global_load_dwordx4 v[2:5], v[158:159], off offset:256
	s_waitcnt vmcnt(0)
	v_pk_mul_f32 v[2:3], v[2:3], v[10:11]
	v_pk_mul_f32 v[4:5], v[4:5], v[12:13]
	v_cvt_pk_bf16_f32 v2, v2, v3
	v_cvt_pk_bf16_f32 v3, v4, v5
	global_store_dwordx2 v[14:15], v[2:3], off offset:1152 sc1
	global_load_dwordx4 v[2:5], v[158:159], off offset:320
	s_waitcnt vmcnt(0)
	v_pk_mul_f32 v[2:3], v[2:3], v[6:7]
	v_pk_mul_f32 v[4:5], v[4:5], v[8:9]
	v_cvt_pk_bf16_f32 v2, v2, v3
	v_cvt_pk_bf16_f32 v3, v4, v5
	global_store_dwordx2 v[14:15], v[2:3], off offset:1184 sc1
	global_load_dwordx4 v[2:5], v[158:159], off offset:384
	v_pk_mul_f32 v[6:7], v[26:27], v[16:17] op_sel_hi:[1,0]
	v_pk_mul_f32 v[8:9], v[56:57], v[16:17] op_sel_hi:[1,0]
	s_waitcnt vmcnt(0)
	v_pk_mul_f32 v[2:3], v[2:3], v[6:7]
	v_pk_mul_f32 v[4:5], v[4:5], v[8:9]
	v_cvt_pk_bf16_f32 v2, v2, v3
	v_cvt_pk_bf16_f32 v3, v4, v5
	global_store_dwordx2 v[14:15], v[2:3], off offset:1216 sc1
	global_load_dwordx4 v[2:5], v[158:159], off offset:448
	v_pk_mul_f32 v[6:7], v[46:47], v[16:17] op_sel_hi:[1,0]
	v_pk_mul_f32 v[8:9], v[48:49], v[16:17] op_sel_hi:[1,0]
	s_waitcnt vmcnt(0)
	v_pk_mul_f32 v[2:3], v[6:7], v[2:3]
	v_pk_mul_f32 v[4:5], v[8:9], v[4:5]
	v_cvt_pk_bf16_f32 v2, v2, v3
	v_cvt_pk_bf16_f32 v3, v4, v5
	global_store_dwordx2 v[14:15], v[2:3], off offset:1248 sc1
	s_waitcnt vmcnt(0) lgkmcnt(0)
	s_barrier
	s_cbranch_scc1 .LBB0_540

; __device__ __forceinline__ unsigned cvtpk(float lo, float hi) { f32x2 v = {lo, hi}; bf16x2_t b = __builtin_convertvector(v, bf16x2_t); return __builtin_bit_cast(unsigned, b); }
; __device__ __forceinline__ float bflo(unsigned w) { return __uint_as_float(w << 16); }
; __device__ __forceinline__ float bfhi(unsigned w) { return __uint_as_float(w & 0xffff0000u); }
; __device__ __forceinline__ float rstd_from(const float* st, int row, int np, float inv_dim) {
;     float s = 0.f;
;     if (np == 1) s = st[(size_t)row * 16];
;     else { const f32x4* p = (const f32x4*)(st + (size_t)row * 16);
; #pragma unroll 4
;         for (int i = 0; i < np / 4; ++i) { const f32x4 v = p[i]; s += (v[0] + v[1]) + (v[2] + v[3]); } }
;     return __builtin_amdgcn_rsqf(s * inv_dim + EPS);
; __device__ __forceinline__ void sgu_unit(LAS unsigned char* lds, int x, bf16_t* UQ, const bf16_t* VA, const float* stv, const float* sgn, const bf16_t* SW, const float* sgb) {
;     ...
;     const int chunk = x >> 1, half = x & 1, r0 = chunk * 128;
; #pragma unroll
;     for (int i = 0; i < 8; ++i) {
;         const int id = tid + 512 * i, s = id >> 5, ch = id & 31, g2 = ch >> 3, d8 = ch & 7;
;         const u32x4 v = *(const u32x4*)(VA + (size_t)(r0 + s) * 512 + 256 * half + 8 * ch);
;         const float rs = rstd_from(stv, r0 + s, 8, 1.0f / 512.0f);
;         const f32x4 g0 = *(const f32x4*)(sgn + 256 * half + 8 * ch), g1 = *(const f32x4*)(sgn + 256 * half + 8 * ch + 4);
;         u32x4 o; o.x = cvtpk(bflo(v.x) * rs * g0[0], bfhi(v.x) * rs * g0[1]); o.y = cvtpk(bflo(v.y) * rs * g0[2], bfhi(v.y) * rs * g0[3]);
;         o.z = cvtpk(bflo(v.z) * rs * g1[0], bfhi(v.z) * rs * g1[1]); o.w = cvtpk(bflo(v.w) * rs * g1[2], bfhi(v.w) * rs * g1[3]);
.LBB0_542:
	s_and_b32 s2, s6, 1
	s_and_b32 s7, s4, 0xffffff80
	v_or_b32_e32 v2, s4, v87
	v_or_b32_e32 v4, s4, v88
	v_or_b32_e32 v6, s4, v89
	s_mov_b32 s3, s1
	s_lshl_b32 s0, s2, 9
	s_lshl_b32 s2, s2, 10
	v_or_b32_e32 v8, s7, v1
	v_or_b32_e32 v14, s7, v84
	v_or_b32_e32 v12, s7, v85
	v_or_b32_e32 v10, s7, v86
	v_ashrrev_i32_e32 v3, 31, v2
	v_ashrrev_i32_e32 v5, 31, v4
	v_ashrrev_i32_e32 v7, 31, v6
	v_add_u32_e32 v16, s7, v90
	v_lshl_add_u64 v[22:23], v[68:69], 0, s[0:1]
	v_lshl_add_u64 v[18:19], v[70:71], 0, s[2:3]
	v_ashrrev_i32_e32 v9, 31, v8
	v_ashrrev_i32_e32 v15, 31, v14
	v_ashrrev_i32_e32 v13, 31, v12
	v_ashrrev_i32_e32 v11, 31, v10
	v_lshlrev_b64 v[20:21], 10, v[2:3]
	v_lshlrev_b64 v[24:25], 6, v[2:3]
	v_lshlrev_b64 v[26:27], 10, v[4:5]
	v_lshlrev_b64 v[28:29], 6, v[4:5]
	v_lshlrev_b64 v[30:31], 10, v[6:7]
	v_lshlrev_b64 v[32:33], 6, v[6:7]
	v_ashrrev_i32_e32 v17, 31, v16
	v_lshlrev_b64 v[40:41], 10, v[8:9]
	v_lshlrev_b64 v[42:43], 6, v[8:9]
	global_load_dwordx4 v[2:5], v[18:19], off offset:16
	global_load_dwordx4 v[6:9], v[18:19], off
	v_lshlrev_b64 v[50:51], 6, v[14:15]
	v_lshlrev_b64 v[52:53], 10, v[12:13]
	v_lshlrev_b64 v[54:55], 6, v[12:13]
	v_lshlrev_b64 v[56:57], 10, v[10:11]
	v_lshlrev_b64 v[58:59], 6, v[10:11]
	v_lshl_add_u64 v[18:19], v[22:23], 0, v[20:21]
	v_lshl_add_u64 v[20:21], s[38:39], 0, v[24:25]
	v_lshl_add_u64 v[44:45], v[22:23], 0, v[26:27]
	v_lshl_add_u64 v[46:47], s[38:39], 0, v[28:29]
	v_lshl_add_u64 v[60:61], v[22:23], 0, v[30:31]
	v_lshlrev_b64 v[48:49], 10, v[14:15]
	v_lshl_add_u64 v[62:63], s[38:39], 0, v[32:33]
	v_lshlrev_b64 v[64:65], 10, v[16:17]
	v_lshlrev_b64 v[76:77], 6, v[16:17]
	global_load_dwordx4 v[24:27], v[20:21], off
	global_load_dwordx4 v[10:13], v[20:21], off offset:16
	global_load_dwordx4 v[28:31], v[18:19], off
	global_load_dwordx4 v[32:35], v[46:47], off
	global_load_dwordx4 v[14:17], v[46:47], off offset:16
	global_load_dwordx4 v[36:39], v[44:45], off
	v_lshl_add_u64 v[78:79], v[22:23], 0, v[40:41]
	v_lshl_add_u64 v[80:81], s[38:39], 0, v[42:43]
	global_load_dwordx4 v[40:43], v[60:61], off
	global_load_dwordx4 v[44:47], v[62:63], off
	global_load_dwordx4 v[18:21], v[62:63], off offset:16
	v_lshl_add_u64 v[114:115], s[38:39], 0, v[50:51]
	v_lshl_add_u64 v[116:117], v[22:23], 0, v[52:53]
	v_lshl_add_u64 v[122:123], s[38:39], 0, v[54:55]
	v_lshl_add_u64 v[124:125], v[22:23], 0, v[56:57]
	v_lshl_add_u64 v[130:131], s[38:39], 0, v[58:59]
	v_lshl_add_u64 v[82:83], v[22:23], 0, v[48:49]
	v_lshl_add_u64 v[22:23], v[22:23], 0, v[64:65]
	v_lshl_add_u64 v[64:65], s[38:39], 0, v[76:77]
	global_load_dwordx4 v[48:51], v[80:81], off
	global_load_dwordx4 v[52:55], v[80:81], off offset:16
	global_load_dwordx4 v[56:59], v[78:79], off
	global_load_dwordx4 v[60:63], v[114:115], off
	global_load_dwordx4 v[102:105], v[114:115], off offset:16
	global_load_dwordx4 v[106:109], v[82:83], off
	global_load_dwordx4 v[110:113], v[116:117], off
	s_nop 0
	global_load_dwordx4 v[114:117], v[122:123], off
	global_load_dwordx4 v[118:121], v[122:123], off offset:16
	s_nop 0
	global_load_dwordx4 v[122:125], v[124:125], off
	s_nop 0
	global_load_dwordx4 v[126:129], v[130:131], off
	s_nop 0
	global_load_dwordx4 v[130:133], v[130:131], off offset:16
	s_nop 0
	global_load_dwordx4 v[134:137], v[22:23], off
	global_load_dwordx4 v[138:141], v[64:65], off
	global_load_dwordx4 v[142:145], v[64:65], off offset:16
	v_readfirstlane_b32 s11, v171
	s_bfe_u32 s14, s11, 0x20006
	s_lshr_b32 s11, s11, 2
	s_and_b32 s3, s11, 0x3fffffc0
	v_or_b32_e32 v99, s3, v91
	s_lshl_b32 s11, s14, 7
	v_add_u32_e32 v146, s7, v99
	s_or_b32 s0, s0, s11
	v_ashrrev_i32_e32 v147, 31, v146
	v_lshl_add_u64 v[76:77], v[74:75], 0, s[0:1]
	v_lshlrev_b64 v[64:65], 11, v[146:147]
	v_lshl_add_u64 v[82:83], v[76:77], 0, v[64:65]
	v_add_u32_e32 v66, s0, v99
	v_lshlrev_b64 v[22:23], 8, v[66:67]
	v_lshl_add_u64 v[22:23], v[72:73], 0, v[22:23]
	s_mul_i32 s2, s14, 0x4800
	v_add_u32_e32 v101, s2, v92
	v_or_b32_e32 v100, 16, v99
	v_lshl_add_u64 v[78:79], v[66:67], 2, s[18:19]
	v_add_u32_e32 v66, s0, v100
	v_lshlrev_b64 v[80:81], 8, v[66:67]
	v_lshl_add_u64 v[80:81], v[72:73], 0, v[80:81]
	s_add_i32 s6, s6, s30
	s_add_i32 s4, s4, s5
	s_cmpk_lt_i32 s6, 0x300
	s_waitcnt vmcnt(14)
	v_mov_b32_e32 v156, v48
	s_waitcnt vmcnt(13)
	v_mov_b32_e32 v157, v52
	v_mov_b32_e32 v52, v49
	v_mov_b32_e32 v64, v24
	v_mov_b32_e32 v65, v10
	v_mov_b32_e32 v10, v25
	v_mov_b32_e32 v24, v26
	v_mov_b32_e32 v25, v12
	v_mov_b32_e32 v12, v27
	v_mov_b32_e32 v148, v32
	v_mov_b32_e32 v149, v14
	v_mov_b32_e32 v14, v33
	v_mov_b32_e32 v32, v34
	v_mov_b32_e32 v33, v16
	v_mov_b32_e32 v16, v35
	v_mov_b32_e32 v152, v44
	v_mov_b32_e32 v153, v18
	v_mov_b32_e32 v18, v45
	v_mov_b32_e32 v44, v46
	v_mov_b32_e32 v45, v20
	v_mov_b32_e32 v20, v47
	v_mov_b32_e32 v48, v50
	v_mov_b32_e32 v49, v54
	v_mov_b32_e32 v54, v51
	s_waitcnt vmcnt(11)
	v_mov_b32_e32 v160, v60
	s_waitcnt vmcnt(10)
	v_mov_b32_e32 v161, v102
	v_mov_b32_e32 v102, v61
	v_mov_b32_e32 v60, v62
	v_mov_b32_e32 v61, v104
	v_mov_b32_e32 v104, v63
	s_waitcnt vmcnt(7)
	v_mov_b32_e32 v164, v114
	s_waitcnt vmcnt(6)
	v_mov_b32_e32 v165, v118
	v_mov_b32_e32 v118, v115
	v_mov_b32_e32 v114, v116
	v_mov_b32_e32 v115, v120
	v_mov_b32_e32 v120, v117
	s_waitcnt vmcnt(4)
	v_mov_b32_e32 v168, v126
	s_waitcnt vmcnt(3)
	v_mov_b32_e32 v169, v130
	v_mov_b32_e32 v130, v127
	v_mov_b32_e32 v126, v128
	v_mov_b32_e32 v127, v132
	v_mov_b32_e32 v132, v129
	v_pk_add_f32 v[10:11], v[64:65], v[10:11]
	v_pk_add_f32 v[12:13], v[24:25], v[12:13]
	v_pk_add_f32 v[14:15], v[148:149], v[14:15]
	v_pk_add_f32 v[16:17], v[32:33], v[16:17]
	v_pk_add_f32 v[18:19], v[152:153], v[18:19]
	v_pk_add_f32 v[20:21], v[44:45], v[20:21]
	s_waitcnt vmcnt(1)
; __device__ __forceinline__ unsigned cvtpk(float lo, float hi) { f32x2 v = {lo, hi}; bf16x2_t b = __builtin_convertvector(v, bf16x2_t); return __builtin_bit_cast(unsigned, b); }
; __device__ __forceinline__ float bflo(unsigned w) { return __uint_as_float(w << 16); }
; __device__ __forceinline__ float bfhi(unsigned w) { return __uint_as_float(w & 0xffff0000u); }
; __device__ __forceinline__ void sgu_unit(LAS unsigned char* lds, int x, bf16_t* UQ, const bf16_t* VA, const float* stv, const float* sgn, const bf16_t* SW, const float* sgb) {
;     ...
;         const float rs = rstd_from(stv, r0 + s, 8, 1.0f / 512.0f);
;         const f32x4 g0 = *(const f32x4*)(sgn + 256 * half + 8 * ch), g1 = *(const f32x4*)(sgn + 256 * half + 8 * ch + 4);
;         u32x4 o; o.x = cvtpk(bflo(v.x) * rs * g0[0], bfhi(v.x) * rs * g0[1]); o.y = cvtpk(bflo(v.y) * rs * g0[2], bfhi(v.y) * rs * g0[3]);
;         o.z = cvtpk(bflo(v.z) * rs * g1[0], bfhi(v.z) * rs * g1[1]); o.w = cvtpk(bflo(v.w) * rs * g1[2], bfhi(v.w) * rs * g1[3]);
	v_mov_b32_e32 v24, v138
	s_waitcnt vmcnt(0)
	v_mov_b32_e32 v25, v142
	v_mov_b32_e32 v142, v139
	v_mov_b32_e32 v32, v140
	v_mov_b32_e32 v33, v144
	v_mov_b32_e32 v144, v141
	v_pk_add_f32 v[52:53], v[156:157], v[52:53]
	v_pk_add_f32 v[48:49], v[48:49], v[54:55]
	v_pk_add_f32 v[54:55], v[160:161], v[102:103]
	v_pk_add_f32 v[60:61], v[60:61], v[104:105]
	v_pk_add_f32 v[102:103], v[164:165], v[118:119]
	v_pk_add_f32 v[104:105], v[114:115], v[120:121]
	v_pk_add_f32 v[114:115], v[168:169], v[130:131]
	v_pk_add_f32 v[118:119], v[126:127], v[132:133]
	v_pk_add_f32 v[10:11], v[10:11], v[12:13]
	v_pk_add_f32 v[12:13], v[14:15], v[16:17]
	v_pk_add_f32 v[14:15], v[18:19], v[20:21]
	v_pk_add_f32 v[16:17], v[24:25], v[142:143]
	v_pk_add_f32 v[18:19], v[32:33], v[144:145]
	v_pk_add_f32 v[20:21], v[52:53], v[48:49]
	v_pk_add_f32 v[24:25], v[54:55], v[60:61]
	v_pk_add_f32 v[32:33], v[102:103], v[104:105]
	v_pk_add_f32 v[48:49], v[114:115], v[118:119]
	v_add_f32_e32 v10, 0, v10
	v_add_f32_e32 v12, 0, v12
	v_add_f32_e32 v14, 0, v14
	v_pk_add_f32 v[16:17], v[16:17], v[18:19]
	v_add_f32_e32 v18, 0, v20
	v_add_f32_e32 v19, 0, v24
	v_add_f32_e32 v20, 0, v32
	v_add_f32_e32 v24, 0, v48
	v_add_f32_e32 v10, v10, v11
	v_add_f32_e32 v11, v12, v13
	v_add_f32_e32 v12, v14, v15
	v_add_f32_e32 v13, 0, v16
	v_add_f32_e32 v14, v18, v21
	v_add_f32_e32 v15, v19, v25
	v_add_f32_e32 v16, v20, v33
	v_add_f32_e32 v18, v24, v49
	v_fmamk_f32 v10, v10, 0x3b000000, v93
	v_fmamk_f32 v11, v11, 0x3b000000, v93
	v_fmamk_f32 v19, v12, 0x3b000000, v93
	v_add_f32_e32 v13, v13, v17
	v_fmamk_f32 v17, v14, 0x3b000000, v93
	v_fmamk_f32 v15, v15, 0x3b000000, v93
	v_fmamk_f32 v20, v16, 0x3b000000, v93
	v_fmamk_f32 v21, v18, 0x3b000000, v93
	v_rsq_f32_e32 v10, v10
	v_rsq_f32_e32 v12, v11
	v_rsq_f32_e32 v14, v19
	v_fmamk_f32 v11, v13, 0x3b000000, v93
	v_rsq_f32_e32 v16, v17
	v_rsq_f32_e32 v18, v15
	v_rsq_f32_e32 v20, v20
	v_rsq_f32_e32 v24, v21
	v_rsq_f32_e32 v32, v11
	v_lshlrev_b32_e32 v26, 16, v28
	v_and_b32_e32 v27, 0xffff0000, v28
	v_lshlrev_b32_e32 v28, 16, v29
	v_and_b32_e32 v29, 0xffff0000, v29
	v_lshlrev_b32_e32 v146, 16, v30
	v_and_b32_e32 v147, 0xffff0000, v30
	v_lshlrev_b32_e32 v30, 16, v31
	v_and_b32_e32 v31, 0xffff0000, v31
	v_lshlrev_b32_e32 v34, 16, v36
	v_and_b32_e32 v35, 0xffff0000, v36
	v_lshlrev_b32_e32 v36, 16, v37
	v_and_b32_e32 v37, 0xffff0000, v37
	v_lshlrev_b32_e32 v150, 16, v38
	v_and_b32_e32 v151, 0xffff0000, v38
	v_lshlrev_b32_e32 v38, 16, v39
	v_and_b32_e32 v39, 0xffff0000, v39
	v_lshlrev_b32_e32 v46, 16, v40
	v_and_b32_e32 v47, 0xffff0000, v40
	v_lshlrev_b32_e32 v40, 16, v41
	v_and_b32_e32 v41, 0xffff0000, v41
	v_lshlrev_b32_e32 v154, 16, v42
	v_and_b32_e32 v155, 0xffff0000, v42
	v_lshlrev_b32_e32 v42, 16, v43
	v_and_b32_e32 v43, 0xffff0000, v43
	v_lshlrev_b32_e32 v50, 16, v56
	v_and_b32_e32 v51, 0xffff0000, v56
	v_lshlrev_b32_e32 v56, 16, v57
	v_and_b32_e32 v57, 0xffff0000, v57
	v_lshlrev_b32_e32 v158, 16, v58
	v_and_b32_e32 v159, 0xffff0000, v58
	v_lshlrev_b32_e32 v58, 16, v59
	v_and_b32_e32 v59, 0xffff0000, v59
	v_lshlrev_b32_e32 v62, 16, v106
	v_and_b32_e32 v63, 0xffff0000, v106
	v_lshlrev_b32_e32 v106, 16, v107
	v_and_b32_e32 v107, 0xffff0000, v107
	v_lshlrev_b32_e32 v162, 16, v108
	v_and_b32_e32 v163, 0xffff0000, v108
	v_lshlrev_b32_e32 v108, 16, v109
	v_and_b32_e32 v109, 0xffff0000, v109
	v_lshlrev_b32_e32 v116, 16, v110
	v_and_b32_e32 v117, 0xffff0000, v110
	v_lshlrev_b32_e32 v110, 16, v111
	v_and_b32_e32 v111, 0xffff0000, v111
	v_lshlrev_b32_e32 v166, 16, v112
	v_and_b32_e32 v167, 0xffff0000, v112
	v_lshlrev_b32_e32 v112, 16, v113
	v_and_b32_e32 v113, 0xffff0000, v113
	v_lshlrev_b32_e32 v128, 16, v122
	v_and_b32_e32 v129, 0xffff0000, v122
	v_lshlrev_b32_e32 v122, 16, v123
	v_and_b32_e32 v123, 0xffff0000, v123
	v_lshlrev_b32_e32 v172, 16, v124
	v_and_b32_e32 v173, 0xffff0000, v124
	v_lshlrev_b32_e32 v124, 16, v125
	v_and_b32_e32 v125, 0xffff0000, v125
	v_lshlrev_b32_e32 v44, 16, v134
	v_and_b32_e32 v45, 0xffff0000, v134
	v_lshlrev_b32_e32 v64, 16, v135
	v_and_b32_e32 v65, 0xffff0000, v135
	v_lshlrev_b32_e32 v134, 16, v136
	v_and_b32_e32 v135, 0xffff0000, v136
	v_lshlrev_b32_e32 v136, 16, v137
	v_and_b32_e32 v137, 0xffff0000, v137
	v_pk_mul_f32 v[26:27], v[10:11], v[26:27] op_sel_hi:[0,1]
	v_pk_mul_f32 v[28:29], v[10:11], v[28:29] op_sel_hi:[0,1]
	v_pk_mul_f32 v[48:49], v[10:11], v[146:147] op_sel_hi:[0,1]
	v_pk_mul_f32 v[10:11], v[10:11], v[30:31] op_sel_hi:[0,1]
	v_pk_mul_f32 v[30:31], v[12:13], v[34:35] op_sel_hi:[0,1]
	v_pk_mul_f32 v[34:35], v[12:13], v[36:37] op_sel_hi:[0,1]
	v_pk_mul_f32 v[36:37], v[12:13], v[150:151] op_sel_hi:[0,1]
	v_pk_mul_f32 v[12:13], v[12:13], v[38:39] op_sel_hi:[0,1]
	v_pk_mul_f32 v[38:39], v[14:15], v[46:47] op_sel_hi:[0,1]
	v_pk_mul_f32 v[40:41], v[14:15], v[40:41] op_sel_hi:[0,1]
	v_pk_mul_f32 v[46:47], v[14:15], v[154:155] op_sel_hi:[0,1]
	v_pk_mul_f32 v[14:15], v[14:15], v[42:43] op_sel_hi:[0,1]
	v_pk_mul_f32 v[42:43], v[16:17], v[50:51] op_sel_hi:[0,1]
	v_pk_mul_f32 v[50:51], v[16:17], v[56:57] op_sel_hi:[0,1]
	v_pk_mul_f32 v[52:53], v[16:17], v[158:159] op_sel_hi:[0,1]
	v_pk_mul_f32 v[16:17], v[16:17], v[58:59] op_sel_hi:[0,1]
	v_pk_mul_f32 v[54:55], v[18:19], v[62:63] op_sel_hi:[0,1]
	v_pk_mul_f32 v[56:57], v[18:19], v[106:107] op_sel_hi:[0,1]
	v_pk_mul_f32 v[58:59], v[18:19], v[162:163] op_sel_hi:[0,1]
	v_pk_mul_f32 v[18:19], v[18:19], v[108:109] op_sel_hi:[0,1]
	v_pk_mul_f32 v[60:61], v[20:21], v[116:117] op_sel_hi:[0,1]
	v_pk_mul_f32 v[62:63], v[20:21], v[110:111] op_sel_hi:[0,1]
	v_pk_mul_f32 v[102:103], v[20:21], v[166:167] op_sel_hi:[0,1]
	v_pk_mul_f32 v[20:21], v[20:21], v[112:113] op_sel_hi:[0,1]
; #define LAS __attribute__((address_space(3)))
; __device__ __forceinline__ unsigned cvtpk(float lo, float hi) { f32x2 v = {lo, hi}; bf16x2_t b = __builtin_convertvector(v, bf16x2_t); return __builtin_bit_cast(unsigned, b); }
; __device__ __forceinline__ float bflo(unsigned w) { return __uint_as_float(w << 16); }
; __device__ __forceinline__ float bfhi(unsigned w) { return __uint_as_float(w & 0xffff0000u); }
; __device__ __forceinline__ s16x4 tr_read(const LAS unsigned char* p) { return __builtin_bit_cast(s16x4, __builtin_amdgcn_ds_read_tr16_b64_v4i16((LAS s16x4*)p)); }
; __device__ __forceinline__ void sgu_unit(LAS unsigned char* lds, int x, bf16_t* UQ, const bf16_t* VA, const float* stv, const float* sgn, const bf16_t* SW, const float* sgb) {
;     ...
;         u32x4 o; o.x = cvtpk(bflo(v.x) * rs * g0[0], bfhi(v.x) * rs * g0[1]); o.y = cvtpk(bflo(v.y) * rs * g0[2], bfhi(v.y) * rs * g0[3]);
;         o.z = cvtpk(bflo(v.z) * rs * g1[0], bfhi(v.z) * rs * g1[1]); o.w = cvtpk(bflo(v.w) * rs * g1[2], bfhi(v.w) * rs * g1[3]);
;         *(LAS u32x4*)(lds + g2 * SG_TILE + s * SG_P + d8 * 16) = o;
;     }
;     __syncthreads();
;     const int g2 = w & 3, th = w >> 2, g = 4 * half + g2;
;     const LAS unsigned char* tb = lds + g2 * SG_TILE + (4 * fq + (r16 >> 2)) * SG_P + (r16 & 3) * 8;
;     bf16x8 af[4][4];
; #pragma unroll
;     for (int dt = 0; dt < 4; ++dt)
; #pragma unroll
;         for (int ks = 0; ks < 4; ++ks) { const s16x4 lo = tr_read(tb + (32 * ks) * SG_P + dt * 32), hi = tr_read(tb + (32 * ks + 16) * SG_P + dt * 32);
;             af[dt][ks] = (bf16x8){lo[0], lo[1], lo[2], lo[3], hi[0], hi[1], hi[2], hi[3]}; }
; #pragma unroll
;     for (int tt = 0; tt < 4; ++tt) {
;         const int t = 64 * th + 16 * tt + r16;
;         bf16x8 bfr[4];
; #pragma unroll
;         for (int ks = 0; ks < 4; ++ks) bfr[ks] = *(const bf16x8*)(SW + ((size_t)(g * 128 + t) * 128 + 32 * ks + 8 * fq));
;         const float bt = sgb[g * 128 + t];
;         bf16_t* up = UQ + (size_t)(r0 + t) * DM + 64 * g + 4 * fq;
; #pragma unroll
;         for (int dt = 0; dt < 4; ++dt) {
;             f32x4 a = (f32x4){0.f, 0.f, 0.f, 0.f};
; #pragma unroll
;             for (int ks = 0; ks < 4; ++ks) a = __builtin_amdgcn_mfma_f32_16x16x32_bf16(af[dt][ks], bfr[ks], a, 0, 0, 0);
;             const u32x2 uv = *(const u32x2*)(up + 16 * dt);
	v_pk_mul_f32 v[104:105], v[24:25], v[128:129] op_sel_hi:[0,1]
	v_pk_mul_f32 v[106:107], v[24:25], v[122:123] op_sel_hi:[0,1]
	v_pk_mul_f32 v[108:109], v[24:25], v[172:173] op_sel_hi:[0,1]
	v_pk_mul_f32 v[24:25], v[24:25], v[124:125] op_sel_hi:[0,1]
	v_pk_mul_f32 v[26:27], v[6:7], v[26:27]
	v_pk_mul_f32 v[28:29], v[8:9], v[28:29]
	v_pk_mul_f32 v[48:49], v[2:3], v[48:49]
	v_pk_mul_f32 v[110:111], v[4:5], v[10:11]
	v_pk_mul_f32 v[34:35], v[8:9], v[34:35]
	v_pk_mul_f32 v[36:37], v[2:3], v[36:37]
	v_pk_mul_f32 v[38:39], v[6:7], v[38:39]
	v_pk_mul_f32 v[40:41], v[8:9], v[40:41]
	v_pk_mul_f32 v[44:45], v[32:33], v[44:45] op_sel_hi:[0,1]
	v_pk_mul_f32 v[64:65], v[32:33], v[64:65] op_sel_hi:[0,1]
	v_pk_mul_f32 v[116:117], v[32:33], v[134:135] op_sel_hi:[0,1]
	v_pk_mul_f32 v[32:33], v[32:33], v[136:137] op_sel_hi:[0,1]
	v_pk_mul_f32 v[42:43], v[6:7], v[42:43]
	v_pk_mul_f32 v[50:51], v[8:9], v[50:51]
	v_pk_mul_f32 v[52:53], v[2:3], v[52:53]
	v_pk_mul_f32 v[118:119], v[4:5], v[16:17]
	v_pk_mul_f32 v[30:31], v[6:7], v[30:31]
	v_pk_mul_f32 v[112:113], v[4:5], v[12:13]
	v_pk_mul_f32 v[46:47], v[2:3], v[46:47]
	v_pk_mul_f32 v[114:115], v[4:5], v[14:15]
	v_pk_mul_f32 v[54:55], v[6:7], v[54:55]
	v_pk_mul_f32 v[56:57], v[8:9], v[56:57]
	v_pk_mul_f32 v[58:59], v[2:3], v[58:59]
	v_pk_mul_f32 v[120:121], v[4:5], v[18:19]
	v_pk_mul_f32 v[60:61], v[6:7], v[60:61]
	v_pk_mul_f32 v[62:63], v[8:9], v[62:63]
	v_pk_mul_f32 v[102:103], v[2:3], v[102:103]
	v_pk_mul_f32 v[122:123], v[4:5], v[20:21]
	v_pk_mul_f32 v[104:105], v[6:7], v[104:105]
	v_pk_mul_f32 v[106:107], v[8:9], v[106:107]
	v_pk_mul_f32 v[108:109], v[2:3], v[108:109]
	v_pk_mul_f32 v[124:125], v[4:5], v[24:25]
	v_cvt_pk_bf16_f32 v10, v26, v27
	v_cvt_pk_bf16_f32 v11, v28, v29
	v_cvt_pk_bf16_f32 v12, v48, v49
	v_cvt_pk_bf16_f32 v13, v110, v111
	v_cvt_pk_bf16_f32 v15, v34, v35
	v_cvt_pk_bf16_f32 v16, v36, v37
	v_cvt_pk_bf16_f32 v18, v38, v39
	v_cvt_pk_bf16_f32 v19, v40, v41
	v_pk_mul_f32 v[34:35], v[6:7], v[44:45]
	v_pk_mul_f32 v[36:37], v[8:9], v[64:65]
	v_pk_mul_f32 v[38:39], v[2:3], v[116:117]
	v_pk_mul_f32 v[40:41], v[4:5], v[32:33]
	v_cvt_pk_bf16_f32 v2, v42, v43
	v_cvt_pk_bf16_f32 v3, v50, v51
	v_cvt_pk_bf16_f32 v4, v52, v53
	v_cvt_pk_bf16_f32 v5, v118, v119
	v_cvt_pk_bf16_f32 v14, v30, v31
	v_cvt_pk_bf16_f32 v17, v112, v113
	v_cvt_pk_bf16_f32 v20, v46, v47
	v_cvt_pk_bf16_f32 v21, v114, v115
	v_cvt_pk_bf16_f32 v6, v54, v55
	v_cvt_pk_bf16_f32 v7, v56, v57
	v_cvt_pk_bf16_f32 v8, v58, v59
	v_cvt_pk_bf16_f32 v9, v120, v121
	v_cvt_pk_bf16_f32 v24, v60, v61
	v_cvt_pk_bf16_f32 v25, v62, v63
	v_cvt_pk_bf16_f32 v26, v102, v103
	v_cvt_pk_bf16_f32 v27, v122, v123
	v_cvt_pk_bf16_f32 v28, v104, v105
	v_cvt_pk_bf16_f32 v29, v106, v107
	v_cvt_pk_bf16_f32 v30, v108, v109
	v_cvt_pk_bf16_f32 v31, v124, v125
	v_cvt_pk_bf16_f32 v32, v34, v35
	v_cvt_pk_bf16_f32 v33, v36, v37
	v_cvt_pk_bf16_f32 v34, v38, v39
	v_cvt_pk_bf16_f32 v35, v40, v41
	ds_write_b128 v94, v[2:5]
	ds_write_b128 v95, v[6:9]
	ds_write_b128 v94, v[24:27] offset:4608
	ds_write_b128 v96, v[28:31]
	ds_write_b128 v94, v[10:13] offset:9216
	ds_write_b128 v97, v[14:17]
	ds_write_b128 v94, v[18:21] offset:13824
	ds_write_b128 v98, v[32:35]
	s_waitcnt lgkmcnt(0)
	s_barrier
	global_load_dwordx4 v[2:5], v[22:23], off
	global_load_dwordx4 v[10:13], v[22:23], off offset:64
	global_load_dwordx4 v[102:105], v[22:23], off offset:128
	ds_read_b64_tr_b16 v[62:63], v101
	ds_read_b64_tr_b16 v[64:65], v101 offset:2304
	ds_read_b64_tr_b16 v[60:61], v101 offset:2336
	global_load_dwordx2 v[126:127], v[82:83], off
	ds_read_b64_tr_b16 v[58:59], v101 offset:32
	ds_read_b64_tr_b16 v[54:55], v101 offset:64
	ds_read_b64_tr_b16 v[38:39], v101 offset:96
	ds_read_b64_tr_b16 v[56:57], v101 offset:2368
	ds_read_b64_tr_b16 v[40:41], v101 offset:2400
	global_load_dwordx2 v[128:129], v[82:83], off offset:32
	global_load_dwordx4 v[106:109], v[22:23], off offset:192
	ds_read_b64_tr_b16 v[44:45], v101 offset:6912
	global_load_dwordx2 v[130:131], v[82:83], off offset:64
	ds_read_b64_tr_b16 v[42:43], v101 offset:4608
	ds_read_b64_tr_b16 v[46:47], v101 offset:4640
	ds_read_b64_tr_b16 v[34:35], v101 offset:4672
	ds_read_b64_tr_b16 v[30:31], v101 offset:4704
	global_load_dwordx2 v[132:133], v[82:83], off offset:96
	ds_read_b64_tr_b16 v[48:49], v101 offset:6944
	ds_read_b64_tr_b16 v[36:37], v101 offset:6976
	ds_read_b64_tr_b16 v[32:33], v101 offset:7008
	global_load_dword v66, v[78:79], off
	s_waitcnt vmcnt(8) lgkmcnt(14)
	v_mfma_f32_16x16x32_bf16 v[6:9], v[62:65], v[2:5], 0
	s_waitcnt vmcnt(5)
	v_lshlrev_b32_e32 v134, 16, v126
	s_waitcnt lgkmcnt(9)
	v_mfma_f32_16x16x32_bf16 v[18:21], v[54:57], v[2:5], 0
	v_and_b32_e32 v135, 0xffff0000, v126
	v_lshlrev_b32_e32 v126, 16, v127
	v_and_b32_e32 v127, 0xffff0000, v127
	v_mfma_f32_16x16x32_bf16 v[14:17], v[58:61], v[2:5], 0
	s_waitcnt vmcnt(4)
	v_lshlrev_b32_e32 v136, 16, v128
	v_and_b32_e32 v137, 0xffff0000, v128
	v_lshlrev_b32_e32 v128, 16, v129
	s_waitcnt lgkmcnt(8)
	v_mfma_f32_16x16x32_bf16 v[110:113], v[38:41], v[2:5], 0
	ds_read_b64_tr_b16 v[50:51], v101 offset:9216
	ds_read_b64_tr_b16 v[2:3], v101 offset:13824
	ds_read_b64_tr_b16 v[4:5], v101 offset:16128
	ds_read_b64_tr_b16 v[52:53], v101 offset:11520
	ds_read_b64_tr_b16 v[28:29], v101 offset:11552
	v_and_b32_e32 v129, 0xffff0000, v129
	s_waitcnt lgkmcnt(11)
	v_mfma_f32_16x16x32_bf16 v[114:117], v[42:45], v[10:13], v[6:9]
	s_nop 2
	ds_read_b64_tr_b16 v[8:9], v101 offset:16160
	ds_read_b64_tr_b16 v[26:27], v101 offset:9248
	ds_read_b64_tr_b16 v[22:23], v101 offset:9280
	s_waitcnt vmcnt(2)
	v_lshlrev_b32_e32 v138, 16, v130
	v_and_b32_e32 v139, 0xffff0000, v130
	s_waitcnt lgkmcnt(9)
; __device__ __forceinline__ unsigned cvtpk(float lo, float hi) { f32x2 v = {lo, hi}; bf16x2_t b = __builtin_convertvector(v, bf16x2_t); return __builtin_bit_cast(unsigned, b); }
; __device__ __forceinline__ float bflo(unsigned w) { return __uint_as_float(w << 16); }
; __device__ __forceinline__ float bfhi(unsigned w) { return __uint_as_float(w & 0xffff0000u); }
; __device__ __forceinline__ void sgu_unit(LAS unsigned char* lds, int x, bf16_t* UQ, const bf16_t* VA, const float* stv, const float* sgn, const bf16_t* SW, const float* sgb) {
;     ...
; #pragma unroll
;     for (int tt = 0; tt < 4; ++tt) {
;         const int t = 64 * th + 16 * tt + r16;
;         bf16x8 bfr[4];
; #pragma unroll
;         for (int ks = 0; ks < 4; ++ks) bfr[ks] = *(const bf16x8*)(SW + ((size_t)(g * 128 + t) * 128 + 32 * ks + 8 * fq));
;         const float bt = sgb[g * 128 + t];
;         bf16_t* up = UQ + (size_t)(r0 + t) * DM + 64 * g + 4 * fq;
; #pragma unroll
;         for (int dt = 0; dt < 4; ++dt) {
;             f32x4 a = (f32x4){0.f, 0.f, 0.f, 0.f};
; #pragma unroll
;             for (int ks = 0; ks < 4; ++ks) a = __builtin_amdgcn_mfma_f32_16x16x32_bf16(af[dt][ks], bfr[ks], a, 0, 0, 0);
;             const u32x2 uv = *(const u32x2*)(up + 16 * dt);
;             u32x2 wv; wv.x = cvtpk(bflo(uv.x) * (a[0] + bt), bfhi(uv.x) * (a[1] + bt)); wv.y = cvtpk(bflo(uv.y) * (a[2] + bt), bfhi(uv.y) * (a[3] + bt));
;             *(u32x2*)(up + 16 * dt) = wv;
;         }
	v_mfma_f32_16x16x32_bf16 v[122:125], v[34:37], v[10:13], v[18:21]
	s_nop 2
	ds_read_b64_tr_b16 v[18:19], v101 offset:9312
	ds_read_b64_tr_b16 v[24:25], v101 offset:11584
	ds_read_b64_tr_b16 v[20:21], v101 offset:11616
	v_lshlrev_b32_e32 v130, 16, v131
	v_and_b32_e32 v131, 0xffff0000, v131
	v_mfma_f32_16x16x32_bf16 v[118:121], v[46:49], v[10:13], v[14:17]
	s_waitcnt vmcnt(1)
	v_lshlrev_b32_e32 v140, 16, v132
	v_and_b32_e32 v141, 0xffff0000, v132
	s_waitcnt lgkmcnt(11)
	v_mfma_f32_16x16x32_bf16 v[110:113], v[30:33], v[10:13], v[110:113]
	ds_read_b64_tr_b16 v[6:7], v101 offset:13856
	ds_read_b64_tr_b16 v[14:15], v101 offset:13888
	ds_read_b64_tr_b16 v[10:11], v101 offset:13920
	ds_read_b64_tr_b16 v[16:17], v101 offset:16192
	ds_read_b64_tr_b16 v[12:13], v101 offset:16224
	s_waitcnt lgkmcnt(12)
	v_mfma_f32_16x16x32_bf16 v[114:117], v[50:53], v[102:105], v[114:117]
	s_waitcnt lgkmcnt(9)
	v_mfma_f32_16x16x32_bf16 v[118:121], v[26:29], v[102:105], v[118:121]
	s_waitcnt lgkmcnt(6)
	v_mfma_f32_16x16x32_bf16 v[122:125], v[22:25], v[102:105], v[122:125]
	s_waitcnt lgkmcnt(5)
	v_mfma_f32_16x16x32_bf16 v[102:105], v[18:21], v[102:105], v[110:113]
	v_mfma_f32_16x16x32_bf16 v[110:113], v[2:5], v[106:109], v[114:117]
	s_waitcnt lgkmcnt(4)
	v_mfma_f32_16x16x32_bf16 v[114:117], v[6:9], v[106:109], v[118:121]
	s_waitcnt lgkmcnt(1)
	v_mfma_f32_16x16x32_bf16 v[118:121], v[14:17], v[106:109], v[122:125]
	s_waitcnt lgkmcnt(0)
	v_mfma_f32_16x16x32_bf16 v[102:105], v[10:13], v[106:109], v[102:105]
	s_waitcnt vmcnt(0)
	s_nop 0
	v_pk_add_f32 v[106:107], v[66:67], v[110:111] op_sel_hi:[0,1]
	v_pk_add_f32 v[108:109], v[66:67], v[112:113] op_sel_hi:[0,1]
	v_lshlrev_b32_e32 v122, 16, v133
	v_and_b32_e32 v123, 0xffff0000, v133
	v_pk_add_f32 v[110:111], v[66:67], v[114:115] op_sel_hi:[0,1]
	v_pk_add_f32 v[112:113], v[66:67], v[116:117] op_sel_hi:[0,1]
	v_pk_add_f32 v[114:115], v[66:67], v[118:119] op_sel_hi:[0,1]
	v_pk_add_f32 v[116:117], v[66:67], v[120:121] op_sel_hi:[0,1]
	v_pk_add_f32 v[102:103], v[66:67], v[102:103] op_sel_hi:[0,1]
	v_pk_add_f32 v[104:105], v[66:67], v[104:105] op_sel_hi:[0,1]
	v_pk_mul_f32 v[106:107], v[106:107], v[134:135]
	v_pk_mul_f32 v[108:109], v[108:109], v[126:127]
	v_pk_mul_f32 v[110:111], v[110:111], v[136:137]
	v_pk_mul_f32 v[112:113], v[112:113], v[128:129]
	v_pk_mul_f32 v[114:115], v[114:115], v[138:139]
	v_pk_mul_f32 v[116:117], v[116:117], v[130:131]
	v_pk_mul_f32 v[102:103], v[102:103], v[140:141]
	v_pk_mul_f32 v[104:105], v[104:105], v[122:123]
	v_cvt_pk_bf16_f32 v106, v106, v107
	v_cvt_pk_bf16_f32 v107, v108, v109
	v_cvt_pk_bf16_f32 v108, v110, v111
	v_cvt_pk_bf16_f32 v109, v112, v113
	v_cvt_pk_bf16_f32 v110, v114, v115
	v_cvt_pk_bf16_f32 v111, v116, v117
	v_cvt_pk_bf16_f32 v102, v102, v103
	v_cvt_pk_bf16_f32 v103, v104, v105
	global_store_dwordx2 v[82:83], v[106:107], off sc1
	global_store_dwordx2 v[82:83], v[108:109], off offset:32 sc1
	global_store_dwordx2 v[82:83], v[110:111], off offset:64 sc1
	global_store_dwordx2 v[82:83], v[102:103], off offset:96 sc1
	global_load_dwordx4 v[102:105], v[80:81], off
	s_nop 0
	global_load_dwordx4 v[106:109], v[80:81], off offset:64
	s_waitcnt vmcnt(1)
	v_mfma_f32_16x16x32_bf16 v[110:113], v[62:65], v[102:105], 0
	v_add_u32_e32 v82, s7, v100
	v_or_b32_e32 v140, 32, v99
	v_ashrrev_i32_e32 v83, 31, v82
	v_mfma_f32_16x16x32_bf16 v[114:117], v[58:61], v[102:105], 0
	v_add_u32_e32 v66, s0, v140
	v_lshlrev_b64 v[82:83], 11, v[82:83]
	v_lshlrev_b64 v[100:101], 8, v[66:67]
	v_mfma_f32_16x16x32_bf16 v[118:121], v[54:57], v[102:105], 0
	v_lshl_add_u64 v[122:123], v[76:77], 0, v[82:83]
	v_lshl_add_u64 v[124:125], v[72:73], 0, v[100:101]
	global_load_dwordx2 v[126:127], v[122:123], off
	global_load_dwordx2 v[128:129], v[122:123], off offset:32
	global_load_dwordx2 v[130:131], v[122:123], off offset:64
	v_mfma_f32_16x16x32_bf16 v[102:105], v[38:41], v[102:105], 0
	v_or_b32_e32 v99, 48, v99
	s_waitcnt vmcnt(2)
	v_lshlrev_b32_e32 v134, 16, v126
	v_mfma_f32_16x16x32_bf16 v[110:113], v[42:45], v[106:109], v[110:113]
	v_and_b32_e32 v135, 0xffff0000, v126
	v_lshlrev_b32_e32 v126, 16, v127
	v_and_b32_e32 v127, 0xffff0000, v127
	v_mfma_f32_16x16x32_bf16 v[114:117], v[46:49], v[106:109], v[114:117]
	s_waitcnt vmcnt(0)
	v_lshlrev_b32_e32 v136, 16, v130
	v_and_b32_e32 v137, 0xffff0000, v130
	v_lshlrev_b32_e32 v130, 16, v131
	v_mfma_f32_16x16x32_bf16 v[118:121], v[34:37], v[106:109], v[118:121]
	v_and_b32_e32 v131, 0xffff0000, v131
	v_mfma_f32_16x16x32_bf16 v[100:103], v[30:33], v[106:109], v[102:105]
	s_nop 2
	global_load_dwordx4 v[104:107], v[80:81], off offset:128
	s_nop 0
	global_load_dwordx4 v[80:83], v[80:81], off offset:192
	s_nop 0
	global_load_dword v66, v[78:79], off offset:64
	global_load_dwordx2 v[132:133], v[122:123], off offset:96
	s_waitcnt vmcnt(3)
	v_mfma_f32_16x16x32_bf16 v[108:111], v[50:53], v[104:107], v[110:113]
	s_waitcnt vmcnt(0)
; __device__ __forceinline__ unsigned cvtpk(float lo, float hi) { f32x2 v = {lo, hi}; bf16x2_t b = __builtin_convertvector(v, bf16x2_t); return __builtin_bit_cast(unsigned, b); }
; __device__ __forceinline__ float bflo(unsigned w) { return __uint_as_float(w << 16); }
; __device__ __forceinline__ float bfhi(unsigned w) { return __uint_as_float(w & 0xffff0000u); }
; __device__ __forceinline__ void sgu_unit(LAS unsigned char* lds, int x, bf16_t* UQ, const bf16_t* VA, const float* stv, const float* sgn, const bf16_t* SW, const float* sgb) {
;     ...
; #pragma unroll
;     for (int tt = 0; tt < 4; ++tt) {
;         const int t = 64 * th + 16 * tt + r16;
;         bf16x8 bfr[4];
; #pragma unroll
;         for (int ks = 0; ks < 4; ++ks) bfr[ks] = *(const bf16x8*)(SW + ((size_t)(g * 128 + t) * 128 + 32 * ks + 8 * fq));
;         const float bt = sgb[g * 128 + t];
;         bf16_t* up = UQ + (size_t)(r0 + t) * DM + 64 * g + 4 * fq;
; #pragma unroll
;         for (int dt = 0; dt < 4; ++dt) {
;             f32x4 a = (f32x4){0.f, 0.f, 0.f, 0.f};
; #pragma unroll
;             for (int ks = 0; ks < 4; ++ks) a = __builtin_amdgcn_mfma_f32_16x16x32_bf16(af[dt][ks], bfr[ks], a, 0, 0, 0);
;             const u32x2 uv = *(const u32x2*)(up + 16 * dt);
;             u32x2 wv; wv.x = cvtpk(bflo(uv.x) * (a[0] + bt), bfhi(uv.x) * (a[1] + bt)); wv.y = cvtpk(bflo(uv.y) * (a[2] + bt), bfhi(uv.y) * (a[3] + bt));
;             *(u32x2*)(up + 16 * dt) = wv;
;         }
	v_lshlrev_b32_e32 v138, 16, v132
	v_mfma_f32_16x16x32_bf16 v[112:115], v[26:29], v[104:107], v[114:117]
	v_and_b32_e32 v139, 0xffff0000, v132
	v_lshlrev_b32_e32 v132, 16, v133
	v_and_b32_e32 v133, 0xffff0000, v133
	v_mfma_f32_16x16x32_bf16 v[116:119], v[22:25], v[104:107], v[118:121]
	v_mfma_f32_16x16x32_bf16 v[100:103], v[18:21], v[104:107], v[100:103]
	s_nop 1
	v_lshlrev_b32_e32 v120, 16, v128
	v_and_b32_e32 v121, 0xffff0000, v128
	v_lshlrev_b32_e32 v128, 16, v129
	v_mfma_f32_16x16x32_bf16 v[104:107], v[2:5], v[80:83], v[108:111]
	v_and_b32_e32 v129, 0xffff0000, v129
	v_mfma_f32_16x16x32_bf16 v[108:111], v[6:9], v[80:83], v[112:115]
	v_mfma_f32_16x16x32_bf16 v[112:115], v[14:17], v[80:83], v[116:119]
	v_mfma_f32_16x16x32_bf16 v[80:83], v[10:13], v[80:83], v[100:103]
	s_nop 1
	v_add_u32_e32 v116, s7, v140
	v_ashrrev_i32_e32 v117, 31, v116
	v_lshlrev_b64 v[116:117], 11, v[116:117]
	v_pk_add_f32 v[100:101], v[66:67], v[104:105] op_sel_hi:[0,1]
	v_pk_add_f32 v[102:103], v[66:67], v[106:107] op_sel_hi:[0,1]
	v_pk_add_f32 v[104:105], v[66:67], v[108:109] op_sel_hi:[0,1]
	v_pk_add_f32 v[106:107], v[66:67], v[110:111] op_sel_hi:[0,1]
	v_pk_add_f32 v[108:109], v[66:67], v[112:113] op_sel_hi:[0,1]
	v_pk_add_f32 v[110:111], v[66:67], v[114:115] op_sel_hi:[0,1]
	v_pk_add_f32 v[80:81], v[66:67], v[80:81] op_sel_hi:[0,1]
	v_pk_add_f32 v[82:83], v[66:67], v[82:83] op_sel_hi:[0,1]
	v_pk_mul_f32 v[100:101], v[100:101], v[134:135]
	v_pk_mul_f32 v[102:103], v[102:103], v[126:127]
	v_pk_mul_f32 v[104:105], v[104:105], v[120:121]
	v_pk_mul_f32 v[106:107], v[106:107], v[128:129]
	v_pk_mul_f32 v[108:109], v[108:109], v[136:137]
	v_pk_mul_f32 v[110:111], v[110:111], v[130:131]
	v_pk_mul_f32 v[80:81], v[80:81], v[138:139]
	v_pk_mul_f32 v[82:83], v[82:83], v[132:133]
	v_cvt_pk_bf16_f32 v100, v100, v101
	v_cvt_pk_bf16_f32 v101, v102, v103
	v_cvt_pk_bf16_f32 v102, v104, v105
	v_cvt_pk_bf16_f32 v103, v106, v107
	v_cvt_pk_bf16_f32 v104, v108, v109
	v_cvt_pk_bf16_f32 v105, v110, v111
	v_cvt_pk_bf16_f32 v80, v80, v81
	v_cvt_pk_bf16_f32 v81, v82, v83
	global_store_dwordx2 v[122:123], v[100:101], off sc1
	global_store_dwordx2 v[122:123], v[102:103], off offset:32 sc1
	global_store_dwordx2 v[122:123], v[104:105], off offset:64 sc1
	global_store_dwordx2 v[122:123], v[80:81], off offset:96 sc1
	global_load_dwordx4 v[80:83], v[124:125], off
	s_nop 0
	global_load_dwordx4 v[100:103], v[124:125], off offset:64
	s_waitcnt vmcnt(1)
	v_mfma_f32_16x16x32_bf16 v[104:107], v[62:65], v[80:83], 0
	v_add_u32_e32 v66, s0, v99
	v_lshl_add_u64 v[120:121], v[76:77], 0, v[116:117]
	v_lshlrev_b64 v[116:117], 8, v[66:67]
	v_mfma_f32_16x16x32_bf16 v[108:111], v[58:61], v[80:83], 0
	v_lshl_add_u64 v[122:123], v[72:73], 0, v[116:117]
	global_load_dwordx2 v[126:127], v[120:121], off
	global_load_dwordx2 v[128:129], v[120:121], off offset:32
	global_load_dwordx2 v[130:131], v[120:121], off offset:64
	s_waitcnt vmcnt(2)
	v_lshlrev_b32_e32 v132, 16, v126
	v_mfma_f32_16x16x32_bf16 v[112:115], v[54:57], v[80:83], 0
	v_and_b32_e32 v133, 0xffff0000, v126
	v_lshlrev_b32_e32 v126, 16, v127
	v_and_b32_e32 v127, 0xffff0000, v127
	v_mfma_f32_16x16x32_bf16 v[80:83], v[38:41], v[80:83], 0
	s_waitcnt vmcnt(1)
	v_lshlrev_b32_e32 v134, 16, v128
	v_and_b32_e32 v135, 0xffff0000, v128
	v_lshlrev_b32_e32 v128, 16, v129
	v_mfma_f32_16x16x32_bf16 v[104:107], v[42:45], v[100:103], v[104:107]
	v_and_b32_e32 v129, 0xffff0000, v129
	s_waitcnt vmcnt(0)
	v_lshlrev_b32_e32 v136, 16, v130
	v_and_b32_e32 v137, 0xffff0000, v130
	v_mfma_f32_16x16x32_bf16 v[108:111], v[46:49], v[100:103], v[108:111]
	v_lshlrev_b32_e32 v130, 16, v131
	v_and_b32_e32 v131, 0xffff0000, v131
	v_mfma_f32_16x16x32_bf16 v[112:115], v[34:37], v[100:103], v[112:115]
	v_mfma_f32_16x16x32_bf16 v[80:83], v[30:33], v[100:103], v[80:83]
	global_load_dwordx4 v[100:103], v[124:125], off offset:128
	global_load_dwordx4 v[116:119], v[124:125], off offset:192
	global_load_dword v66, v[78:79], off offset:128
	s_nop 0
	global_load_dwordx2 v[124:125], v[120:121], off offset:96
	s_waitcnt vmcnt(3)
	v_mfma_f32_16x16x32_bf16 v[104:107], v[50:53], v[100:103], v[104:107]
	s_waitcnt vmcnt(0)
; __device__ __forceinline__ unsigned cvtpk(float lo, float hi) { f32x2 v = {lo, hi}; bf16x2_t b = __builtin_convertvector(v, bf16x2_t); return __builtin_bit_cast(unsigned, b); }
; __device__ __forceinline__ float bflo(unsigned w) { return __uint_as_float(w << 16); }
; __device__ __forceinline__ float bfhi(unsigned w) { return __uint_as_float(w & 0xffff0000u); }
; __device__ __forceinline__ void sgu_unit(LAS unsigned char* lds, int x, bf16_t* UQ, const bf16_t* VA, const float* stv, const float* sgn, const bf16_t* SW, const float* sgb) {
;     ...
; #pragma unroll
;     for (int tt = 0; tt < 4; ++tt) {
;         const int t = 64 * th + 16 * tt + r16;
;         bf16x8 bfr[4];
; #pragma unroll
;         for (int ks = 0; ks < 4; ++ks) bfr[ks] = *(const bf16x8*)(SW + ((size_t)(g * 128 + t) * 128 + 32 * ks + 8 * fq));
;         const float bt = sgb[g * 128 + t];
;         bf16_t* up = UQ + (size_t)(r0 + t) * DM + 64 * g + 4 * fq;
; #pragma unroll
;         for (int dt = 0; dt < 4; ++dt) {
;             f32x4 a = (f32x4){0.f, 0.f, 0.f, 0.f};
; #pragma unroll
;             for (int ks = 0; ks < 4; ++ks) a = __builtin_amdgcn_mfma_f32_16x16x32_bf16(af[dt][ks], bfr[ks], a, 0, 0, 0);
;             const u32x2 uv = *(const u32x2*)(up + 16 * dt);
;             u32x2 wv; wv.x = cvtpk(bflo(uv.x) * (a[0] + bt), bfhi(uv.x) * (a[1] + bt)); wv.y = cvtpk(bflo(uv.y) * (a[2] + bt), bfhi(uv.y) * (a[3] + bt));
;             *(u32x2*)(up + 16 * dt) = wv;
;         }
;     }
;     __syncthreads();
	v_lshlrev_b32_e32 v138, 16, v124
	v_mfma_f32_16x16x32_bf16 v[108:111], v[26:29], v[100:103], v[108:111]
	v_and_b32_e32 v139, 0xffff0000, v124
	v_lshlrev_b32_e32 v124, 16, v125
	v_and_b32_e32 v125, 0xffff0000, v125
	v_mfma_f32_16x16x32_bf16 v[112:115], v[22:25], v[100:103], v[112:115]
	v_mfma_f32_16x16x32_bf16 v[80:83], v[18:21], v[100:103], v[80:83]
	v_mfma_f32_16x16x32_bf16 v[100:103], v[2:5], v[116:119], v[104:107]
	v_mfma_f32_16x16x32_bf16 v[104:107], v[6:9], v[116:119], v[108:111]
	v_mfma_f32_16x16x32_bf16 v[108:111], v[14:17], v[116:119], v[112:115]
	s_nop 5
	v_add_f32_e64 v100, v66, v100
	v_add_f32_e64 v101, v66, v101
	v_pk_add_f32 v[102:103], v[66:67], v[102:103] op_sel_hi:[0,1]
	v_pk_add_f32 v[104:105], v[66:67], v[104:105] op_sel_hi:[0,1]
	v_mfma_f32_16x16x32_bf16 v[80:83], v[10:13], v[116:119], v[80:83]
	v_add_f32_e64 v106, v66, v106
	v_add_f32_e64 v107, v66, v107
	v_pk_add_f32 v[108:109], v[66:67], v[108:109] op_sel_hi:[0,1]
	v_pk_add_f32 v[110:111], v[66:67], v[110:111] op_sel_hi:[0,1]
	v_pk_mul_f32 v[100:101], v[100:101], v[132:133]
	v_pk_mul_f32 v[102:103], v[102:103], v[126:127]
	s_nop 1
	v_pk_add_f32 v[80:81], v[66:67], v[80:81] op_sel_hi:[0,1]
	v_pk_add_f32 v[82:83], v[66:67], v[82:83] op_sel_hi:[0,1]
	v_pk_mul_f32 v[104:105], v[104:105], v[134:135]
	v_pk_mul_f32 v[106:107], v[106:107], v[128:129]
	v_pk_mul_f32 v[108:109], v[108:109], v[136:137]
	v_pk_mul_f32 v[110:111], v[110:111], v[130:131]
	v_pk_mul_f32 v[80:81], v[80:81], v[138:139]
	v_pk_mul_f32 v[82:83], v[82:83], v[124:125]
	v_cvt_pk_bf16_f32 v100, v100, v101
	v_cvt_pk_bf16_f32 v101, v102, v103
	v_cvt_pk_bf16_f32 v102, v104, v105
	v_cvt_pk_bf16_f32 v103, v106, v107
	v_cvt_pk_bf16_f32 v104, v108, v109
	v_cvt_pk_bf16_f32 v105, v110, v111
	v_cvt_pk_bf16_f32 v80, v80, v81
	v_cvt_pk_bf16_f32 v81, v82, v83
	global_store_dwordx2 v[120:121], v[100:101], off sc1
	global_store_dwordx2 v[120:121], v[102:103], off offset:32 sc1
	global_store_dwordx2 v[120:121], v[104:105], off offset:64 sc1
	global_store_dwordx2 v[120:121], v[80:81], off offset:96 sc1
	global_load_dwordx4 v[80:83], v[122:123], off
	s_nop 0
	global_load_dwordx4 v[100:103], v[122:123], off offset:64
	s_waitcnt vmcnt(1)
	v_mfma_f32_16x16x32_bf16 v[62:65], v[62:65], v[80:83], 0
	v_mfma_f32_16x16x32_bf16 v[58:61], v[58:61], v[80:83], 0
	v_mfma_f32_16x16x32_bf16 v[54:57], v[54:57], v[80:83], 0
	v_mfma_f32_16x16x32_bf16 v[38:41], v[38:41], v[80:83], 0
	v_add_u32_e32 v80, s7, v99
	v_ashrrev_i32_e32 v81, 31, v80
	s_waitcnt vmcnt(0)
	v_mfma_f32_16x16x32_bf16 v[42:45], v[42:45], v[100:103], v[62:65]
	s_nop 2
	v_lshlrev_b64 v[62:63], 11, v[80:81]
	v_lshl_add_u64 v[62:63], v[76:77], 0, v[62:63]
	global_load_dwordx2 v[64:65], v[62:63], off
	v_mfma_f32_16x16x32_bf16 v[46:49], v[46:49], v[100:103], v[58:61]
	s_nop 2
	global_load_dwordx2 v[58:59], v[62:63], off offset:32
	global_load_dwordx2 v[60:61], v[62:63], off offset:64
	global_load_dwordx2 v[76:77], v[62:63], off offset:96
	v_mfma_f32_16x16x32_bf16 v[34:37], v[34:37], v[100:103], v[54:57]
	s_nop 2
	global_load_dwordx4 v[54:57], v[122:123], off offset:128
	v_mfma_f32_16x16x32_bf16 v[30:33], v[30:33], v[100:103], v[38:41]
	s_nop 2
	global_load_dwordx4 v[38:41], v[122:123], off offset:192
	s_waitcnt vmcnt(1)
	v_mfma_f32_16x16x32_bf16 v[42:45], v[50:53], v[54:57], v[42:45]
	global_load_dword v50, v[78:79], off offset:192
	v_mfma_f32_16x16x32_bf16 v[26:29], v[26:29], v[54:57], v[46:49]
	v_mfma_f32_16x16x32_bf16 v[22:25], v[22:25], v[54:57], v[34:37]
	s_nop 1
	v_lshlrev_b32_e32 v46, 16, v64
	v_and_b32_e32 v47, 0xffff0000, v64
	v_mfma_f32_16x16x32_bf16 v[18:21], v[18:21], v[54:57], v[30:33]
	v_lshlrev_b32_e32 v34, 16, v65
	v_and_b32_e32 v35, 0xffff0000, v65
	v_lshlrev_b32_e32 v36, 16, v60
	s_waitcnt vmcnt(1)
	v_mfma_f32_16x16x32_bf16 v[2:5], v[2:5], v[38:41], v[42:45]
	v_lshlrev_b32_e32 v30, 16, v58
	v_and_b32_e32 v31, 0xffff0000, v58
	v_lshlrev_b32_e32 v32, 16, v59
	v_mfma_f32_16x16x32_bf16 v[6:9], v[6:9], v[38:41], v[26:29]
	v_and_b32_e32 v33, 0xffff0000, v59
	v_and_b32_e32 v37, 0xffff0000, v60
	s_waitcnt vmcnt(0)
	s_nop 0
	v_pk_add_f32 v[2:3], v[50:51], v[2:3] op_sel_hi:[0,1]
	v_mfma_f32_16x16x32_bf16 v[14:17], v[14:17], v[38:41], v[22:25]
	v_add_f32_e64 v4, v50, v4
	v_add_f32_e64 v5, v50, v5
	v_lshlrev_b32_e32 v26, 16, v61
	v_and_b32_e32 v27, 0xffff0000, v61
	v_mfma_f32_16x16x32_bf16 v[10:13], v[10:13], v[38:41], v[18:21]
	v_lshlrev_b32_e32 v28, 16, v76
	v_and_b32_e32 v29, 0xffff0000, v76
	v_lshlrev_b32_e32 v22, 16, v77
	v_and_b32_e32 v23, 0xffff0000, v77
	v_pk_add_f32 v[6:7], v[50:51], v[6:7] op_sel_hi:[0,1]
	v_pk_add_f32 v[8:9], v[50:51], v[8:9] op_sel_hi:[0,1]
	v_pk_add_f32 v[14:15], v[50:51], v[14:15] op_sel_hi:[0,1]
	v_pk_add_f32 v[16:17], v[50:51], v[16:17] op_sel_hi:[0,1]
	v_pk_add_f32 v[10:11], v[50:51], v[10:11] op_sel_hi:[0,1]
	v_pk_add_f32 v[12:13], v[50:51], v[12:13] op_sel_hi:[0,1]
	v_pk_mul_f32 v[2:3], v[2:3], v[46:47]
	v_pk_mul_f32 v[4:5], v[4:5], v[34:35]
	v_pk_mul_f32 v[6:7], v[6:7], v[30:31]
	v_pk_mul_f32 v[8:9], v[8:9], v[32:33]
	v_pk_mul_f32 v[14:15], v[14:15], v[36:37]
	v_pk_mul_f32 v[16:17], v[16:17], v[26:27]
	v_pk_mul_f32 v[10:11], v[10:11], v[28:29]
	v_pk_mul_f32 v[12:13], v[12:13], v[22:23]
	v_cvt_pk_bf16_f32 v2, v2, v3
	v_cvt_pk_bf16_f32 v3, v4, v5
	v_cvt_pk_bf16_f32 v4, v6, v7
	v_cvt_pk_bf16_f32 v5, v8, v9
	v_cvt_pk_bf16_f32 v6, v14, v15
	v_cvt_pk_bf16_f32 v7, v16, v17
	v_cvt_pk_bf16_f32 v8, v10, v11
	v_cvt_pk_bf16_f32 v9, v12, v13
	global_store_dwordx2 v[62:63], v[2:3], off sc1
	global_store_dwordx2 v[62:63], v[4:5], off offset:32 sc1
	global_store_dwordx2 v[62:63], v[6:7], off offset:64 sc1
	global_store_dwordx2 v[62:63], v[8:9], off offset:96 sc1
	s_barrier
	s_cbranch_scc1 .LBB0_542

; #define LAS __attribute__((address_space(3)))
; __device__ __forceinline__ void rstd8_lds(int rrel, int fq, float inv_dim, float (&rs)[2][4]) {
;     ...
;         for (int m = 0; m < 4; ++m) v[ai][m] = *(const LAS f32x4*)(lds + STAB_OFF + (rrel + ai * 128 + m * 16) * 64 + fq * 16);
; #pragma unroll
;     for (int ai = 0; ai < 2; ++ai)
; #pragma unroll
;         for (int m = 0; m < 4; ++m) { float q = (v[ai][m][0] + v[ai][m][1]) + (v[ai][m][2] + v[ai][m][3]); q += __shfl_xor(q, 16); q += __shfl_xor(q, 32); rs[ai][m] = __builtin_amdgcn_rsqf(q * inv_dim + EPS); }
;     __device__ __forceinline__ void operator()(const Acc& acc, const Unit& u, int wr, int wc, int fr, int fq) const {
;         bf16_t* base = u.pn < 4 ? GA : GB; const int col = (u.pn & 3) * 256 + wc * 32 + fq * 8;
;         const float* bp = gbias + u.pn * 256 + wc * 32 + fq * 8;
;         f32x4 bv[2][2];
; #pragma unroll
;         for (int bj = 0; bj < 2; ++bj)
; #pragma unroll
;             for (int n = 0; n < 2; ++n) bv[bj][n] = *(const f32x4*)(bp + bj * 128 + 4 * n) * (-LOG2E);
;         float rsv[2][4]; rstd8_lds(wr * 64 + fr, fq, 1.0f / 1024.0f, rsv);
.LBB0_622:
	s_cmp_lt_i32 s63, 4
	s_cselect_b32 s45, s17, s55
	s_cselect_b32 s44, s16, s54
	s_lshl_b32 s46, s63, 8
	s_ashr_i32 s47, s46, 31
	v_lshl_add_u64 v[160:161], s[46:47], 2, v[140:141]
	global_load_dwordx4 v[152:155], v[160:161], off
	global_load_dwordx4 v[156:159], v[160:161], off offset:16
	global_load_dwordx4 v[180:183], v[160:161], off offset:512
	global_load_dwordx4 v[184:187], v[160:161], off offset:528
	v_and_b32_e32 v168, 64, v178
	v_xor_b32_e32 v138, 16, v178
	v_add_u32_e32 v168, 64, v168
	v_xor_b32_e32 v169, 32, v178
	v_cmp_lt_i32_e32 vcc, v138, v168
	ds_read_b128 v[160:163], v177
	ds_read_b128 v[164:167], v177 offset:1024
	ds_read_b128 v[188:191], v177 offset:2048
	ds_read_b128 v[192:195], v177 offset:3072
	ds_read_b128 v[196:199], v177 offset:8192
	ds_read_b128 v[200:203], v177 offset:9216
	ds_read_b128 v[204:207], v177 offset:10240
	ds_read_b128 v[208:211], v177 offset:11264
	v_cndmask_b32_e32 v138, v178, v138, vcc
	v_cmp_lt_i32_e32 vcc, v169, v168
	v_lshlrev_b32_e32 v138, 2, v138
	s_and_b32 s25, s46, 0x300
	v_cndmask_b32_e32 v168, v178, v169, vcc
	v_lshlrev_b32_e32 v213, 2, v168
	s_waitcnt lgkmcnt(0)
	v_mov_b32_e32 v168, v161
	v_mov_b32_e32 v169, v162
	v_mov_b32_e32 v161, v163
	v_mov_b32_e32 v162, v165
	v_mov_b32_e32 v163, v166
	v_mov_b32_e32 v165, v167
	v_mov_b32_e32 v166, v189
	v_mov_b32_e32 v167, v190
	v_mov_b32_e32 v189, v191
	v_pk_add_f32 v[160:161], v[168:169], v[160:161]
	v_pk_add_f32 v[162:163], v[162:163], v[164:165]
	v_mov_b32_e32 v190, v193
	v_mov_b32_e32 v191, v194
	v_mov_b32_e32 v193, v195
	v_pk_add_f32 v[164:165], v[166:167], v[188:189]
	v_add_f32_e32 v160, v160, v161
	v_add_f32_e32 v161, v162, v163
	v_pk_add_f32 v[166:167], v[190:191], v[192:193]
	v_add_f32_e32 v162, v164, v165
	ds_bpermute_b32 v164, v138, v160
	ds_bpermute_b32 v165, v138, v161
	v_add_f32_e32 v163, v166, v167
	ds_bpermute_b32 v166, v138, v162
	v_mov_b32_e32 v194, v197
	v_mov_b32_e32 v195, v198
	v_mov_b32_e32 v197, v199
	s_waitcnt lgkmcnt(0)
	v_add_f32_e32 v160, v160, v164
	v_add_f32_e32 v161, v161, v165
	v_pk_add_f32 v[168:169], v[194:195], v[196:197]
	ds_bpermute_b32 v167, v138, v163
	v_add_f32_e32 v162, v162, v166
	ds_bpermute_b32 v164, v213, v160
	ds_bpermute_b32 v165, v213, v161
	v_add_f32_e32 v168, v168, v169
	ds_bpermute_b32 v166, v213, v162
	ds_bpermute_b32 v169, v138, v168
	s_waitcnt lgkmcnt(0)
	v_add_f32_e32 v188, v163, v167
	v_add_f32_e32 v160, v160, v164
	v_add_f32_e32 v161, v161, v165
	ds_bpermute_b32 v189, v213, v188
	v_add_f32_e32 v162, v162, v166
	v_fmamk_f32 v160, v160, 0x3a800000, v179
	v_fmamk_f32 v161, v161, 0x3a800000, v179
	v_fmamk_f32 v162, v162, 0x3a800000, v179
	v_rsq_f32_e32 v190, v160
	v_rsq_f32_e32 v191, v161
	v_rsq_f32_e32 v192, v162
	v_or_b32_e32 v212, s25, v173
	s_andn2_b64 vcc, exec, s[2:3]
	s_mov_b64 s[2:3], -1
	s_waitcnt vmcnt(0)
	v_pk_mul_f32 v[164:165], v[154:155], s[12:13] op_sel_hi:[1,0]
	v_pk_mul_f32 v[160:161], v[158:159], s[12:13] op_sel_hi:[1,0]
	v_pk_mul_f32 v[158:159], v[180:181], s[12:13] op_sel_hi:[1,0]
	v_add_f32_e32 v181, v168, v169
	v_mov_b32_e32 v168, v201
	v_mov_b32_e32 v169, v202
	v_mov_b32_e32 v201, v203
	v_pk_mul_f32 v[162:163], v[156:157], s[12:13] op_sel_hi:[1,0]
	v_pk_mul_f32 v[156:157], v[182:183], s[12:13] op_sel_hi:[1,0]
	ds_bpermute_b32 v182, v213, v181
	v_pk_add_f32 v[168:169], v[168:169], v[200:201]
	s_waitcnt lgkmcnt(1)
	v_add_f32_e32 v180, v188, v189
	v_add_f32_e32 v168, v168, v169
	ds_bpermute_b32 v169, v138, v168
	v_fmamk_f32 v180, v180, 0x3a800000, v179
	v_rsq_f32_e32 v183, v180
	s_waitcnt lgkmcnt(1)
	v_add_f32_e32 v180, v181, v182
	v_fmamk_f32 v180, v180, 0x3a800000, v179
	v_rsq_f32_e32 v189, v180
	s_waitcnt lgkmcnt(0)
	v_add_f32_e32 v180, v168, v169
	v_mov_b32_e32 v168, v205
	v_mov_b32_e32 v169, v206
	v_mov_b32_e32 v205, v207
	v_pk_add_f32 v[168:169], v[168:169], v[204:205]
	v_pk_mul_f32 v[154:155], v[184:185], s[12:13] op_sel_hi:[1,0]
	v_add_f32_e32 v182, v168, v169
	v_mov_b32_e32 v168, v209
	v_mov_b32_e32 v169, v210
	v_mov_b32_e32 v209, v211
	v_pk_add_f32 v[168:169], v[168:169], v[208:209]
	ds_bpermute_b32 v184, v138, v182
	v_add_f32_e32 v168, v168, v169
	ds_bpermute_b32 v138, v138, v168
	ds_bpermute_b32 v181, v213, v180
	v_pk_mul_f32 v[166:167], v[152:153], s[12:13] op_sel_hi:[1,0]
	v_mul_f32_e32 v188, 0xbfb8aa3b, v190
	v_pk_fma_f32 v[126:127], v[126:127], v[188:189], v[166:167] op_sel_hi:[1,0,1]
	s_waitcnt lgkmcnt(1)
	v_add_f32_e32 v138, v168, v138
	ds_bpermute_b32 v168, v213, v138
	s_waitcnt lgkmcnt(1)
	v_add_f32_e32 v169, v180, v181
	v_add_f32_e32 v180, v182, v184
	ds_bpermute_b32 v181, v213, v180
	v_exp_f32_e32 v184, v126
	v_exp_f32_e32 v185, v127
	s_waitcnt lgkmcnt(1)
	v_add_f32_e32 v138, v138, v168
	v_fmamk_f32 v169, v169, 0x3a800000, v179
	v_fmamk_f32 v138, v138, 0x3a800000, v179
	v_pk_fma_f32 v[128:129], v[128:129], v[188:189], v[164:165] op_sel_hi:[1,0,1]
	v_pk_fma_f32 v[122:123], v[122:123], v[188:189], v[162:163] op_sel_hi:[1,0,1]
	v_rsq_f32_e32 v182, v169
	s_waitcnt lgkmcnt(0)
; __device__ __forceinline__ f32x4 sig_from_negl2(f32x4 t) { return rcp_4(exp2_4(t) + 1.0f); }
; __device__ __forceinline__ u32x2 pack4(f32x4 v) { u32x2 w; w.x = cvtpk(v[0], v[1]); w.y = cvtpk(v[2], v[3]); return w; }
;     __device__ __forceinline__ void operator()(const Acc& acc, const Unit& u, int wr, int wc, int fr, int fq) const {
;     ...
;         for (int ai = 0; ai < 2; ++ai)
; #pragma unroll
;             for (int m = 0; m < 4; ++m) {
;                 const int r = u.pm * 256 + ai * 128 + wr * 64 + m * 16 + fr;
;                 const float nrs = -LOG2E * rsv[ai][m];
; #pragma unroll
;                 for (int bj = 0; bj < 2; ++bj) {
;                     const u32x2 p0 = pack4(sig_from_negl2(acc[ai][bj][m][0] * nrs + bv[bj][0])), p1 = pack4(sig_from_negl2(acc[ai][bj][m][1] * nrs + bv[bj][1]));
;                     u32x4 w; w.x = p0.x; w.y = p0.y; w.z = p1.x; w.w = p1.y;
;                     *(u32x4*)(base + (size_t)r * DM + col + bj * 128) = w;
;                 }
;             }
	v_add_f32_e32 v169, v180, v181
	v_rsq_f32_e32 v180, v138
	v_lshlrev_b32_e32 v138, 1, v212
	v_exp_f32_e32 v128, v128
	v_exp_f32_e32 v129, v129
	v_pk_add_f32 v[184:185], v[184:185], 1.0 op_sel_hi:[1,0]
	v_exp_f32_e32 v122, v122
	v_exp_f32_e32 v123, v123
	v_pk_fma_f32 v[124:125], v[124:125], v[188:189], v[160:161] op_sel_hi:[1,0,1]
	v_lshl_add_u64 v[126:127], s[44:45], 0, v[138:139]
	v_rcp_f32_e32 v138, v184
	v_rcp_f32_e32 v184, v185
	v_exp_f32_e32 v124, v124
	v_exp_f32_e32 v125, v125
	v_pk_mul_f32 v[152:153], v[186:187], s[12:13] op_sel_hi:[1,0]
	v_fmamk_f32 v169, v169, 0x3a800000, v179
	v_lshl_add_u32 v168, s42, 8, v1
	v_rsq_f32_e32 v181, v169
	v_ashrrev_i32_e32 v169, 31, v168
	v_pk_add_f32 v[128:129], v[128:129], 1.0 op_sel_hi:[1,0]
	v_pk_add_f32 v[122:123], v[122:123], 1.0 op_sel_hi:[1,0]
	v_pk_fma_f32 v[120:121], v[120:121], v[188:189], v[156:157] op_sel_hi:[1,0,1]
	v_pk_fma_f32 v[118:119], v[118:119], v[188:189], v[158:159] op_sel_hi:[1,0,1]
	v_pk_fma_f32 v[116:117], v[116:117], v[188:189], v[152:153] op_sel_hi:[1,0,1]
	v_pk_fma_f32 v[114:115], v[114:115], v[188:189], v[154:155] op_sel_hi:[1,0,1]
	v_rcp_f32_e32 v185, v128
	v_rcp_f32_e32 v186, v129
	v_lshlrev_b64 v[128:129], 11, v[168:169]
	v_cvt_pk_bf16_f32 v184, v138, v184
	v_rcp_f32_e32 v138, v122
	v_rcp_f32_e32 v169, v123
	v_pk_add_f32 v[122:123], v[124:125], 1.0 op_sel_hi:[1,0]
	v_exp_f32_e32 v118, v118
	v_exp_f32_e32 v120, v120
	v_exp_f32_e32 v121, v121
	v_exp_f32_e32 v119, v119
	v_exp_f32_e32 v114, v114
	v_exp_f32_e32 v116, v116
	v_exp_f32_e32 v117, v117
	v_exp_f32_e32 v115, v115
	v_rcp_f32_e32 v122, v122
	v_rcp_f32_e32 v123, v123
	v_pk_add_f32 v[120:121], v[120:121], 1.0 op_sel_hi:[1,0]
	v_pk_add_f32 v[118:119], v[118:119], 1.0 op_sel_hi:[1,0]
	v_pk_add_f32 v[116:117], v[116:117], 1.0 op_sel_hi:[1,0]
	v_pk_add_f32 v[114:115], v[114:115], 1.0 op_sel_hi:[1,0]
	v_cvt_pk_bf16_f32 v187, v122, v123
	v_rcp_f32_e32 v118, v118
	v_rcp_f32_e32 v119, v119
	v_rcp_f32_e32 v120, v120
	v_rcp_f32_e32 v121, v121
	v_rcp_f32_e32 v122, v114
	v_rcp_f32_e32 v123, v115
	v_rcp_f32_e32 v124, v116
	v_rcp_f32_e32 v117, v117
	v_lshl_add_u64 v[128:129], v[126:127], 0, v[128:129]
	v_cvt_pk_bf16_f32 v114, v118, v119
	v_cvt_pk_bf16_f32 v115, v120, v121
	v_cvt_pk_bf16_f32 v116, v122, v123
	v_cvt_pk_bf16_f32 v117, v124, v117
	global_store_dwordx4 v[128:129], v[114:117], off offset:256 sc1
	v_cvt_pk_bf16_f32 v185, v185, v186
	v_cvt_pk_bf16_f32 v186, v138, v169
	v_mul_f32_e32 v114, 0xbfb8aa3b, v191
	v_pk_fma_f32 v[110:111], v[110:111], v[114:115], v[166:167] op_sel_hi:[1,0,1]
	v_pk_fma_f32 v[112:113], v[112:113], v[114:115], v[164:165] op_sel_hi:[1,0,1]
	v_exp_f32_e32 v110, v110
	v_exp_f32_e32 v111, v111
	v_exp_f32_e32 v112, v112
	v_exp_f32_e32 v113, v113
	v_or_b32_e32 v116, 16, v168
	v_pk_add_f32 v[110:111], v[110:111], 1.0 op_sel_hi:[1,0]
	v_ashrrev_i32_e32 v117, 31, v116
	v_rcp_f32_e32 v115, v110
	v_pk_add_f32 v[112:113], v[112:113], 1.0 op_sel_hi:[1,0]
	v_rcp_f32_e32 v118, v111
	v_rcp_f32_e32 v112, v112
	v_pk_fma_f32 v[106:107], v[106:107], v[114:115], v[162:163] op_sel_hi:[1,0,1]
	v_pk_fma_f32 v[108:109], v[108:109], v[114:115], v[160:161] op_sel_hi:[1,0,1]
	v_exp_f32_e32 v106, v106
	v_exp_f32_e32 v107, v107
	v_rcp_f32_e32 v113, v113
	v_exp_f32_e32 v108, v108
	v_exp_f32_e32 v109, v109
	v_lshlrev_b64 v[110:111], 11, v[116:117]
	v_pk_add_f32 v[106:107], v[106:107], 1.0 op_sel_hi:[1,0]
	v_pk_fma_f32 v[104:105], v[104:105], v[114:115], v[156:157] op_sel_hi:[1,0,1]
	v_pk_fma_f32 v[102:103], v[102:103], v[114:115], v[158:159] op_sel_hi:[1,0,1]
	v_pk_fma_f32 v[100:101], v[100:101], v[114:115], v[152:153] op_sel_hi:[1,0,1]
	v_pk_fma_f32 v[98:99], v[98:99], v[114:115], v[154:155] op_sel_hi:[1,0,1]
	v_lshl_add_u64 v[116:117], v[126:127], 0, v[110:111]
	v_cvt_pk_bf16_f32 v111, v112, v113
	v_rcp_f32_e32 v112, v106
	v_rcp_f32_e32 v113, v107
	v_pk_add_f32 v[106:107], v[108:109], 1.0 op_sel_hi:[1,0]
	v_exp_f32_e32 v102, v102
	v_exp_f32_e32 v104, v104
	v_exp_f32_e32 v105, v105
	v_exp_f32_e32 v103, v103
	v_exp_f32_e32 v98, v98
	v_exp_f32_e32 v100, v100
	v_exp_f32_e32 v101, v101
	v_exp_f32_e32 v99, v99
	v_rcp_f32_e32 v106, v106
	v_rcp_f32_e32 v107, v107
	v_pk_add_f32 v[104:105], v[104:105], 1.0 op_sel_hi:[1,0]
	v_pk_add_f32 v[102:103], v[102:103], 1.0 op_sel_hi:[1,0]
	v_pk_add_f32 v[100:101], v[100:101], 1.0 op_sel_hi:[1,0]
	v_pk_add_f32 v[98:99], v[98:99], 1.0 op_sel_hi:[1,0]
	v_cvt_pk_bf16_f32 v112, v112, v113
	v_cvt_pk_bf16_f32 v113, v106, v107
	v_rcp_f32_e32 v102, v102
	v_rcp_f32_e32 v103, v103
	v_rcp_f32_e32 v104, v104
	v_rcp_f32_e32 v105, v105
	v_rcp_f32_e32 v106, v98
	v_rcp_f32_e32 v107, v99
	v_rcp_f32_e32 v108, v100
	v_rcp_f32_e32 v101, v101
	v_cvt_pk_bf16_f32 v98, v102, v103
	v_cvt_pk_bf16_f32 v99, v104, v105
	v_cvt_pk_bf16_f32 v100, v106, v107
	v_cvt_pk_bf16_f32 v101, v108, v101
	global_store_dwordx4 v[116:117], v[98:101], off offset:256 sc1
	v_cvt_pk_bf16_f32 v110, v115, v118
	global_store_dwordx4 v[128:129], v[184:187], off sc1
	v_mul_f32_e32 v98, 0xbfb8aa3b, v192
	v_pk_fma_f32 v[94:95], v[94:95], v[98:99], v[166:167] op_sel_hi:[1,0,1]
	v_pk_fma_f32 v[96:97], v[96:97], v[98:99], v[164:165] op_sel_hi:[1,0,1]
	v_exp_f32_e32 v94, v94
	v_exp_f32_e32 v95, v95
	v_exp_f32_e32 v96, v96
	v_exp_f32_e32 v97, v97
	v_or_b32_e32 v100, 32, v168
	v_pk_add_f32 v[94:95], v[94:95], 1.0 op_sel_hi:[1,0]
	v_ashrrev_i32_e32 v101, 31, v100
	v_rcp_f32_e32 v99, v94
	v_pk_add_f32 v[96:97], v[96:97], 1.0 op_sel_hi:[1,0]
	v_rcp_f32_e32 v102, v95
	v_rcp_f32_e32 v96, v96
	v_pk_fma_f32 v[90:91], v[90:91], v[98:99], v[162:163] op_sel_hi:[1,0,1]
	v_pk_fma_f32 v[92:93], v[92:93], v[98:99], v[160:161] op_sel_hi:[1,0,1]
	v_exp_f32_e32 v90, v90
; __device__ __forceinline__ f32x4 sig_from_negl2(f32x4 t) { return rcp_4(exp2_4(t) + 1.0f); }
; __device__ __forceinline__ u32x2 pack4(f32x4 v) { u32x2 w; w.x = cvtpk(v[0], v[1]); w.y = cvtpk(v[2], v[3]); return w; }
;     __device__ __forceinline__ void operator()(const Acc& acc, const Unit& u, int wr, int wc, int fr, int fq) const {
;     ...
;         for (int ai = 0; ai < 2; ++ai)
; #pragma unroll
;             for (int m = 0; m < 4; ++m) {
;                 const int r = u.pm * 256 + ai * 128 + wr * 64 + m * 16 + fr;
;                 const float nrs = -LOG2E * rsv[ai][m];
; #pragma unroll
;                 for (int bj = 0; bj < 2; ++bj) {
;                     const u32x2 p0 = pack4(sig_from_negl2(acc[ai][bj][m][0] * nrs + bv[bj][0])), p1 = pack4(sig_from_negl2(acc[ai][bj][m][1] * nrs + bv[bj][1]));
;                     u32x4 w; w.x = p0.x; w.y = p0.y; w.z = p1.x; w.w = p1.y;
;                     *(u32x4*)(base + (size_t)r * DM + col + bj * 128) = w;
;                 }
;             }
	v_exp_f32_e32 v91, v91
	v_rcp_f32_e32 v97, v97
	v_exp_f32_e32 v92, v92
	v_exp_f32_e32 v93, v93
	v_lshlrev_b64 v[94:95], 11, v[100:101]
	v_pk_add_f32 v[90:91], v[90:91], 1.0 op_sel_hi:[1,0]
	v_pk_fma_f32 v[88:89], v[88:89], v[98:99], v[156:157] op_sel_hi:[1,0,1]
	v_pk_fma_f32 v[86:87], v[86:87], v[98:99], v[158:159] op_sel_hi:[1,0,1]
	v_pk_fma_f32 v[84:85], v[84:85], v[98:99], v[152:153] op_sel_hi:[1,0,1]
	v_pk_fma_f32 v[82:83], v[82:83], v[98:99], v[154:155] op_sel_hi:[1,0,1]
	v_lshl_add_u64 v[100:101], v[126:127], 0, v[94:95]
	v_cvt_pk_bf16_f32 v95, v96, v97
	v_rcp_f32_e32 v96, v90
	v_rcp_f32_e32 v97, v91
	v_pk_add_f32 v[90:91], v[92:93], 1.0 op_sel_hi:[1,0]
	v_exp_f32_e32 v86, v86
	v_exp_f32_e32 v88, v88
	v_exp_f32_e32 v89, v89
	v_exp_f32_e32 v87, v87
	v_exp_f32_e32 v82, v82
	v_exp_f32_e32 v84, v84
	v_exp_f32_e32 v85, v85
	v_exp_f32_e32 v83, v83
	v_rcp_f32_e32 v90, v90
	v_rcp_f32_e32 v91, v91
	v_pk_add_f32 v[88:89], v[88:89], 1.0 op_sel_hi:[1,0]
	v_pk_add_f32 v[86:87], v[86:87], 1.0 op_sel_hi:[1,0]
	v_pk_add_f32 v[84:85], v[84:85], 1.0 op_sel_hi:[1,0]
	v_pk_add_f32 v[82:83], v[82:83], 1.0 op_sel_hi:[1,0]
	v_cvt_pk_bf16_f32 v96, v96, v97
	v_cvt_pk_bf16_f32 v97, v90, v91
	v_rcp_f32_e32 v86, v86
	v_rcp_f32_e32 v87, v87
	v_rcp_f32_e32 v88, v88
	v_rcp_f32_e32 v89, v89
	v_rcp_f32_e32 v90, v82
	v_rcp_f32_e32 v91, v83
	v_rcp_f32_e32 v92, v84
	v_rcp_f32_e32 v85, v85
	v_cvt_pk_bf16_f32 v82, v86, v87
	v_cvt_pk_bf16_f32 v83, v88, v89
	v_cvt_pk_bf16_f32 v84, v90, v91
	v_cvt_pk_bf16_f32 v85, v92, v85
	global_store_dwordx4 v[100:101], v[82:85], off offset:256 sc1
	v_cvt_pk_bf16_f32 v94, v99, v102
	global_store_dwordx4 v[116:117], v[110:113], off sc1
	v_mul_f32_e32 v82, 0xbfb8aa3b, v183
	v_pk_fma_f32 v[78:79], v[78:79], v[82:83], v[166:167] op_sel_hi:[1,0,1]
	v_pk_fma_f32 v[80:81], v[80:81], v[82:83], v[164:165] op_sel_hi:[1,0,1]
	v_exp_f32_e32 v78, v78
	v_exp_f32_e32 v79, v79
	v_exp_f32_e32 v80, v80
	v_exp_f32_e32 v81, v81
	v_or_b32_e32 v84, 48, v168
	v_pk_add_f32 v[78:79], v[78:79], 1.0 op_sel_hi:[1,0]
	v_ashrrev_i32_e32 v85, 31, v84
	v_rcp_f32_e32 v83, v78
	v_pk_add_f32 v[80:81], v[80:81], 1.0 op_sel_hi:[1,0]
	v_rcp_f32_e32 v86, v79
	v_rcp_f32_e32 v80, v80
	v_pk_fma_f32 v[74:75], v[74:75], v[82:83], v[162:163] op_sel_hi:[1,0,1]
	v_pk_fma_f32 v[76:77], v[76:77], v[82:83], v[160:161] op_sel_hi:[1,0,1]
	v_exp_f32_e32 v74, v74
	v_exp_f32_e32 v75, v75
	v_rcp_f32_e32 v81, v81
	v_exp_f32_e32 v76, v76
	v_exp_f32_e32 v77, v77
	v_lshlrev_b64 v[78:79], 11, v[84:85]
	v_pk_add_f32 v[74:75], v[74:75], 1.0 op_sel_hi:[1,0]
	v_pk_fma_f32 v[72:73], v[72:73], v[82:83], v[156:157] op_sel_hi:[1,0,1]
	v_pk_fma_f32 v[70:71], v[70:71], v[82:83], v[158:159] op_sel_hi:[1,0,1]
	v_pk_fma_f32 v[68:69], v[68:69], v[82:83], v[152:153] op_sel_hi:[1,0,1]
	v_pk_fma_f32 v[66:67], v[66:67], v[82:83], v[154:155] op_sel_hi:[1,0,1]
	v_lshl_add_u64 v[84:85], v[126:127], 0, v[78:79]
	v_cvt_pk_bf16_f32 v79, v80, v81
	v_rcp_f32_e32 v80, v74
	v_rcp_f32_e32 v81, v75
	v_pk_add_f32 v[74:75], v[76:77], 1.0 op_sel_hi:[1,0]
	v_exp_f32_e32 v70, v70
	v_exp_f32_e32 v72, v72
	v_exp_f32_e32 v73, v73
	v_exp_f32_e32 v71, v71
	v_exp_f32_e32 v66, v66
	v_exp_f32_e32 v68, v68
	v_exp_f32_e32 v69, v69
	v_exp_f32_e32 v67, v67
	v_rcp_f32_e32 v74, v74
	v_rcp_f32_e32 v75, v75
	v_pk_add_f32 v[72:73], v[72:73], 1.0 op_sel_hi:[1,0]
	v_pk_add_f32 v[70:71], v[70:71], 1.0 op_sel_hi:[1,0]
	v_pk_add_f32 v[68:69], v[68:69], 1.0 op_sel_hi:[1,0]
	v_pk_add_f32 v[66:67], v[66:67], 1.0 op_sel_hi:[1,0]
	v_cvt_pk_bf16_f32 v80, v80, v81
	v_cvt_pk_bf16_f32 v81, v74, v75
	v_rcp_f32_e32 v70, v70
	v_rcp_f32_e32 v71, v71
	v_rcp_f32_e32 v72, v72
	v_rcp_f32_e32 v73, v73
	v_rcp_f32_e32 v74, v66
	v_rcp_f32_e32 v75, v67
	v_rcp_f32_e32 v76, v68
	v_rcp_f32_e32 v69, v69
	v_cvt_pk_bf16_f32 v66, v70, v71
	v_cvt_pk_bf16_f32 v67, v72, v73
	v_cvt_pk_bf16_f32 v68, v74, v75
	v_cvt_pk_bf16_f32 v69, v76, v69
	global_store_dwordx4 v[84:85], v[66:69], off offset:256 sc1
	v_cvt_pk_bf16_f32 v78, v83, v86
	global_store_dwordx4 v[100:101], v[94:97], off sc1
	v_mul_f32_e32 v66, 0xbfb8aa3b, v189
	v_pk_fma_f32 v[62:63], v[62:63], v[66:67], v[166:167] op_sel_hi:[1,0,1]
	v_pk_fma_f32 v[64:65], v[64:65], v[66:67], v[164:165] op_sel_hi:[1,0,1]
	v_exp_f32_e32 v62, v62
	v_exp_f32_e32 v63, v63
	v_exp_f32_e32 v64, v64
	v_exp_f32_e32 v65, v65
	v_add_u32_e32 v68, 0x80, v168
	v_pk_add_f32 v[62:63], v[62:63], 1.0 op_sel_hi:[1,0]
	v_ashrrev_i32_e32 v69, 31, v68
	v_rcp_f32_e32 v67, v62
	v_pk_add_f32 v[64:65], v[64:65], 1.0 op_sel_hi:[1,0]
	v_rcp_f32_e32 v70, v63
	v_rcp_f32_e32 v64, v64
	v_pk_fma_f32 v[58:59], v[58:59], v[66:67], v[162:163] op_sel_hi:[1,0,1]
	v_pk_fma_f32 v[60:61], v[60:61], v[66:67], v[160:161] op_sel_hi:[1,0,1]
	v_exp_f32_e32 v58, v58
	v_exp_f32_e32 v59, v59
	v_rcp_f32_e32 v65, v65
	v_exp_f32_e32 v60, v60
	v_exp_f32_e32 v61, v61
	v_lshlrev_b64 v[62:63], 11, v[68:69]
	v_pk_add_f32 v[58:59], v[58:59], 1.0 op_sel_hi:[1,0]
	v_pk_fma_f32 v[56:57], v[56:57], v[66:67], v[156:157] op_sel_hi:[1,0,1]
	v_pk_fma_f32 v[54:55], v[54:55], v[66:67], v[158:159] op_sel_hi:[1,0,1]
	v_pk_fma_f32 v[52:53], v[52:53], v[66:67], v[152:153] op_sel_hi:[1,0,1]
	v_pk_fma_f32 v[50:51], v[50:51], v[66:67], v[154:155] op_sel_hi:[1,0,1]
	v_lshl_add_u64 v[68:69], v[126:127], 0, v[62:63]
	v_cvt_pk_bf16_f32 v63, v64, v65
	v_rcp_f32_e32 v64, v58
	v_rcp_f32_e32 v65, v59
	v_pk_add_f32 v[58:59], v[60:61], 1.0 op_sel_hi:[1,0]
	v_exp_f32_e32 v54, v54
	v_exp_f32_e32 v56, v56
	v_exp_f32_e32 v57, v57
	v_exp_f32_e32 v55, v55
	v_exp_f32_e32 v50, v50
	v_exp_f32_e32 v52, v52
	v_exp_f32_e32 v53, v53
	v_exp_f32_e32 v51, v51
	v_rcp_f32_e32 v58, v58
	v_rcp_f32_e32 v59, v59
	v_pk_add_f32 v[56:57], v[56:57], 1.0 op_sel_hi:[1,0]
; __device__ __forceinline__ f32x4 sig_from_negl2(f32x4 t) { return rcp_4(exp2_4(t) + 1.0f); }
; __device__ __forceinline__ u32x2 pack4(f32x4 v) { u32x2 w; w.x = cvtpk(v[0], v[1]); w.y = cvtpk(v[2], v[3]); return w; }
;     __device__ __forceinline__ void operator()(const Acc& acc, const Unit& u, int wr, int wc, int fr, int fq) const {
;     ...
;         for (int ai = 0; ai < 2; ++ai)
; #pragma unroll
;             for (int m = 0; m < 4; ++m) {
;                 const int r = u.pm * 256 + ai * 128 + wr * 64 + m * 16 + fr;
;                 const float nrs = -LOG2E * rsv[ai][m];
; #pragma unroll
;                 for (int bj = 0; bj < 2; ++bj) {
;                     const u32x2 p0 = pack4(sig_from_negl2(acc[ai][bj][m][0] * nrs + bv[bj][0])), p1 = pack4(sig_from_negl2(acc[ai][bj][m][1] * nrs + bv[bj][1]));
;                     u32x4 w; w.x = p0.x; w.y = p0.y; w.z = p1.x; w.w = p1.y;
;                     *(u32x4*)(base + (size_t)r * DM + col + bj * 128) = w;
;                 }
;             }
	v_pk_add_f32 v[54:55], v[54:55], 1.0 op_sel_hi:[1,0]
	v_pk_add_f32 v[52:53], v[52:53], 1.0 op_sel_hi:[1,0]
	v_pk_add_f32 v[50:51], v[50:51], 1.0 op_sel_hi:[1,0]
	v_cvt_pk_bf16_f32 v64, v64, v65
	v_cvt_pk_bf16_f32 v65, v58, v59
	v_rcp_f32_e32 v54, v54
	v_rcp_f32_e32 v55, v55
	v_rcp_f32_e32 v56, v56
	v_rcp_f32_e32 v57, v57
	v_rcp_f32_e32 v58, v50
	v_rcp_f32_e32 v59, v51
	v_rcp_f32_e32 v60, v52
	v_rcp_f32_e32 v53, v53
	v_cvt_pk_bf16_f32 v50, v54, v55
	v_cvt_pk_bf16_f32 v51, v56, v57
	v_cvt_pk_bf16_f32 v52, v58, v59
	v_cvt_pk_bf16_f32 v53, v60, v53
	global_store_dwordx4 v[68:69], v[50:53], off offset:256 sc1
	v_cvt_pk_bf16_f32 v62, v67, v70
	global_store_dwordx4 v[84:85], v[78:81], off sc1
	v_mul_f32_e32 v50, 0xbfb8aa3b, v182
	v_pk_fma_f32 v[46:47], v[46:47], v[50:51], v[166:167] op_sel_hi:[1,0,1]
	v_pk_fma_f32 v[48:49], v[48:49], v[50:51], v[164:165] op_sel_hi:[1,0,1]
	v_exp_f32_e32 v46, v46
	v_exp_f32_e32 v47, v47
	v_exp_f32_e32 v48, v48
	v_exp_f32_e32 v49, v49
	v_add_u32_e32 v52, 0x90, v168
	v_pk_add_f32 v[46:47], v[46:47], 1.0 op_sel_hi:[1,0]
	v_ashrrev_i32_e32 v53, 31, v52
	v_rcp_f32_e32 v51, v46
	v_pk_add_f32 v[48:49], v[48:49], 1.0 op_sel_hi:[1,0]
	v_rcp_f32_e32 v54, v47
	v_rcp_f32_e32 v48, v48
	v_pk_fma_f32 v[42:43], v[42:43], v[50:51], v[162:163] op_sel_hi:[1,0,1]
	v_pk_fma_f32 v[44:45], v[44:45], v[50:51], v[160:161] op_sel_hi:[1,0,1]
	v_exp_f32_e32 v42, v42
	v_exp_f32_e32 v43, v43
	v_rcp_f32_e32 v49, v49
	v_exp_f32_e32 v44, v44
	v_exp_f32_e32 v45, v45
	v_lshlrev_b64 v[46:47], 11, v[52:53]
	v_pk_add_f32 v[42:43], v[42:43], 1.0 op_sel_hi:[1,0]
	v_pk_fma_f32 v[40:41], v[40:41], v[50:51], v[156:157] op_sel_hi:[1,0,1]
	v_pk_fma_f32 v[38:39], v[38:39], v[50:51], v[158:159] op_sel_hi:[1,0,1]
	v_pk_fma_f32 v[36:37], v[36:37], v[50:51], v[152:153] op_sel_hi:[1,0,1]
	v_pk_fma_f32 v[34:35], v[34:35], v[50:51], v[154:155] op_sel_hi:[1,0,1]
	v_lshl_add_u64 v[52:53], v[126:127], 0, v[46:47]
	v_cvt_pk_bf16_f32 v47, v48, v49
	v_rcp_f32_e32 v48, v42
	v_rcp_f32_e32 v49, v43
	v_pk_add_f32 v[42:43], v[44:45], 1.0 op_sel_hi:[1,0]
	v_exp_f32_e32 v38, v38
	v_exp_f32_e32 v40, v40
	v_exp_f32_e32 v41, v41
	v_exp_f32_e32 v39, v39
	v_exp_f32_e32 v34, v34
	v_exp_f32_e32 v36, v36
	v_exp_f32_e32 v37, v37
	v_exp_f32_e32 v35, v35
	v_rcp_f32_e32 v42, v42
	v_rcp_f32_e32 v43, v43
	v_pk_add_f32 v[40:41], v[40:41], 1.0 op_sel_hi:[1,0]
	v_pk_add_f32 v[38:39], v[38:39], 1.0 op_sel_hi:[1,0]
	v_pk_add_f32 v[36:37], v[36:37], 1.0 op_sel_hi:[1,0]
	v_pk_add_f32 v[34:35], v[34:35], 1.0 op_sel_hi:[1,0]
	v_cvt_pk_bf16_f32 v48, v48, v49
	v_cvt_pk_bf16_f32 v49, v42, v43
	v_rcp_f32_e32 v38, v38
	v_rcp_f32_e32 v39, v39
	v_rcp_f32_e32 v40, v40
	v_rcp_f32_e32 v41, v41
	v_rcp_f32_e32 v42, v34
	v_rcp_f32_e32 v43, v35
	v_rcp_f32_e32 v44, v36
	v_rcp_f32_e32 v37, v37
	v_cvt_pk_bf16_f32 v34, v38, v39
	v_cvt_pk_bf16_f32 v35, v40, v41
	v_cvt_pk_bf16_f32 v36, v42, v43
	v_cvt_pk_bf16_f32 v37, v44, v37
	global_store_dwordx4 v[52:53], v[34:37], off offset:256 sc1
	v_cvt_pk_bf16_f32 v46, v51, v54
	global_store_dwordx4 v[68:69], v[62:65], off sc1
	v_mul_f32_e32 v34, 0xbfb8aa3b, v181
	v_pk_fma_f32 v[30:31], v[30:31], v[34:35], v[166:167] op_sel_hi:[1,0,1]
	v_pk_fma_f32 v[32:33], v[32:33], v[34:35], v[164:165] op_sel_hi:[1,0,1]
	v_exp_f32_e32 v30, v30
	v_exp_f32_e32 v31, v31
	v_exp_f32_e32 v32, v32
	v_exp_f32_e32 v33, v33
	v_add_u32_e32 v36, 0xa0, v168
	v_pk_add_f32 v[30:31], v[30:31], 1.0 op_sel_hi:[1,0]
	v_ashrrev_i32_e32 v37, 31, v36
	v_rcp_f32_e32 v35, v30
	v_pk_add_f32 v[32:33], v[32:33], 1.0 op_sel_hi:[1,0]
	v_rcp_f32_e32 v38, v31
	v_rcp_f32_e32 v32, v32
	v_pk_fma_f32 v[26:27], v[26:27], v[34:35], v[162:163] op_sel_hi:[1,0,1]
	v_pk_fma_f32 v[28:29], v[28:29], v[34:35], v[160:161] op_sel_hi:[1,0,1]
	v_exp_f32_e32 v26, v26
	v_exp_f32_e32 v27, v27
	v_rcp_f32_e32 v33, v33
	v_exp_f32_e32 v28, v28
	v_exp_f32_e32 v29, v29
	v_lshlrev_b64 v[30:31], 11, v[36:37]
	v_pk_add_f32 v[26:27], v[26:27], 1.0 op_sel_hi:[1,0]
	v_pk_fma_f32 v[24:25], v[24:25], v[34:35], v[156:157] op_sel_hi:[1,0,1]
	v_pk_fma_f32 v[22:23], v[22:23], v[34:35], v[158:159] op_sel_hi:[1,0,1]
	v_pk_fma_f32 v[20:21], v[20:21], v[34:35], v[152:153] op_sel_hi:[1,0,1]
	v_pk_fma_f32 v[18:19], v[18:19], v[34:35], v[154:155] op_sel_hi:[1,0,1]
; __device__ __forceinline__ f32x4 sig_from_negl2(f32x4 t) { return rcp_4(exp2_4(t) + 1.0f); }
; __device__ __forceinline__ u32x2 pack4(f32x4 v) { u32x2 w; w.x = cvtpk(v[0], v[1]); w.y = cvtpk(v[2], v[3]); return w; }
; #define PG8_BAR __builtin_amdgcn_s_barrier()
; #define PG8_STATS(pm_) do { if constexpr (Epi::STAB) { if (wr == 1) { const char* _sb = (const char*)E.st + (size_t)(pm_) * 16384 + (size_t)lane * 16; \
;         _Pragma("unroll") for (int _i = 0; _i < 4; ++_i) __builtin_amdgcn_global_load_lds((const unsigned*)(_sb + ((wid - 4) + 4 * _i) * 1024), (LAS unsigned*)(lds + STAB_OFF + ((wid - 4) + 4 * _i) * 1024), 16, 0, 0); } } } while (0)
; template <class Epi>
; __device__ __forceinline__ void gemm_phase(LAS unsigned char* lds, const Gemm g, const StaticOrder& S, const Epi& E) {
;     ...
;         if (wr == 1) PG8_BAR;
;         PG8_STATS(cur.pm);
;     __device__ __forceinline__ void operator()(const Acc& acc, const Unit& u, int wr, int wc, int fr, int fq) const {
;     ...
;         for (int ai = 0; ai < 2; ++ai)
; #pragma unroll
;             for (int m = 0; m < 4; ++m) {
;                 const int r = u.pm * 256 + ai * 128 + wr * 64 + m * 16 + fr;
;                 const float nrs = -LOG2E * rsv[ai][m];
; #pragma unroll
;                 for (int bj = 0; bj < 2; ++bj) {
;                     const u32x2 p0 = pack4(sig_from_negl2(acc[ai][bj][m][0] * nrs + bv[bj][0])), p1 = pack4(sig_from_negl2(acc[ai][bj][m][1] * nrs + bv[bj][1]));
;                     u32x4 w; w.x = p0.x; w.y = p0.y; w.z = p1.x; w.w = p1.y;
;                     *(u32x4*)(base + (size_t)r * DM + col + bj * 128) = w;
;                 }
;             }
	v_lshl_add_u64 v[36:37], v[126:127], 0, v[30:31]
	v_cvt_pk_bf16_f32 v31, v32, v33
	v_rcp_f32_e32 v32, v26
	v_rcp_f32_e32 v33, v27
	v_pk_add_f32 v[26:27], v[28:29], 1.0 op_sel_hi:[1,0]
	v_exp_f32_e32 v22, v22
	v_exp_f32_e32 v24, v24
	v_exp_f32_e32 v25, v25
	v_exp_f32_e32 v23, v23
	v_exp_f32_e32 v18, v18
	v_exp_f32_e32 v20, v20
	v_exp_f32_e32 v21, v21
	v_exp_f32_e32 v19, v19
	v_rcp_f32_e32 v26, v26
	v_rcp_f32_e32 v27, v27
	v_pk_add_f32 v[24:25], v[24:25], 1.0 op_sel_hi:[1,0]
	v_pk_add_f32 v[22:23], v[22:23], 1.0 op_sel_hi:[1,0]
	v_pk_add_f32 v[20:21], v[20:21], 1.0 op_sel_hi:[1,0]
	v_pk_add_f32 v[18:19], v[18:19], 1.0 op_sel_hi:[1,0]
	v_cvt_pk_bf16_f32 v32, v32, v33
	v_cvt_pk_bf16_f32 v33, v26, v27
	v_rcp_f32_e32 v22, v22
	v_rcp_f32_e32 v23, v23
	v_rcp_f32_e32 v24, v24
	v_rcp_f32_e32 v25, v25
	v_rcp_f32_e32 v26, v18
	v_rcp_f32_e32 v27, v19
	v_rcp_f32_e32 v28, v20
	v_rcp_f32_e32 v21, v21
	v_cvt_pk_bf16_f32 v18, v22, v23
	v_cvt_pk_bf16_f32 v19, v24, v25
	v_cvt_pk_bf16_f32 v20, v26, v27
	v_cvt_pk_bf16_f32 v21, v28, v21
	global_store_dwordx4 v[36:37], v[18:21], off offset:256 sc1
	v_cvt_pk_bf16_f32 v30, v35, v38
	global_store_dwordx4 v[52:53], v[46:49], off sc1
	v_mul_f32_e32 v18, 0xbfb8aa3b, v180
	v_pk_fma_f32 v[14:15], v[14:15], v[18:19], v[166:167] op_sel_hi:[1,0,1]
	v_pk_fma_f32 v[16:17], v[16:17], v[18:19], v[164:165] op_sel_hi:[1,0,1]
	v_exp_f32_e32 v14, v14
	v_exp_f32_e32 v15, v15
	v_exp_f32_e32 v16, v16
	v_exp_f32_e32 v17, v17
	v_add_u32_e32 v20, 0xb0, v168
	v_pk_add_f32 v[14:15], v[14:15], 1.0 op_sel_hi:[1,0]
	v_ashrrev_i32_e32 v21, 31, v20
	v_rcp_f32_e32 v19, v14
	v_pk_add_f32 v[16:17], v[16:17], 1.0 op_sel_hi:[1,0]
	v_rcp_f32_e32 v22, v15
	v_rcp_f32_e32 v16, v16
	v_pk_fma_f32 v[10:11], v[10:11], v[18:19], v[162:163] op_sel_hi:[1,0,1]
	v_pk_fma_f32 v[12:13], v[12:13], v[18:19], v[160:161] op_sel_hi:[1,0,1]
	v_exp_f32_e32 v10, v10
	v_exp_f32_e32 v11, v11
	v_rcp_f32_e32 v17, v17
	v_exp_f32_e32 v12, v12
	v_exp_f32_e32 v13, v13
	v_lshlrev_b64 v[14:15], 11, v[20:21]
	v_pk_add_f32 v[10:11], v[10:11], 1.0 op_sel_hi:[1,0]
	v_pk_fma_f32 v[8:9], v[8:9], v[18:19], v[156:157] op_sel_hi:[1,0,1]
	v_pk_fma_f32 v[6:7], v[6:7], v[18:19], v[158:159] op_sel_hi:[1,0,1]
	v_pk_fma_f32 v[4:5], v[4:5], v[18:19], v[152:153] op_sel_hi:[1,0,1]
	v_pk_fma_f32 v[2:3], v[2:3], v[18:19], v[154:155] op_sel_hi:[1,0,1]
	v_lshl_add_u64 v[20:21], v[126:127], 0, v[14:15]
	v_cvt_pk_bf16_f32 v15, v16, v17
	v_rcp_f32_e32 v16, v10
	v_rcp_f32_e32 v17, v11
	v_pk_add_f32 v[10:11], v[12:13], 1.0 op_sel_hi:[1,0]
	v_exp_f32_e32 v6, v6
	v_exp_f32_e32 v8, v8
	v_exp_f32_e32 v9, v9
	v_exp_f32_e32 v7, v7
	v_exp_f32_e32 v2, v2
	v_exp_f32_e32 v4, v4
	v_exp_f32_e32 v5, v5
	v_exp_f32_e32 v3, v3
	v_rcp_f32_e32 v10, v10
	v_rcp_f32_e32 v11, v11
	v_pk_add_f32 v[8:9], v[8:9], 1.0 op_sel_hi:[1,0]
	v_pk_add_f32 v[6:7], v[6:7], 1.0 op_sel_hi:[1,0]
	v_pk_add_f32 v[4:5], v[4:5], 1.0 op_sel_hi:[1,0]
	v_pk_add_f32 v[2:3], v[2:3], 1.0 op_sel_hi:[1,0]
	v_cvt_pk_bf16_f32 v16, v16, v17
	v_cvt_pk_bf16_f32 v17, v10, v11
	v_rcp_f32_e32 v6, v6
	v_rcp_f32_e32 v7, v7
	v_rcp_f32_e32 v8, v8
	v_rcp_f32_e32 v9, v9
	v_rcp_f32_e32 v10, v2
	v_rcp_f32_e32 v11, v3
	v_rcp_f32_e32 v12, v4
	v_rcp_f32_e32 v5, v5
	v_cvt_pk_bf16_f32 v14, v19, v22
	v_cvt_pk_bf16_f32 v2, v6, v7
	v_cvt_pk_bf16_f32 v3, v8, v9
	v_cvt_pk_bf16_f32 v4, v10, v11
	v_cvt_pk_bf16_f32 v5, v12, v5
	global_store_dwordx4 v[36:37], v[30:33], off sc1
	global_store_dwordx4 v[20:21], v[14:17], off sc1
	global_store_dwordx4 v[20:21], v[2:5], off offset:256 sc1
	s_cbranch_vccnz .LBB0_615
	s_and_b64 vcc, exec, s[0:1]
	s_cbranch_vccnz .LBB0_614
	s_lshl_b64 s[2:3], s[26:27], 14
	v_lshl_add_u64 v[2:3], v[142:143], 0, s[2:3]
	s_add_i32 s2, 0, 0x20400
	v_lshl_add_u64 v[4:5], v[2:3], 0, s[14:15]
	s_add_i32 m0, s2, s14
	s_barrier
	global_load_lds_dwordx4 v[4:5], off
	v_lshl_add_u64 v[4:5], v[2:3], 0, s[6:7]
	s_add_i32 m0, s2, s6
	s_nop 0
	global_load_lds_dwordx4 v[4:5], off
	v_lshl_add_u64 v[4:5], v[2:3], 0, s[20:21]
	s_add_i32 m0, s2, s20
	v_lshl_add_u64 v[2:3], v[2:3], 0, s[22:23]
	global_load_lds_dwordx4 v[4:5], off
	s_add_i32 m0, s2, s22
	s_nop 0
	global_load_lds_dwordx4 v[2:3], off
	s_branch .LBB0_614

; __device__ __forceinline__ unsigned cvtpk(float lo, float hi) { f32x2 v = {lo, hi}; bf16x2_t b = __builtin_convertvector(v, bf16x2_t); return __builtin_bit_cast(unsigned, b); }
; __device__ __forceinline__ float bflo(unsigned w) { return __uint_as_float(w << 16); }
; __device__ __forceinline__ float bfhi(unsigned w) { return __uint_as_float(w & 0xffff0000u); }
; #define FENCE() asm volatile("" ::: "memory")
;     __device__ __forceinline__ void operator()(const Acc& acc, const Unit& u, int wr, int wc, int fr, int fq) const {
;         const int col = u.pn * 256 + wc * 32 + fq * 8;
;         u32x4 gb[2][4][2];
; #pragma unroll
;         for (int ai = 0; ai < 2; ++ai)
; #pragma unroll
;             for (int m = 0; m < 4; ++m)
; #pragma unroll
;                 for (int bj = 0; bj < 2; ++bj) gb[ai][m][bj] = *(const u32x4*)(GB + (size_t)(u.pm * 256 + ai * 128 + wr * 64 + m * 16 + fr) * DM + col + bj * 128);
;         FENCE();
; #pragma unroll
;         for (int ai = 0; ai < 2; ++ai)
; #pragma unroll
;             for (int m = 0; m < 4; ++m) {
;                 const int r = u.pm * 256 + ai * 128 + wr * 64 + m * 16 + fr;
; #pragma unroll
;                 for (int bj = 0; bj < 2; ++bj) {
;                     const u32x4 b = gb[ai][m][bj];
;                     const f32x4 v0 = acc[ai][bj][m][0], v1 = acc[ai][bj][m][1];
;                     u32x4 w; w.x = cvtpk(v0[0] * bflo(b.x), v0[1] * bfhi(b.x)); w.y = cvtpk(v0[2] * bflo(b.y), v0[3] * bfhi(b.y));
;                     w.z = cvtpk(v1[0] * bflo(b.z), v1[1] * bfhi(b.z)); w.w = cvtpk(v1[2] * bflo(b.w), v1[3] * bfhi(b.w));
;                     *(u32x4*)(MG + (size_t)r * DM + col + bj * 128) = w;
.LBB0_705:
	v_ashrrev_i32_e32 v153, 31, v152
	v_lshlrev_b64 v[4:5], 1, v[152:153]
	v_ashrrev_i32_e32 v151, 31, v150
	v_lshl_add_u64 v[134:135], s[8:9], 0, v[4:5]
	v_lshlrev_b64 v[136:137], 11, v[150:151]
	v_lshl_add_u64 v[138:139], v[134:135], 0, v[136:137]
	global_load_dwordx4 v[202:205], v[138:139], off
	global_load_dwordx4 v[206:209], v[138:139], off offset:256
	v_or_b32_e32 v138, 16, v150
	v_ashrrev_i32_e32 v139, 31, v138
	v_lshlrev_b64 v[230:231], 11, v[138:139]
	v_lshl_add_u64 v[138:139], v[134:135], 0, v[230:231]
	global_load_dwordx4 v[210:213], v[138:139], off
	global_load_dwordx4 v[214:217], v[138:139], off offset:256
	v_or_b32_e32 v140, 32, v150
	v_or_b32_e32 v142, 48, v150
	v_add_u32_e32 v144, 0x80, v150
	v_add_u32_e32 v146, 0x90, v150
	v_add_u32_e32 v148, 0xa0, v150
	v_add_u32_e32 v150, 0xb0, v150
	v_ashrrev_i32_e32 v141, 31, v140
	v_ashrrev_i32_e32 v143, 31, v142
	v_ashrrev_i32_e32 v145, 31, v144
	v_ashrrev_i32_e32 v147, 31, v146
	v_ashrrev_i32_e32 v149, 31, v148
	v_ashrrev_i32_e32 v151, 31, v150
	v_lshlrev_b64 v[232:233], 11, v[140:141]
	v_lshlrev_b64 v[196:197], 11, v[142:143]
	v_lshlrev_b64 v[194:195], 11, v[144:145]
	v_lshlrev_b64 v[192:193], 11, v[146:147]
	v_lshlrev_b64 v[190:191], 11, v[148:149]
	v_lshlrev_b64 v[188:189], 11, v[150:151]
	v_lshl_add_u64 v[136:137], s[16:17], 0, v[136:137]
	v_lshl_add_u64 v[138:139], v[134:135], 0, v[232:233]
	v_lshl_add_u64 v[140:141], v[134:135], 0, v[196:197]
	v_lshl_add_u64 v[142:143], v[134:135], 0, v[194:195]
	v_lshl_add_u64 v[144:145], v[134:135], 0, v[192:193]
	v_lshl_add_u64 v[234:235], v[134:135], 0, v[190:191]
	v_lshl_add_u64 v[134:135], v[134:135], 0, v[188:189]
	v_lshl_add_u64 v[236:237], v[136:137], 0, v[4:5]
	global_load_dwordx4 v[218:221], v[138:139], off
	global_load_dwordx4 v[222:225], v[138:139], off offset:256
	global_load_dwordx4 v[226:229], v[140:141], off
	global_load_dwordx4 v[166:169], v[140:141], off offset:256
	global_load_dwordx4 v[162:165], v[142:143], off
	global_load_dwordx4 v[158:161], v[142:143], off offset:256
	global_load_dwordx4 v[154:157], v[144:145], off
	global_load_dwordx4 v[150:153], v[144:145], off offset:256
	global_load_dwordx4 v[146:149], v[234:235], off
	s_nop 0
	global_load_dwordx4 v[142:145], v[234:235], off offset:256
	global_load_dwordx4 v[138:141], v[134:135], off
	s_nop 0
	global_load_dwordx4 v[134:137], v[134:135], off offset:256
	s_andn2_b64 vcc, exec, s[0:1]
	s_mov_b64 s[0:1], -1
	s_waitcnt vmcnt(0)
	v_lshlrev_b32_e32 v234, 16, v202
	v_and_b32_e32 v235, 0xffff0000, v202
	v_lshlrev_b32_e32 v202, 16, v203
	v_and_b32_e32 v203, 0xffff0000, v203
	v_lshlrev_b32_e32 v238, 16, v204
	v_and_b32_e32 v239, 0xffff0000, v204
	v_lshlrev_b32_e32 v204, 16, v205
	v_and_b32_e32 v205, 0xffff0000, v205
	v_lshlrev_b32_e32 v240, 16, v206
	v_and_b32_e32 v241, 0xffff0000, v206
	v_lshlrev_b32_e32 v206, 16, v207
	v_and_b32_e32 v207, 0xffff0000, v207
	v_lshlrev_b32_e32 v242, 16, v208
	v_and_b32_e32 v243, 0xffff0000, v208
	v_lshlrev_b32_e32 v208, 16, v209
	v_and_b32_e32 v209, 0xffff0000, v209
	v_pk_mul_f32 v[130:131], v[130:131], v[234:235]
	v_pk_mul_f32 v[132:133], v[132:133], v[202:203]
	v_pk_mul_f32 v[126:127], v[126:127], v[238:239]
	v_pk_mul_f32 v[128:129], v[128:129], v[204:205]
	v_pk_mul_f32 v[122:123], v[122:123], v[240:241]
	v_pk_mul_f32 v[124:125], v[124:125], v[206:207]
	v_pk_mul_f32 v[202:203], v[118:119], v[242:243]
	v_pk_mul_f32 v[204:205], v[120:121], v[208:209]
	v_cvt_pk_bf16_f32 v118, v130, v131
	v_cvt_pk_bf16_f32 v119, v132, v133
	v_cvt_pk_bf16_f32 v120, v126, v127
	v_cvt_pk_bf16_f32 v121, v128, v129
	v_lshlrev_b32_e32 v244, 16, v210
	v_cvt_pk_bf16_f32 v122, v122, v123
	v_cvt_pk_bf16_f32 v123, v124, v125
	v_cvt_pk_bf16_f32 v124, v202, v203
	v_cvt_pk_bf16_f32 v125, v204, v205
	global_store_dwordx4 v[236:237], v[118:121], off sc1
	global_store_dwordx4 v[236:237], v[122:125], off offset:256 sc1
	v_and_b32_e32 v245, 0xffff0000, v210
	v_lshlrev_b32_e32 v118, 16, v211
	v_and_b32_e32 v119, 0xffff0000, v211
	v_pk_mul_f32 v[114:115], v[114:115], v[244:245]
	v_pk_mul_f32 v[116:117], v[116:117], v[118:119]
	v_cvt_pk_bf16_f32 v114, v114, v115
	v_cvt_pk_bf16_f32 v115, v116, v117
	v_lshlrev_b32_e32 v116, 16, v212
	v_and_b32_e32 v117, 0xffff0000, v212
	v_pk_mul_f32 v[110:111], v[110:111], v[116:117]
	s_nop 0
	v_cvt_pk_bf16_f32 v116, v110, v111
	v_lshlrev_b32_e32 v110, 16, v213
	v_and_b32_e32 v111, 0xffff0000, v213
	v_pk_mul_f32 v[110:111], v[112:113], v[110:111]
	v_lshlrev_b32_e32 v112, 16, v214
	v_and_b32_e32 v113, 0xffff0000, v214
	v_pk_mul_f32 v[106:107], v[106:107], v[112:113]
	v_lshlrev_b32_e32 v112, 16, v215
	v_and_b32_e32 v113, 0xffff0000, v215
	v_pk_mul_f32 v[108:109], v[108:109], v[112:113]
	v_cvt_pk_bf16_f32 v106, v106, v107
	v_cvt_pk_bf16_f32 v107, v108, v109
	v_lshlrev_b32_e32 v108, 16, v216
	v_and_b32_e32 v109, 0xffff0000, v216
	v_pk_mul_f32 v[102:103], v[102:103], v[108:109]
	v_cvt_pk_bf16_f32 v117, v110, v111
	v_cvt_pk_bf16_f32 v108, v102, v103
	v_lshlrev_b32_e32 v102, 16, v217
	v_and_b32_e32 v103, 0xffff0000, v217
	v_pk_mul_f32 v[102:103], v[104:105], v[102:103]
	v_lshl_add_u64 v[110:111], s[16:17], 0, v[230:231]
	v_cvt_pk_bf16_f32 v109, v102, v103
	v_lshlrev_b32_e32 v102, 16, v218
	v_and_b32_e32 v103, 0xffff0000, v218
	v_pk_mul_f32 v[98:99], v[98:99], v[102:103]
	v_lshlrev_b32_e32 v102, 16, v219
	v_and_b32_e32 v103, 0xffff0000, v219
	v_pk_mul_f32 v[100:101], v[100:101], v[102:103]
	v_cvt_pk_bf16_f32 v98, v98, v99
	v_cvt_pk_bf16_f32 v99, v100, v101
	v_lshlrev_b32_e32 v100, 16, v220
	v_and_b32_e32 v101, 0xffff0000, v220
	v_pk_mul_f32 v[94:95], v[94:95], v[100:101]
	v_lshl_add_u64 v[110:111], v[110:111], 0, v[4:5]
	v_cvt_pk_bf16_f32 v100, v94, v95
; __device__ __forceinline__ unsigned cvtpk(float lo, float hi) { f32x2 v = {lo, hi}; bf16x2_t b = __builtin_convertvector(v, bf16x2_t); return __builtin_bit_cast(unsigned, b); }
; __device__ __forceinline__ float bflo(unsigned w) { return __uint_as_float(w << 16); }
; __device__ __forceinline__ float bfhi(unsigned w) { return __uint_as_float(w & 0xffff0000u); }
;     __device__ __forceinline__ void operator()(const Acc& acc, const Unit& u, int wr, int wc, int fr, int fq) const {
;     ...
; #pragma unroll
;                 for (int bj = 0; bj < 2; ++bj) {
;                     const u32x4 b = gb[ai][m][bj];
;                     const f32x4 v0 = acc[ai][bj][m][0], v1 = acc[ai][bj][m][1];
;                     u32x4 w; w.x = cvtpk(v0[0] * bflo(b.x), v0[1] * bfhi(b.x)); w.y = cvtpk(v0[2] * bflo(b.y), v0[3] * bfhi(b.y));
;                     w.z = cvtpk(v1[0] * bflo(b.z), v1[1] * bfhi(b.z)); w.w = cvtpk(v1[2] * bflo(b.w), v1[3] * bfhi(b.w));
;                     *(u32x4*)(MG + (size_t)r * DM + col + bj * 128) = w;
	v_lshlrev_b32_e32 v94, 16, v221
	v_and_b32_e32 v95, 0xffff0000, v221
	v_pk_mul_f32 v[94:95], v[96:97], v[94:95]
	v_lshlrev_b32_e32 v96, 16, v222
	v_and_b32_e32 v97, 0xffff0000, v222
	v_pk_mul_f32 v[90:91], v[90:91], v[96:97]
	v_lshlrev_b32_e32 v96, 16, v223
	v_and_b32_e32 v97, 0xffff0000, v223
	v_pk_mul_f32 v[92:93], v[92:93], v[96:97]
	v_cvt_pk_bf16_f32 v90, v90, v91
	v_cvt_pk_bf16_f32 v91, v92, v93
	v_lshlrev_b32_e32 v92, 16, v224
	v_and_b32_e32 v93, 0xffff0000, v224
	v_pk_mul_f32 v[86:87], v[86:87], v[92:93]
	v_cvt_pk_bf16_f32 v101, v94, v95
	v_cvt_pk_bf16_f32 v92, v86, v87
	v_lshlrev_b32_e32 v86, 16, v225
	v_and_b32_e32 v87, 0xffff0000, v225
	v_pk_mul_f32 v[86:87], v[88:89], v[86:87]
	v_lshl_add_u64 v[94:95], s[16:17], 0, v[232:233]
	v_cvt_pk_bf16_f32 v93, v86, v87
	v_lshlrev_b32_e32 v86, 16, v226
	v_and_b32_e32 v87, 0xffff0000, v226
	v_pk_mul_f32 v[82:83], v[82:83], v[86:87]
	v_lshlrev_b32_e32 v86, 16, v227
	v_and_b32_e32 v87, 0xffff0000, v227
	v_pk_mul_f32 v[84:85], v[84:85], v[86:87]
	v_cvt_pk_bf16_f32 v82, v82, v83
	v_cvt_pk_bf16_f32 v83, v84, v85
	v_lshlrev_b32_e32 v84, 16, v228
	v_and_b32_e32 v85, 0xffff0000, v228
	v_pk_mul_f32 v[78:79], v[78:79], v[84:85]
	v_lshl_add_u64 v[94:95], v[94:95], 0, v[4:5]
	v_cvt_pk_bf16_f32 v84, v78, v79
	v_lshlrev_b32_e32 v78, 16, v229
	v_and_b32_e32 v79, 0xffff0000, v229
	v_pk_mul_f32 v[78:79], v[80:81], v[78:79]
	v_lshlrev_b32_e32 v80, 16, v166
	v_and_b32_e32 v81, 0xffff0000, v166
	v_pk_mul_f32 v[74:75], v[74:75], v[80:81]
	v_lshlrev_b32_e32 v80, 16, v167
	v_and_b32_e32 v81, 0xffff0000, v167
	v_pk_mul_f32 v[76:77], v[76:77], v[80:81]
	v_cvt_pk_bf16_f32 v74, v74, v75
	v_cvt_pk_bf16_f32 v75, v76, v77
	v_lshlrev_b32_e32 v76, 16, v168
	v_and_b32_e32 v77, 0xffff0000, v168
	v_pk_mul_f32 v[70:71], v[70:71], v[76:77]
	v_cvt_pk_bf16_f32 v85, v78, v79
	v_cvt_pk_bf16_f32 v76, v70, v71
	v_lshlrev_b32_e32 v70, 16, v169
	v_and_b32_e32 v71, 0xffff0000, v169
	v_pk_mul_f32 v[70:71], v[72:73], v[70:71]
	v_lshl_add_u64 v[78:79], s[16:17], 0, v[196:197]
	v_cvt_pk_bf16_f32 v77, v70, v71
	v_lshlrev_b32_e32 v70, 16, v162
	v_and_b32_e32 v71, 0xffff0000, v162
	v_pk_mul_f32 v[66:67], v[66:67], v[70:71]
	v_lshlrev_b32_e32 v70, 16, v163
	v_and_b32_e32 v71, 0xffff0000, v163
	v_pk_mul_f32 v[68:69], v[68:69], v[70:71]
	v_cvt_pk_bf16_f32 v66, v66, v67
	v_cvt_pk_bf16_f32 v67, v68, v69
	v_lshlrev_b32_e32 v68, 16, v164
	v_and_b32_e32 v69, 0xffff0000, v164
	v_pk_mul_f32 v[62:63], v[62:63], v[68:69]
	v_lshl_add_u64 v[78:79], v[78:79], 0, v[4:5]
	v_cvt_pk_bf16_f32 v68, v62, v63
	v_lshlrev_b32_e32 v62, 16, v165
	v_and_b32_e32 v63, 0xffff0000, v165
	v_pk_mul_f32 v[62:63], v[64:65], v[62:63]
	v_lshlrev_b32_e32 v64, 16, v158
	v_and_b32_e32 v65, 0xffff0000, v158
	v_pk_mul_f32 v[58:59], v[58:59], v[64:65]
	v_lshlrev_b32_e32 v64, 16, v159
	v_and_b32_e32 v65, 0xffff0000, v159
	v_pk_mul_f32 v[60:61], v[60:61], v[64:65]
	v_cvt_pk_bf16_f32 v58, v58, v59
	v_cvt_pk_bf16_f32 v59, v60, v61
	v_lshlrev_b32_e32 v60, 16, v160
	v_and_b32_e32 v61, 0xffff0000, v160
	v_pk_mul_f32 v[54:55], v[54:55], v[60:61]
	v_cvt_pk_bf16_f32 v69, v62, v63
	v_cvt_pk_bf16_f32 v60, v54, v55
	v_lshlrev_b32_e32 v54, 16, v161
	v_and_b32_e32 v55, 0xffff0000, v161
	v_pk_mul_f32 v[54:55], v[56:57], v[54:55]
	v_lshl_add_u64 v[62:63], s[16:17], 0, v[194:195]
	v_cvt_pk_bf16_f32 v61, v54, v55
	v_lshlrev_b32_e32 v54, 16, v154
	v_and_b32_e32 v55, 0xffff0000, v154
	v_pk_mul_f32 v[50:51], v[50:51], v[54:55]
	v_lshlrev_b32_e32 v54, 16, v155
	v_and_b32_e32 v55, 0xffff0000, v155
	v_pk_mul_f32 v[52:53], v[52:53], v[54:55]
	v_cvt_pk_bf16_f32 v50, v50, v51
	v_cvt_pk_bf16_f32 v51, v52, v53
	v_lshlrev_b32_e32 v52, 16, v156
	v_and_b32_e32 v53, 0xffff0000, v156
	v_pk_mul_f32 v[46:47], v[46:47], v[52:53]
	v_lshl_add_u64 v[62:63], v[62:63], 0, v[4:5]
	v_cvt_pk_bf16_f32 v52, v46, v47
	v_lshlrev_b32_e32 v46, 16, v157
	v_and_b32_e32 v47, 0xffff0000, v157
	v_pk_mul_f32 v[46:47], v[48:49], v[46:47]
	v_lshlrev_b32_e32 v48, 16, v150
	v_and_b32_e32 v49, 0xffff0000, v150
	v_pk_mul_f32 v[42:43], v[42:43], v[48:49]
; __device__ __forceinline__ unsigned cvtpk(float lo, float hi) { f32x2 v = {lo, hi}; bf16x2_t b = __builtin_convertvector(v, bf16x2_t); return __builtin_bit_cast(unsigned, b); }
; __device__ __forceinline__ float bflo(unsigned w) { return __uint_as_float(w << 16); }
; __device__ __forceinline__ float bfhi(unsigned w) { return __uint_as_float(w & 0xffff0000u); }
; #define PG8_BAR __builtin_amdgcn_s_barrier()
; #define FENCE() asm volatile("" ::: "memory")
; template <class Epi>
; __device__ __forceinline__ void gemm_phase(LAS unsigned char* lds, const Gemm g, const StaticOrder& S, const Epi& E) {
;     ...
;         if (wr == 1) PG8_BAR;
;     __device__ __forceinline__ void operator()(const Acc& acc, const Unit& u, int wr, int wc, int fr, int fq) const {
;     ...
; #pragma unroll
;                 for (int bj = 0; bj < 2; ++bj) {
;                     const u32x4 b = gb[ai][m][bj];
;                     const f32x4 v0 = acc[ai][bj][m][0], v1 = acc[ai][bj][m][1];
;                     u32x4 w; w.x = cvtpk(v0[0] * bflo(b.x), v0[1] * bfhi(b.x)); w.y = cvtpk(v0[2] * bflo(b.y), v0[3] * bfhi(b.y));
;                     w.z = cvtpk(v1[0] * bflo(b.z), v1[1] * bfhi(b.z)); w.w = cvtpk(v1[2] * bflo(b.w), v1[3] * bfhi(b.w));
;                     *(u32x4*)(MG + (size_t)r * DM + col + bj * 128) = w;
;                 }
;                 if (m & 1) FENCE();
;             }
	v_lshlrev_b32_e32 v48, 16, v151
	v_and_b32_e32 v49, 0xffff0000, v151
	v_pk_mul_f32 v[44:45], v[44:45], v[48:49]
	v_cvt_pk_bf16_f32 v42, v42, v43
	v_cvt_pk_bf16_f32 v43, v44, v45
	v_lshlrev_b32_e32 v44, 16, v152
	v_and_b32_e32 v45, 0xffff0000, v152
	v_pk_mul_f32 v[38:39], v[38:39], v[44:45]
	v_cvt_pk_bf16_f32 v53, v46, v47
	v_cvt_pk_bf16_f32 v44, v38, v39
	v_lshlrev_b32_e32 v38, 16, v153
	v_and_b32_e32 v39, 0xffff0000, v153
	v_pk_mul_f32 v[38:39], v[40:41], v[38:39]
	v_lshl_add_u64 v[46:47], s[16:17], 0, v[192:193]
	v_cvt_pk_bf16_f32 v45, v38, v39
	v_lshlrev_b32_e32 v38, 16, v146
	v_and_b32_e32 v39, 0xffff0000, v146
	v_pk_mul_f32 v[34:35], v[34:35], v[38:39]
	v_lshlrev_b32_e32 v38, 16, v147
	v_and_b32_e32 v39, 0xffff0000, v147
	v_pk_mul_f32 v[36:37], v[36:37], v[38:39]
	v_cvt_pk_bf16_f32 v34, v34, v35
	v_cvt_pk_bf16_f32 v35, v36, v37
	v_lshlrev_b32_e32 v36, 16, v148
	v_and_b32_e32 v37, 0xffff0000, v148
	v_pk_mul_f32 v[30:31], v[30:31], v[36:37]
	v_lshl_add_u64 v[46:47], v[46:47], 0, v[4:5]
	v_cvt_pk_bf16_f32 v36, v30, v31
	v_lshlrev_b32_e32 v30, 16, v149
	v_and_b32_e32 v31, 0xffff0000, v149
	v_pk_mul_f32 v[30:31], v[32:33], v[30:31]
	v_lshlrev_b32_e32 v32, 16, v142
	v_and_b32_e32 v33, 0xffff0000, v142
	v_pk_mul_f32 v[26:27], v[26:27], v[32:33]
	v_lshlrev_b32_e32 v32, 16, v143
	v_and_b32_e32 v33, 0xffff0000, v143
	v_pk_mul_f32 v[28:29], v[28:29], v[32:33]
	v_cvt_pk_bf16_f32 v26, v26, v27
	v_cvt_pk_bf16_f32 v27, v28, v29
	v_lshlrev_b32_e32 v28, 16, v144
	v_and_b32_e32 v29, 0xffff0000, v144
	v_pk_mul_f32 v[22:23], v[22:23], v[28:29]
	v_cvt_pk_bf16_f32 v37, v30, v31
	v_cvt_pk_bf16_f32 v28, v22, v23
	v_lshlrev_b32_e32 v22, 16, v145
	v_and_b32_e32 v23, 0xffff0000, v145
	v_pk_mul_f32 v[22:23], v[24:25], v[22:23]
	v_lshl_add_u64 v[30:31], s[16:17], 0, v[190:191]
	v_cvt_pk_bf16_f32 v29, v22, v23
	v_lshlrev_b32_e32 v22, 16, v138
	v_and_b32_e32 v23, 0xffff0000, v138
	v_pk_mul_f32 v[18:19], v[18:19], v[22:23]
	v_lshlrev_b32_e32 v22, 16, v139
	v_and_b32_e32 v23, 0xffff0000, v139
	v_pk_mul_f32 v[20:21], v[20:21], v[22:23]
	v_cvt_pk_bf16_f32 v18, v18, v19
	v_cvt_pk_bf16_f32 v19, v20, v21
	v_lshlrev_b32_e32 v20, 16, v140
	v_and_b32_e32 v21, 0xffff0000, v140
	v_pk_mul_f32 v[14:15], v[14:15], v[20:21]
	v_lshl_add_u64 v[30:31], v[30:31], 0, v[4:5]
	v_cvt_pk_bf16_f32 v20, v14, v15
	v_lshlrev_b32_e32 v14, 16, v141
	v_and_b32_e32 v15, 0xffff0000, v141
	v_pk_mul_f32 v[14:15], v[16:17], v[14:15]
	global_store_dwordx4 v[110:111], v[114:117], off sc1
	v_cvt_pk_bf16_f32 v21, v14, v15
	v_lshl_add_u64 v[14:15], s[16:17], 0, v[188:189]
	v_lshl_add_u64 v[14:15], v[14:15], 0, v[4:5]
	v_lshlrev_b32_e32 v4, 16, v134
	v_and_b32_e32 v5, 0xffff0000, v134
	v_pk_mul_f32 v[4:5], v[10:11], v[4:5]
	v_lshlrev_b32_e32 v10, 16, v135
	v_and_b32_e32 v11, 0xffff0000, v135
	v_pk_mul_f32 v[10:11], v[12:13], v[10:11]
	v_cvt_pk_bf16_f32 v4, v4, v5
	v_cvt_pk_bf16_f32 v5, v10, v11
	v_lshlrev_b32_e32 v10, 16, v136
	v_and_b32_e32 v11, 0xffff0000, v136
	global_store_dwordx4 v[110:111], v[106:109], off offset:256 sc1
	v_pk_mul_f32 v[6:7], v[6:7], v[10:11]
	v_lshlrev_b32_e32 v10, 16, v137
	v_and_b32_e32 v11, 0xffff0000, v137
	global_store_dwordx4 v[94:95], v[98:101], off sc1
	global_store_dwordx4 v[94:95], v[90:93], off offset:256 sc1
	global_store_dwordx4 v[78:79], v[82:85], off sc1
	global_store_dwordx4 v[78:79], v[74:77], off offset:256 sc1
	v_pk_mul_f32 v[8:9], v[8:9], v[10:11]
	global_store_dwordx4 v[62:63], v[66:69], off sc1
	global_store_dwordx4 v[62:63], v[58:61], off offset:256 sc1
	global_store_dwordx4 v[46:47], v[50:53], off sc1
	global_store_dwordx4 v[46:47], v[42:45], off offset:256 sc1
	v_cvt_pk_bf16_f32 v6, v6, v7
	v_cvt_pk_bf16_f32 v7, v8, v9
	global_store_dwordx4 v[30:31], v[34:37], off sc1
	global_store_dwordx4 v[30:31], v[26:29], off offset:256 sc1
	global_store_dwordx4 v[14:15], v[18:21], off sc1
	global_store_dwordx4 v[14:15], v[4:7], off offset:256 sc1
	s_cbranch_vccnz .LBB0_696
	s_andn2_b64 vcc, exec, s[6:7]
	s_cbranch_vccnz .LBB0_695
	s_barrier
	s_branch .LBB0_695

;     __device__ __forceinline__ void operator()(const Acc& acc, const Unit& u, int wr, int wc, int fr, int fq) const {
;         const int col = u.pn * 256 + wc * 32 + fq * 8;
;         const int rb = u.pm * 256 + wr * 64 + fr;
;         const float* bbase = RES_BF16 ? nullptr : (rb < MP ? baseA : baseB) + (size_t)rb * DM + col;
;         const bf16_t* rbase = RES_BF16 ? resb + (size_t)rb * DM + col : nullptr;
;         f32x4 pre[2][2][2]; u32x4 preb[2][2];
; #pragma unroll
;         for (int bj = 0; bj < 2; ++bj) {
;             if constexpr (RES_BF16) preb[0][bj] = *(const u32x4*)(rbase + bj * 128);
;             else { pre[0][bj][0] = *(const f32x4*)(bbase + bj * 128); pre[0][bj][1] = *(const f32x4*)(bbase + bj * 128 + 4); }
;         }
; #pragma unroll
;         for (int i = 0; i < 8; ++i) {
;             const int ai = i >> 2, m = i & 3, cb = i & 1, nb = cb ^ 1;
;             if (i < 7) { const int ai2 = (i + 1) >> 2, m2 = (i + 1) & 3; const size_t ro = (size_t)(ai2 * 128 + m2 * 16) * DM;
; #pragma unroll
;                 for (int bj = 0; bj < 2; ++bj) {
;                     if constexpr (RES_BF16) preb[nb][bj] = *(const u32x4*)(rbase + ro + bj * 128);
;                     else { pre[nb][bj][0] = *(const f32x4*)(bbase + ro + bj * 128); pre[nb][bj][1] = *(const f32x4*)(bbase + ro + bj * 128 + 4); }
;                 }
;             }
;             FENCE();
;             const int r = rb + ai * 128 + m * 16;
;             float q = 0.f;
; #pragma unroll
;             for (int bj = 0; bj < 2; ++bj) {
;                 f32x4 b0, b1;
;                 if constexpr (RES_BF16) { const u32x4 w = preb[cb][bj]; b0 = (f32x4){bflo(w.x), bfhi(w.x), bflo(w.y), bfhi(w.y)}; b1 = (f32x4){bflo(w.z), bfhi(w.z), bflo(w.w), bfhi(w.w)}; }
;                 else { b0 = pre[cb][bj][0]; b1 = pre[cb][bj][1]; }
;                 const f32x4 v0 = b0 + acc[ai][bj][m][0] * scale, v1 = b1 + acc[ai][bj][m][1] * scale;
;                 if constexpr (OUT_F32) { float* op = out + (size_t)r * DM + col + bj * 128; *(f32x4*)op = v0; *(f32x4*)(op + 4) = v1; }
;                 q += (v0[0] * v0[0] + v0[1] * v0[1]) + (v0[2] * v0[2] + v0[3] * v0[3]) + (v1[0] * v1[0] + v1[1] * v1[1]) + (v1[2] * v1[2] + v1[3] * v1[3]);
;                 if (xb) { u32x4 w; w.x = cvtpk(v0[0], v0[1]); w.y = cvtpk(v0[2], v0[3]); w.z = cvtpk(v1[0], v1[1]); w.w = cvtpk(v1[2], v1[3]);
.LBB0_788:
	v_lshl_add_u32 v158, s26, 8, v1
	v_lshl_or_b32 v154, s6, 8, v161
	v_ashrrev_i32_e32 v159, 31, v158
	v_lshlrev_b64 v[166:167], 11, v[158:159]
	v_ashrrev_i32_e32 v155, 31, v154
	v_lshl_add_u64 v[130:131], s[34:35], 0, v[166:167]
	v_lshlrev_b64 v[168:169], 1, v[154:155]
	v_lshl_add_u64 v[156:157], v[130:131], 0, v[168:169]
	global_load_dwordx4 v[172:175], v[156:157], off
	global_load_dwordx4 v[176:179], v[156:157], off offset:256
	v_add_co_u32_e32 v130, vcc, s52, v156
	v_and_b32_e32 v181, 64, v165
	s_nop 0
	v_addc_co_u32_e32 v131, vcc, 0, v157, vcc
	global_load_dwordx4 v[134:137], v[130:131], off
	s_nop 0
	global_load_dwordx4 v[130:133], v[130:131], off offset:256
	v_xor_b32_e32 v180, 16, v165
	v_add_u32_e32 v181, 64, v181
	v_xor_b32_e32 v182, 32, v165
	v_cmp_lt_i32_e32 vcc, v180, v181
	s_lshl_b32 s26, s6, 2
	s_ashr_i32 s27, s26, 31
	v_cndmask_b32_e32 v183, v165, v180, vcc
	v_cmp_lt_i32_e32 vcc, v182, v181
	v_lshl_add_u64 v[180:181], s[36:37], 0, v[166:167]
	v_lshl_add_u64 v[168:169], v[180:181], 0, v[168:169]
	v_cndmask_b32_e32 v188, v165, v182, vcc
	v_lshlrev_b32_e32 v166, 2, v183
	s_waitcnt vmcnt(0)
	v_lshlrev_b32_e32 v180, 16, v172
	v_and_b32_e32 v181, 0xffff0000, v172
	v_lshlrev_b32_e32 v172, 16, v173
	v_and_b32_e32 v173, 0xffff0000, v173
	v_lshlrev_b32_e32 v184, 16, v176
	v_and_b32_e32 v185, 0xffff0000, v176
	v_lshlrev_b32_e32 v176, 16, v177
	v_and_b32_e32 v177, 0xffff0000, v177
	v_lshlrev_b32_e32 v182, 16, v174
	v_and_b32_e32 v183, 0xffff0000, v174
	v_lshlrev_b32_e32 v174, 16, v175
	v_and_b32_e32 v175, 0xffff0000, v175
	v_lshlrev_b32_e32 v186, 16, v178
	v_and_b32_e32 v187, 0xffff0000, v178
	v_lshlrev_b32_e32 v178, 16, v179
	v_and_b32_e32 v179, 0xffff0000, v179
	v_pk_add_f32 v[128:129], v[128:129], v[172:173]
	v_pk_add_f32 v[126:127], v[126:127], v[180:181]
	v_pk_add_f32 v[120:121], v[120:121], v[176:177]
	v_pk_add_f32 v[118:119], v[118:119], v[184:185]
	v_pk_add_f32 v[124:125], v[124:125], v[174:175]
	v_pk_add_f32 v[122:123], v[122:123], v[182:183]
	v_pk_add_f32 v[172:173], v[116:117], v[178:179]
	v_pk_add_f32 v[174:175], v[114:115], v[186:187]
	v_mul_f32_e32 v116, v127, v127
	v_mul_f32_e32 v117, v129, v129
	v_cvt_pk_bf16_f32 v114, v126, v127
	v_cvt_pk_bf16_f32 v115, v128, v129
	v_mul_f32_e32 v127, v119, v119
	v_mul_f32_e32 v129, v121, v121
	v_mul_f32_e32 v167, v123, v123
	v_mul_f32_e32 v177, v175, v175
	v_fmac_f32_e32 v116, v126, v126
	v_fmac_f32_e32 v117, v128, v128
	v_fmac_f32_e32 v127, v118, v118
	v_fmac_f32_e32 v129, v120, v120
	v_mul_f32_e32 v176, v125, v125
	v_mul_f32_e32 v178, v173, v173
	v_fmac_f32_e32 v167, v122, v122
	v_fmac_f32_e32 v177, v174, v174
	v_add_f32_e32 v116, v116, v117
	v_add_f32_e32 v117, v127, v129
	v_fmac_f32_e32 v176, v124, v124
	v_fmac_f32_e32 v178, v172, v172
	v_add_f32_e32 v116, v167, v116
	v_add_f32_e32 v117, v177, v117
	v_add_f32_e32 v116, v176, v116
	v_add_f32_e32 v117, v178, v117
	v_add_f32_e32 v126, v116, v117
	ds_bpermute_b32 v127, v166, v126
	v_cvt_pk_bf16_f32 v116, v122, v123
	v_cvt_pk_bf16_f32 v117, v124, v125
	global_store_dwordx4 v[168:169], v[114:117], off sc1
	v_lshlrev_b32_e32 v124, 2, v188
	v_cvt_pk_bf16_f32 v118, v118, v119
	s_waitcnt lgkmcnt(0)
	v_add_f32_e32 v114, v126, v127
	ds_bpermute_b32 v115, v124, v114
	v_cvt_pk_bf16_f32 v119, v120, v121
	v_cvt_pk_bf16_f32 v120, v174, v175
	v_cvt_pk_bf16_f32 v121, v172, v173
	global_store_dwordx4 v[168:169], v[118:121], off offset:256 sc1
	s_and_saveexec_b64 s[38:39], s[0:1]
	s_cbranch_execz .LBB0_790
	v_lshlrev_b64 v[116:117], 6, v[158:159]
	v_lshl_add_u64 v[116:117], s[74:75], 0, v[116:117]
	v_lshl_add_u64 v[116:117], s[26:27], 2, v[116:117]
	s_lshl_b32 s6, s49, 2
	v_lshl_add_u64 v[116:117], v[116:117], 0, s[6:7]
	s_waitcnt lgkmcnt(0)
	v_add_f32_e32 v114, v114, v115
	global_store_dword v[116:117], v114, off sc1
.LBB0_790:
	s_or_b64 exec, exec, s[38:39]
	v_add_co_u32_e32 v114, vcc, 0x10000, v156
	v_lshlrev_b32_e32 v128, 16, v134
	s_waitcnt lgkmcnt(0)
	v_addc_co_u32_e32 v115, vcc, 0, v157, vcc
	global_load_dwordx4 v[118:121], v[114:115], off
	s_nop 0
	global_load_dwordx4 v[114:117], v[114:115], off offset:256
	v_and_b32_e32 v129, 0xffff0000, v134
	v_lshlrev_b32_e32 v134, 16, v135
	v_and_b32_e32 v135, 0xffff0000, v135
	v_lshlrev_b32_e32 v168, 16, v136
	v_and_b32_e32 v169, 0xffff0000, v136
	v_lshlrev_b32_e32 v136, 16, v137
	v_and_b32_e32 v137, 0xffff0000, v137
	v_pk_add_f32 v[112:113], v[112:113], v[134:135]
	v_pk_add_f32 v[110:111], v[110:111], v[128:129]
	v_pk_add_f32 v[128:129], v[108:109], v[136:137]
	v_pk_add_f32 v[108:109], v[106:107], v[168:169]
	v_mul_f32_e32 v106, v111, v111
	v_mul_f32_e32 v107, v113, v113
	v_fmac_f32_e32 v106, v110, v110
	v_fmac_f32_e32 v107, v112, v112
	v_add_f32_e32 v106, v106, v107
	v_mul_f32_e32 v107, v109, v109
	v_fmac_f32_e32 v107, v108, v108
	v_add_f32_e32 v106, v107, v106
	v_mul_f32_e32 v107, v129, v129
	v_fmac_f32_e32 v107, v128, v128
	v_add_f32_e32 v125, v107, v106
	v_cvt_pk_bf16_f32 v106, v110, v111
	v_cvt_pk_bf16_f32 v107, v112, v113
	v_lshlrev_b32_e32 v110, 16, v130
	v_and_b32_e32 v111, 0xffff0000, v130
	v_lshlrev_b32_e32 v112, 16, v131
	v_and_b32_e32 v113, 0xffff0000, v131
	v_cvt_pk_bf16_f32 v108, v108, v109
	v_cvt_pk_bf16_f32 v109, v128, v129
	v_lshlrev_b32_e32 v128, 16, v132
	v_and_b32_e32 v129, 0xffff0000, v132
	v_pk_add_f32 v[104:105], v[104:105], v[112:113]
	v_pk_add_f32 v[102:103], v[102:103], v[110:111]
	v_pk_add_f32 v[112:113], v[98:99], v[128:129]
	v_mul_f32_e32 v98, v103, v103
	v_mul_f32_e32 v99, v105, v105
	v_fmac_f32_e32 v98, v102, v102
	v_fmac_f32_e32 v99, v104, v104
	v_lshlrev_b32_e32 v130, 16, v133
	v_and_b32_e32 v131, 0xffff0000, v133
	v_add_f32_e32 v98, v98, v99
	v_mul_f32_e32 v99, v113, v113
	v_pk_add_f32 v[110:111], v[100:101], v[130:131]
	v_fmac_f32_e32 v99, v112, v112
	v_add_f32_e32 v98, v99, v98
	v_mul_f32_e32 v99, v111, v111
	v_fmac_f32_e32 v99, v110, v110
	v_add_f32_e32 v98, v99, v98
	v_add_f32_e32 v101, v125, v98
	ds_bpermute_b32 v125, v166, v101
	v_or_b32_e32 v122, 16, v158
	v_ashrrev_i32_e32 v123, 31, v122
	v_lshlrev_b64 v[126:127], 11, v[122:123]
	v_lshl_add_u64 v[98:99], s[36:37], 0, v[126:127]
	v_lshl_add_u64 v[126:127], v[154:155], 1, v[98:99]
	s_waitcnt lgkmcnt(0)
	v_add_f32_e32 v98, v101, v125
	ds_bpermute_b32 v99, v124, v98
	v_cvt_pk_bf16_f32 v100, v102, v103
	v_cvt_pk_bf16_f32 v101, v104, v105
	v_cvt_pk_bf16_f32 v102, v112, v113
	v_cvt_pk_bf16_f32 v103, v110, v111
	global_store_dwordx4 v[126:127], v[106:109], off sc1
	global_store_dwordx4 v[126:127], v[100:103], off offset:256 sc1
	s_and_saveexec_b64 s[38:39], s[0:1]
	s_cbranch_execz .LBB0_792
	v_lshlrev_b64 v[100:101], 6, v[122:123]
	v_lshl_add_u64 v[100:101], s[74:75], 0, v[100:101]
	v_lshl_add_u64 v[100:101], s[26:27], 2, v[100:101]
	s_lshl_b32 s6, s49, 2
	v_lshl_add_u64 v[100:101], v[100:101], 0, s[6:7]
	s_waitcnt lgkmcnt(0)
	v_add_f32_e32 v98, v98, v99
	global_store_dword v[100:101], v98, off sc1
; __device__ __forceinline__ float bflo(unsigned w) { return __uint_as_float(w << 16); }
; #define FENCE() asm volatile("" ::: "memory")
;     __device__ __forceinline__ void operator()(const Acc& acc, const Unit& u, int wr, int wc, int fr, int fq) const {
;     ...
;         for (int bj = 0; bj < 2; ++bj) {
;             if constexpr (RES_BF16) preb[0][bj] = *(const u32x4*)(rbase + bj * 128);
;             else { pre[0][bj][0] = *(const f32x4*)(bbase + bj * 128); pre[0][bj][1] = *(const f32x4*)(bbase + bj * 128 + 4); }
;         }
; #pragma unroll
;         for (int i = 0; i < 8; ++i) {
;             const int ai = i >> 2, m = i & 3, cb = i & 1, nb = cb ^ 1;
;             if (i < 7) { const int ai2 = (i + 1) >> 2, m2 = (i + 1) & 3; const size_t ro = (size_t)(ai2 * 128 + m2 * 16) * DM;
; #pragma unroll
;                 for (int bj = 0; bj < 2; ++bj) {
;                     if constexpr (RES_BF16) preb[nb][bj] = *(const u32x4*)(rbase + ro + bj * 128);
;                     else { pre[nb][bj][0] = *(const f32x4*)(bbase + ro + bj * 128); pre[nb][bj][1] = *(const f32x4*)(bbase + ro + bj * 128 + 4); }
;                 }
;             }
;             FENCE();
;             const int r = rb + ai * 128 + m * 16;
;             float q = 0.f;
; #pragma unroll
;             for (int bj = 0; bj < 2; ++bj) {
;                 f32x4 b0, b1;
;                 if constexpr (RES_BF16) { const u32x4 w = preb[cb][bj]; b0 = (f32x4){bflo(w.x), bfhi(w.x), bflo(w.y), bfhi(w.y)}; b1 = (f32x4){bflo(w.z), bfhi(w.z), bflo(w.w), bfhi(w.w)}; }
;                 else { b0 = pre[cb][bj][0]; b1 = pre[cb][bj][1]; }
;                 const f32x4 v0 = b0 + acc[ai][bj][m][0] * scale, v1 = b1 + acc[ai][bj][m][1] * scale;
;                 if constexpr (OUT_F32) { float* op = out + (size_t)r * DM + col + bj * 128; *(f32x4*)op = v0; *(f32x4*)(op + 4) = v1; }
;                 q += (v0[0] * v0[0] + v0[1] * v0[1]) + (v0[2] * v0[2] + v0[3] * v0[3]) + (v1[0] * v1[0] + v1[1] * v1[1]) + (v1[2] * v1[2] + v1[3] * v1[3]);
;                 if (xb) { u32x4 w; w.x = cvtpk(v0[0], v0[1]); w.y = cvtpk(v0[2], v0[3]); w.z = cvtpk(v1[0], v1[1]); w.w = cvtpk(v1[2], v1[3]);
;                     *(u32x4*)(xb + (size_t)r * DM + col + bj * 128) = w; }
;             }
;             q += __shfl_xor(q, 16); q += __shfl_xor(q, 32);
;             if (fq == 0) st[(size_t)r * 16 + u.pn * 4 + wc] = q;
.LBB0_792:
	s_or_b64 exec, exec, s[38:39]
	v_add_co_u32_e32 v98, vcc, 0x18000, v156
	s_waitcnt vmcnt(3)
	v_lshlrev_b32_e32 v110, 16, v118
	s_waitcnt lgkmcnt(0)
	v_addc_co_u32_e32 v99, vcc, 0, v157, vcc
	global_load_dwordx4 v[102:105], v[98:99], off
	s_nop 0
	global_load_dwordx4 v[98:101], v[98:99], off offset:256
	v_and_b32_e32 v111, 0xffff0000, v118
	v_lshlrev_b32_e32 v112, 16, v119
	v_and_b32_e32 v113, 0xffff0000, v119
	v_lshlrev_b32_e32 v118, 16, v120
	v_and_b32_e32 v119, 0xffff0000, v120
	v_lshlrev_b32_e32 v120, 16, v121
	v_and_b32_e32 v121, 0xffff0000, v121
	v_pk_add_f32 v[96:97], v[96:97], v[112:113]
	v_pk_add_f32 v[94:95], v[94:95], v[110:111]
	v_pk_add_f32 v[110:111], v[92:93], v[120:121]
	v_pk_add_f32 v[92:93], v[90:91], v[118:119]
	v_mul_f32_e32 v90, v95, v95
	v_mul_f32_e32 v91, v97, v97
	v_fmac_f32_e32 v90, v94, v94
	v_fmac_f32_e32 v91, v96, v96
	v_add_f32_e32 v90, v90, v91
	v_mul_f32_e32 v91, v93, v93
	v_fmac_f32_e32 v91, v92, v92
	v_add_f32_e32 v90, v91, v90
	v_mul_f32_e32 v91, v111, v111
	v_fmac_f32_e32 v91, v110, v110
	v_add_f32_e32 v118, v91, v90
	v_cvt_pk_bf16_f32 v90, v94, v95
	v_cvt_pk_bf16_f32 v91, v96, v97
	s_waitcnt vmcnt(4)
	v_lshlrev_b32_e32 v94, 16, v114
	v_and_b32_e32 v95, 0xffff0000, v114
	v_lshlrev_b32_e32 v96, 16, v115
	v_and_b32_e32 v97, 0xffff0000, v115
	v_cvt_pk_bf16_f32 v92, v92, v93
	v_cvt_pk_bf16_f32 v93, v110, v111
	v_lshlrev_b32_e32 v110, 16, v116
	v_and_b32_e32 v111, 0xffff0000, v116
	v_pk_add_f32 v[88:89], v[88:89], v[96:97]
	v_pk_add_f32 v[86:87], v[86:87], v[94:95]
	v_pk_add_f32 v[96:97], v[82:83], v[110:111]
	v_mul_f32_e32 v82, v87, v87
	v_mul_f32_e32 v83, v89, v89
	v_fmac_f32_e32 v82, v86, v86
	v_fmac_f32_e32 v83, v88, v88
	v_lshlrev_b32_e32 v112, 16, v117
	v_and_b32_e32 v113, 0xffff0000, v117
	v_add_f32_e32 v82, v82, v83
	v_mul_f32_e32 v83, v97, v97
	v_pk_add_f32 v[94:95], v[84:85], v[112:113]
	v_fmac_f32_e32 v83, v96, v96
	v_add_f32_e32 v82, v83, v82
	v_mul_f32_e32 v83, v95, v95
	v_fmac_f32_e32 v83, v94, v94
	v_add_f32_e32 v82, v83, v82
	v_add_f32_e32 v85, v118, v82
	ds_bpermute_b32 v110, v166, v85
	v_or_b32_e32 v106, 32, v158
	v_ashrrev_i32_e32 v107, 31, v106
	v_lshlrev_b64 v[108:109], 11, v[106:107]
	v_lshl_add_u64 v[82:83], s[36:37], 0, v[108:109]
	v_lshl_add_u64 v[108:109], v[154:155], 1, v[82:83]
	s_waitcnt lgkmcnt(0)
	v_add_f32_e32 v82, v85, v110
	ds_bpermute_b32 v83, v124, v82
	v_cvt_pk_bf16_f32 v84, v86, v87
	v_cvt_pk_bf16_f32 v85, v88, v89
	v_cvt_pk_bf16_f32 v86, v96, v97
	v_cvt_pk_bf16_f32 v87, v94, v95
	global_store_dwordx4 v[108:109], v[90:93], off sc1
	global_store_dwordx4 v[108:109], v[84:87], off offset:256 sc1
	s_and_saveexec_b64 s[38:39], s[0:1]
	s_cbranch_execz .LBB0_794
	v_lshlrev_b64 v[84:85], 6, v[106:107]
	v_lshl_add_u64 v[84:85], s[74:75], 0, v[84:85]
	v_lshl_add_u64 v[84:85], s[26:27], 2, v[84:85]
	s_lshl_b32 s6, s49, 2
	v_lshl_add_u64 v[84:85], v[84:85], 0, s[6:7]
	s_waitcnt lgkmcnt(0)
	v_add_f32_e32 v82, v82, v83
	global_store_dword v[84:85], v82, off sc1
.LBB0_794:
	s_or_b64 exec, exec, s[38:39]
	v_add_co_u32_e32 v82, vcc, 0x40000, v156
	s_waitcnt vmcnt(3)
	v_lshlrev_b32_e32 v94, 16, v102
	s_waitcnt lgkmcnt(0)
	v_addc_co_u32_e32 v83, vcc, 0, v157, vcc
	global_load_dwordx4 v[86:89], v[82:83], off
	s_nop 0
	global_load_dwordx4 v[82:85], v[82:83], off offset:256
	v_and_b32_e32 v95, 0xffff0000, v102
	v_lshlrev_b32_e32 v96, 16, v103
	v_and_b32_e32 v97, 0xffff0000, v103
	v_lshlrev_b32_e32 v102, 16, v104
	v_and_b32_e32 v103, 0xffff0000, v104
	v_lshlrev_b32_e32 v104, 16, v105
	v_and_b32_e32 v105, 0xffff0000, v105
	v_pk_add_f32 v[80:81], v[80:81], v[96:97]
	v_pk_add_f32 v[78:79], v[78:79], v[94:95]
	v_pk_add_f32 v[94:95], v[76:77], v[104:105]
	v_pk_add_f32 v[76:77], v[74:75], v[102:103]
	v_mul_f32_e32 v74, v79, v79
	v_mul_f32_e32 v75, v81, v81
	v_fmac_f32_e32 v74, v78, v78
	v_fmac_f32_e32 v75, v80, v80
	v_add_f32_e32 v74, v74, v75
	v_mul_f32_e32 v75, v77, v77
	v_fmac_f32_e32 v75, v76, v76
	v_add_f32_e32 v74, v75, v74
	v_mul_f32_e32 v75, v95, v95
	v_fmac_f32_e32 v75, v94, v94
	v_add_f32_e32 v102, v75, v74
	v_cvt_pk_bf16_f32 v74, v78, v79
	v_cvt_pk_bf16_f32 v75, v80, v81
	s_waitcnt vmcnt(4)
	v_lshlrev_b32_e32 v78, 16, v98
	v_and_b32_e32 v79, 0xffff0000, v98
	v_lshlrev_b32_e32 v80, 16, v99
	v_and_b32_e32 v81, 0xffff0000, v99
	v_cvt_pk_bf16_f32 v76, v76, v77
	v_cvt_pk_bf16_f32 v77, v94, v95
	v_lshlrev_b32_e32 v94, 16, v100
	v_and_b32_e32 v95, 0xffff0000, v100
	v_pk_add_f32 v[72:73], v[72:73], v[80:81]
	v_pk_add_f32 v[70:71], v[70:71], v[78:79]
	v_pk_add_f32 v[80:81], v[66:67], v[94:95]
	v_mul_f32_e32 v66, v71, v71
	v_mul_f32_e32 v67, v73, v73
	v_fmac_f32_e32 v66, v70, v70
	v_fmac_f32_e32 v67, v72, v72
	v_lshlrev_b32_e32 v96, 16, v101
	v_and_b32_e32 v97, 0xffff0000, v101
	v_add_f32_e32 v66, v66, v67
	v_mul_f32_e32 v67, v81, v81
	v_pk_add_f32 v[78:79], v[68:69], v[96:97]
	v_fmac_f32_e32 v67, v80, v80
	v_add_f32_e32 v66, v67, v66
	v_mul_f32_e32 v67, v79, v79
	v_fmac_f32_e32 v67, v78, v78
	v_add_f32_e32 v66, v67, v66
	v_add_f32_e32 v69, v102, v66
	ds_bpermute_b32 v94, v166, v69
	v_or_b32_e32 v90, 48, v158
	v_ashrrev_i32_e32 v91, 31, v90
	v_lshlrev_b64 v[92:93], 11, v[90:91]
	v_lshl_add_u64 v[66:67], s[36:37], 0, v[92:93]
	v_lshl_add_u64 v[92:93], v[154:155], 1, v[66:67]
	s_waitcnt lgkmcnt(0)
	v_add_f32_e32 v66, v69, v94
	ds_bpermute_b32 v67, v124, v66
	v_cvt_pk_bf16_f32 v68, v70, v71
	v_cvt_pk_bf16_f32 v69, v72, v73
	v_cvt_pk_bf16_f32 v70, v80, v81
	v_cvt_pk_bf16_f32 v71, v78, v79
	global_store_dwordx4 v[92:93], v[74:77], off sc1
	global_store_dwordx4 v[92:93], v[68:71], off offset:256 sc1
	s_and_saveexec_b64 s[38:39], s[0:1]
	s_cbranch_execz .LBB0_796
	v_lshlrev_b64 v[68:69], 6, v[90:91]
	v_lshl_add_u64 v[68:69], s[74:75], 0, v[68:69]
	v_lshl_add_u64 v[68:69], s[26:27], 2, v[68:69]
	s_lshl_b32 s6, s49, 2
	v_lshl_add_u64 v[68:69], v[68:69], 0, s[6:7]
	s_waitcnt lgkmcnt(0)
	v_add_f32_e32 v66, v66, v67
	global_store_dword v[68:69], v66, off sc1
; __device__ __forceinline__ float bflo(unsigned w) { return __uint_as_float(w << 16); }
; #define FENCE() asm volatile("" ::: "memory")
;     __device__ __forceinline__ void operator()(const Acc& acc, const Unit& u, int wr, int wc, int fr, int fq) const {
;     ...
;         for (int bj = 0; bj < 2; ++bj) {
;             if constexpr (RES_BF16) preb[0][bj] = *(const u32x4*)(rbase + bj * 128);
;             else { pre[0][bj][0] = *(const f32x4*)(bbase + bj * 128); pre[0][bj][1] = *(const f32x4*)(bbase + bj * 128 + 4); }
;         }
; #pragma unroll
;         for (int i = 0; i < 8; ++i) {
;             const int ai = i >> 2, m = i & 3, cb = i & 1, nb = cb ^ 1;
;             if (i < 7) { const int ai2 = (i + 1) >> 2, m2 = (i + 1) & 3; const size_t ro = (size_t)(ai2 * 128 + m2 * 16) * DM;
; #pragma unroll
;                 for (int bj = 0; bj < 2; ++bj) {
;                     if constexpr (RES_BF16) preb[nb][bj] = *(const u32x4*)(rbase + ro + bj * 128);
;                     else { pre[nb][bj][0] = *(const f32x4*)(bbase + ro + bj * 128); pre[nb][bj][1] = *(const f32x4*)(bbase + ro + bj * 128 + 4); }
;                 }
;             }
;             FENCE();
;             const int r = rb + ai * 128 + m * 16;
;             float q = 0.f;
; #pragma unroll
;             for (int bj = 0; bj < 2; ++bj) {
;                 f32x4 b0, b1;
;                 if constexpr (RES_BF16) { const u32x4 w = preb[cb][bj]; b0 = (f32x4){bflo(w.x), bfhi(w.x), bflo(w.y), bfhi(w.y)}; b1 = (f32x4){bflo(w.z), bfhi(w.z), bflo(w.w), bfhi(w.w)}; }
;                 else { b0 = pre[cb][bj][0]; b1 = pre[cb][bj][1]; }
;                 const f32x4 v0 = b0 + acc[ai][bj][m][0] * scale, v1 = b1 + acc[ai][bj][m][1] * scale;
;                 if constexpr (OUT_F32) { float* op = out + (size_t)r * DM + col + bj * 128; *(f32x4*)op = v0; *(f32x4*)(op + 4) = v1; }
;                 q += (v0[0] * v0[0] + v0[1] * v0[1]) + (v0[2] * v0[2] + v0[3] * v0[3]) + (v1[0] * v1[0] + v1[1] * v1[1]) + (v1[2] * v1[2] + v1[3] * v1[3]);
;                 if (xb) { u32x4 w; w.x = cvtpk(v0[0], v0[1]); w.y = cvtpk(v0[2], v0[3]); w.z = cvtpk(v1[0], v1[1]); w.w = cvtpk(v1[2], v1[3]);
;                     *(u32x4*)(xb + (size_t)r * DM + col + bj * 128) = w; }
;             }
;             q += __shfl_xor(q, 16); q += __shfl_xor(q, 32);
;             if (fq == 0) st[(size_t)r * 16 + u.pn * 4 + wc] = q;
.LBB0_796:
	s_or_b64 exec, exec, s[38:39]
	v_add_co_u32_e32 v66, vcc, 0x48000, v156
	s_waitcnt vmcnt(3)
	v_lshlrev_b32_e32 v78, 16, v86
	s_waitcnt lgkmcnt(0)
	v_addc_co_u32_e32 v67, vcc, 0, v157, vcc
	global_load_dwordx4 v[70:73], v[66:67], off
	s_nop 0
	global_load_dwordx4 v[66:69], v[66:67], off offset:256
	v_and_b32_e32 v79, 0xffff0000, v86
	v_lshlrev_b32_e32 v80, 16, v87
	v_and_b32_e32 v81, 0xffff0000, v87
	v_lshlrev_b32_e32 v86, 16, v88
	v_and_b32_e32 v87, 0xffff0000, v88
	v_lshlrev_b32_e32 v88, 16, v89
	v_and_b32_e32 v89, 0xffff0000, v89
	v_pk_add_f32 v[64:65], v[64:65], v[80:81]
	v_pk_add_f32 v[62:63], v[62:63], v[78:79]
	v_pk_add_f32 v[78:79], v[60:61], v[88:89]
	v_pk_add_f32 v[60:61], v[58:59], v[86:87]
	v_mul_f32_e32 v58, v63, v63
	v_mul_f32_e32 v59, v65, v65
	v_fmac_f32_e32 v58, v62, v62
	v_fmac_f32_e32 v59, v64, v64
	v_add_f32_e32 v58, v58, v59
	v_mul_f32_e32 v59, v61, v61
	v_fmac_f32_e32 v59, v60, v60
	v_add_f32_e32 v58, v59, v58
	v_mul_f32_e32 v59, v79, v79
	v_fmac_f32_e32 v59, v78, v78
	v_add_f32_e32 v86, v59, v58
	v_cvt_pk_bf16_f32 v58, v62, v63
	v_cvt_pk_bf16_f32 v59, v64, v65
	s_waitcnt vmcnt(4)
	v_lshlrev_b32_e32 v62, 16, v82
	v_and_b32_e32 v63, 0xffff0000, v82
	v_lshlrev_b32_e32 v64, 16, v83
	v_and_b32_e32 v65, 0xffff0000, v83
	v_cvt_pk_bf16_f32 v60, v60, v61
	v_cvt_pk_bf16_f32 v61, v78, v79
	v_lshlrev_b32_e32 v78, 16, v84
	v_and_b32_e32 v79, 0xffff0000, v84
	v_pk_add_f32 v[56:57], v[56:57], v[64:65]
	v_pk_add_f32 v[54:55], v[54:55], v[62:63]
	v_pk_add_f32 v[64:65], v[50:51], v[78:79]
	v_mul_f32_e32 v50, v55, v55
	v_mul_f32_e32 v51, v57, v57
	v_fmac_f32_e32 v50, v54, v54
	v_fmac_f32_e32 v51, v56, v56
	v_lshlrev_b32_e32 v80, 16, v85
	v_and_b32_e32 v81, 0xffff0000, v85
	v_add_f32_e32 v50, v50, v51
	v_mul_f32_e32 v51, v65, v65
	v_pk_add_f32 v[62:63], v[52:53], v[80:81]
	v_fmac_f32_e32 v51, v64, v64
	v_add_f32_e32 v50, v51, v50
	v_mul_f32_e32 v51, v63, v63
	v_fmac_f32_e32 v51, v62, v62
	v_add_f32_e32 v50, v51, v50
	v_add_f32_e32 v53, v86, v50
	ds_bpermute_b32 v78, v166, v53
	v_add_u32_e32 v74, 0x80, v158
	v_ashrrev_i32_e32 v75, 31, v74
	v_lshlrev_b64 v[76:77], 11, v[74:75]
	v_lshl_add_u64 v[50:51], s[36:37], 0, v[76:77]
	v_lshl_add_u64 v[76:77], v[154:155], 1, v[50:51]
	s_waitcnt lgkmcnt(0)
	v_add_f32_e32 v50, v53, v78
	ds_bpermute_b32 v51, v124, v50
	v_cvt_pk_bf16_f32 v52, v54, v55
	v_cvt_pk_bf16_f32 v53, v56, v57
	v_cvt_pk_bf16_f32 v54, v64, v65
	v_cvt_pk_bf16_f32 v55, v62, v63
	global_store_dwordx4 v[76:77], v[58:61], off sc1
	global_store_dwordx4 v[76:77], v[52:55], off offset:256 sc1
	s_and_saveexec_b64 s[38:39], s[0:1]
	s_cbranch_execz .LBB0_798
	v_lshlrev_b64 v[52:53], 6, v[74:75]
	v_lshl_add_u64 v[52:53], s[74:75], 0, v[52:53]
	v_lshl_add_u64 v[52:53], s[26:27], 2, v[52:53]
	s_lshl_b32 s6, s49, 2
	v_lshl_add_u64 v[52:53], v[52:53], 0, s[6:7]
	s_waitcnt lgkmcnt(0)
	v_add_f32_e32 v50, v50, v51
	global_store_dword v[52:53], v50, off sc1
.LBB0_798:
	s_or_b64 exec, exec, s[38:39]
	v_add_co_u32_e32 v50, vcc, 0x50000, v156
	s_waitcnt vmcnt(3)
	v_lshlrev_b32_e32 v62, 16, v70
	s_waitcnt lgkmcnt(0)
	v_addc_co_u32_e32 v51, vcc, 0, v157, vcc
	global_load_dwordx4 v[54:57], v[50:51], off
	s_nop 0
	global_load_dwordx4 v[50:53], v[50:51], off offset:256
	v_and_b32_e32 v63, 0xffff0000, v70
	v_lshlrev_b32_e32 v64, 16, v71
	v_and_b32_e32 v65, 0xffff0000, v71
	v_lshlrev_b32_e32 v70, 16, v72
	v_and_b32_e32 v71, 0xffff0000, v72
	v_lshlrev_b32_e32 v72, 16, v73
	v_and_b32_e32 v73, 0xffff0000, v73
	v_pk_add_f32 v[48:49], v[48:49], v[64:65]
	v_pk_add_f32 v[46:47], v[46:47], v[62:63]
	v_pk_add_f32 v[62:63], v[44:45], v[72:73]
	v_pk_add_f32 v[44:45], v[42:43], v[70:71]
	v_mul_f32_e32 v42, v47, v47
	v_mul_f32_e32 v43, v49, v49
	v_fmac_f32_e32 v42, v46, v46
	v_fmac_f32_e32 v43, v48, v48
	v_add_f32_e32 v42, v42, v43
	v_mul_f32_e32 v43, v45, v45
	v_fmac_f32_e32 v43, v44, v44
	v_add_f32_e32 v42, v43, v42
	v_mul_f32_e32 v43, v63, v63
	v_fmac_f32_e32 v43, v62, v62
	v_add_f32_e32 v70, v43, v42
	v_cvt_pk_bf16_f32 v42, v46, v47
	v_cvt_pk_bf16_f32 v43, v48, v49
	s_waitcnt vmcnt(4)
	v_lshlrev_b32_e32 v46, 16, v66
	v_and_b32_e32 v47, 0xffff0000, v66
	v_lshlrev_b32_e32 v48, 16, v67
	v_and_b32_e32 v49, 0xffff0000, v67
	v_cvt_pk_bf16_f32 v44, v44, v45
	v_cvt_pk_bf16_f32 v45, v62, v63
	v_lshlrev_b32_e32 v62, 16, v68
	v_and_b32_e32 v63, 0xffff0000, v68
	v_pk_add_f32 v[40:41], v[40:41], v[48:49]
	v_pk_add_f32 v[38:39], v[38:39], v[46:47]
	v_pk_add_f32 v[48:49], v[34:35], v[62:63]
	v_mul_f32_e32 v34, v39, v39
	v_mul_f32_e32 v35, v41, v41
	v_fmac_f32_e32 v34, v38, v38
	v_fmac_f32_e32 v35, v40, v40
	v_lshlrev_b32_e32 v64, 16, v69
	v_and_b32_e32 v65, 0xffff0000, v69
	v_add_f32_e32 v34, v34, v35
	v_mul_f32_e32 v35, v49, v49
	v_pk_add_f32 v[46:47], v[36:37], v[64:65]
	v_fmac_f32_e32 v35, v48, v48
	v_add_f32_e32 v34, v35, v34
	v_mul_f32_e32 v35, v47, v47
	v_fmac_f32_e32 v35, v46, v46
	v_add_f32_e32 v34, v35, v34
	v_add_f32_e32 v37, v70, v34
	ds_bpermute_b32 v62, v166, v37
	v_or_b32_e32 v58, 16, v74
	v_ashrrev_i32_e32 v59, 31, v58
	v_lshlrev_b64 v[60:61], 11, v[58:59]
	v_lshl_add_u64 v[34:35], s[36:37], 0, v[60:61]
	v_lshl_add_u64 v[60:61], v[154:155], 1, v[34:35]
	s_waitcnt lgkmcnt(0)
	v_add_f32_e32 v34, v37, v62
	ds_bpermute_b32 v35, v124, v34
	v_cvt_pk_bf16_f32 v36, v38, v39
	v_cvt_pk_bf16_f32 v37, v40, v41
	v_cvt_pk_bf16_f32 v38, v48, v49
	v_cvt_pk_bf16_f32 v39, v46, v47
	global_store_dwordx4 v[60:61], v[42:45], off sc1
	global_store_dwordx4 v[60:61], v[36:39], off offset:256 sc1
	s_and_saveexec_b64 s[38:39], s[0:1]
	s_cbranch_execz .LBB0_800
	v_lshlrev_b64 v[36:37], 6, v[58:59]
	v_lshl_add_u64 v[36:37], s[74:75], 0, v[36:37]
	v_lshl_add_u64 v[36:37], s[26:27], 2, v[36:37]
	s_lshl_b32 s6, s49, 2
	v_lshl_add_u64 v[36:37], v[36:37], 0, s[6:7]
	s_waitcnt lgkmcnt(0)
	v_add_f32_e32 v34, v34, v35
	global_store_dword v[36:37], v34, off sc1
; __device__ __forceinline__ float bflo(unsigned w) { return __uint_as_float(w << 16); }
; #define FENCE() asm volatile("" ::: "memory")
;     __device__ __forceinline__ void operator()(const Acc& acc, const Unit& u, int wr, int wc, int fr, int fq) const {
;     ...
;         for (int bj = 0; bj < 2; ++bj) {
;             if constexpr (RES_BF16) preb[0][bj] = *(const u32x4*)(rbase + bj * 128);
;             else { pre[0][bj][0] = *(const f32x4*)(bbase + bj * 128); pre[0][bj][1] = *(const f32x4*)(bbase + bj * 128 + 4); }
;         }
; #pragma unroll
;         for (int i = 0; i < 8; ++i) {
;             const int ai = i >> 2, m = i & 3, cb = i & 1, nb = cb ^ 1;
;             if (i < 7) { const int ai2 = (i + 1) >> 2, m2 = (i + 1) & 3; const size_t ro = (size_t)(ai2 * 128 + m2 * 16) * DM;
; #pragma unroll
;                 for (int bj = 0; bj < 2; ++bj) {
;                     if constexpr (RES_BF16) preb[nb][bj] = *(const u32x4*)(rbase + ro + bj * 128);
;                     else { pre[nb][bj][0] = *(const f32x4*)(bbase + ro + bj * 128); pre[nb][bj][1] = *(const f32x4*)(bbase + ro + bj * 128 + 4); }
;                 }
;             }
;             FENCE();
;             const int r = rb + ai * 128 + m * 16;
;             float q = 0.f;
; #pragma unroll
;             for (int bj = 0; bj < 2; ++bj) {
;                 f32x4 b0, b1;
;                 if constexpr (RES_BF16) { const u32x4 w = preb[cb][bj]; b0 = (f32x4){bflo(w.x), bfhi(w.x), bflo(w.y), bfhi(w.y)}; b1 = (f32x4){bflo(w.z), bfhi(w.z), bflo(w.w), bfhi(w.w)}; }
;                 else { b0 = pre[cb][bj][0]; b1 = pre[cb][bj][1]; }
;                 const f32x4 v0 = b0 + acc[ai][bj][m][0] * scale, v1 = b1 + acc[ai][bj][m][1] * scale;
;                 if constexpr (OUT_F32) { float* op = out + (size_t)r * DM + col + bj * 128; *(f32x4*)op = v0; *(f32x4*)(op + 4) = v1; }
;                 q += (v0[0] * v0[0] + v0[1] * v0[1]) + (v0[2] * v0[2] + v0[3] * v0[3]) + (v1[0] * v1[0] + v1[1] * v1[1]) + (v1[2] * v1[2] + v1[3] * v1[3]);
;                 if (xb) { u32x4 w; w.x = cvtpk(v0[0], v0[1]); w.y = cvtpk(v0[2], v0[3]); w.z = cvtpk(v1[0], v1[1]); w.w = cvtpk(v1[2], v1[3]);
;                     *(u32x4*)(xb + (size_t)r * DM + col + bj * 128) = w; }
;             }
;             q += __shfl_xor(q, 16); q += __shfl_xor(q, 32);
;             if (fq == 0) st[(size_t)r * 16 + u.pn * 4 + wc] = q;
.LBB0_800:
	s_or_b64 exec, exec, s[38:39]
	v_add_co_u32_e32 v34, vcc, 0x58000, v156
	s_waitcnt vmcnt(3)
	v_lshlrev_b32_e32 v46, 16, v54
	s_waitcnt lgkmcnt(0)
	v_addc_co_u32_e32 v35, vcc, 0, v157, vcc
	global_load_dwordx4 v[38:41], v[34:35], off
	s_nop 0
	global_load_dwordx4 v[34:37], v[34:35], off offset:256
	v_and_b32_e32 v47, 0xffff0000, v54
	v_lshlrev_b32_e32 v48, 16, v55
	v_and_b32_e32 v49, 0xffff0000, v55
	v_lshlrev_b32_e32 v54, 16, v56
	v_and_b32_e32 v55, 0xffff0000, v56
	v_lshlrev_b32_e32 v56, 16, v57
	v_and_b32_e32 v57, 0xffff0000, v57
	v_pk_add_f32 v[32:33], v[32:33], v[48:49]
	v_pk_add_f32 v[30:31], v[30:31], v[46:47]
	v_pk_add_f32 v[46:47], v[28:29], v[56:57]
	v_pk_add_f32 v[28:29], v[26:27], v[54:55]
	v_mul_f32_e32 v26, v31, v31
	v_mul_f32_e32 v27, v33, v33
	v_fmac_f32_e32 v26, v30, v30
	v_fmac_f32_e32 v27, v32, v32
	v_add_f32_e32 v26, v26, v27
	v_mul_f32_e32 v27, v29, v29
	v_fmac_f32_e32 v27, v28, v28
	v_add_f32_e32 v26, v27, v26
	v_mul_f32_e32 v27, v47, v47
	v_fmac_f32_e32 v27, v46, v46
	v_add_f32_e32 v54, v27, v26
	v_cvt_pk_bf16_f32 v26, v30, v31
	v_cvt_pk_bf16_f32 v27, v32, v33
	s_waitcnt vmcnt(4)
	v_lshlrev_b32_e32 v30, 16, v50
	v_and_b32_e32 v31, 0xffff0000, v50
	v_lshlrev_b32_e32 v32, 16, v51
	v_and_b32_e32 v33, 0xffff0000, v51
	v_cvt_pk_bf16_f32 v28, v28, v29
	v_cvt_pk_bf16_f32 v29, v46, v47
	v_lshlrev_b32_e32 v46, 16, v52
	v_and_b32_e32 v47, 0xffff0000, v52
	v_pk_add_f32 v[24:25], v[24:25], v[32:33]
	v_pk_add_f32 v[22:23], v[22:23], v[30:31]
	v_pk_add_f32 v[32:33], v[18:19], v[46:47]
	v_mul_f32_e32 v18, v23, v23
	v_mul_f32_e32 v19, v25, v25
	v_fmac_f32_e32 v18, v22, v22
	v_fmac_f32_e32 v19, v24, v24
	v_lshlrev_b32_e32 v48, 16, v53
	v_and_b32_e32 v49, 0xffff0000, v53
	v_add_f32_e32 v18, v18, v19
	v_mul_f32_e32 v19, v33, v33
	v_pk_add_f32 v[30:31], v[20:21], v[48:49]
	v_fmac_f32_e32 v19, v32, v32
	v_add_f32_e32 v18, v19, v18
	v_mul_f32_e32 v19, v31, v31
	v_fmac_f32_e32 v19, v30, v30
	v_add_f32_e32 v18, v19, v18
	v_add_f32_e32 v21, v54, v18
	ds_bpermute_b32 v46, v166, v21
	v_or_b32_e32 v42, 32, v74
	v_ashrrev_i32_e32 v43, 31, v42
	v_lshlrev_b64 v[44:45], 11, v[42:43]
	v_lshl_add_u64 v[18:19], s[36:37], 0, v[44:45]
	v_lshl_add_u64 v[44:45], v[154:155], 1, v[18:19]
	s_waitcnt lgkmcnt(0)
	v_add_f32_e32 v18, v21, v46
	ds_bpermute_b32 v19, v124, v18
	v_cvt_pk_bf16_f32 v20, v22, v23
	v_cvt_pk_bf16_f32 v21, v24, v25
	v_cvt_pk_bf16_f32 v22, v32, v33
	v_cvt_pk_bf16_f32 v23, v30, v31
	global_store_dwordx4 v[44:45], v[26:29], off sc1
	global_store_dwordx4 v[44:45], v[20:23], off offset:256 sc1
	s_and_saveexec_b64 s[38:39], s[0:1]
	s_cbranch_execz .LBB0_802
	v_lshlrev_b64 v[20:21], 6, v[42:43]
	v_lshl_add_u64 v[20:21], s[74:75], 0, v[20:21]
	v_lshl_add_u64 v[20:21], s[26:27], 2, v[20:21]
	s_lshl_b32 s6, s49, 2
	v_lshl_add_u64 v[20:21], v[20:21], 0, s[6:7]
	s_waitcnt lgkmcnt(0)
	v_add_f32_e32 v18, v18, v19
	global_store_dword v[20:21], v18, off sc1
.LBB0_802:
	s_or_b64 exec, exec, s[38:39]
	s_waitcnt vmcnt(3)
	v_lshlrev_b32_e32 v22, 16, v38
	v_and_b32_e32 v23, 0xffff0000, v38
	v_lshlrev_b32_e32 v24, 16, v39
	v_and_b32_e32 v25, 0xffff0000, v39
	v_lshlrev_b32_e32 v26, 16, v40
	v_and_b32_e32 v27, 0xffff0000, v40
	v_lshlrev_b32_e32 v28, 16, v41
	v_and_b32_e32 v29, 0xffff0000, v41
	v_pk_add_f32 v[16:17], v[16:17], v[24:25]
	v_pk_add_f32 v[14:15], v[14:15], v[22:23]
	v_pk_add_f32 v[22:23], v[12:13], v[28:29]
	v_pk_add_f32 v[12:13], v[10:11], v[26:27]
	v_mul_f32_e32 v10, v15, v15
	v_mul_f32_e32 v11, v17, v17
	v_fmac_f32_e32 v10, v14, v14
	v_fmac_f32_e32 v11, v16, v16
	v_add_f32_e32 v10, v10, v11
	v_mul_f32_e32 v11, v13, v13
	v_fmac_f32_e32 v11, v12, v12
	v_add_f32_e32 v10, v11, v10
	v_mul_f32_e32 v11, v23, v23
	v_fmac_f32_e32 v11, v22, v22
	v_add_f32_e32 v26, v11, v10
	v_cvt_pk_bf16_f32 v10, v14, v15
	v_cvt_pk_bf16_f32 v11, v16, v17
	s_waitcnt vmcnt(2)
	v_lshlrev_b32_e32 v14, 16, v34
	v_and_b32_e32 v15, 0xffff0000, v34
	v_lshlrev_b32_e32 v16, 16, v35
	v_and_b32_e32 v17, 0xffff0000, v35
	v_cvt_pk_bf16_f32 v12, v12, v13
	v_cvt_pk_bf16_f32 v13, v22, v23
	v_lshlrev_b32_e32 v22, 16, v36
	v_and_b32_e32 v23, 0xffff0000, v36
	v_pk_add_f32 v[8:9], v[8:9], v[16:17]
	v_pk_add_f32 v[6:7], v[6:7], v[14:15]
	v_pk_add_f32 v[16:17], v[2:3], v[22:23]
	v_mul_f32_e32 v2, v7, v7
	v_mul_f32_e32 v3, v9, v9
	v_fmac_f32_e32 v2, v6, v6
	v_fmac_f32_e32 v3, v8, v8
	v_lshlrev_b32_e32 v24, 16, v37
	v_and_b32_e32 v25, 0xffff0000, v37
	v_add_f32_e32 v2, v2, v3
	v_mul_f32_e32 v3, v17, v17
	v_pk_add_f32 v[14:15], v[4:5], v[24:25]
	v_fmac_f32_e32 v3, v16, v16
	v_add_f32_e32 v2, v3, v2
	v_mul_f32_e32 v3, v15, v15
	v_fmac_f32_e32 v3, v14, v14
	v_add_f32_e32 v2, v3, v2
	v_add_f32_e32 v5, v26, v2
	ds_bpermute_b32 v22, v166, v5
	v_or_b32_e32 v18, 48, v74
	s_waitcnt lgkmcnt(1)
	v_ashrrev_i32_e32 v19, 31, v18
	v_lshlrev_b64 v[20:21], 11, v[18:19]
	v_lshl_add_u64 v[2:3], s[36:37], 0, v[20:21]
	v_lshl_add_u64 v[20:21], v[154:155], 1, v[2:3]
	s_waitcnt lgkmcnt(0)
	v_add_f32_e32 v2, v5, v22
	ds_bpermute_b32 v3, v124, v2
	v_cvt_pk_bf16_f32 v4, v6, v7
	v_cvt_pk_bf16_f32 v5, v8, v9
	v_cvt_pk_bf16_f32 v6, v16, v17
	v_cvt_pk_bf16_f32 v7, v14, v15
	global_store_dwordx4 v[20:21], v[10:13], off sc1
	global_store_dwordx4 v[20:21], v[4:7], off offset:256 sc1
	s_and_saveexec_b64 s[38:39], s[0:1]
	s_cbranch_execz .LBB0_804
	v_lshlrev_b64 v[4:5], 6, v[18:19]
	v_lshl_add_u64 v[4:5], s[74:75], 0, v[4:5]
	v_lshl_add_u64 v[4:5], s[26:27], 2, v[4:5]
	s_lshl_b32 s6, s49, 2
	v_lshl_add_u64 v[4:5], v[4:5], 0, s[6:7]
	s_waitcnt lgkmcnt(0)
	v_add_f32_e32 v2, v2, v3
	global_store_dword v[4:5], v2, off sc1

; #define LAS __attribute__((address_space(3)))
; __device__ __forceinline__ f32x4 sig_from_negl2(f32x4 t) { return rcp_4(exp2_4(t) + 1.0f); }
; __device__ __forceinline__ u32x2 pack4(f32x4 v) { u32x2 w; w.x = cvtpk(v[0], v[1]); w.y = cvtpk(v[2], v[3]); return w; }
; __device__ __forceinline__ void rstd8_lds(int rrel, int fq, float inv_dim, float (&rs)[2][4]) {
;     const LAS unsigned char* lds = (const LAS unsigned char*)0;
;     f32x4 v[2][4];
; #pragma unroll
;     for (int ai = 0; ai < 2; ++ai)
; #pragma unroll
;         for (int m = 0; m < 4; ++m) v[ai][m] = *(const LAS f32x4*)(lds + STAB_OFF + (rrel + ai * 128 + m * 16) * 64 + fq * 16);
; #pragma unroll
;     for (int ai = 0; ai < 2; ++ai)
; #pragma unroll
;         for (int m = 0; m < 4; ++m) { float q = (v[ai][m][0] + v[ai][m][1]) + (v[ai][m][2] + v[ai][m][3]); q += __shfl_xor(q, 16); q += __shfl_xor(q, 32); rs[ai][m] = __builtin_amdgcn_rsqf(q * inv_dim + EPS); }
; }
;     __device__ __forceinline__ void operator()(const Acc& acc, const Unit& u, int wr, int wc, int fr, int fq) const {
;         const int col = u.pn * 128 + wc * 32 + fq * 8;
;         float rsv[2][4]; rstd8_lds(wr * 64 + fr, fq, 1.0f / 1024.0f, rsv);
; #pragma unroll
;         for (int ai = 0; ai < 2; ++ai)
; #pragma unroll
;             for (int m = 0; m < 4; ++m) {
;                 const int r = u.pm * 256 + ai * 128 + wr * 64 + m * 16 + fr;
;                 const float rs = rsv[ai][m], nrs = -LOG2E * rs, rs2 = rs * rs;
;                 u32x4 w;
; #pragma unroll
;                 for (int n = 0; n < 2; ++n) {
;                     const f32x4 ga = acc[ai][0][m][n], ua = acc[ai][1][m][n];
;                     const f32x4 sg = sig_from_negl2(ga * nrs);
;                     const u32x2 pk = pack4((ga * ua) * rs2 * sg);
.LBB0_887:
	ds_read_b128 v[156:159], v153
	ds_read_b128 v[160:163], v153 offset:1024
	ds_read_b128 v[164:167], v153 offset:2048
	ds_read_b128 v[172:175], v153 offset:3072
	v_and_b32_e32 v176, 64, v154
	v_xor_b32_e32 v169, 16, v154
	v_add_u32_e32 v178, 64, v176
	v_cmp_lt_i32_e32 vcc, v169, v178
	s_waitcnt lgkmcnt(0)
	v_mov_b32_e32 v176, v157
	v_mov_b32_e32 v177, v158
	v_mov_b32_e32 v157, v159
	v_cndmask_b32_e32 v169, v154, v169, vcc
	v_pk_add_f32 v[156:157], v[176:177], v[156:157]
	v_lshlrev_b32_e32 v169, 2, v169
	v_add_f32_e32 v156, v156, v157
	ds_bpermute_b32 v157, v169, v156
	v_xor_b32_e32 v158, 32, v154
	v_cmp_lt_i32_e32 vcc, v158, v178
	v_pk_mul_f32 v[124:125], v[128:129], v[124:125]
	v_pk_mul_f32 v[122:123], v[126:127], v[122:123]
	v_cndmask_b32_e32 v158, v154, v158, vcc
	v_lshlrev_b32_e32 v190, 2, v158
	s_waitcnt lgkmcnt(0)
	v_add_f32_e32 v188, v156, v157
	ds_bpermute_b32 v189, v190, v188
	ds_read_b128 v[156:159], v153 offset:8192
	ds_read_b128 v[176:179], v153 offset:9216
	ds_read_b128 v[180:183], v153 offset:10240
	ds_read_b128 v[184:187], v153 offset:11264
	v_pk_mul_f32 v[114:115], v[118:119], v[114:115]
	v_pk_mul_f32 v[116:117], v[120:121], v[116:117]
	v_lshl_or_b32 v168, s42, 7, v149
	s_waitcnt lgkmcnt(0)
	v_add_f32_e32 v191, v188, v189
	v_mov_b32_e32 v188, v161
	v_mov_b32_e32 v189, v162
	v_mov_b32_e32 v161, v163
	v_pk_add_f32 v[160:161], v[188:189], v[160:161]
	v_pk_mul_f32 v[106:107], v[110:111], v[106:107]
	v_add_f32_e32 v162, v160, v161
	v_mov_b32_e32 v160, v165
	v_mov_b32_e32 v161, v166
	v_mov_b32_e32 v165, v167
	v_pk_add_f32 v[160:161], v[160:161], v[164:165]
	ds_bpermute_b32 v163, v169, v162
	v_add_f32_e32 v160, v160, v161
	ds_bpermute_b32 v161, v169, v160
	v_fmamk_f32 v164, v191, 0x3a800000, v155
	v_rsq_f32_e32 v166, v164
	s_waitcnt lgkmcnt(0)
	v_add_f32_e32 v162, v162, v163
	ds_bpermute_b32 v163, v190, v162
	v_add_f32_e32 v164, v160, v161
	v_mov_b32_e32 v160, v173
	v_mov_b32_e32 v161, v174
	v_mov_b32_e32 v173, v175
	v_pk_add_f32 v[160:161], v[160:161], v[172:173]
	s_waitcnt lgkmcnt(0)
	v_add_f32_e32 v162, v162, v163
	v_add_f32_e32 v160, v160, v161
	ds_bpermute_b32 v161, v169, v160
	ds_bpermute_b32 v165, v190, v164
	v_fmamk_f32 v162, v162, 0x3a800000, v155
	v_rsq_f32_e32 v167, v162
	v_pk_mul_f32 v[108:109], v[112:113], v[108:109]
	s_waitcnt lgkmcnt(0)
	v_add_f32_e32 v163, v160, v161
	v_mov_b32_e32 v160, v157
	v_mov_b32_e32 v161, v158
	v_mov_b32_e32 v157, v159
	v_pk_add_f32 v[156:157], v[160:161], v[156:157]
	v_add_f32_e32 v162, v164, v165
	v_add_f32_e32 v156, v156, v157
	ds_bpermute_b32 v157, v169, v156
	ds_bpermute_b32 v164, v190, v163
	v_fmamk_f32 v158, v162, 0x3a800000, v155
	v_rsq_f32_e32 v159, v158
	v_pk_mul_f32 v[100:101], v[104:105], v[100:101]
	s_waitcnt lgkmcnt(0)
	v_add_f32_e32 v160, v156, v157
	v_mov_b32_e32 v156, v177
	v_mov_b32_e32 v157, v178
	v_mov_b32_e32 v177, v179
	ds_bpermute_b32 v161, v190, v160
	v_pk_add_f32 v[156:157], v[156:157], v[176:177]
	v_add_f32_e32 v158, v163, v164
	v_add_f32_e32 v156, v156, v157
	ds_bpermute_b32 v157, v169, v156
	v_fmamk_f32 v158, v158, 0x3a800000, v155
	v_rsq_f32_e32 v172, v158
	s_waitcnt lgkmcnt(0)
	v_add_f32_e32 v158, v160, v161
	v_fmamk_f32 v158, v158, 0x3a800000, v155
	v_rsq_f32_e32 v161, v158
	v_add_f32_e32 v158, v156, v157
	v_mov_b32_e32 v156, v181
	v_mov_b32_e32 v157, v182
	v_mov_b32_e32 v181, v183
	v_pk_add_f32 v[156:157], v[156:157], v[180:181]
	ds_bpermute_b32 v160, v190, v158
	v_add_f32_e32 v162, v156, v157
	ds_bpermute_b32 v163, v169, v162
	v_mov_b32_e32 v156, v185
	v_mov_b32_e32 v157, v186
	s_waitcnt lgkmcnt(0)
	v_add_f32_e32 v158, v158, v160
	v_fmamk_f32 v158, v158, 0x3a800000, v155
	v_add_f32_e32 v160, v162, v163
	ds_bpermute_b32 v162, v190, v160
	v_rsq_f32_e32 v173, v158
	v_mov_b32_e32 v185, v187
	v_pk_add_f32 v[156:157], v[156:157], v[184:185]
	v_pk_mul_f32 v[98:99], v[102:103], v[98:99]
	s_waitcnt lgkmcnt(0)
	v_add_f32_e32 v158, v160, v162
	v_mul_f32_e32 v160, 0xbfb8aa3b, v166
	v_pk_mul_f32 v[162:163], v[128:129], v[160:161] op_sel_hi:[1,0]
	v_pk_mul_f32 v[164:165], v[126:127], v[160:161] op_sel_hi:[1,0]
	v_exp_f32_e32 v162, v162
	v_exp_f32_e32 v164, v164
	v_exp_f32_e32 v163, v163
	v_exp_f32_e32 v165, v165
	v_add_f32_e32 v156, v156, v157
	ds_bpermute_b32 v157, v169, v156
	v_pk_add_f32 v[162:163], v[162:163], 1.0 op_sel_hi:[1,0]
	v_pk_add_f32 v[164:165], v[164:165], 1.0 op_sel_hi:[1,0]
	v_rcp_f32_e32 v162, v162
	v_rcp_f32_e32 v164, v164
	v_rcp_f32_e32 v165, v165
	v_rcp_f32_e32 v163, v163
	v_pk_mul_f32 v[126:127], v[120:121], v[160:161] op_sel_hi:[1,0]
	v_pk_mul_f32 v[128:129], v[118:119], v[160:161] op_sel_hi:[1,0]
	v_exp_f32_e32 v126, v126
	v_exp_f32_e32 v128, v128
	v_exp_f32_e32 v127, v127
	v_exp_f32_e32 v129, v129
	v_mul_f32_e32 v166, v166, v166
	v_pk_mul_f32 v[122:123], v[122:123], v[166:167] op_sel_hi:[1,0]
	v_pk_mul_f32 v[124:125], v[124:125], v[166:167] op_sel_hi:[1,0]
	s_waitcnt lgkmcnt(0)
	v_add_f32_e32 v156, v156, v157
	v_pk_mul_f32 v[124:125], v[124:125], v[162:163]
	v_pk_mul_f32 v[122:123], v[122:123], v[164:165]
	ds_bpermute_b32 v157, v190, v156
	v_cvt_pk_bf16_f32 v122, v122, v123
	v_cvt_pk_bf16_f32 v123, v124, v125
	v_pk_add_f32 v[124:125], v[126:127], 1.0 op_sel_hi:[1,0]
	v_pk_add_f32 v[126:127], v[128:129], 1.0 op_sel_hi:[1,0]
	v_rcp_f32_e32 v124, v124
	v_rcp_f32_e32 v126, v126
	v_rcp_f32_e32 v127, v127
	v_rcp_f32_e32 v125, v125
	v_pk_mul_f32 v[114:115], v[114:115], v[166:167] op_sel_hi:[1,0]
	v_mul_f32_e32 v120, 0xbfb8aa3b, v167
	s_waitcnt lgkmcnt(0)
; __device__ __forceinline__ f32x4 sig_from_negl2(f32x4 t) { return rcp_4(exp2_4(t) + 1.0f); }
; __device__ __forceinline__ u32x2 pack4(f32x4 v) { u32x2 w; w.x = cvtpk(v[0], v[1]); w.y = cvtpk(v[2], v[3]); return w; }
;     __device__ __forceinline__ void operator()(const Acc& acc, const Unit& u, int wr, int wc, int fr, int fq) const {
;     ...
;             for (int m = 0; m < 4; ++m) {
;                 const int r = u.pm * 256 + ai * 128 + wr * 64 + m * 16 + fr;
;                 const float rs = rsv[ai][m], nrs = -LOG2E * rs, rs2 = rs * rs;
;                 u32x4 w;
; #pragma unroll
;                 for (int n = 0; n < 2; ++n) {
;                     const f32x4 ga = acc[ai][0][m][n], ua = acc[ai][1][m][n];
;                     const f32x4 sg = sig_from_negl2(ga * nrs);
;                     const u32x2 pk = pack4((ga * ua) * rs2 * sg);
;                     if (n == 0) { w.x = pk.x; w.y = pk.y; } else { w.z = pk.x; w.w = pk.y; }
;                 }
;                 *(u32x4*)(O + (size_t)r * DFF + col) = w;
;             }
	v_add_f32_e32 v156, v156, v157
	v_pk_mul_f32 v[114:115], v[114:115], v[126:127]
	v_pk_mul_f32 v[126:127], v[112:113], v[120:121] op_sel_hi:[1,0]
	v_pk_mul_f32 v[128:129], v[110:111], v[120:121] op_sel_hi:[1,0]
	v_fmamk_f32 v156, v156, 0x3a800000, v155
	v_pk_mul_f32 v[116:117], v[116:117], v[166:167] op_sel_hi:[1,0]
	v_exp_f32_e32 v128, v128
	v_exp_f32_e32 v126, v126
	v_exp_f32_e32 v127, v127
	v_exp_f32_e32 v129, v129
	v_rsq_f32_e32 v157, v156
	v_lshl_add_u32 v156, s40, 8, v1
	v_ashrrev_i32_e32 v169, 31, v168
	v_pk_mul_f32 v[116:117], v[116:117], v[124:125]
	v_cvt_pk_bf16_f32 v124, v114, v115
	v_mov_b64_e32 v[114:115], s[16:17]
	v_cvt_pk_bf16_f32 v125, v116, v117
	v_mad_i64_i32 v[118:119], s[44:45], v156, s60, v[114:115]
	v_lshlrev_b64 v[116:117], 1, v[168:169]
	v_lshl_add_u64 v[118:119], v[118:119], 0, v[116:117]
	global_store_dwordx4 v[118:119], v[122:125], off sc1
	v_pk_mul_f32 v[110:111], v[104:105], v[120:121] op_sel_hi:[1,0]
	v_mul_f32_e32 v118, v167, v167
	v_pk_add_f32 v[122:123], v[126:127], 1.0 op_sel_hi:[1,0]
	v_pk_add_f32 v[124:125], v[128:129], 1.0 op_sel_hi:[1,0]
	v_rcp_f32_e32 v122, v122
	v_rcp_f32_e32 v124, v124
	v_rcp_f32_e32 v125, v125
	v_rcp_f32_e32 v123, v123
	v_exp_f32_e32 v110, v110
	v_exp_f32_e32 v111, v111
	v_pk_mul_f32 v[106:107], v[106:107], v[118:119] op_sel_hi:[1,0]
	v_pk_mul_f32 v[108:109], v[108:109], v[118:119] op_sel_hi:[1,0]
	v_pk_mul_f32 v[106:107], v[106:107], v[124:125]
	v_pk_mul_f32 v[108:109], v[108:109], v[122:123]
	v_cvt_pk_bf16_f32 v106, v106, v107
	v_cvt_pk_bf16_f32 v107, v108, v109
	v_pk_add_f32 v[108:109], v[110:111], 1.0 op_sel_hi:[1,0]
	v_pk_mul_f32 v[112:113], v[102:103], v[120:121] op_sel_hi:[1,0]
	v_rcp_f32_e32 v108, v108
	v_rcp_f32_e32 v109, v109
	v_exp_f32_e32 v112, v112
	v_exp_f32_e32 v113, v113
	v_pk_mul_f32 v[100:101], v[100:101], v[118:119] op_sel_hi:[1,0]
	v_pk_mul_f32 v[98:99], v[98:99], v[118:119] op_sel_hi:[1,0]
	v_pk_mul_f32 v[100:101], v[100:101], v[108:109]
	v_pk_add_f32 v[110:111], v[112:113], 1.0 op_sel_hi:[1,0]
	v_cvt_pk_bf16_f32 v109, v100, v101
	v_mul_f32_e32 v100, 0xbfb8aa3b, v159
	v_rcp_f32_e32 v110, v110
	v_rcp_f32_e32 v111, v111
	v_pk_mul_f32 v[102:103], v[96:97], v[100:101] op_sel_hi:[1,0]
	v_pk_mul_f32 v[104:105], v[94:95], v[100:101] op_sel_hi:[1,0]
	v_exp_f32_e32 v102, v102
	v_exp_f32_e32 v104, v104
	v_exp_f32_e32 v103, v103
	v_exp_f32_e32 v105, v105
	v_pk_mul_f32 v[98:99], v[98:99], v[110:111]
	v_pk_mul_f32 v[90:91], v[94:95], v[90:91]
	v_cvt_pk_bf16_f32 v108, v98, v99
	v_or_b32_e32 v98, 16, v156
	v_pk_add_f32 v[102:103], v[102:103], 1.0 op_sel_hi:[1,0]
	v_pk_add_f32 v[104:105], v[104:105], 1.0 op_sel_hi:[1,0]
	v_mad_i64_i32 v[98:99], s[44:45], v98, s60, v[114:115]
	v_rcp_f32_e32 v104, v104
	v_rcp_f32_e32 v105, v105
	v_rcp_f32_e32 v102, v102
	v_rcp_f32_e32 v103, v103
	v_pk_mul_f32 v[94:95], v[88:89], v[100:101] op_sel_hi:[1,0]
	v_lshl_add_u64 v[98:99], v[98:99], 0, v[116:117]
	v_exp_f32_e32 v94, v94
	v_exp_f32_e32 v95, v95
	global_store_dwordx4 v[98:99], v[106:109], off sc1
	v_mul_f32_e32 v98, v159, v159
	v_pk_mul_f32 v[92:93], v[96:97], v[92:93]
	v_pk_mul_f32 v[90:91], v[90:91], v[98:99] op_sel_hi:[1,0]
	v_pk_mul_f32 v[92:93], v[92:93], v[98:99] op_sel_hi:[1,0]
	v_pk_mul_f32 v[90:91], v[90:91], v[104:105]
	v_pk_mul_f32 v[92:93], v[92:93], v[102:103]
	v_cvt_pk_bf16_f32 v90, v90, v91
	v_cvt_pk_bf16_f32 v91, v92, v93
	v_pk_add_f32 v[92:93], v[94:95], 1.0 op_sel_hi:[1,0]
	v_pk_mul_f32 v[96:97], v[86:87], v[100:101] op_sel_hi:[1,0]
	v_rcp_f32_e32 v92, v92
	v_rcp_f32_e32 v93, v93
	v_exp_f32_e32 v96, v96
	v_exp_f32_e32 v97, v97
	v_pk_mul_f32 v[84:85], v[88:89], v[84:85]
	v_pk_mul_f32 v[82:83], v[86:87], v[82:83]
	v_pk_mul_f32 v[84:85], v[84:85], v[98:99] op_sel_hi:[1,0]
	v_pk_add_f32 v[94:95], v[96:97], 1.0 op_sel_hi:[1,0]
	v_pk_mul_f32 v[84:85], v[84:85], v[92:93]
	v_rcp_f32_e32 v94, v94
	v_cvt_pk_bf16_f32 v93, v84, v85
	v_mul_f32_e32 v84, 0xbfb8aa3b, v172
	v_rcp_f32_e32 v95, v95
	v_pk_mul_f32 v[86:87], v[80:81], v[84:85] op_sel_hi:[1,0]
	v_pk_mul_f32 v[88:89], v[78:79], v[84:85] op_sel_hi:[1,0]
	v_exp_f32_e32 v86, v86
	v_exp_f32_e32 v88, v88
	v_exp_f32_e32 v87, v87
	v_exp_f32_e32 v89, v89
	v_pk_mul_f32 v[82:83], v[82:83], v[98:99] op_sel_hi:[1,0]
	v_pk_mul_f32 v[76:77], v[80:81], v[76:77]
	v_pk_mul_f32 v[82:83], v[82:83], v[94:95]
	v_pk_add_f32 v[86:87], v[86:87], 1.0 op_sel_hi:[1,0]
	v_cvt_pk_bf16_f32 v92, v82, v83
	v_or_b32_e32 v82, 32, v156
	v_pk_add_f32 v[88:89], v[88:89], 1.0 op_sel_hi:[1,0]
	v_mad_i64_i32 v[82:83], s[44:45], v82, s60, v[114:115]
	v_rcp_f32_e32 v88, v88
	v_rcp_f32_e32 v89, v89
	v_rcp_f32_e32 v86, v86
	v_rcp_f32_e32 v87, v87
	v_pk_mul_f32 v[74:75], v[78:79], v[74:75]
	v_pk_mul_f32 v[78:79], v[72:73], v[84:85] op_sel_hi:[1,0]
	v_pk_mul_f32 v[80:81], v[70:71], v[84:85] op_sel_hi:[1,0]
	v_lshl_add_u64 v[82:83], v[82:83], 0, v[116:117]
	v_exp_f32_e32 v80, v80
	v_exp_f32_e32 v78, v78
	v_exp_f32_e32 v79, v79
	v_exp_f32_e32 v81, v81
	global_store_dwordx4 v[82:83], v[90:93], off sc1
	v_mul_f32_e32 v82, v172, v172
	v_pk_mul_f32 v[74:75], v[74:75], v[82:83] op_sel_hi:[1,0]
	v_pk_mul_f32 v[76:77], v[76:77], v[82:83] op_sel_hi:[1,0]
	v_pk_mul_f32 v[74:75], v[74:75], v[88:89]
	v_pk_mul_f32 v[76:77], v[76:77], v[86:87]
	v_cvt_pk_bf16_f32 v74, v74, v75
	v_cvt_pk_bf16_f32 v75, v76, v77
	v_pk_add_f32 v[76:77], v[78:79], 1.0 op_sel_hi:[1,0]
	v_pk_add_f32 v[78:79], v[80:81], 1.0 op_sel_hi:[1,0]
	v_rcp_f32_e32 v76, v76
	v_rcp_f32_e32 v78, v78
	v_rcp_f32_e32 v79, v79
	v_rcp_f32_e32 v77, v77
	v_pk_mul_f32 v[66:67], v[70:71], v[66:67]
	v_pk_mul_f32 v[68:69], v[72:73], v[68:69]
	v_pk_mul_f32 v[66:67], v[66:67], v[82:83] op_sel_hi:[1,0]
	v_pk_mul_f32 v[68:69], v[68:69], v[82:83] op_sel_hi:[1,0]
; __device__ __forceinline__ f32x4 sig_from_negl2(f32x4 t) { return rcp_4(exp2_4(t) + 1.0f); }
; __device__ __forceinline__ u32x2 pack4(f32x4 v) { u32x2 w; w.x = cvtpk(v[0], v[1]); w.y = cvtpk(v[2], v[3]); return w; }
;     __device__ __forceinline__ void operator()(const Acc& acc, const Unit& u, int wr, int wc, int fr, int fq) const {
;     ...
;             for (int m = 0; m < 4; ++m) {
;                 const int r = u.pm * 256 + ai * 128 + wr * 64 + m * 16 + fr;
;                 const float rs = rsv[ai][m], nrs = -LOG2E * rs, rs2 = rs * rs;
;                 u32x4 w;
; #pragma unroll
;                 for (int n = 0; n < 2; ++n) {
;                     const f32x4 ga = acc[ai][0][m][n], ua = acc[ai][1][m][n];
;                     const f32x4 sg = sig_from_negl2(ga * nrs);
;                     const u32x2 pk = pack4((ga * ua) * rs2 * sg);
;                     if (n == 0) { w.x = pk.x; w.y = pk.y; } else { w.z = pk.x; w.w = pk.y; }
;                 }
;                 *(u32x4*)(O + (size_t)r * DFF + col) = w;
;             }
	v_pk_mul_f32 v[66:67], v[66:67], v[78:79]
	v_pk_mul_f32 v[68:69], v[68:69], v[76:77]
	v_cvt_pk_bf16_f32 v76, v66, v67
	v_or_b32_e32 v66, 48, v156
	v_mad_i64_i32 v[66:67], s[44:45], v66, s60, v[114:115]
	v_cvt_pk_bf16_f32 v77, v68, v69
	v_lshl_add_u64 v[66:67], v[66:67], 0, v[116:117]
	global_store_dwordx4 v[66:67], v[74:77], off sc1
	v_mul_f32_e32 v66, 0xbfb8aa3b, v161
	v_pk_mul_f32 v[68:69], v[64:65], v[66:67] op_sel_hi:[1,0]
	v_pk_mul_f32 v[70:71], v[62:63], v[66:67] op_sel_hi:[1,0]
	v_exp_f32_e32 v68, v68
	v_exp_f32_e32 v70, v70
	v_exp_f32_e32 v69, v69
	v_exp_f32_e32 v71, v71
	v_add_u32_e32 v67, 0x80, v156
	v_pk_mul_f32 v[58:59], v[62:63], v[58:59]
	v_pk_add_f32 v[68:69], v[68:69], 1.0 op_sel_hi:[1,0]
	v_pk_add_f32 v[70:71], v[70:71], 1.0 op_sel_hi:[1,0]
	v_rcp_f32_e32 v68, v68
	v_rcp_f32_e32 v70, v70
	v_rcp_f32_e32 v71, v71
	v_rcp_f32_e32 v69, v69
	v_pk_mul_f32 v[62:63], v[56:57], v[66:67] op_sel_hi:[1,0]
	v_mul_f32_e32 v72, v161, v161
	v_exp_f32_e32 v62, v62
	v_exp_f32_e32 v63, v63
	v_pk_mul_f32 v[60:61], v[64:65], v[60:61]
	v_pk_mul_f32 v[58:59], v[58:59], v[72:73] op_sel_hi:[1,0]
	v_pk_mul_f32 v[60:61], v[60:61], v[72:73] op_sel_hi:[1,0]
	v_pk_mul_f32 v[58:59], v[58:59], v[70:71]
	v_pk_mul_f32 v[60:61], v[60:61], v[68:69]
	v_cvt_pk_bf16_f32 v58, v58, v59
	v_cvt_pk_bf16_f32 v59, v60, v61
	v_pk_add_f32 v[60:61], v[62:63], 1.0 op_sel_hi:[1,0]
	v_pk_mul_f32 v[64:65], v[54:55], v[66:67] op_sel_hi:[1,0]
	v_rcp_f32_e32 v60, v60
	v_rcp_f32_e32 v61, v61
	v_exp_f32_e32 v64, v64
	v_exp_f32_e32 v65, v65
	v_pk_mul_f32 v[52:53], v[56:57], v[52:53]
	v_pk_mul_f32 v[50:51], v[54:55], v[50:51]
	v_pk_mul_f32 v[52:53], v[52:53], v[72:73] op_sel_hi:[1,0]
	v_pk_add_f32 v[62:63], v[64:65], 1.0 op_sel_hi:[1,0]
	v_pk_mul_f32 v[52:53], v[52:53], v[60:61]
	v_rcp_f32_e32 v62, v62
	v_cvt_pk_bf16_f32 v61, v52, v53
	v_mul_f32_e32 v52, 0xbfb8aa3b, v173
	v_pk_mul_f32 v[54:55], v[48:49], v[52:53] op_sel_hi:[1,0]
	v_pk_mul_f32 v[56:57], v[46:47], v[52:53] op_sel_hi:[1,0]
	v_rcp_f32_e32 v63, v63
	v_exp_f32_e32 v56, v56
	v_exp_f32_e32 v54, v54
	v_exp_f32_e32 v55, v55
	v_exp_f32_e32 v57, v57
	v_pk_mul_f32 v[50:51], v[50:51], v[72:73] op_sel_hi:[1,0]
	v_pk_mul_f32 v[42:43], v[46:47], v[42:43]
	v_pk_mul_f32 v[50:51], v[50:51], v[62:63]
	v_pk_add_f32 v[54:55], v[54:55], 1.0 op_sel_hi:[1,0]
	v_pk_add_f32 v[56:57], v[56:57], 1.0 op_sel_hi:[1,0]
	v_cvt_pk_bf16_f32 v60, v50, v51
	v_mad_i64_i32 v[50:51], s[44:45], v67, s60, v[114:115]
	v_rcp_f32_e32 v56, v56
	v_rcp_f32_e32 v57, v57
	v_rcp_f32_e32 v54, v54
	v_rcp_f32_e32 v55, v55
	v_pk_mul_f32 v[46:47], v[40:41], v[52:53] op_sel_hi:[1,0]
	v_lshl_add_u64 v[50:51], v[50:51], 0, v[116:117]
	v_exp_f32_e32 v46, v46
	v_exp_f32_e32 v47, v47
	global_store_dwordx4 v[50:51], v[58:61], off sc1
	v_mul_f32_e32 v50, v173, v173
	v_pk_mul_f32 v[44:45], v[48:49], v[44:45]
	v_pk_mul_f32 v[42:43], v[42:43], v[50:51] op_sel_hi:[1,0]
	v_pk_mul_f32 v[44:45], v[44:45], v[50:51] op_sel_hi:[1,0]
	v_pk_mul_f32 v[42:43], v[42:43], v[56:57]
	v_pk_mul_f32 v[44:45], v[44:45], v[54:55]
	v_cvt_pk_bf16_f32 v42, v42, v43
	v_cvt_pk_bf16_f32 v43, v44, v45
	v_pk_add_f32 v[44:45], v[46:47], 1.0 op_sel_hi:[1,0]
	v_fmamk_f32 v158, v158, 0x3a800000, v155
	v_pk_mul_f32 v[48:49], v[38:39], v[52:53] op_sel_hi:[1,0]
	v_rcp_f32_e32 v44, v44
	v_rcp_f32_e32 v45, v45
	v_rsq_f32_e32 v158, v158
	v_exp_f32_e32 v48, v48
	v_exp_f32_e32 v49, v49
	v_pk_mul_f32 v[36:37], v[40:41], v[36:37]
	v_pk_mul_f32 v[34:35], v[38:39], v[34:35]
	v_pk_mul_f32 v[36:37], v[36:37], v[50:51] op_sel_hi:[1,0]
	v_pk_add_f32 v[46:47], v[48:49], 1.0 op_sel_hi:[1,0]
	v_pk_mul_f32 v[36:37], v[36:37], v[44:45]
	v_rcp_f32_e32 v46, v46
	v_cvt_pk_bf16_f32 v45, v36, v37
	v_mul_f32_e32 v36, 0xbfb8aa3b, v158
	v_rcp_f32_e32 v47, v47
	v_pk_mul_f32 v[38:39], v[32:33], v[36:37] op_sel_hi:[1,0]
	v_pk_mul_f32 v[40:41], v[30:31], v[36:37] op_sel_hi:[1,0]
	v_exp_f32_e32 v38, v38
	v_exp_f32_e32 v40, v40
	v_exp_f32_e32 v39, v39
	v_exp_f32_e32 v41, v41
	v_pk_mul_f32 v[34:35], v[34:35], v[50:51] op_sel_hi:[1,0]
	v_pk_mul_f32 v[26:27], v[30:31], v[26:27]
	v_pk_mul_f32 v[34:35], v[34:35], v[46:47]
	v_pk_add_f32 v[38:39], v[38:39], 1.0 op_sel_hi:[1,0]
; __device__ __forceinline__ f32x4 sig_from_negl2(f32x4 t) { return rcp_4(exp2_4(t) + 1.0f); }
; __device__ __forceinline__ u32x2 pack4(f32x4 v) { u32x2 w; w.x = cvtpk(v[0], v[1]); w.y = cvtpk(v[2], v[3]); return w; }
; #define PG8_BAR __builtin_amdgcn_s_barrier()
; #define PG8_STATS(pm_) do { if constexpr (Epi::STAB) { if (wr == 1) { const char* _sb = (const char*)E.st + (size_t)(pm_) * 16384 + (size_t)lane * 16; \
;         _Pragma("unroll") for (int _i = 0; _i < 4; ++_i) __builtin_amdgcn_global_load_lds((const unsigned*)(_sb + ((wid - 4) + 4 * _i) * 1024), (LAS unsigned*)(lds + STAB_OFF + ((wid - 4) + 4 * _i) * 1024), 16, 0, 0); } } } while (0)
; template <class Epi>
; __device__ __forceinline__ void gemm_phase(LAS unsigned char* lds, const Gemm g, const StaticOrder& S, const Epi& E) {
;     ...
;         if (wr == 0) PG8_BAR;
;         E(acc, cur, wr, wc, fr, fq);
;         if (!has_next) break;
; #pragma unroll
;         for (int a = 0; a < 2; ++a)
; #pragma unroll
;             for (int b = 0; b < 2; ++b)
; #pragma unroll
;                 for (int m = 0; m < 4; ++m)
; #pragma unroll
;                     for (int n = 0; n < 2; ++n) acc[a][b][m][n] = (f32x4){0.f, 0.f, 0.f, 0.f};
;         cur = nxt; cA = nA; cB = nB; ++ui;
;         if (wr == 1) PG8_BAR;
;         PG8_STATS(cur.pm);
;     __device__ __forceinline__ void operator()(const Acc& acc, const Unit& u, int wr, int wc, int fr, int fq) const {
;     ...
;             for (int m = 0; m < 4; ++m) {
;                 const int r = u.pm * 256 + ai * 128 + wr * 64 + m * 16 + fr;
;                 const float rs = rsv[ai][m], nrs = -LOG2E * rs, rs2 = rs * rs;
;                 u32x4 w;
; #pragma unroll
;                 for (int n = 0; n < 2; ++n) {
;                     const f32x4 ga = acc[ai][0][m][n], ua = acc[ai][1][m][n];
;                     const f32x4 sg = sig_from_negl2(ga * nrs);
;                     const u32x2 pk = pack4((ga * ua) * rs2 * sg);
;                     if (n == 0) { w.x = pk.x; w.y = pk.y; } else { w.z = pk.x; w.w = pk.y; }
;                 }
;                 *(u32x4*)(O + (size_t)r * DFF + col) = w;
;             }
	v_cvt_pk_bf16_f32 v44, v34, v35
	v_add_u32_e32 v34, 0x90, v156
	v_pk_add_f32 v[40:41], v[40:41], 1.0 op_sel_hi:[1,0]
	v_mad_i64_i32 v[34:35], s[44:45], v34, s60, v[114:115]
	v_rcp_f32_e32 v40, v40
	v_rcp_f32_e32 v41, v41
	v_rcp_f32_e32 v38, v38
	v_rcp_f32_e32 v39, v39
	v_pk_mul_f32 v[30:31], v[24:25], v[36:37] op_sel_hi:[1,0]
	v_lshl_add_u64 v[34:35], v[34:35], 0, v[116:117]
	v_exp_f32_e32 v30, v30
	v_exp_f32_e32 v31, v31
	global_store_dwordx4 v[34:35], v[42:45], off sc1
	v_mul_f32_e32 v34, v158, v158
	v_pk_mul_f32 v[28:29], v[32:33], v[28:29]
	v_pk_mul_f32 v[26:27], v[26:27], v[34:35] op_sel_hi:[1,0]
	v_pk_mul_f32 v[28:29], v[28:29], v[34:35] op_sel_hi:[1,0]
	v_pk_mul_f32 v[26:27], v[26:27], v[40:41]
	v_pk_mul_f32 v[28:29], v[28:29], v[38:39]
	v_cvt_pk_bf16_f32 v26, v26, v27
	v_cvt_pk_bf16_f32 v27, v28, v29
	v_pk_add_f32 v[28:29], v[30:31], 1.0 op_sel_hi:[1,0]
	v_pk_mul_f32 v[32:33], v[22:23], v[36:37] op_sel_hi:[1,0]
	v_rcp_f32_e32 v28, v28
	v_rcp_f32_e32 v29, v29
	v_exp_f32_e32 v32, v32
	v_exp_f32_e32 v33, v33
	v_pk_mul_f32 v[20:21], v[24:25], v[20:21]
	v_pk_mul_f32 v[18:19], v[22:23], v[18:19]
	v_pk_mul_f32 v[20:21], v[20:21], v[34:35] op_sel_hi:[1,0]
	v_pk_add_f32 v[30:31], v[32:33], 1.0 op_sel_hi:[1,0]
	v_pk_mul_f32 v[20:21], v[20:21], v[28:29]
	v_rcp_f32_e32 v30, v30
	v_cvt_pk_bf16_f32 v29, v20, v21
	v_mul_f32_e32 v20, 0xbfb8aa3b, v157
	v_rcp_f32_e32 v31, v31
	v_pk_mul_f32 v[22:23], v[16:17], v[20:21] op_sel_hi:[1,0]
	v_pk_mul_f32 v[24:25], v[14:15], v[20:21] op_sel_hi:[1,0]
	v_exp_f32_e32 v22, v22
	v_exp_f32_e32 v24, v24
	v_exp_f32_e32 v23, v23
	v_exp_f32_e32 v25, v25
	v_pk_mul_f32 v[18:19], v[18:19], v[34:35] op_sel_hi:[1,0]
	v_pk_mul_f32 v[12:13], v[16:17], v[12:13]
	v_pk_mul_f32 v[18:19], v[18:19], v[30:31]
	v_pk_add_f32 v[22:23], v[22:23], 1.0 op_sel_hi:[1,0]
	v_cvt_pk_bf16_f32 v28, v18, v19
	v_add_u32_e32 v18, 0xa0, v156
	v_pk_add_f32 v[24:25], v[24:25], 1.0 op_sel_hi:[1,0]
	v_mad_i64_i32 v[18:19], s[44:45], v18, s60, v[114:115]
	v_rcp_f32_e32 v24, v24
	v_rcp_f32_e32 v25, v25
	v_rcp_f32_e32 v22, v22
	v_rcp_f32_e32 v23, v23
	v_pk_mul_f32 v[10:11], v[14:15], v[10:11]
	v_pk_mul_f32 v[14:15], v[8:9], v[20:21] op_sel_hi:[1,0]
	v_pk_mul_f32 v[16:17], v[6:7], v[20:21] op_sel_hi:[1,0]
	v_lshl_add_u64 v[18:19], v[18:19], 0, v[116:117]
	v_exp_f32_e32 v16, v16
	v_exp_f32_e32 v14, v14
	v_exp_f32_e32 v15, v15
	v_exp_f32_e32 v17, v17
	global_store_dwordx4 v[18:19], v[26:29], off sc1
	v_mul_f32_e32 v18, v157, v157
	v_pk_mul_f32 v[10:11], v[10:11], v[18:19] op_sel_hi:[1,0]
	v_pk_mul_f32 v[12:13], v[12:13], v[18:19] op_sel_hi:[1,0]
	v_pk_mul_f32 v[10:11], v[10:11], v[24:25]
	v_pk_mul_f32 v[12:13], v[12:13], v[22:23]
	v_cvt_pk_bf16_f32 v10, v10, v11
	v_cvt_pk_bf16_f32 v11, v12, v13
	v_pk_add_f32 v[12:13], v[14:15], 1.0 op_sel_hi:[1,0]
	v_pk_add_f32 v[14:15], v[16:17], 1.0 op_sel_hi:[1,0]
	v_rcp_f32_e32 v12, v12
	v_rcp_f32_e32 v14, v14
	v_rcp_f32_e32 v15, v15
	v_rcp_f32_e32 v13, v13
	v_pk_mul_f32 v[2:3], v[6:7], v[2:3]
	v_pk_mul_f32 v[4:5], v[8:9], v[4:5]
	v_pk_mul_f32 v[2:3], v[2:3], v[18:19] op_sel_hi:[1,0]
	v_pk_mul_f32 v[4:5], v[4:5], v[18:19] op_sel_hi:[1,0]
	v_pk_mul_f32 v[2:3], v[2:3], v[14:15]
	v_pk_mul_f32 v[4:5], v[4:5], v[12:13]
	v_cvt_pk_bf16_f32 v12, v2, v3
	v_add_u32_e32 v2, 0xb0, v156
	v_mad_i64_i32 v[2:3], s[44:45], v2, s60, v[114:115]
	v_cvt_pk_bf16_f32 v13, v4, v5
	v_lshl_add_u64 v[2:3], v[2:3], 0, v[116:117]
	s_andn2_b64 vcc, exec, s[2:3]
	s_mov_b64 s[2:3], -1
	global_store_dwordx4 v[2:3], v[10:13], off sc1
	s_cbranch_vccnz .LBB0_880
	s_and_b64 vcc, exec, s[0:1]
	s_cbranch_vccnz .LBB0_879
	s_lshl_b64 s[2:3], s[24:25], 14
	v_lshl_add_u64 v[2:3], v[138:139], 0, s[2:3]
	s_add_i32 s2, 0, 0x20400
	v_lshl_add_u64 v[4:5], v[2:3], 0, s[12:13]
	s_add_i32 m0, s2, s12
	s_barrier
	global_load_lds_dwordx4 v[4:5], off
	v_lshl_add_u64 v[4:5], v[2:3], 0, s[6:7]
	s_add_i32 m0, s2, s6
	s_nop 0
	global_load_lds_dwordx4 v[4:5], off
	v_lshl_add_u64 v[4:5], v[2:3], 0, s[18:19]
	s_add_i32 m0, s2, s18
	v_lshl_add_u64 v[2:3], v[2:3], 0, s[20:21]
	global_load_lds_dwordx4 v[4:5], off
	s_add_i32 m0, s2, s20
	s_nop 0
	global_load_lds_dwordx4 v[2:3], off
	s_branch .LBB0_879

;     __device__ __forceinline__ void operator()(const Acc& acc, const Unit& u, int wr, int wc, int fr, int fq) const {
;         const int col = u.pn * 256 + wc * 32 + fq * 8;
;         const int rb = u.pm * 256 + wr * 64 + fr;
;         const float* bbase = RES_BF16 ? nullptr : (rb < MP ? baseA : baseB) + (size_t)rb * DM + col;
;         const bf16_t* rbase = RES_BF16 ? resb + (size_t)rb * DM + col : nullptr;
;         f32x4 pre[2][2][2]; u32x4 preb[2][2];
; #pragma unroll
;         for (int bj = 0; bj < 2; ++bj) {
;             if constexpr (RES_BF16) preb[0][bj] = *(const u32x4*)(rbase + bj * 128);
;             else { pre[0][bj][0] = *(const f32x4*)(bbase + bj * 128); pre[0][bj][1] = *(const f32x4*)(bbase + bj * 128 + 4); }
;         }
; #pragma unroll
;         for (int i = 0; i < 8; ++i) {
;             const int ai = i >> 2, m = i & 3, cb = i & 1, nb = cb ^ 1;
;             if (i < 7) { const int ai2 = (i + 1) >> 2, m2 = (i + 1) & 3; const size_t ro = (size_t)(ai2 * 128 + m2 * 16) * DM;
; #pragma unroll
;                 for (int bj = 0; bj < 2; ++bj) {
;                     if constexpr (RES_BF16) preb[nb][bj] = *(const u32x4*)(rbase + ro + bj * 128);
;                     else { pre[nb][bj][0] = *(const f32x4*)(bbase + ro + bj * 128); pre[nb][bj][1] = *(const f32x4*)(bbase + ro + bj * 128 + 4); }
;                 }
;             }
;             FENCE();
;             const int r = rb + ai * 128 + m * 16;
;             float q = 0.f;
; #pragma unroll
;             for (int bj = 0; bj < 2; ++bj) {
;                 f32x4 b0, b1;
;                 if constexpr (RES_BF16) { const u32x4 w = preb[cb][bj]; b0 = (f32x4){bflo(w.x), bfhi(w.x), bflo(w.y), bfhi(w.y)}; b1 = (f32x4){bflo(w.z), bfhi(w.z), bflo(w.w), bfhi(w.w)}; }
;                 else { b0 = pre[cb][bj][0]; b1 = pre[cb][bj][1]; }
;                 const f32x4 v0 = b0 + acc[ai][bj][m][0] * scale, v1 = b1 + acc[ai][bj][m][1] * scale;
;                 if constexpr (OUT_F32) { float* op = out + (size_t)r * DM + col + bj * 128; *(f32x4*)op = v0; *(f32x4*)(op + 4) = v1; }
;                 q += (v0[0] * v0[0] + v0[1] * v0[1]) + (v0[2] * v0[2] + v0[3] * v0[3]) + (v1[0] * v1[0] + v1[1] * v1[1]) + (v1[2] * v1[2] + v1[3] * v1[3]);
;                 if (xb) { u32x4 w; w.x = cvtpk(v0[0], v0[1]); w.y = cvtpk(v0[2], v0[3]); w.z = cvtpk(v1[0], v1[1]); w.w = cvtpk(v1[2], v1[3]);
.LBB0_974:
	v_lshl_add_u32 v158, s56, 8, v1
	v_lshl_or_b32 v154, s8, 8, v161
	v_ashrrev_i32_e32 v159, 31, v158
	v_lshlrev_b64 v[166:167], 11, v[158:159]
	v_ashrrev_i32_e32 v155, 31, v154
	v_lshl_add_u64 v[130:131], s[36:37], 0, v[166:167]
	v_lshlrev_b64 v[168:169], 1, v[154:155]
	v_lshl_add_u64 v[156:157], v[130:131], 0, v[168:169]
	global_load_dwordx4 v[172:175], v[156:157], off
	global_load_dwordx4 v[176:179], v[156:157], off offset:256
	v_add_co_u32_e32 v130, vcc, s46, v156
	v_and_b32_e32 v181, 64, v165
	s_nop 0
	v_addc_co_u32_e32 v131, vcc, 0, v157, vcc
	global_load_dwordx4 v[134:137], v[130:131], off
	s_nop 0
	global_load_dwordx4 v[130:133], v[130:131], off offset:256
	v_xor_b32_e32 v180, 16, v165
	v_add_u32_e32 v181, 64, v181
	v_xor_b32_e32 v182, 32, v165
	v_cmp_lt_i32_e32 vcc, v180, v181
	s_lshl_b32 s22, s8, 2
	s_ashr_i32 s23, s22, 31
	v_cndmask_b32_e32 v183, v165, v180, vcc
	v_cmp_lt_i32_e32 vcc, v182, v181
	v_lshl_add_u64 v[180:181], s[34:35], 0, v[166:167]
	v_lshl_add_u64 v[168:169], v[180:181], 0, v[168:169]
	v_cndmask_b32_e32 v188, v165, v182, vcc
	v_lshlrev_b32_e32 v166, 2, v183
	s_waitcnt vmcnt(0)
	v_lshlrev_b32_e32 v180, 16, v172
	v_and_b32_e32 v181, 0xffff0000, v172
	v_lshlrev_b32_e32 v172, 16, v173
	v_and_b32_e32 v173, 0xffff0000, v173
	v_lshlrev_b32_e32 v184, 16, v176
	v_and_b32_e32 v185, 0xffff0000, v176
	v_lshlrev_b32_e32 v176, 16, v177
	v_and_b32_e32 v177, 0xffff0000, v177
	v_lshlrev_b32_e32 v182, 16, v174
	v_and_b32_e32 v183, 0xffff0000, v174
	v_lshlrev_b32_e32 v174, 16, v175
	v_and_b32_e32 v175, 0xffff0000, v175
	v_lshlrev_b32_e32 v186, 16, v178
	v_and_b32_e32 v187, 0xffff0000, v178
	v_lshlrev_b32_e32 v178, 16, v179
	v_and_b32_e32 v179, 0xffff0000, v179
	v_pk_fma_f32 v[128:129], v[128:129], 0.5, v[172:173] op_sel_hi:[1,0,1]
	v_pk_fma_f32 v[126:127], v[126:127], 0.5, v[180:181] op_sel_hi:[1,0,1]
	v_pk_fma_f32 v[120:121], v[120:121], 0.5, v[176:177] op_sel_hi:[1,0,1]
	v_pk_fma_f32 v[118:119], v[118:119], 0.5, v[184:185] op_sel_hi:[1,0,1]
	v_pk_fma_f32 v[124:125], v[124:125], 0.5, v[174:175] op_sel_hi:[1,0,1]
	v_pk_fma_f32 v[122:123], v[122:123], 0.5, v[182:183] op_sel_hi:[1,0,1]
	v_pk_fma_f32 v[172:173], v[116:117], 0.5, v[178:179] op_sel_hi:[1,0,1]
	v_pk_fma_f32 v[174:175], v[114:115], 0.5, v[186:187] op_sel_hi:[1,0,1]
	v_mul_f32_e32 v116, v127, v127
	v_mul_f32_e32 v117, v129, v129
	v_cvt_pk_bf16_f32 v114, v126, v127
	v_cvt_pk_bf16_f32 v115, v128, v129
	v_mul_f32_e32 v127, v119, v119
	v_mul_f32_e32 v129, v121, v121
	v_mul_f32_e32 v167, v123, v123
	v_mul_f32_e32 v177, v175, v175
	v_fmac_f32_e32 v116, v126, v126
	v_fmac_f32_e32 v117, v128, v128
	v_fmac_f32_e32 v127, v118, v118
	v_fmac_f32_e32 v129, v120, v120
	v_mul_f32_e32 v176, v125, v125
	v_mul_f32_e32 v178, v173, v173
	v_fmac_f32_e32 v167, v122, v122
	v_fmac_f32_e32 v177, v174, v174
	v_add_f32_e32 v116, v116, v117
	v_add_f32_e32 v117, v127, v129
	v_fmac_f32_e32 v176, v124, v124
	v_fmac_f32_e32 v178, v172, v172
	v_add_f32_e32 v116, v167, v116
	v_add_f32_e32 v117, v177, v117
	v_add_f32_e32 v116, v176, v116
	v_add_f32_e32 v117, v178, v117
	v_add_f32_e32 v126, v116, v117
	ds_bpermute_b32 v127, v166, v126
	v_cvt_pk_bf16_f32 v116, v122, v123
	v_cvt_pk_bf16_f32 v117, v124, v125
	global_store_dwordx4 v[168:169], v[114:117], off sc1
	v_lshlrev_b32_e32 v124, 2, v188
	v_cvt_pk_bf16_f32 v118, v118, v119
	s_waitcnt lgkmcnt(0)
	v_add_f32_e32 v114, v126, v127
	ds_bpermute_b32 v115, v124, v114
	v_cvt_pk_bf16_f32 v119, v120, v121
	v_cvt_pk_bf16_f32 v120, v174, v175
	v_cvt_pk_bf16_f32 v121, v172, v173
	global_store_dwordx4 v[168:169], v[118:121], off offset:256 sc1
	s_and_saveexec_b64 s[24:25], s[0:1]
	s_cbranch_execz .LBB0_976
	v_lshlrev_b64 v[116:117], 6, v[158:159]
	v_lshl_add_u64 v[116:117], s[74:75], 0, v[116:117]
	v_lshl_add_u64 v[116:117], s[22:23], 2, v[116:117]
	s_lshl_b32 s8, s43, 2
	v_lshl_add_u64 v[116:117], v[116:117], 0, s[8:9]
	s_waitcnt lgkmcnt(0)
	v_add_f32_e32 v114, v114, v115
	global_store_dword v[116:117], v114, off sc1
.LBB0_976:
	s_or_b64 exec, exec, s[24:25]
	v_add_co_u32_e32 v114, vcc, 0x10000, v156
	v_lshlrev_b32_e32 v128, 16, v134
	s_waitcnt lgkmcnt(0)
	v_addc_co_u32_e32 v115, vcc, 0, v157, vcc
	global_load_dwordx4 v[118:121], v[114:115], off
	s_nop 0
	global_load_dwordx4 v[114:117], v[114:115], off offset:256
	v_and_b32_e32 v129, 0xffff0000, v134
	v_lshlrev_b32_e32 v134, 16, v135
	v_and_b32_e32 v135, 0xffff0000, v135
	v_lshlrev_b32_e32 v168, 16, v136
	v_and_b32_e32 v169, 0xffff0000, v136
	v_lshlrev_b32_e32 v136, 16, v137
	v_and_b32_e32 v137, 0xffff0000, v137
	v_pk_fma_f32 v[112:113], v[112:113], 0.5, v[134:135] op_sel_hi:[1,0,1]
	v_pk_fma_f32 v[110:111], v[110:111], 0.5, v[128:129] op_sel_hi:[1,0,1]
	v_pk_fma_f32 v[128:129], v[108:109], 0.5, v[136:137] op_sel_hi:[1,0,1]
	v_pk_fma_f32 v[108:109], v[106:107], 0.5, v[168:169] op_sel_hi:[1,0,1]
	v_mul_f32_e32 v106, v111, v111
	v_mul_f32_e32 v107, v113, v113
	v_fmac_f32_e32 v106, v110, v110
	v_fmac_f32_e32 v107, v112, v112
	v_add_f32_e32 v106, v106, v107
	v_mul_f32_e32 v107, v109, v109
	v_fmac_f32_e32 v107, v108, v108
	v_add_f32_e32 v106, v107, v106
	v_mul_f32_e32 v107, v129, v129
	v_fmac_f32_e32 v107, v128, v128
	v_add_f32_e32 v125, v107, v106
	v_cvt_pk_bf16_f32 v106, v110, v111
	v_cvt_pk_bf16_f32 v107, v112, v113
	v_lshlrev_b32_e32 v110, 16, v130
	v_and_b32_e32 v111, 0xffff0000, v130
	v_lshlrev_b32_e32 v112, 16, v131
	v_and_b32_e32 v113, 0xffff0000, v131
	v_cvt_pk_bf16_f32 v108, v108, v109
	v_cvt_pk_bf16_f32 v109, v128, v129
	v_lshlrev_b32_e32 v128, 16, v132
	v_and_b32_e32 v129, 0xffff0000, v132
	v_pk_fma_f32 v[104:105], v[104:105], 0.5, v[112:113] op_sel_hi:[1,0,1]
	v_pk_fma_f32 v[102:103], v[102:103], 0.5, v[110:111] op_sel_hi:[1,0,1]
	v_pk_fma_f32 v[112:113], v[98:99], 0.5, v[128:129] op_sel_hi:[1,0,1]
	v_mul_f32_e32 v98, v103, v103
	v_mul_f32_e32 v99, v105, v105
	v_fmac_f32_e32 v98, v102, v102
	v_fmac_f32_e32 v99, v104, v104
	v_lshlrev_b32_e32 v130, 16, v133
	v_and_b32_e32 v131, 0xffff0000, v133
	v_add_f32_e32 v98, v98, v99
	v_mul_f32_e32 v99, v113, v113
	v_pk_fma_f32 v[110:111], v[100:101], 0.5, v[130:131] op_sel_hi:[1,0,1]
	v_fmac_f32_e32 v99, v112, v112
	v_add_f32_e32 v98, v99, v98
	v_mul_f32_e32 v99, v111, v111
	v_fmac_f32_e32 v99, v110, v110
	v_add_f32_e32 v98, v99, v98
	v_add_f32_e32 v101, v125, v98
	ds_bpermute_b32 v125, v166, v101
	v_or_b32_e32 v122, 16, v158
	v_ashrrev_i32_e32 v123, 31, v122
	v_lshlrev_b64 v[126:127], 11, v[122:123]
	v_lshl_add_u64 v[98:99], s[34:35], 0, v[126:127]
	v_lshl_add_u64 v[126:127], v[154:155], 1, v[98:99]
	s_waitcnt lgkmcnt(0)
	v_add_f32_e32 v98, v101, v125
	ds_bpermute_b32 v99, v124, v98
	v_cvt_pk_bf16_f32 v100, v102, v103
	v_cvt_pk_bf16_f32 v101, v104, v105
	v_cvt_pk_bf16_f32 v102, v112, v113
	v_cvt_pk_bf16_f32 v103, v110, v111
	global_store_dwordx4 v[126:127], v[106:109], off sc1
	global_store_dwordx4 v[126:127], v[100:103], off offset:256 sc1
	s_and_saveexec_b64 s[24:25], s[0:1]
	s_cbranch_execz .LBB0_978
; __device__ __forceinline__ float bflo(unsigned w) { return __uint_as_float(w << 16); }
; #define FENCE() asm volatile("" ::: "memory")
;     __device__ __forceinline__ void operator()(const Acc& acc, const Unit& u, int wr, int wc, int fr, int fq) const {
;     ...
;         for (int bj = 0; bj < 2; ++bj) {
;             if constexpr (RES_BF16) preb[0][bj] = *(const u32x4*)(rbase + bj * 128);
;             else { pre[0][bj][0] = *(const f32x4*)(bbase + bj * 128); pre[0][bj][1] = *(const f32x4*)(bbase + bj * 128 + 4); }
;         }
; #pragma unroll
;         for (int i = 0; i < 8; ++i) {
;             const int ai = i >> 2, m = i & 3, cb = i & 1, nb = cb ^ 1;
;             if (i < 7) { const int ai2 = (i + 1) >> 2, m2 = (i + 1) & 3; const size_t ro = (size_t)(ai2 * 128 + m2 * 16) * DM;
; #pragma unroll
;                 for (int bj = 0; bj < 2; ++bj) {
;                     if constexpr (RES_BF16) preb[nb][bj] = *(const u32x4*)(rbase + ro + bj * 128);
;                     else { pre[nb][bj][0] = *(const f32x4*)(bbase + ro + bj * 128); pre[nb][bj][1] = *(const f32x4*)(bbase + ro + bj * 128 + 4); }
;                 }
;             }
;             FENCE();
;             const int r = rb + ai * 128 + m * 16;
;             float q = 0.f;
; #pragma unroll
;             for (int bj = 0; bj < 2; ++bj) {
;                 f32x4 b0, b1;
;                 if constexpr (RES_BF16) { const u32x4 w = preb[cb][bj]; b0 = (f32x4){bflo(w.x), bfhi(w.x), bflo(w.y), bfhi(w.y)}; b1 = (f32x4){bflo(w.z), bfhi(w.z), bflo(w.w), bfhi(w.w)}; }
;                 else { b0 = pre[cb][bj][0]; b1 = pre[cb][bj][1]; }
;                 const f32x4 v0 = b0 + acc[ai][bj][m][0] * scale, v1 = b1 + acc[ai][bj][m][1] * scale;
;                 if constexpr (OUT_F32) { float* op = out + (size_t)r * DM + col + bj * 128; *(f32x4*)op = v0; *(f32x4*)(op + 4) = v1; }
;                 q += (v0[0] * v0[0] + v0[1] * v0[1]) + (v0[2] * v0[2] + v0[3] * v0[3]) + (v1[0] * v1[0] + v1[1] * v1[1]) + (v1[2] * v1[2] + v1[3] * v1[3]);
;                 if (xb) { u32x4 w; w.x = cvtpk(v0[0], v0[1]); w.y = cvtpk(v0[2], v0[3]); w.z = cvtpk(v1[0], v1[1]); w.w = cvtpk(v1[2], v1[3]);
;                     *(u32x4*)(xb + (size_t)r * DM + col + bj * 128) = w; }
;             }
;             q += __shfl_xor(q, 16); q += __shfl_xor(q, 32);
;             if (fq == 0) st[(size_t)r * 16 + u.pn * 4 + wc] = q;
	v_lshlrev_b64 v[100:101], 6, v[122:123]
	v_lshl_add_u64 v[100:101], s[74:75], 0, v[100:101]
	v_lshl_add_u64 v[100:101], s[22:23], 2, v[100:101]
	s_lshl_b32 s8, s43, 2
	v_lshl_add_u64 v[100:101], v[100:101], 0, s[8:9]
	s_waitcnt lgkmcnt(0)
	v_add_f32_e32 v98, v98, v99
	global_store_dword v[100:101], v98, off sc1
.LBB0_978:
	s_or_b64 exec, exec, s[24:25]
	v_add_co_u32_e32 v98, vcc, 0x18000, v156
	s_waitcnt vmcnt(3)
	v_lshlrev_b32_e32 v110, 16, v118
	s_waitcnt lgkmcnt(0)
	v_addc_co_u32_e32 v99, vcc, 0, v157, vcc
	global_load_dwordx4 v[102:105], v[98:99], off
	s_nop 0
	global_load_dwordx4 v[98:101], v[98:99], off offset:256
	v_and_b32_e32 v111, 0xffff0000, v118
	v_lshlrev_b32_e32 v112, 16, v119
	v_and_b32_e32 v113, 0xffff0000, v119
	v_lshlrev_b32_e32 v118, 16, v120
	v_and_b32_e32 v119, 0xffff0000, v120
	v_lshlrev_b32_e32 v120, 16, v121
	v_and_b32_e32 v121, 0xffff0000, v121
	v_pk_fma_f32 v[96:97], v[96:97], 0.5, v[112:113] op_sel_hi:[1,0,1]
	v_pk_fma_f32 v[94:95], v[94:95], 0.5, v[110:111] op_sel_hi:[1,0,1]
	v_pk_fma_f32 v[110:111], v[92:93], 0.5, v[120:121] op_sel_hi:[1,0,1]
	v_pk_fma_f32 v[92:93], v[90:91], 0.5, v[118:119] op_sel_hi:[1,0,1]
	v_mul_f32_e32 v90, v95, v95
	v_mul_f32_e32 v91, v97, v97
	v_fmac_f32_e32 v90, v94, v94
	v_fmac_f32_e32 v91, v96, v96
	v_add_f32_e32 v90, v90, v91
	v_mul_f32_e32 v91, v93, v93
	v_fmac_f32_e32 v91, v92, v92
	v_add_f32_e32 v90, v91, v90
	v_mul_f32_e32 v91, v111, v111
	v_fmac_f32_e32 v91, v110, v110
	v_add_f32_e32 v118, v91, v90
	v_cvt_pk_bf16_f32 v90, v94, v95
	v_cvt_pk_bf16_f32 v91, v96, v97
	s_waitcnt vmcnt(4)
	v_lshlrev_b32_e32 v94, 16, v114
	v_and_b32_e32 v95, 0xffff0000, v114
	v_lshlrev_b32_e32 v96, 16, v115
	v_and_b32_e32 v97, 0xffff0000, v115
	v_cvt_pk_bf16_f32 v92, v92, v93
	v_cvt_pk_bf16_f32 v93, v110, v111
	v_lshlrev_b32_e32 v110, 16, v116
	v_and_b32_e32 v111, 0xffff0000, v116
	v_pk_fma_f32 v[88:89], v[88:89], 0.5, v[96:97] op_sel_hi:[1,0,1]
	v_pk_fma_f32 v[86:87], v[86:87], 0.5, v[94:95] op_sel_hi:[1,0,1]
	v_pk_fma_f32 v[96:97], v[82:83], 0.5, v[110:111] op_sel_hi:[1,0,1]
	v_mul_f32_e32 v82, v87, v87
	v_mul_f32_e32 v83, v89, v89
	v_fmac_f32_e32 v82, v86, v86
	v_fmac_f32_e32 v83, v88, v88
	v_lshlrev_b32_e32 v112, 16, v117
	v_and_b32_e32 v113, 0xffff0000, v117
	v_add_f32_e32 v82, v82, v83
	v_mul_f32_e32 v83, v97, v97
	v_pk_fma_f32 v[94:95], v[84:85], 0.5, v[112:113] op_sel_hi:[1,0,1]
	v_fmac_f32_e32 v83, v96, v96
	v_add_f32_e32 v82, v83, v82
	v_mul_f32_e32 v83, v95, v95
	v_fmac_f32_e32 v83, v94, v94
	v_add_f32_e32 v82, v83, v82
	v_add_f32_e32 v85, v118, v82
	ds_bpermute_b32 v110, v166, v85
	v_or_b32_e32 v106, 32, v158
	v_ashrrev_i32_e32 v107, 31, v106
	v_lshlrev_b64 v[108:109], 11, v[106:107]
	v_lshl_add_u64 v[82:83], s[34:35], 0, v[108:109]
	v_lshl_add_u64 v[108:109], v[154:155], 1, v[82:83]
	s_waitcnt lgkmcnt(0)
	v_add_f32_e32 v82, v85, v110
	ds_bpermute_b32 v83, v124, v82
	v_cvt_pk_bf16_f32 v84, v86, v87
	v_cvt_pk_bf16_f32 v85, v88, v89
	v_cvt_pk_bf16_f32 v86, v96, v97
	v_cvt_pk_bf16_f32 v87, v94, v95
	global_store_dwordx4 v[108:109], v[90:93], off sc1
	global_store_dwordx4 v[108:109], v[84:87], off offset:256 sc1
	s_and_saveexec_b64 s[24:25], s[0:1]
	s_cbranch_execz .LBB0_980
	v_lshlrev_b64 v[84:85], 6, v[106:107]
	v_lshl_add_u64 v[84:85], s[74:75], 0, v[84:85]
	v_lshl_add_u64 v[84:85], s[22:23], 2, v[84:85]
	s_lshl_b32 s8, s43, 2
	v_lshl_add_u64 v[84:85], v[84:85], 0, s[8:9]
	s_waitcnt lgkmcnt(0)
	v_add_f32_e32 v82, v82, v83
	global_store_dword v[84:85], v82, off sc1
.LBB0_980:
	s_or_b64 exec, exec, s[24:25]
	v_add_co_u32_e32 v82, vcc, 0x40000, v156
	s_waitcnt vmcnt(3)
	v_lshlrev_b32_e32 v94, 16, v102
	s_waitcnt lgkmcnt(0)
	v_addc_co_u32_e32 v83, vcc, 0, v157, vcc
	global_load_dwordx4 v[86:89], v[82:83], off
	s_nop 0
	global_load_dwordx4 v[82:85], v[82:83], off offset:256
	v_and_b32_e32 v95, 0xffff0000, v102
	v_lshlrev_b32_e32 v96, 16, v103
	v_and_b32_e32 v97, 0xffff0000, v103
	v_lshlrev_b32_e32 v102, 16, v104
	v_and_b32_e32 v103, 0xffff0000, v104
	v_lshlrev_b32_e32 v104, 16, v105
	v_and_b32_e32 v105, 0xffff0000, v105
	v_pk_fma_f32 v[80:81], v[80:81], 0.5, v[96:97] op_sel_hi:[1,0,1]
	v_pk_fma_f32 v[78:79], v[78:79], 0.5, v[94:95] op_sel_hi:[1,0,1]
	v_pk_fma_f32 v[94:95], v[76:77], 0.5, v[104:105] op_sel_hi:[1,0,1]
	v_pk_fma_f32 v[76:77], v[74:75], 0.5, v[102:103] op_sel_hi:[1,0,1]
	v_mul_f32_e32 v74, v79, v79
	v_mul_f32_e32 v75, v81, v81
	v_fmac_f32_e32 v74, v78, v78
	v_fmac_f32_e32 v75, v80, v80
	v_add_f32_e32 v74, v74, v75
	v_mul_f32_e32 v75, v77, v77
	v_fmac_f32_e32 v75, v76, v76
	v_add_f32_e32 v74, v75, v74
	v_mul_f32_e32 v75, v95, v95
	v_fmac_f32_e32 v75, v94, v94
	v_add_f32_e32 v102, v75, v74
	v_cvt_pk_bf16_f32 v74, v78, v79
	v_cvt_pk_bf16_f32 v75, v80, v81
	s_waitcnt vmcnt(4)
	v_lshlrev_b32_e32 v78, 16, v98
	v_and_b32_e32 v79, 0xffff0000, v98
	v_lshlrev_b32_e32 v80, 16, v99
	v_and_b32_e32 v81, 0xffff0000, v99
	v_cvt_pk_bf16_f32 v76, v76, v77
	v_cvt_pk_bf16_f32 v77, v94, v95
	v_lshlrev_b32_e32 v94, 16, v100
	v_and_b32_e32 v95, 0xffff0000, v100
	v_pk_fma_f32 v[72:73], v[72:73], 0.5, v[80:81] op_sel_hi:[1,0,1]
	v_pk_fma_f32 v[70:71], v[70:71], 0.5, v[78:79] op_sel_hi:[1,0,1]
	v_pk_fma_f32 v[80:81], v[66:67], 0.5, v[94:95] op_sel_hi:[1,0,1]
	v_mul_f32_e32 v66, v71, v71
	v_mul_f32_e32 v67, v73, v73
	v_fmac_f32_e32 v66, v70, v70
	v_fmac_f32_e32 v67, v72, v72
	v_lshlrev_b32_e32 v96, 16, v101
	v_and_b32_e32 v97, 0xffff0000, v101
	v_add_f32_e32 v66, v66, v67
	v_mul_f32_e32 v67, v81, v81
	v_pk_fma_f32 v[78:79], v[68:69], 0.5, v[96:97] op_sel_hi:[1,0,1]
	v_fmac_f32_e32 v67, v80, v80
	v_add_f32_e32 v66, v67, v66
	v_mul_f32_e32 v67, v79, v79
	v_fmac_f32_e32 v67, v78, v78
	v_add_f32_e32 v66, v67, v66
	v_add_f32_e32 v69, v102, v66
	ds_bpermute_b32 v94, v166, v69
	v_or_b32_e32 v90, 48, v158
	v_ashrrev_i32_e32 v91, 31, v90
	v_lshlrev_b64 v[92:93], 11, v[90:91]
	v_lshl_add_u64 v[66:67], s[34:35], 0, v[92:93]
	v_lshl_add_u64 v[92:93], v[154:155], 1, v[66:67]
	s_waitcnt lgkmcnt(0)
	v_add_f32_e32 v66, v69, v94
	ds_bpermute_b32 v67, v124, v66
	v_cvt_pk_bf16_f32 v68, v70, v71
	v_cvt_pk_bf16_f32 v69, v72, v73
	v_cvt_pk_bf16_f32 v70, v80, v81
	v_cvt_pk_bf16_f32 v71, v78, v79
	global_store_dwordx4 v[92:93], v[74:77], off sc1
	global_store_dwordx4 v[92:93], v[68:71], off offset:256 sc1
	s_and_saveexec_b64 s[24:25], s[0:1]
	s_cbranch_execz .LBB0_982
	v_lshlrev_b64 v[68:69], 6, v[90:91]
	v_lshl_add_u64 v[68:69], s[74:75], 0, v[68:69]
	v_lshl_add_u64 v[68:69], s[22:23], 2, v[68:69]
	s_lshl_b32 s8, s43, 2
	v_lshl_add_u64 v[68:69], v[68:69], 0, s[8:9]
	s_waitcnt lgkmcnt(0)
	v_add_f32_e32 v66, v66, v67
	global_store_dword v[68:69], v66, off sc1
; __device__ __forceinline__ float bflo(unsigned w) { return __uint_as_float(w << 16); }
; #define FENCE() asm volatile("" ::: "memory")
;     __device__ __forceinline__ void operator()(const Acc& acc, const Unit& u, int wr, int wc, int fr, int fq) const {
;     ...
;         for (int bj = 0; bj < 2; ++bj) {
;             if constexpr (RES_BF16) preb[0][bj] = *(const u32x4*)(rbase + bj * 128);
;             else { pre[0][bj][0] = *(const f32x4*)(bbase + bj * 128); pre[0][bj][1] = *(const f32x4*)(bbase + bj * 128 + 4); }
;         }
; #pragma unroll
;         for (int i = 0; i < 8; ++i) {
;             const int ai = i >> 2, m = i & 3, cb = i & 1, nb = cb ^ 1;
;             if (i < 7) { const int ai2 = (i + 1) >> 2, m2 = (i + 1) & 3; const size_t ro = (size_t)(ai2 * 128 + m2 * 16) * DM;
; #pragma unroll
;                 for (int bj = 0; bj < 2; ++bj) {
;                     if constexpr (RES_BF16) preb[nb][bj] = *(const u32x4*)(rbase + ro + bj * 128);
;                     else { pre[nb][bj][0] = *(const f32x4*)(bbase + ro + bj * 128); pre[nb][bj][1] = *(const f32x4*)(bbase + ro + bj * 128 + 4); }
;                 }
;             }
;             FENCE();
;             const int r = rb + ai * 128 + m * 16;
;             float q = 0.f;
; #pragma unroll
;             for (int bj = 0; bj < 2; ++bj) {
;                 f32x4 b0, b1;
;                 if constexpr (RES_BF16) { const u32x4 w = preb[cb][bj]; b0 = (f32x4){bflo(w.x), bfhi(w.x), bflo(w.y), bfhi(w.y)}; b1 = (f32x4){bflo(w.z), bfhi(w.z), bflo(w.w), bfhi(w.w)}; }
;                 else { b0 = pre[cb][bj][0]; b1 = pre[cb][bj][1]; }
;                 const f32x4 v0 = b0 + acc[ai][bj][m][0] * scale, v1 = b1 + acc[ai][bj][m][1] * scale;
;                 if constexpr (OUT_F32) { float* op = out + (size_t)r * DM + col + bj * 128; *(f32x4*)op = v0; *(f32x4*)(op + 4) = v1; }
;                 q += (v0[0] * v0[0] + v0[1] * v0[1]) + (v0[2] * v0[2] + v0[3] * v0[3]) + (v1[0] * v1[0] + v1[1] * v1[1]) + (v1[2] * v1[2] + v1[3] * v1[3]);
;                 if (xb) { u32x4 w; w.x = cvtpk(v0[0], v0[1]); w.y = cvtpk(v0[2], v0[3]); w.z = cvtpk(v1[0], v1[1]); w.w = cvtpk(v1[2], v1[3]);
;                     *(u32x4*)(xb + (size_t)r * DM + col + bj * 128) = w; }
;             }
;             q += __shfl_xor(q, 16); q += __shfl_xor(q, 32);
;             if (fq == 0) st[(size_t)r * 16 + u.pn * 4 + wc] = q;
.LBB0_982:
	s_or_b64 exec, exec, s[24:25]
	v_add_co_u32_e32 v66, vcc, 0x48000, v156
	s_waitcnt vmcnt(3)
	v_lshlrev_b32_e32 v78, 16, v86
	s_waitcnt lgkmcnt(0)
	v_addc_co_u32_e32 v67, vcc, 0, v157, vcc
	global_load_dwordx4 v[70:73], v[66:67], off
	s_nop 0
	global_load_dwordx4 v[66:69], v[66:67], off offset:256
	v_and_b32_e32 v79, 0xffff0000, v86
	v_lshlrev_b32_e32 v80, 16, v87
	v_and_b32_e32 v81, 0xffff0000, v87
	v_lshlrev_b32_e32 v86, 16, v88
	v_and_b32_e32 v87, 0xffff0000, v88
	v_lshlrev_b32_e32 v88, 16, v89
	v_and_b32_e32 v89, 0xffff0000, v89
	v_pk_fma_f32 v[64:65], v[64:65], 0.5, v[80:81] op_sel_hi:[1,0,1]
	v_pk_fma_f32 v[62:63], v[62:63], 0.5, v[78:79] op_sel_hi:[1,0,1]
	v_pk_fma_f32 v[78:79], v[60:61], 0.5, v[88:89] op_sel_hi:[1,0,1]
	v_pk_fma_f32 v[60:61], v[58:59], 0.5, v[86:87] op_sel_hi:[1,0,1]
	v_mul_f32_e32 v58, v63, v63
	v_mul_f32_e32 v59, v65, v65
	v_fmac_f32_e32 v58, v62, v62
	v_fmac_f32_e32 v59, v64, v64
	v_add_f32_e32 v58, v58, v59
	v_mul_f32_e32 v59, v61, v61
	v_fmac_f32_e32 v59, v60, v60
	v_add_f32_e32 v58, v59, v58
	v_mul_f32_e32 v59, v79, v79
	v_fmac_f32_e32 v59, v78, v78
	v_add_f32_e32 v86, v59, v58
	v_cvt_pk_bf16_f32 v58, v62, v63
	v_cvt_pk_bf16_f32 v59, v64, v65
	s_waitcnt vmcnt(4)
	v_lshlrev_b32_e32 v62, 16, v82
	v_and_b32_e32 v63, 0xffff0000, v82
	v_lshlrev_b32_e32 v64, 16, v83
	v_and_b32_e32 v65, 0xffff0000, v83
	v_cvt_pk_bf16_f32 v60, v60, v61
	v_cvt_pk_bf16_f32 v61, v78, v79
	v_lshlrev_b32_e32 v78, 16, v84
	v_and_b32_e32 v79, 0xffff0000, v84
	v_pk_fma_f32 v[56:57], v[56:57], 0.5, v[64:65] op_sel_hi:[1,0,1]
	v_pk_fma_f32 v[54:55], v[54:55], 0.5, v[62:63] op_sel_hi:[1,0,1]
	v_pk_fma_f32 v[64:65], v[50:51], 0.5, v[78:79] op_sel_hi:[1,0,1]
	v_mul_f32_e32 v50, v55, v55
	v_mul_f32_e32 v51, v57, v57
	v_fmac_f32_e32 v50, v54, v54
	v_fmac_f32_e32 v51, v56, v56
	v_lshlrev_b32_e32 v80, 16, v85
	v_and_b32_e32 v81, 0xffff0000, v85
	v_add_f32_e32 v50, v50, v51
	v_mul_f32_e32 v51, v65, v65
	v_pk_fma_f32 v[62:63], v[52:53], 0.5, v[80:81] op_sel_hi:[1,0,1]
	v_fmac_f32_e32 v51, v64, v64
	v_add_f32_e32 v50, v51, v50
	v_mul_f32_e32 v51, v63, v63
	v_fmac_f32_e32 v51, v62, v62
	v_add_f32_e32 v50, v51, v50
	v_add_f32_e32 v53, v86, v50
	ds_bpermute_b32 v78, v166, v53
	v_add_u32_e32 v74, 0x80, v158
	v_ashrrev_i32_e32 v75, 31, v74
	v_lshlrev_b64 v[76:77], 11, v[74:75]
	v_lshl_add_u64 v[50:51], s[34:35], 0, v[76:77]
	v_lshl_add_u64 v[76:77], v[154:155], 1, v[50:51]
	s_waitcnt lgkmcnt(0)
	v_add_f32_e32 v50, v53, v78
	ds_bpermute_b32 v51, v124, v50
	v_cvt_pk_bf16_f32 v52, v54, v55
	v_cvt_pk_bf16_f32 v53, v56, v57
	v_cvt_pk_bf16_f32 v54, v64, v65
	v_cvt_pk_bf16_f32 v55, v62, v63
	global_store_dwordx4 v[76:77], v[58:61], off sc1
	global_store_dwordx4 v[76:77], v[52:55], off offset:256 sc1
	s_and_saveexec_b64 s[24:25], s[0:1]
	s_cbranch_execz .LBB0_984
	v_lshlrev_b64 v[52:53], 6, v[74:75]
	v_lshl_add_u64 v[52:53], s[74:75], 0, v[52:53]
	v_lshl_add_u64 v[52:53], s[22:23], 2, v[52:53]
	s_lshl_b32 s8, s43, 2
	v_lshl_add_u64 v[52:53], v[52:53], 0, s[8:9]
	s_waitcnt lgkmcnt(0)
	v_add_f32_e32 v50, v50, v51
	global_store_dword v[52:53], v50, off sc1
.LBB0_984:
	s_or_b64 exec, exec, s[24:25]
	v_add_co_u32_e32 v50, vcc, 0x50000, v156
	s_waitcnt vmcnt(3)
	v_lshlrev_b32_e32 v62, 16, v70
	s_waitcnt lgkmcnt(0)
	v_addc_co_u32_e32 v51, vcc, 0, v157, vcc
	global_load_dwordx4 v[54:57], v[50:51], off
	s_nop 0
	global_load_dwordx4 v[50:53], v[50:51], off offset:256
	v_and_b32_e32 v63, 0xffff0000, v70
	v_lshlrev_b32_e32 v64, 16, v71
	v_and_b32_e32 v65, 0xffff0000, v71
	v_lshlrev_b32_e32 v70, 16, v72
	v_and_b32_e32 v71, 0xffff0000, v72
	v_lshlrev_b32_e32 v72, 16, v73
	v_and_b32_e32 v73, 0xffff0000, v73
	v_pk_fma_f32 v[48:49], v[48:49], 0.5, v[64:65] op_sel_hi:[1,0,1]
	v_pk_fma_f32 v[46:47], v[46:47], 0.5, v[62:63] op_sel_hi:[1,0,1]
	v_pk_fma_f32 v[62:63], v[44:45], 0.5, v[72:73] op_sel_hi:[1,0,1]
	v_pk_fma_f32 v[44:45], v[42:43], 0.5, v[70:71] op_sel_hi:[1,0,1]
	v_mul_f32_e32 v42, v47, v47
	v_mul_f32_e32 v43, v49, v49
	v_fmac_f32_e32 v42, v46, v46
	v_fmac_f32_e32 v43, v48, v48
	v_add_f32_e32 v42, v42, v43
	v_mul_f32_e32 v43, v45, v45
	v_fmac_f32_e32 v43, v44, v44
	v_add_f32_e32 v42, v43, v42
	v_mul_f32_e32 v43, v63, v63
	v_fmac_f32_e32 v43, v62, v62
	v_add_f32_e32 v70, v43, v42
	v_cvt_pk_bf16_f32 v42, v46, v47
	v_cvt_pk_bf16_f32 v43, v48, v49
	s_waitcnt vmcnt(4)
	v_lshlrev_b32_e32 v46, 16, v66
	v_and_b32_e32 v47, 0xffff0000, v66
	v_lshlrev_b32_e32 v48, 16, v67
	v_and_b32_e32 v49, 0xffff0000, v67
	v_cvt_pk_bf16_f32 v44, v44, v45
	v_cvt_pk_bf16_f32 v45, v62, v63
	v_lshlrev_b32_e32 v62, 16, v68
	v_and_b32_e32 v63, 0xffff0000, v68
	v_pk_fma_f32 v[40:41], v[40:41], 0.5, v[48:49] op_sel_hi:[1,0,1]
	v_pk_fma_f32 v[38:39], v[38:39], 0.5, v[46:47] op_sel_hi:[1,0,1]
	v_pk_fma_f32 v[48:49], v[34:35], 0.5, v[62:63] op_sel_hi:[1,0,1]
	v_mul_f32_e32 v34, v39, v39
	v_mul_f32_e32 v35, v41, v41
	v_fmac_f32_e32 v34, v38, v38
	v_fmac_f32_e32 v35, v40, v40
	v_lshlrev_b32_e32 v64, 16, v69
	v_and_b32_e32 v65, 0xffff0000, v69
	v_add_f32_e32 v34, v34, v35
	v_mul_f32_e32 v35, v49, v49
	v_pk_fma_f32 v[46:47], v[36:37], 0.5, v[64:65] op_sel_hi:[1,0,1]
	v_fmac_f32_e32 v35, v48, v48
	v_add_f32_e32 v34, v35, v34
	v_mul_f32_e32 v35, v47, v47
	v_fmac_f32_e32 v35, v46, v46
	v_add_f32_e32 v34, v35, v34
	v_add_f32_e32 v37, v70, v34
	ds_bpermute_b32 v62, v166, v37
	v_or_b32_e32 v58, 16, v74
	v_ashrrev_i32_e32 v59, 31, v58
	v_lshlrev_b64 v[60:61], 11, v[58:59]
	v_lshl_add_u64 v[34:35], s[34:35], 0, v[60:61]
	v_lshl_add_u64 v[60:61], v[154:155], 1, v[34:35]
	s_waitcnt lgkmcnt(0)
	v_add_f32_e32 v34, v37, v62
	ds_bpermute_b32 v35, v124, v34
	v_cvt_pk_bf16_f32 v36, v38, v39
	v_cvt_pk_bf16_f32 v37, v40, v41
	v_cvt_pk_bf16_f32 v38, v48, v49
	v_cvt_pk_bf16_f32 v39, v46, v47
	global_store_dwordx4 v[60:61], v[42:45], off sc1
	global_store_dwordx4 v[60:61], v[36:39], off offset:256 sc1
	s_and_saveexec_b64 s[24:25], s[0:1]
	s_cbranch_execz .LBB0_986
	v_lshlrev_b64 v[36:37], 6, v[58:59]
	v_lshl_add_u64 v[36:37], s[74:75], 0, v[36:37]
	v_lshl_add_u64 v[36:37], s[22:23], 2, v[36:37]
	s_lshl_b32 s8, s43, 2
	v_lshl_add_u64 v[36:37], v[36:37], 0, s[8:9]
	s_waitcnt lgkmcnt(0)
	v_add_f32_e32 v34, v34, v35
	global_store_dword v[36:37], v34, off sc1
; __device__ __forceinline__ float bflo(unsigned w) { return __uint_as_float(w << 16); }
; #define FENCE() asm volatile("" ::: "memory")
;     __device__ __forceinline__ void operator()(const Acc& acc, const Unit& u, int wr, int wc, int fr, int fq) const {
;     ...
;         for (int bj = 0; bj < 2; ++bj) {
;             if constexpr (RES_BF16) preb[0][bj] = *(const u32x4*)(rbase + bj * 128);
;             else { pre[0][bj][0] = *(const f32x4*)(bbase + bj * 128); pre[0][bj][1] = *(const f32x4*)(bbase + bj * 128 + 4); }
;         }
; #pragma unroll
;         for (int i = 0; i < 8; ++i) {
;             const int ai = i >> 2, m = i & 3, cb = i & 1, nb = cb ^ 1;
;             if (i < 7) { const int ai2 = (i + 1) >> 2, m2 = (i + 1) & 3; const size_t ro = (size_t)(ai2 * 128 + m2 * 16) * DM;
; #pragma unroll
;                 for (int bj = 0; bj < 2; ++bj) {
;                     if constexpr (RES_BF16) preb[nb][bj] = *(const u32x4*)(rbase + ro + bj * 128);
;                     else { pre[nb][bj][0] = *(const f32x4*)(bbase + ro + bj * 128); pre[nb][bj][1] = *(const f32x4*)(bbase + ro + bj * 128 + 4); }
;                 }
;             }
;             FENCE();
;             const int r = rb + ai * 128 + m * 16;
;             float q = 0.f;
; #pragma unroll
;             for (int bj = 0; bj < 2; ++bj) {
;                 f32x4 b0, b1;
;                 if constexpr (RES_BF16) { const u32x4 w = preb[cb][bj]; b0 = (f32x4){bflo(w.x), bfhi(w.x), bflo(w.y), bfhi(w.y)}; b1 = (f32x4){bflo(w.z), bfhi(w.z), bflo(w.w), bfhi(w.w)}; }
;                 else { b0 = pre[cb][bj][0]; b1 = pre[cb][bj][1]; }
;                 const f32x4 v0 = b0 + acc[ai][bj][m][0] * scale, v1 = b1 + acc[ai][bj][m][1] * scale;
;                 if constexpr (OUT_F32) { float* op = out + (size_t)r * DM + col + bj * 128; *(f32x4*)op = v0; *(f32x4*)(op + 4) = v1; }
;                 q += (v0[0] * v0[0] + v0[1] * v0[1]) + (v0[2] * v0[2] + v0[3] * v0[3]) + (v1[0] * v1[0] + v1[1] * v1[1]) + (v1[2] * v1[2] + v1[3] * v1[3]);
;                 if (xb) { u32x4 w; w.x = cvtpk(v0[0], v0[1]); w.y = cvtpk(v0[2], v0[3]); w.z = cvtpk(v1[0], v1[1]); w.w = cvtpk(v1[2], v1[3]);
;                     *(u32x4*)(xb + (size_t)r * DM + col + bj * 128) = w; }
;             }
;             q += __shfl_xor(q, 16); q += __shfl_xor(q, 32);
;             if (fq == 0) st[(size_t)r * 16 + u.pn * 4 + wc] = q;
.LBB0_986:
	s_or_b64 exec, exec, s[24:25]
	v_add_co_u32_e32 v34, vcc, 0x58000, v156
	s_waitcnt vmcnt(3)
	v_lshlrev_b32_e32 v46, 16, v54
	s_waitcnt lgkmcnt(0)
	v_addc_co_u32_e32 v35, vcc, 0, v157, vcc
	global_load_dwordx4 v[38:41], v[34:35], off
	s_nop 0
	global_load_dwordx4 v[34:37], v[34:35], off offset:256
	v_and_b32_e32 v47, 0xffff0000, v54
	v_lshlrev_b32_e32 v48, 16, v55
	v_and_b32_e32 v49, 0xffff0000, v55
	v_lshlrev_b32_e32 v54, 16, v56
	v_and_b32_e32 v55, 0xffff0000, v56
	v_lshlrev_b32_e32 v56, 16, v57
	v_and_b32_e32 v57, 0xffff0000, v57
	v_pk_fma_f32 v[32:33], v[32:33], 0.5, v[48:49] op_sel_hi:[1,0,1]
	v_pk_fma_f32 v[30:31], v[30:31], 0.5, v[46:47] op_sel_hi:[1,0,1]
	v_pk_fma_f32 v[46:47], v[28:29], 0.5, v[56:57] op_sel_hi:[1,0,1]
	v_pk_fma_f32 v[28:29], v[26:27], 0.5, v[54:55] op_sel_hi:[1,0,1]
	v_mul_f32_e32 v26, v31, v31
	v_mul_f32_e32 v27, v33, v33
	v_fmac_f32_e32 v26, v30, v30
	v_fmac_f32_e32 v27, v32, v32
	v_add_f32_e32 v26, v26, v27
	v_mul_f32_e32 v27, v29, v29
	v_fmac_f32_e32 v27, v28, v28
	v_add_f32_e32 v26, v27, v26
	v_mul_f32_e32 v27, v47, v47
	v_fmac_f32_e32 v27, v46, v46
	v_add_f32_e32 v54, v27, v26
	v_cvt_pk_bf16_f32 v26, v30, v31
	v_cvt_pk_bf16_f32 v27, v32, v33
	s_waitcnt vmcnt(4)
	v_lshlrev_b32_e32 v30, 16, v50
	v_and_b32_e32 v31, 0xffff0000, v50
	v_lshlrev_b32_e32 v32, 16, v51
	v_and_b32_e32 v33, 0xffff0000, v51
	v_cvt_pk_bf16_f32 v28, v28, v29
	v_cvt_pk_bf16_f32 v29, v46, v47
	v_lshlrev_b32_e32 v46, 16, v52
	v_and_b32_e32 v47, 0xffff0000, v52
	v_pk_fma_f32 v[24:25], v[24:25], 0.5, v[32:33] op_sel_hi:[1,0,1]
	v_pk_fma_f32 v[22:23], v[22:23], 0.5, v[30:31] op_sel_hi:[1,0,1]
	v_pk_fma_f32 v[32:33], v[18:19], 0.5, v[46:47] op_sel_hi:[1,0,1]
	v_mul_f32_e32 v18, v23, v23
	v_mul_f32_e32 v19, v25, v25
	v_fmac_f32_e32 v18, v22, v22
	v_fmac_f32_e32 v19, v24, v24
	v_lshlrev_b32_e32 v48, 16, v53
	v_and_b32_e32 v49, 0xffff0000, v53
	v_add_f32_e32 v18, v18, v19
	v_mul_f32_e32 v19, v33, v33
	v_pk_fma_f32 v[30:31], v[20:21], 0.5, v[48:49] op_sel_hi:[1,0,1]
	v_fmac_f32_e32 v19, v32, v32
	v_add_f32_e32 v18, v19, v18
	v_mul_f32_e32 v19, v31, v31
	v_fmac_f32_e32 v19, v30, v30
	v_add_f32_e32 v18, v19, v18
	v_add_f32_e32 v21, v54, v18
	ds_bpermute_b32 v46, v166, v21
	v_or_b32_e32 v42, 32, v74
	v_ashrrev_i32_e32 v43, 31, v42
	v_lshlrev_b64 v[44:45], 11, v[42:43]
	v_lshl_add_u64 v[18:19], s[34:35], 0, v[44:45]
	v_lshl_add_u64 v[44:45], v[154:155], 1, v[18:19]
	s_waitcnt lgkmcnt(0)
	v_add_f32_e32 v18, v21, v46
	ds_bpermute_b32 v19, v124, v18
	v_cvt_pk_bf16_f32 v20, v22, v23
	v_cvt_pk_bf16_f32 v21, v24, v25
	v_cvt_pk_bf16_f32 v22, v32, v33
	v_cvt_pk_bf16_f32 v23, v30, v31
	global_store_dwordx4 v[44:45], v[26:29], off sc1
	global_store_dwordx4 v[44:45], v[20:23], off offset:256 sc1
	s_and_saveexec_b64 s[24:25], s[0:1]
	s_cbranch_execz .LBB0_988
	v_lshlrev_b64 v[20:21], 6, v[42:43]
	v_lshl_add_u64 v[20:21], s[74:75], 0, v[20:21]
	v_lshl_add_u64 v[20:21], s[22:23], 2, v[20:21]
	s_lshl_b32 s8, s43, 2
	v_lshl_add_u64 v[20:21], v[20:21], 0, s[8:9]
	s_waitcnt lgkmcnt(0)
	v_add_f32_e32 v18, v18, v19
	global_store_dword v[20:21], v18, off sc1
.LBB0_988:
	s_or_b64 exec, exec, s[24:25]
	s_waitcnt vmcnt(3)
	v_lshlrev_b32_e32 v22, 16, v38
	v_and_b32_e32 v23, 0xffff0000, v38
	v_lshlrev_b32_e32 v24, 16, v39
	v_and_b32_e32 v25, 0xffff0000, v39
	v_lshlrev_b32_e32 v26, 16, v40
	v_and_b32_e32 v27, 0xffff0000, v40
	v_lshlrev_b32_e32 v28, 16, v41
	v_and_b32_e32 v29, 0xffff0000, v41
	v_pk_fma_f32 v[16:17], v[16:17], 0.5, v[24:25] op_sel_hi:[1,0,1]
	v_pk_fma_f32 v[14:15], v[14:15], 0.5, v[22:23] op_sel_hi:[1,0,1]
	v_pk_fma_f32 v[22:23], v[12:13], 0.5, v[28:29] op_sel_hi:[1,0,1]
	v_pk_fma_f32 v[12:13], v[10:11], 0.5, v[26:27] op_sel_hi:[1,0,1]
	v_mul_f32_e32 v10, v15, v15
	v_mul_f32_e32 v11, v17, v17
	v_fmac_f32_e32 v10, v14, v14
	v_fmac_f32_e32 v11, v16, v16
	v_add_f32_e32 v10, v10, v11
	v_mul_f32_e32 v11, v13, v13
	v_fmac_f32_e32 v11, v12, v12
	v_add_f32_e32 v10, v11, v10
	v_mul_f32_e32 v11, v23, v23
	v_fmac_f32_e32 v11, v22, v22
	v_add_f32_e32 v26, v11, v10
	v_cvt_pk_bf16_f32 v10, v14, v15
	v_cvt_pk_bf16_f32 v11, v16, v17
	s_waitcnt vmcnt(2)
	v_lshlrev_b32_e32 v14, 16, v34
	v_and_b32_e32 v15, 0xffff0000, v34
	v_lshlrev_b32_e32 v16, 16, v35
	v_and_b32_e32 v17, 0xffff0000, v35
	v_cvt_pk_bf16_f32 v12, v12, v13
	v_cvt_pk_bf16_f32 v13, v22, v23
	v_lshlrev_b32_e32 v22, 16, v36
	v_and_b32_e32 v23, 0xffff0000, v36
	v_pk_fma_f32 v[8:9], v[8:9], 0.5, v[16:17] op_sel_hi:[1,0,1]
	v_pk_fma_f32 v[6:7], v[6:7], 0.5, v[14:15] op_sel_hi:[1,0,1]
	v_pk_fma_f32 v[16:17], v[2:3], 0.5, v[22:23] op_sel_hi:[1,0,1]
	v_mul_f32_e32 v2, v7, v7
	v_mul_f32_e32 v3, v9, v9
	v_fmac_f32_e32 v2, v6, v6
	v_fmac_f32_e32 v3, v8, v8
	v_lshlrev_b32_e32 v24, 16, v37
	v_and_b32_e32 v25, 0xffff0000, v37
	v_add_f32_e32 v2, v2, v3
	v_mul_f32_e32 v3, v17, v17
	v_pk_fma_f32 v[14:15], v[4:5], 0.5, v[24:25] op_sel_hi:[1,0,1]
	v_fmac_f32_e32 v3, v16, v16
	v_add_f32_e32 v2, v3, v2
	v_mul_f32_e32 v3, v15, v15
	v_fmac_f32_e32 v3, v14, v14
	v_add_f32_e32 v2, v3, v2
	v_add_f32_e32 v5, v26, v2
	ds_bpermute_b32 v22, v166, v5
	v_or_b32_e32 v18, 48, v74
	s_waitcnt lgkmcnt(1)
	v_ashrrev_i32_e32 v19, 31, v18
	v_lshlrev_b64 v[20:21], 11, v[18:19]
	v_lshl_add_u64 v[2:3], s[34:35], 0, v[20:21]
	v_lshl_add_u64 v[20:21], v[154:155], 1, v[2:3]
	s_waitcnt lgkmcnt(0)
	v_add_f32_e32 v2, v5, v22
	ds_bpermute_b32 v3, v124, v2
	v_cvt_pk_bf16_f32 v4, v6, v7
	v_cvt_pk_bf16_f32 v5, v8, v9
	v_cvt_pk_bf16_f32 v6, v16, v17
	v_cvt_pk_bf16_f32 v7, v14, v15
	global_store_dwordx4 v[20:21], v[10:13], off sc1
	global_store_dwordx4 v[20:21], v[4:7], off offset:256 sc1
	s_and_saveexec_b64 s[24:25], s[0:1]
	s_cbranch_execz .LBB0_990
	v_lshlrev_b64 v[4:5], 6, v[18:19]
	v_lshl_add_u64 v[4:5], s[74:75], 0, v[4:5]
	v_lshl_add_u64 v[4:5], s[22:23], 2, v[4:5]
	s_lshl_b32 s8, s43, 2
	v_lshl_add_u64 v[4:5], v[4:5], 0, s[8:9]
	s_waitcnt lgkmcnt(0)
	v_add_f32_e32 v2, v2, v3
	global_store_dword v[4:5], v2, off sc1

; __device__ __forceinline__ float bflo(unsigned w) { return __uint_as_float(w << 16); }
; __device__ __forceinline__ float bfhi(unsigned w) { return __uint_as_float(w & 0xffff0000u); }
; __device__ __forceinline__ float rstd_from(const float* st, int row, int np, float inv_dim) {
;     float s = 0.f;
;     if (np == 1) s = st[(size_t)row * 16];
;     else { const f32x4* p = (const f32x4*)(st + (size_t)row * 16);
; #pragma unroll 4
;         for (int i = 0; i < np / 4; ++i) { const f32x4 v = p[i]; s += (v[0] + v[1]) + (v[2] + v[3]); } }
;     return __builtin_amdgcn_rsqf(s * inv_dim + EPS);
; }
; __global__ void __launch_bounds__(512, 2) fwd_megakernel(Params P) {
;     ...
;     if (IN(10)) {
;         const float* fn = P.in[25];
;         f32x4 gv[4];
; #pragma unroll
;         for (int j = 0; j < 4; ++j) gv[j] = ((const f32x4*)fn)[lane + 64 * j];
;         for (int m = vcu * 8 + wave; m < MT; m += G * 16) {
;             const int m1 = m + G * 8; const bool has1 = m1 < MT; const int mb = has1 ? m1 : m;
;             const float rs0 = rstd_from(STA, m, 16, 1.0f / 1024.0f), rs1 = rstd_from(STA, mb, 16, 1.0f / 1024.0f);
;             const u32x2* s0 = (const u32x2*)(XB + (size_t)m * DM) + lane; const u32x2* s1 = (const u32x2*)(XB + (size_t)mb * DM) + lane;
;             u32x2 v0[4], v1[4];
; #pragma unroll
;             for (int j = 0; j < 4; ++j) { v0[j] = s0[64 * j]; v1[j] = s1[64 * j]; }
;             f32x4* x40 = (f32x4*)(P.out + (size_t)m * DM) + lane; f32x4* x41 = (f32x4*)(P.out + (size_t)mb * DM) + lane;
; #pragma unroll
;             for (int j = 0; j < 4; ++j) x40[64 * j] = (f32x4){bflo(v0[j].x), bfhi(v0[j].x), bflo(v0[j].y), bfhi(v0[j].y)} * gv[j] * rs0;
;             if (has1) {
; #pragma unroll
;                 for (int j = 0; j < 4; ++j) x41[64 * j] = (f32x4){bflo(v1[j].x), bfhi(v1[j].x), bflo(v1[j].y), bfhi(v1[j].y)} * gv[j] * rs1;
;             }
;         }
;     }
.LBB0_1062:
	s_add_i32 s5, s2, s4
	s_cmp_lt_i32 s5, 0xc000
	s_cselect_b32 s0, s5, s2
	s_ashr_i32 s3, s2, 31
	s_lshl_b64 s[6:7], s[2:3], 6
	s_add_u32 s6, s74, s6
	s_addc_u32 s7, s75, s7
	global_load_dwordx4 v[46:49], v33, s[6:7]
	global_load_dwordx4 v[50:53], v33, s[6:7] offset:16
	global_load_dwordx4 v[54:57], v33, s[6:7] offset:32
	global_load_dwordx4 v[58:61], v33, s[6:7] offset:48
	s_ashr_i32 s1, s0, 31
	s_lshl_b64 s[6:7], s[0:1], 6
	s_add_u32 s6, s74, s6
	s_addc_u32 s7, s75, s7
	s_lshl_b64 s[8:9], s[2:3], 11
	v_lshl_add_u64 v[16:17], v[34:35], 0, s[8:9]
	global_load_dwordx2 v[62:63], v[16:17], off
	global_load_dwordx2 v[64:65], v[16:17], off offset:512
	global_load_dwordx2 v[66:67], v[16:17], off offset:1024
	global_load_dwordx2 v[68:69], v[16:17], off offset:1536
	s_lshl_b64 s[8:9], s[0:1], 11
	v_lshl_add_u64 v[70:71], v[34:35], 0, s[8:9]
	global_load_dwordx4 v[16:19], v33, s[6:7] offset:48
	global_load_dwordx4 v[20:23], v33, s[6:7] offset:32
	global_load_dwordx4 v[24:27], v33, s[6:7] offset:16
	global_load_dwordx4 v[28:31], v33, s[6:7]
	global_load_dwordx2 v[44:45], v[70:71], off
	global_load_dwordx2 v[42:43], v[70:71], off offset:512
	global_load_dwordx2 v[40:41], v[70:71], off offset:1024
	global_load_dwordx2 v[38:39], v[70:71], off offset:1536
	s_lshl_b64 s[2:3], s[2:3], 12
	s_cmp_gt_i32 s5, 0xbfff
	v_lshl_add_u64 v[70:71], v[36:37], 0, s[2:3]
	s_waitcnt vmcnt(0)
	v_mov_b32_e32 v72, v47
	v_mov_b32_e32 v73, v48
	v_mov_b32_e32 v47, v49
	v_mov_b32_e32 v48, v51
	v_mov_b32_e32 v49, v52
	v_mov_b32_e32 v51, v53
	v_add_f32_e32 v52, v54, v55
	v_add_f32_e32 v54, v56, v57
	v_mov_b32_e32 v53, v60
	v_mov_b32_e32 v55, v61
	v_pk_add_f32 v[46:47], v[72:73], v[46:47]
	v_pk_add_f32 v[48:49], v[48:49], v[50:51]
	v_pk_add_f32 v[50:51], v[52:53], v[54:55]
	v_add_f32_e32 v52, v46, v47
	v_pk_add_f32 v[46:47], v[48:49], v[48:49] op_sel:[0,1] op_sel_hi:[1,0]
	v_mov_b32_e32 v57, v58
	v_add_f32_e32 v56, 0, v52
	v_mov_b32_e32 v47, v59
	v_pk_add_f32 v[46:47], v[56:57], v[46:47]
	v_lshlrev_b32_e32 v58, 16, v66
	v_pk_add_f32 v[46:47], v[46:47], v[50:51]
	v_and_b32_e32 v59, 0xffff0000, v66
	v_add_f32_e32 v46, v46, v47
	v_fmamk_f32 v46, v46, 0x3a800000, v32
	v_rsq_f32_e32 v66, v46
	v_lshlrev_b32_e32 v48, 16, v62
	v_and_b32_e32 v49, 0xffff0000, v62
	v_lshlrev_b32_e32 v52, 16, v63
	v_and_b32_e32 v53, 0xffff0000, v63
	v_lshlrev_b32_e32 v54, 16, v64
	v_and_b32_e32 v55, 0xffff0000, v64
	v_lshlrev_b32_e32 v56, 16, v65
	v_and_b32_e32 v57, 0xffff0000, v65
	v_lshlrev_b32_e32 v60, 16, v67
	v_and_b32_e32 v61, 0xffff0000, v67
	v_lshlrev_b32_e32 v62, 16, v68
	v_and_b32_e32 v63, 0xffff0000, v68
	v_lshlrev_b32_e32 v64, 16, v69
	v_and_b32_e32 v65, 0xffff0000, v69
	v_pk_mul_f32 v[50:51], v[0:1], v[48:49]
	v_pk_mul_f32 v[48:49], v[2:3], v[52:53]
	v_pk_mul_f32 v[54:55], v[4:5], v[54:55]
	v_pk_mul_f32 v[52:53], v[6:7], v[56:57]
	v_pk_mul_f32 v[58:59], v[8:9], v[58:59]
	v_pk_mul_f32 v[56:57], v[10:11], v[60:61]
	v_pk_mul_f32 v[62:63], v[12:13], v[62:63]
	v_pk_mul_f32 v[60:61], v[14:15], v[64:65]
	v_pk_mul_f32 v[48:49], v[66:67], v[48:49] op_sel_hi:[0,1]
	v_pk_mul_f32 v[46:47], v[66:67], v[50:51] op_sel_hi:[0,1]
	v_pk_mul_f32 v[52:53], v[66:67], v[52:53] op_sel_hi:[0,1]
	v_pk_mul_f32 v[50:51], v[66:67], v[54:55] op_sel_hi:[0,1]
	v_pk_mul_f32 v[56:57], v[66:67], v[56:57] op_sel_hi:[0,1]
	v_pk_mul_f32 v[54:55], v[66:67], v[58:59] op_sel_hi:[0,1]
	v_pk_mul_f32 v[60:61], v[66:67], v[60:61] op_sel_hi:[0,1]
	v_pk_mul_f32 v[58:59], v[66:67], v[62:63] op_sel_hi:[0,1]
	global_store_dwordx4 v[70:71], v[46:49], off sc1
	global_store_dwordx4 v[70:71], v[50:53], off offset:1024 sc1
	global_store_dwordx4 v[70:71], v[54:57], off offset:2048 sc1
	global_store_dwordx4 v[70:71], v[58:61], off offset:3072 sc1
	s_cbranch_scc1 .LBB0_1061
	v_mov_b32_e32 v48, v29
	v_mov_b32_e32 v49, v30
	v_mov_b32_e32 v29, v31
	v_mov_b32_e32 v30, v25
	v_mov_b32_e32 v31, v26
	v_mov_b32_e32 v25, v27
	v_pk_add_f32 v[28:29], v[48:49], v[28:29]
	v_pk_add_f32 v[24:25], v[30:31], v[24:25]
	v_add_f32_e32 v28, v28, v29
	v_pk_add_f32 v[24:25], v[24:25], v[24:25] op_sel:[0,1] op_sel_hi:[1,0]
	v_add_f32_e32 v28, 0, v28
	v_add_f32_e32 v20, v20, v21
	v_add_f32_e32 v22, v22, v23
	v_mov_b32_e32 v29, v16
	v_mov_b32_e32 v25, v17
	v_mov_b32_e32 v21, v18
	v_mov_b32_e32 v23, v19
	v_pk_add_f32 v[16:17], v[28:29], v[24:25]
	v_pk_add_f32 v[18:19], v[20:21], v[22:23]
	s_lshl_b64 s[0:1], s[0:1], 10
	v_pk_add_f32 v[16:17], v[16:17], v[18:19]
	v_lshlrev_b32_e32 v18, 16, v45
	v_add_f32_e32 v16, v16, v17
	v_fmamk_f32 v16, v16, 0x3a800000, v32
	v_rsq_f32_e32 v20, v16
	v_lshlrev_b32_e32 v16, 16, v44
	v_and_b32_e32 v17, 0xffff0000, v44
	v_and_b32_e32 v19, 0xffff0000, v45
	v_pk_mul_f32 v[16:17], v[0:1], v[16:17]
	v_pk_mul_f32 v[18:19], v[2:3], v[18:19]
	v_lshl_add_u64 v[46:47], s[0:1], 2, v[36:37]
	v_pk_mul_f32 v[18:19], v[20:21], v[18:19] op_sel_hi:[0,1]
	v_pk_mul_f32 v[16:17], v[20:21], v[16:17] op_sel_hi:[0,1]
	global_store_dwordx4 v[46:47], v[16:19], off sc1
	s_nop 1
	v_lshlrev_b32_e32 v16, 16, v42
	v_and_b32_e32 v17, 0xffff0000, v42
	v_lshlrev_b32_e32 v18, 16, v43
	v_and_b32_e32 v19, 0xffff0000, v43
	v_pk_mul_f32 v[16:17], v[4:5], v[16:17]
	v_pk_mul_f32 v[18:19], v[6:7], v[18:19]
	v_pk_mul_f32 v[16:17], v[20:21], v[16:17] op_sel_hi:[0,1]
	v_pk_mul_f32 v[18:19], v[20:21], v[18:19] op_sel_hi:[0,1]
	global_store_dwordx4 v[46:47], v[16:19], off offset:1024 sc1
	s_nop 1
	v_lshlrev_b32_e32 v16, 16, v40
	v_and_b32_e32 v17, 0xffff0000, v40
	v_lshlrev_b32_e32 v18, 16, v41
	v_and_b32_e32 v19, 0xffff0000, v41
	v_pk_mul_f32 v[16:17], v[8:9], v[16:17]
	v_pk_mul_f32 v[18:19], v[10:11], v[18:19]
	v_pk_mul_f32 v[16:17], v[20:21], v[16:17] op_sel_hi:[0,1]
	v_pk_mul_f32 v[18:19], v[20:21], v[18:19] op_sel_hi:[0,1]
	global_store_dwordx4 v[46:47], v[16:19], off offset:2048 sc1
	s_nop 1
	v_lshlrev_b32_e32 v16, 16, v38
	v_and_b32_e32 v17, 0xffff0000, v38
	v_lshlrev_b32_e32 v18, 16, v39
	v_and_b32_e32 v19, 0xffff0000, v39
	v_pk_mul_f32 v[16:17], v[12:13], v[16:17]
	v_pk_mul_f32 v[18:19], v[14:15], v[18:19]
	v_pk_mul_f32 v[16:17], v[20:21], v[16:17] op_sel_hi:[0,1]
	v_pk_mul_f32 v[18:19], v[20:21], v[18:19] op_sel_hi:[0,1]
	global_store_dwordx4 v[46:47], v[16:19], off offset:3072 sc1
	s_branch .LBB0_1061
